# P15 hand-written: K~^T tile stores as full 128-byte rows per channel (eight back-to-back 16-byte stores at the end of the chunk)
# speedup vs baseline: 1.0339x; 1.0066x over previous
; DEV int tidx() { return tidx_full() & 255; }
; #define VBID ((int)blockIdx.x * 2 + vhalf())
; DEV void phase_p15(const Params& p, int g) {
;     ...
;   for (int it = VBID; it < 1024; it += NVB) {
;     const int tid = tidx();
;     const int cidx = it >> 1, dir = it & 1;
;     u16* Qp = QK + (size_t)(2 * dir) * NTOK * 512;
;     u16* Kp = Qp + (size_t)NTOK * 512;
;     float lb[2], G[2];
; #pragma unroll
;     for (int cc = 0; cc < 2; ++cc) {
;       const int c = tid + 256 * cc;
;       const float a0 = p.in[I_LB][(0 * 2 + dir) * 512 + c];
;       const float a1 = p.in[I_LB][(1 * 2 + dir) * 512 + c];
;       lb[cc] = 1.f / (1.f + __expf(a1 - a0));
;       G[cc] = 0.f;
;     }
;     u16 xr[3][2][8], qr[3][2][8];
;     ...
;     P15_LOAD(0, 0);
;     P15_LOAD(1, 1);
.LBB0_617:
	v_readfirstlane_b32 s16, v202
	v_readlane_b32 s19, v251, 62
	v_readlane_b32 s0, v251, 41
	v_readlane_b32 s1, v251, 42
	v_readlane_b32 s2, v252, 19
	v_readlane_b32 s3, v252, 20
	v_readlane_b32 s4, v251, 54
	v_readlane_b32 s5, v251, 55
	v_readlane_b32 s12, v249, 22
	v_readlane_b32 s13, v249, 23
	s_bfe_u32 s17, s16, 0x10008
	s_bfe_u32 s18, s16, 0x20006
	s_lshr_b32 s19, s19, 1
	s_lshr_b32 s8, s18, 1
	s_and_b32 s18, s18, 1
	s_lshl_b32 s8, s8, 8
	s_add_u32 s20, s19, s8
	s_mov_b32 s30, 0x800000
	s_mov_b32 s31, 0x3f317217
	s_mov_b32 s34, 0x7f800000
	v_and_b32_e32 v112, 63, v202
	v_lshlrev_b32_e32 v112, 2, v112
	s_lshl_b32 s8, s18, 8
	v_add_u32_e32 v112, s8, v112
	v_lshlrev_b32_e32 v115, 7, v112
	v_lshlrev_b32_e32 v92, 2, v112
	v_lshlrev_b32_e32 v112, 1, v112
	s_lshl_b32 s8, s17, 10
	s_add_u32 s8, s8, 0x800
	v_add_u32_e32 v113, s8, v112
	v_add_u32_e32 v114, 0x2000000, v112
	s_lshl_b32 s8, s17, 11
	v_add_u32_e32 v93, s8, v92
	v_add_u32_e32 v94, 0x1000, v93
	global_load_dwordx4 v[96:99], v93, s[12:13]
	global_load_dwordx4 v[100:103], v94, s[12:13]
	v_mov_b32_e32 v104, v92
	s_lshl_b32 s8, s17, 9
	s_add_u32 s8, s8, s20
	s_lshl_b32 s8, s8, 11
	s_add_u32 s6, s4, s8
	s_addc_u32 s7, s5, 0
	s_add_u32 s6, s6, 0x3b4c100
	s_addc_u32 s7, s7, 0
	s_lshl_b32 s8, s20, 1
	s_add_u32 s8, s8, s17
	s_lshl_b32 s8, s8, 16
	s_add_u32 s4, s4, s8
	s_addc_u32 s5, s5, 0
	s_add_u32 s4, s4, 0x3d4c100
	s_addc_u32 s5, s5, 0
	s_mul_i32 s8, s17, 0
	s_add_u32 s4, s4, s8
	s_addc_u32 s5, s5, 0
	s_lshl_b32 s8, s20, 6
	s_mul_i32 s9, s17, 63
	s_add_u32 s8, s8, s9
	s_mul_i32 s9, s8, 0x1400
	s_add_u32 s0, s0, s9
	s_addc_u32 s1, s1, 0
	s_lshl_b32 s9, s8, 10
	s_add_u32 s2, s2, s9
	s_addc_u32 s3, s3, 0
	s_lshl_b32 s9, s17, 26
	s_add_u32 s2, s2, s9
	s_addc_u32 s3, s3, 0
	s_waitcnt vmcnt(0)
	v_sub_f32_e32 v92, v100, v96
	v_mul_f32_e32 v92, 0x3fb8aa3b, v92
	v_exp_f32_e32 v92, v92
	s_nop 0
	v_add_f32_e32 v92, 1.0, v92
	v_div_scale_f32 v76, s[8:9], v92, v92, 1.0
	v_rcp_f32_e32 v77, v76
	s_nop 0
	v_fma_f32 v78, -v76, v77, 1.0
	v_fmac_f32_e32 v77, v78, v77
	v_div_scale_f32 v78, vcc, 1.0, v92, 1.0
	v_mul_f32_e32 v79, v78, v77
	v_fma_f32 v80, -v76, v79, v78
	v_fmac_f32_e32 v79, v80, v77
	v_fma_f32 v76, -v76, v79, v78
	v_div_fmas_f32 v76, v76, v77, v79
	v_div_fixup_f32 v68, v76, v92, 1.0
	v_sub_f32_e32 v72, 1.0, v68
	v_mov_b32_e32 v64, 0
	v_sub_f32_e32 v93, v101, v97
	v_mul_f32_e32 v93, 0x3fb8aa3b, v93
	v_exp_f32_e32 v93, v93
	s_nop 0
	v_add_f32_e32 v93, 1.0, v93
	v_div_scale_f32 v76, s[8:9], v93, v93, 1.0
	v_rcp_f32_e32 v77, v76
	s_nop 0
	v_fma_f32 v78, -v76, v77, 1.0
	v_fmac_f32_e32 v77, v78, v77
	v_div_scale_f32 v78, vcc, 1.0, v93, 1.0
	v_mul_f32_e32 v79, v78, v77
	v_fma_f32 v80, -v76, v79, v78
	v_fmac_f32_e32 v79, v80, v77
	v_fma_f32 v76, -v76, v79, v78
	v_div_fmas_f32 v76, v76, v77, v79
	v_div_fixup_f32 v69, v76, v93, 1.0
	v_sub_f32_e32 v73, 1.0, v69
	v_mov_b32_e32 v65, 0
	v_sub_f32_e32 v94, v102, v98
	v_mul_f32_e32 v94, 0x3fb8aa3b, v94
	v_exp_f32_e32 v94, v94
	s_nop 0
	v_add_f32_e32 v94, 1.0, v94
	v_div_scale_f32 v76, s[8:9], v94, v94, 1.0
	v_rcp_f32_e32 v77, v76
	s_nop 0
	v_fma_f32 v78, -v76, v77, 1.0
	v_fmac_f32_e32 v77, v78, v77
	v_div_scale_f32 v78, vcc, 1.0, v94, 1.0
	v_mul_f32_e32 v79, v78, v77
	v_fma_f32 v80, -v76, v79, v78
	v_fmac_f32_e32 v79, v80, v77
	v_fma_f32 v76, -v76, v79, v78
	v_div_fmas_f32 v76, v76, v77, v79
	v_div_fixup_f32 v70, v76, v94, 1.0
	v_sub_f32_e32 v74, 1.0, v70
	v_mov_b32_e32 v66, 0
	v_sub_f32_e32 v95, v103, v99
	v_mul_f32_e32 v95, 0x3fb8aa3b, v95
	v_exp_f32_e32 v95, v95
	s_nop 0
	v_add_f32_e32 v95, 1.0, v95
	v_div_scale_f32 v76, s[8:9], v95, v95, 1.0
	v_rcp_f32_e32 v77, v76
	s_nop 0
	v_fma_f32 v78, -v76, v77, 1.0
	v_fmac_f32_e32 v77, v78, v77
	v_div_scale_f32 v78, vcc, 1.0, v95, 1.0
	v_mul_f32_e32 v79, v78, v77
	v_fma_f32 v80, -v76, v79, v78
	v_fmac_f32_e32 v79, v80, v77
	v_fma_f32 v76, -v76, v79, v78
	v_div_fmas_f32 v76, v76, v77, v79
	v_div_fixup_f32 v71, v76, v95, 1.0
	v_sub_f32_e32 v75, 1.0, v71
	v_mov_b32_e32 v67, 0
	v_mov_b32_e32 v115, v115
	v_mov_b32_e32 v109, v104
	v_mov_b32_e32 v164, v104
	s_cmp_eq_u32 s17, 0
	s_cbranch_scc0 .Lp15_d1
	global_load_dwordx2 v[0:1], v113, s[0:1]
	global_load_dwordx2 v[2:3], v112, s[0:1]
	s_add_u32 s0, s0, 0x1400
	s_addc_u32 s1, s1, 0
	global_load_dwordx2 v[4:5], v113, s[0:1]
	global_load_dwordx2 v[6:7], v112, s[0:1]
	s_add_u32 s0, s0, 0x1400
	s_addc_u32 s1, s1, 0
	global_load_dwordx2 v[8:9], v113, s[0:1]
	global_load_dwordx2 v[10:11], v112, s[0:1]
	s_add_u32 s0, s0, 0x1400
	s_addc_u32 s1, s1, 0
	global_load_dwordx2 v[12:13], v113, s[0:1]
	global_load_dwordx2 v[14:15], v112, s[0:1]
	s_add_u32 s0, s0, 0x1400
	s_addc_u32 s1, s1, 0
	global_load_dwordx2 v[16:17], v113, s[0:1]
	global_load_dwordx2 v[18:19], v112, s[0:1]
	s_add_u32 s0, s0, 0x1400
	s_addc_u32 s1, s1, 0
	global_load_dwordx2 v[20:21], v113, s[0:1]
	global_load_dwordx2 v[22:23], v112, s[0:1]
	s_add_u32 s0, s0, 0x1400
	s_addc_u32 s1, s1, 0
	global_load_dwordx2 v[24:25], v113, s[0:1]
	global_load_dwordx2 v[26:27], v112, s[0:1]
	s_add_u32 s0, s0, 0x1400
	s_addc_u32 s1, s1, 0
	global_load_dwordx2 v[28:29], v113, s[0:1]
	global_load_dwordx2 v[30:31], v112, s[0:1]
	s_add_u32 s0, s0, 0x1400
	s_addc_u32 s1, s1, 0
	global_load_dwordx2 v[32:33], v113, s[0:1]
	global_load_dwordx2 v[34:35], v112, s[0:1]
	s_add_u32 s0, s0, 0x1400
	s_addc_u32 s1, s1, 0
	global_load_dwordx2 v[36:37], v113, s[0:1]
	global_load_dwordx2 v[38:39], v112, s[0:1]
	s_add_u32 s0, s0, 0x1400
	s_addc_u32 s1, s1, 0
	global_load_dwordx2 v[40:41], v113, s[0:1]
	global_load_dwordx2 v[42:43], v112, s[0:1]
	s_add_u32 s0, s0, 0x1400
	s_addc_u32 s1, s1, 0
	global_load_dwordx2 v[44:45], v113, s[0:1]
	global_load_dwordx2 v[46:47], v112, s[0:1]
	s_add_u32 s0, s0, 0x1400
	s_addc_u32 s1, s1, 0
	global_load_dwordx2 v[48:49], v113, s[0:1]
	global_load_dwordx2 v[50:51], v112, s[0:1]
	s_add_u32 s0, s0, 0x1400
	s_addc_u32 s1, s1, 0
	global_load_dwordx2 v[52:53], v113, s[0:1]
	global_load_dwordx2 v[54:55], v112, s[0:1]
	s_add_u32 s0, s0, 0x1400
	s_addc_u32 s1, s1, 0
	global_load_dwordx2 v[56:57], v113, s[0:1]
	global_load_dwordx2 v[58:59], v112, s[0:1]
	s_add_u32 s0, s0, 0x1400
	s_addc_u32 s1, s1, 0
	global_load_dwordx2 v[60:61], v113, s[0:1]
	global_load_dwordx2 v[62:63], v112, s[0:1]
	s_add_u32 s0, s0, 0x1400
	s_addc_u32 s1, s1, 0
	s_mov_b32 s35, 0
	s_waitcnt vmcnt(16)
; DEV u16 f2bf(float f) { return (u16)(pack2(f, f) & 0xffffu); }
; DEV float bf2f(u16 h) { return __uint_as_float(((unsigned)h) << 16); }
; DEV float sigmoid_f(float x) { return __builtin_amdgcn_rcpf(1.f + __expf(-x)); }
; DEV void phase_p15(const Params& p, int g) {
;     ...
;     for (int j8 = 0; j8 < 8; ++j8) {
;       const int st = j8 % 3;
;       if (j8 < 6) { P15_LOAD((j8 + 2) % 3, j8 + 2); }
; #pragma unroll
;       for (int cc = 0; cc < 2; ++cc) {
;         const int c = tid + 256 * cc;
;         unsigned kb[8];
; #pragma unroll
;         for (int e = 0; e < 8; ++e) {
;           const int jj = j8 * 8 + e;
;           const int j = dir ? 63 - jj : jj;
;           const size_t tok = (size_t)cidx * 64 + j;
;           const float f = lb[cc] + (1.f - lb[cc]) * sigmoid_f(bf2f(xr[st][cc][e]));
;           G[cc] += __logf(f);
;           const float eg = __expf(G[cc]), ig = __expf(-G[cc]);
;           Qp[tok * 512 + c] = f2bf(bf2f(qr[st][cc][e]) * eg);
;           const u16 kk = f2bf((1.f - f) * ig);
;           Kp[tok * 512 + c] = kk;
;           kb[e] = kk;
;         }
;         const int s0 = dir ? 56 - 8 * j8 : 8 * j8;
;         uint4 w;
;         w.x = dir ? (kb[7] | (kb[6] << 16)) : (kb[0] | (kb[1] << 16));
;         w.y = dir ? (kb[5] | (kb[4] << 16)) : (kb[2] | (kb[3] << 16));
;         w.z = dir ? (kb[3] | (kb[2] << 16)) : (kb[4] | (kb[5] << 16));
;         w.w = dir ? (kb[1] | (kb[0] << 16)) : (kb[6] | (kb[7] << 16));
;         *(uint4*)(KT + (((size_t)cidx * 2 + dir) * 512 + c) * 64 + s0) = w;
;       }
.Lp15_d0_loop:
	s_waitcnt vmcnt(32)
	v_lshlrev_b32_e32 v92, 16, v0
	v_and_b32_e32 v93, 0xffff0000, v0
	v_lshlrev_b32_e32 v94, 16, v1
	v_and_b32_e32 v95, 0xffff0000, v1
	v_mul_f32_e32 v92, 0xbfb8aa3b, v92
	v_mul_f32_e32 v93, 0xbfb8aa3b, v93
	v_mul_f32_e32 v94, 0xbfb8aa3b, v94
	v_mul_f32_e32 v95, 0xbfb8aa3b, v95
	v_exp_f32_e32 v92, v92
	v_exp_f32_e32 v93, v93
	v_exp_f32_e32 v94, v94
	v_exp_f32_e32 v95, v95
	v_add_f32_e32 v92, 1.0, v92
	v_add_f32_e32 v93, 1.0, v93
	v_add_f32_e32 v94, 1.0, v94
	v_add_f32_e32 v95, 1.0, v95
	v_rcp_f32_e32 v92, v92
	v_rcp_f32_e32 v93, v93
	v_rcp_f32_e32 v94, v94
	v_rcp_f32_e32 v95, v95
	v_fma_f32 v96, v72, v92, v68
	v_fma_f32 v97, v73, v93, v69
	v_fma_f32 v98, v74, v94, v70
	v_fma_f32 v99, v75, v95, v71
	v_cmp_gt_f32_e64 s[22:23], s30, v96
	v_cmp_gt_f32_e64 s[24:25], s30, v97
	v_cmp_gt_f32_e64 s[26:27], s30, v98
	v_cmp_gt_f32_e64 s[28:29], s30, v99
	v_cndmask_b32_e64 v92, 0, 32, s[22:23]
	v_cndmask_b32_e64 v93, 0, 32, s[24:25]
	v_cndmask_b32_e64 v94, 0, 32, s[26:27]
	v_cndmask_b32_e64 v95, 0, 32, s[28:29]
	v_ldexp_f32 v92, v96, v92
	v_ldexp_f32 v93, v97, v93
	v_ldexp_f32 v94, v98, v94
	v_ldexp_f32 v95, v99, v95
	v_log_f32_e32 v92, v92
	v_log_f32_e32 v93, v93
	v_log_f32_e32 v94, v94
	v_log_f32_e32 v95, v95
	v_mul_f32_e32 v100, 0x3f317217, v92
	v_mul_f32_e32 v101, 0x3f317217, v93
	v_mul_f32_e32 v102, 0x3f317217, v94
	v_mul_f32_e32 v103, 0x3f317217, v95
	v_fma_f32 v100, v92, s31, -v100
	v_fma_f32 v101, v93, s31, -v101
	v_fma_f32 v102, v94, s31, -v102
	v_fma_f32 v103, v95, s31, -v103
	v_fmac_f32_e32 v100, 0x3377d1cf, v92
	v_fmac_f32_e32 v101, 0x3377d1cf, v93
	v_fmac_f32_e32 v102, 0x3377d1cf, v94
	v_fmac_f32_e32 v103, 0x3377d1cf, v95
	v_fmac_f32_e32 v100, 0x3f317217, v92
	v_fmac_f32_e32 v101, 0x3f317217, v93
	v_fmac_f32_e32 v102, 0x3f317217, v94
	v_fmac_f32_e32 v103, 0x3f317217, v95
	v_cmp_lt_f32_e64 vcc, |v92|, s34
	v_cndmask_b32_e32 v92, v92, v100, vcc
	v_cmp_lt_f32_e64 vcc, |v93|, s34
	v_cndmask_b32_e32 v93, v93, v101, vcc
	v_cmp_lt_f32_e64 vcc, |v94|, s34
	v_cndmask_b32_e32 v94, v94, v102, vcc
	v_cmp_lt_f32_e64 vcc, |v95|, s34
	v_cndmask_b32_e32 v95, v95, v103, vcc
	v_cndmask_b32_e64 v100, 0, v213, s[22:23]
	v_cndmask_b32_e64 v101, 0, v213, s[24:25]
	v_cndmask_b32_e64 v102, 0, v213, s[26:27]
	v_cndmask_b32_e64 v103, 0, v213, s[28:29]
	v_sub_f32_e32 v92, v92, v100
	v_sub_f32_e32 v93, v93, v101
	v_sub_f32_e32 v94, v94, v102
	v_sub_f32_e32 v95, v95, v103
	v_add_f32_e32 v64, v64, v92
	v_add_f32_e32 v65, v65, v93
	v_add_f32_e32 v66, v66, v94
	v_add_f32_e32 v67, v67, v95
	v_mul_f32_e32 v92, 0xbfb8aa3b, v64
	v_mul_f32_e32 v93, 0xbfb8aa3b, v65
	v_mul_f32_e32 v94, 0xbfb8aa3b, v66
	v_mul_f32_e32 v95, 0xbfb8aa3b, v67
	v_mul_f32_e32 v100, 0x3fb8aa3b, v64
	v_mul_f32_e32 v101, 0x3fb8aa3b, v65
	v_mul_f32_e32 v102, 0x3fb8aa3b, v66
	v_mul_f32_e32 v103, 0x3fb8aa3b, v67
	v_exp_f32_e32 v92, v92
	v_exp_f32_e32 v93, v93
	v_exp_f32_e32 v94, v94
	v_exp_f32_e32 v95, v95
	v_exp_f32_e32 v100, v100
	v_exp_f32_e32 v101, v101
	v_exp_f32_e32 v102, v102
	v_exp_f32_e32 v103, v103
	v_sub_f32_e32 v96, 1.0, v96
	v_sub_f32_e32 v97, 1.0, v97
	v_sub_f32_e32 v98, 1.0, v98
	v_sub_f32_e32 v99, 1.0, v99
	v_mul_f32_e32 v96, v96, v92
	v_mul_f32_e32 v97, v97, v93
	v_mul_f32_e32 v98, v98, v94
	v_mul_f32_e32 v99, v99, v95
	v_lshlrev_b32_e32 v92, 16, v2
	v_and_b32_e32 v93, 0xffff0000, v2
	v_lshlrev_b32_e32 v94, 16, v3
	v_and_b32_e32 v95, 0xffff0000, v3
	v_mul_f32_e32 v92, v92, v100
	v_mul_f32_e32 v93, v93, v101
	v_mul_f32_e32 v94, v94, v102
	v_mul_f32_e32 v95, v95, v103
	v_mov_b32_e32 v116, v96
	v_mov_b32_e32 v132, v97
	v_mov_b32_e32 v166, v98
	v_mov_b32_e32 v182, v99
	v_cvt_pk_bf16_f32 v92, v92, v93
	v_cvt_pk_bf16_f32 v93, v94, v95
	v_cvt_pk_bf16_f32 v96, v96, v97
	v_cvt_pk_bf16_f32 v97, v98, v99
	global_store_dwordx2 v112, v[92:93], s[2:3]
	global_store_dwordx2 v114, v[96:97], s[2:3]
	s_add_u32 s2, s2, 0x400
	s_addc_u32 s3, s3, 0
	v_lshlrev_b32_e32 v92, 16, v4
	v_and_b32_e32 v93, 0xffff0000, v4
	v_lshlrev_b32_e32 v94, 16, v5
	v_and_b32_e32 v95, 0xffff0000, v5
	v_mul_f32_e32 v92, 0xbfb8aa3b, v92
	v_mul_f32_e32 v93, 0xbfb8aa3b, v93
	v_mul_f32_e32 v94, 0xbfb8aa3b, v94
	v_mul_f32_e32 v95, 0xbfb8aa3b, v95
	v_exp_f32_e32 v92, v92
	v_exp_f32_e32 v93, v93
	v_exp_f32_e32 v94, v94
	v_exp_f32_e32 v95, v95
	v_add_f32_e32 v92, 1.0, v92
	v_add_f32_e32 v93, 1.0, v93
	v_add_f32_e32 v94, 1.0, v94
	v_add_f32_e32 v95, 1.0, v95
	v_rcp_f32_e32 v92, v92
	v_rcp_f32_e32 v93, v93
	v_rcp_f32_e32 v94, v94
	v_rcp_f32_e32 v95, v95
	v_fma_f32 v96, v72, v92, v68
	v_fma_f32 v97, v73, v93, v69
	v_fma_f32 v98, v74, v94, v70
	v_fma_f32 v99, v75, v95, v71
	v_cmp_gt_f32_e64 s[22:23], s30, v96
	v_cmp_gt_f32_e64 s[24:25], s30, v97
	v_cmp_gt_f32_e64 s[26:27], s30, v98
	v_cmp_gt_f32_e64 s[28:29], s30, v99
	v_cndmask_b32_e64 v92, 0, 32, s[22:23]
	v_cndmask_b32_e64 v93, 0, 32, s[24:25]
	v_cndmask_b32_e64 v94, 0, 32, s[26:27]
	v_cndmask_b32_e64 v95, 0, 32, s[28:29]
	v_ldexp_f32 v92, v96, v92
	v_ldexp_f32 v93, v97, v93
	v_ldexp_f32 v94, v98, v94
	v_ldexp_f32 v95, v99, v95
	v_log_f32_e32 v92, v92
	v_log_f32_e32 v93, v93
	v_log_f32_e32 v94, v94
	v_log_f32_e32 v95, v95
	v_mul_f32_e32 v100, 0x3f317217, v92
	v_mul_f32_e32 v101, 0x3f317217, v93
	v_mul_f32_e32 v102, 0x3f317217, v94
	v_mul_f32_e32 v103, 0x3f317217, v95
	v_fma_f32 v100, v92, s31, -v100
	v_fma_f32 v101, v93, s31, -v101
	v_fma_f32 v102, v94, s31, -v102
	v_fma_f32 v103, v95, s31, -v103
	v_fmac_f32_e32 v100, 0x3377d1cf, v92
	v_fmac_f32_e32 v101, 0x3377d1cf, v93
	v_fmac_f32_e32 v102, 0x3377d1cf, v94
	v_fmac_f32_e32 v103, 0x3377d1cf, v95
	v_fmac_f32_e32 v100, 0x3f317217, v92
	v_fmac_f32_e32 v101, 0x3f317217, v93
	v_fmac_f32_e32 v102, 0x3f317217, v94
; DEV u16 f2bf(float f) { return (u16)(pack2(f, f) & 0xffffu); }
; DEV float bf2f(u16 h) { return __uint_as_float(((unsigned)h) << 16); }
; DEV float sigmoid_f(float x) { return __builtin_amdgcn_rcpf(1.f + __expf(-x)); }
; DEV void phase_p15(const Params& p, int g) {
;     ...
;     for (int j8 = 0; j8 < 8; ++j8) {
;       const int st = j8 % 3;
;       if (j8 < 6) { P15_LOAD((j8 + 2) % 3, j8 + 2); }
; #pragma unroll
;       for (int cc = 0; cc < 2; ++cc) {
;         const int c = tid + 256 * cc;
;         unsigned kb[8];
; #pragma unroll
;         for (int e = 0; e < 8; ++e) {
;           const int jj = j8 * 8 + e;
;           const int j = dir ? 63 - jj : jj;
;           const size_t tok = (size_t)cidx * 64 + j;
;           const float f = lb[cc] + (1.f - lb[cc]) * sigmoid_f(bf2f(xr[st][cc][e]));
;           G[cc] += __logf(f);
;           const float eg = __expf(G[cc]), ig = __expf(-G[cc]);
;           Qp[tok * 512 + c] = f2bf(bf2f(qr[st][cc][e]) * eg);
;           const u16 kk = f2bf((1.f - f) * ig);
;           Kp[tok * 512 + c] = kk;
;           kb[e] = kk;
;         }
;         const int s0 = dir ? 56 - 8 * j8 : 8 * j8;
;         uint4 w;
;         w.x = dir ? (kb[7] | (kb[6] << 16)) : (kb[0] | (kb[1] << 16));
;         w.y = dir ? (kb[5] | (kb[4] << 16)) : (kb[2] | (kb[3] << 16));
;         w.z = dir ? (kb[3] | (kb[2] << 16)) : (kb[4] | (kb[5] << 16));
;         w.w = dir ? (kb[1] | (kb[0] << 16)) : (kb[6] | (kb[7] << 16));
;         *(uint4*)(KT + (((size_t)cidx * 2 + dir) * 512 + c) * 64 + s0) = w;
;       }
	v_fmac_f32_e32 v103, 0x3f317217, v95
	v_cmp_lt_f32_e64 vcc, |v92|, s34
	v_cndmask_b32_e32 v92, v92, v100, vcc
	v_cmp_lt_f32_e64 vcc, |v93|, s34
	v_cndmask_b32_e32 v93, v93, v101, vcc
	v_cmp_lt_f32_e64 vcc, |v94|, s34
	v_cndmask_b32_e32 v94, v94, v102, vcc
	v_cmp_lt_f32_e64 vcc, |v95|, s34
	v_cndmask_b32_e32 v95, v95, v103, vcc
	v_cndmask_b32_e64 v100, 0, v213, s[22:23]
	v_cndmask_b32_e64 v101, 0, v213, s[24:25]
	v_cndmask_b32_e64 v102, 0, v213, s[26:27]
	v_cndmask_b32_e64 v103, 0, v213, s[28:29]
	v_sub_f32_e32 v92, v92, v100
	v_sub_f32_e32 v93, v93, v101
	v_sub_f32_e32 v94, v94, v102
	v_sub_f32_e32 v95, v95, v103
	v_add_f32_e32 v64, v64, v92
	v_add_f32_e32 v65, v65, v93
	v_add_f32_e32 v66, v66, v94
	v_add_f32_e32 v67, v67, v95
	v_mul_f32_e32 v92, 0xbfb8aa3b, v64
	v_mul_f32_e32 v93, 0xbfb8aa3b, v65
	v_mul_f32_e32 v94, 0xbfb8aa3b, v66
	v_mul_f32_e32 v95, 0xbfb8aa3b, v67
	v_mul_f32_e32 v100, 0x3fb8aa3b, v64
	v_mul_f32_e32 v101, 0x3fb8aa3b, v65
	v_mul_f32_e32 v102, 0x3fb8aa3b, v66
	v_mul_f32_e32 v103, 0x3fb8aa3b, v67
	v_exp_f32_e32 v92, v92
	v_exp_f32_e32 v93, v93
	v_exp_f32_e32 v94, v94
	v_exp_f32_e32 v95, v95
	v_exp_f32_e32 v100, v100
	v_exp_f32_e32 v101, v101
	v_exp_f32_e32 v102, v102
	v_exp_f32_e32 v103, v103
	v_sub_f32_e32 v96, 1.0, v96
	v_sub_f32_e32 v97, 1.0, v97
	v_sub_f32_e32 v98, 1.0, v98
	v_sub_f32_e32 v99, 1.0, v99
	v_mul_f32_e32 v96, v96, v92
	v_mul_f32_e32 v97, v97, v93
	v_mul_f32_e32 v98, v98, v94
	v_mul_f32_e32 v99, v99, v95
	v_lshlrev_b32_e32 v92, 16, v6
	v_and_b32_e32 v93, 0xffff0000, v6
	v_lshlrev_b32_e32 v94, 16, v7
	v_and_b32_e32 v95, 0xffff0000, v7
	v_mul_f32_e32 v92, v92, v100
	v_mul_f32_e32 v93, v93, v101
	v_mul_f32_e32 v94, v94, v102
	v_mul_f32_e32 v95, v95, v103
	v_cvt_pk_bf16_f32 v116, v116, v96
	v_cvt_pk_bf16_f32 v132, v132, v97
	v_cvt_pk_bf16_f32 v166, v166, v98
	v_cvt_pk_bf16_f32 v182, v182, v99
	v_cvt_pk_bf16_f32 v92, v92, v93
	v_cvt_pk_bf16_f32 v93, v94, v95
	v_cvt_pk_bf16_f32 v96, v96, v97
	v_cvt_pk_bf16_f32 v97, v98, v99
	global_store_dwordx2 v112, v[92:93], s[2:3]
	global_store_dwordx2 v114, v[96:97], s[2:3]
	s_add_u32 s2, s2, 0x400
	s_addc_u32 s3, s3, 0
	v_lshlrev_b32_e32 v92, 16, v8
	v_and_b32_e32 v93, 0xffff0000, v8
	v_lshlrev_b32_e32 v94, 16, v9
	v_and_b32_e32 v95, 0xffff0000, v9
	v_mul_f32_e32 v92, 0xbfb8aa3b, v92
	v_mul_f32_e32 v93, 0xbfb8aa3b, v93
	v_mul_f32_e32 v94, 0xbfb8aa3b, v94
	v_mul_f32_e32 v95, 0xbfb8aa3b, v95
	v_exp_f32_e32 v92, v92
	v_exp_f32_e32 v93, v93
	v_exp_f32_e32 v94, v94
	v_exp_f32_e32 v95, v95
	v_add_f32_e32 v92, 1.0, v92
	v_add_f32_e32 v93, 1.0, v93
	v_add_f32_e32 v94, 1.0, v94
	v_add_f32_e32 v95, 1.0, v95
	v_rcp_f32_e32 v92, v92
	v_rcp_f32_e32 v93, v93
	v_rcp_f32_e32 v94, v94
	v_rcp_f32_e32 v95, v95
	v_fma_f32 v96, v72, v92, v68
	v_fma_f32 v97, v73, v93, v69
	v_fma_f32 v98, v74, v94, v70
	v_fma_f32 v99, v75, v95, v71
	v_cmp_gt_f32_e64 s[22:23], s30, v96
	v_cmp_gt_f32_e64 s[24:25], s30, v97
	v_cmp_gt_f32_e64 s[26:27], s30, v98
	v_cmp_gt_f32_e64 s[28:29], s30, v99
	v_cndmask_b32_e64 v92, 0, 32, s[22:23]
	v_cndmask_b32_e64 v93, 0, 32, s[24:25]
	v_cndmask_b32_e64 v94, 0, 32, s[26:27]
	v_cndmask_b32_e64 v95, 0, 32, s[28:29]
	v_ldexp_f32 v92, v96, v92
	v_ldexp_f32 v93, v97, v93
	v_ldexp_f32 v94, v98, v94
	v_ldexp_f32 v95, v99, v95
	v_log_f32_e32 v92, v92
	v_log_f32_e32 v93, v93
	v_log_f32_e32 v94, v94
	v_log_f32_e32 v95, v95
	v_mul_f32_e32 v100, 0x3f317217, v92
	v_mul_f32_e32 v101, 0x3f317217, v93
	v_mul_f32_e32 v102, 0x3f317217, v94
	v_mul_f32_e32 v103, 0x3f317217, v95
	v_fma_f32 v100, v92, s31, -v100
	v_fma_f32 v101, v93, s31, -v101
	v_fma_f32 v102, v94, s31, -v102
	v_fma_f32 v103, v95, s31, -v103
	v_fmac_f32_e32 v100, 0x3377d1cf, v92
	v_fmac_f32_e32 v101, 0x3377d1cf, v93
	v_fmac_f32_e32 v102, 0x3377d1cf, v94
	v_fmac_f32_e32 v103, 0x3377d1cf, v95
	v_fmac_f32_e32 v100, 0x3f317217, v92
	v_fmac_f32_e32 v101, 0x3f317217, v93
	v_fmac_f32_e32 v102, 0x3f317217, v94
	v_fmac_f32_e32 v103, 0x3f317217, v95
	v_cmp_lt_f32_e64 vcc, |v92|, s34
	v_cndmask_b32_e32 v92, v92, v100, vcc
	v_cmp_lt_f32_e64 vcc, |v93|, s34
	v_cndmask_b32_e32 v93, v93, v101, vcc
	v_cmp_lt_f32_e64 vcc, |v94|, s34
	v_cndmask_b32_e32 v94, v94, v102, vcc
	v_cmp_lt_f32_e64 vcc, |v95|, s34
	v_cndmask_b32_e32 v95, v95, v103, vcc
	v_cndmask_b32_e64 v100, 0, v213, s[22:23]
	v_cndmask_b32_e64 v101, 0, v213, s[24:25]
	v_cndmask_b32_e64 v102, 0, v213, s[26:27]
	v_cndmask_b32_e64 v103, 0, v213, s[28:29]
	v_sub_f32_e32 v92, v92, v100
	v_sub_f32_e32 v93, v93, v101
	v_sub_f32_e32 v94, v94, v102
	v_sub_f32_e32 v95, v95, v103
	v_add_f32_e32 v64, v64, v92
	v_add_f32_e32 v65, v65, v93
	v_add_f32_e32 v66, v66, v94
	v_add_f32_e32 v67, v67, v95
	v_mul_f32_e32 v92, 0xbfb8aa3b, v64
	v_mul_f32_e32 v93, 0xbfb8aa3b, v65
	v_mul_f32_e32 v94, 0xbfb8aa3b, v66
	v_mul_f32_e32 v95, 0xbfb8aa3b, v67
	v_mul_f32_e32 v100, 0x3fb8aa3b, v64
	v_mul_f32_e32 v101, 0x3fb8aa3b, v65
	v_mul_f32_e32 v102, 0x3fb8aa3b, v66
	v_mul_f32_e32 v103, 0x3fb8aa3b, v67
	v_exp_f32_e32 v92, v92
	v_exp_f32_e32 v93, v93
	v_exp_f32_e32 v94, v94
	v_exp_f32_e32 v95, v95
	v_exp_f32_e32 v100, v100
	v_exp_f32_e32 v101, v101
	v_exp_f32_e32 v102, v102
	v_exp_f32_e32 v103, v103
	v_sub_f32_e32 v96, 1.0, v96
	v_sub_f32_e32 v97, 1.0, v97
	v_sub_f32_e32 v98, 1.0, v98
	v_sub_f32_e32 v99, 1.0, v99
	v_mul_f32_e32 v96, v96, v92
	v_mul_f32_e32 v97, v97, v93
	v_mul_f32_e32 v98, v98, v94
	v_mul_f32_e32 v99, v99, v95
	v_lshlrev_b32_e32 v92, 16, v10
	v_and_b32_e32 v93, 0xffff0000, v10
	v_lshlrev_b32_e32 v94, 16, v11
	v_and_b32_e32 v95, 0xffff0000, v11
	v_mul_f32_e32 v92, v92, v100
	v_mul_f32_e32 v93, v93, v101
	v_mul_f32_e32 v94, v94, v102
	v_mul_f32_e32 v95, v95, v103
	v_mov_b32_e32 v117, v96
; DEV u16 f2bf(float f) { return (u16)(pack2(f, f) & 0xffffu); }
; DEV float bf2f(u16 h) { return __uint_as_float(((unsigned)h) << 16); }
; DEV float sigmoid_f(float x) { return __builtin_amdgcn_rcpf(1.f + __expf(-x)); }
; DEV void phase_p15(const Params& p, int g) {
;     ...
;     for (int j8 = 0; j8 < 8; ++j8) {
;       const int st = j8 % 3;
;       if (j8 < 6) { P15_LOAD((j8 + 2) % 3, j8 + 2); }
; #pragma unroll
;       for (int cc = 0; cc < 2; ++cc) {
;         const int c = tid + 256 * cc;
;         unsigned kb[8];
; #pragma unroll
;         for (int e = 0; e < 8; ++e) {
;           const int jj = j8 * 8 + e;
;           const int j = dir ? 63 - jj : jj;
;           const size_t tok = (size_t)cidx * 64 + j;
;           const float f = lb[cc] + (1.f - lb[cc]) * sigmoid_f(bf2f(xr[st][cc][e]));
;           G[cc] += __logf(f);
;           const float eg = __expf(G[cc]), ig = __expf(-G[cc]);
;           Qp[tok * 512 + c] = f2bf(bf2f(qr[st][cc][e]) * eg);
;           const u16 kk = f2bf((1.f - f) * ig);
;           Kp[tok * 512 + c] = kk;
;           kb[e] = kk;
;         }
;         const int s0 = dir ? 56 - 8 * j8 : 8 * j8;
;         uint4 w;
;         w.x = dir ? (kb[7] | (kb[6] << 16)) : (kb[0] | (kb[1] << 16));
;         w.y = dir ? (kb[5] | (kb[4] << 16)) : (kb[2] | (kb[3] << 16));
;         w.z = dir ? (kb[3] | (kb[2] << 16)) : (kb[4] | (kb[5] << 16));
;         w.w = dir ? (kb[1] | (kb[0] << 16)) : (kb[6] | (kb[7] << 16));
;         *(uint4*)(KT + (((size_t)cidx * 2 + dir) * 512 + c) * 64 + s0) = w;
;       }
	v_mov_b32_e32 v133, v97
	v_mov_b32_e32 v167, v98
	v_mov_b32_e32 v183, v99
	v_cvt_pk_bf16_f32 v92, v92, v93
	v_cvt_pk_bf16_f32 v93, v94, v95
	v_cvt_pk_bf16_f32 v96, v96, v97
	v_cvt_pk_bf16_f32 v97, v98, v99
	global_store_dwordx2 v112, v[92:93], s[2:3]
	global_store_dwordx2 v114, v[96:97], s[2:3]
	s_add_u32 s2, s2, 0x400
	s_addc_u32 s3, s3, 0
	v_lshlrev_b32_e32 v92, 16, v12
	v_and_b32_e32 v93, 0xffff0000, v12
	v_lshlrev_b32_e32 v94, 16, v13
	v_and_b32_e32 v95, 0xffff0000, v13
	v_mul_f32_e32 v92, 0xbfb8aa3b, v92
	v_mul_f32_e32 v93, 0xbfb8aa3b, v93
	v_mul_f32_e32 v94, 0xbfb8aa3b, v94
	v_mul_f32_e32 v95, 0xbfb8aa3b, v95
	v_exp_f32_e32 v92, v92
	v_exp_f32_e32 v93, v93
	v_exp_f32_e32 v94, v94
	v_exp_f32_e32 v95, v95
	v_add_f32_e32 v92, 1.0, v92
	v_add_f32_e32 v93, 1.0, v93
	v_add_f32_e32 v94, 1.0, v94
	v_add_f32_e32 v95, 1.0, v95
	v_rcp_f32_e32 v92, v92
	v_rcp_f32_e32 v93, v93
	v_rcp_f32_e32 v94, v94
	v_rcp_f32_e32 v95, v95
	v_fma_f32 v96, v72, v92, v68
	v_fma_f32 v97, v73, v93, v69
	v_fma_f32 v98, v74, v94, v70
	v_fma_f32 v99, v75, v95, v71
	v_cmp_gt_f32_e64 s[22:23], s30, v96
	v_cmp_gt_f32_e64 s[24:25], s30, v97
	v_cmp_gt_f32_e64 s[26:27], s30, v98
	v_cmp_gt_f32_e64 s[28:29], s30, v99
	v_cndmask_b32_e64 v92, 0, 32, s[22:23]
	v_cndmask_b32_e64 v93, 0, 32, s[24:25]
	v_cndmask_b32_e64 v94, 0, 32, s[26:27]
	v_cndmask_b32_e64 v95, 0, 32, s[28:29]
	v_ldexp_f32 v92, v96, v92
	v_ldexp_f32 v93, v97, v93
	v_ldexp_f32 v94, v98, v94
	v_ldexp_f32 v95, v99, v95
	v_log_f32_e32 v92, v92
	v_log_f32_e32 v93, v93
	v_log_f32_e32 v94, v94
	v_log_f32_e32 v95, v95
	v_mul_f32_e32 v100, 0x3f317217, v92
	v_mul_f32_e32 v101, 0x3f317217, v93
	v_mul_f32_e32 v102, 0x3f317217, v94
	v_mul_f32_e32 v103, 0x3f317217, v95
	v_fma_f32 v100, v92, s31, -v100
	v_fma_f32 v101, v93, s31, -v101
	v_fma_f32 v102, v94, s31, -v102
	v_fma_f32 v103, v95, s31, -v103
	v_fmac_f32_e32 v100, 0x3377d1cf, v92
	v_fmac_f32_e32 v101, 0x3377d1cf, v93
	v_fmac_f32_e32 v102, 0x3377d1cf, v94
	v_fmac_f32_e32 v103, 0x3377d1cf, v95
	v_fmac_f32_e32 v100, 0x3f317217, v92
	v_fmac_f32_e32 v101, 0x3f317217, v93
	v_fmac_f32_e32 v102, 0x3f317217, v94
	v_fmac_f32_e32 v103, 0x3f317217, v95
	v_cmp_lt_f32_e64 vcc, |v92|, s34
	v_cndmask_b32_e32 v92, v92, v100, vcc
	v_cmp_lt_f32_e64 vcc, |v93|, s34
	v_cndmask_b32_e32 v93, v93, v101, vcc
	v_cmp_lt_f32_e64 vcc, |v94|, s34
	v_cndmask_b32_e32 v94, v94, v102, vcc
	v_cmp_lt_f32_e64 vcc, |v95|, s34
	v_cndmask_b32_e32 v95, v95, v103, vcc
	v_cndmask_b32_e64 v100, 0, v213, s[22:23]
	v_cndmask_b32_e64 v101, 0, v213, s[24:25]
	v_cndmask_b32_e64 v102, 0, v213, s[26:27]
	v_cndmask_b32_e64 v103, 0, v213, s[28:29]
	v_sub_f32_e32 v92, v92, v100
	v_sub_f32_e32 v93, v93, v101
	v_sub_f32_e32 v94, v94, v102
	v_sub_f32_e32 v95, v95, v103
	v_add_f32_e32 v64, v64, v92
	v_add_f32_e32 v65, v65, v93
	v_add_f32_e32 v66, v66, v94
	v_add_f32_e32 v67, v67, v95
	v_mul_f32_e32 v92, 0xbfb8aa3b, v64
	v_mul_f32_e32 v93, 0xbfb8aa3b, v65
	v_mul_f32_e32 v94, 0xbfb8aa3b, v66
	v_mul_f32_e32 v95, 0xbfb8aa3b, v67
	v_mul_f32_e32 v100, 0x3fb8aa3b, v64
	v_mul_f32_e32 v101, 0x3fb8aa3b, v65
	v_mul_f32_e32 v102, 0x3fb8aa3b, v66
	v_mul_f32_e32 v103, 0x3fb8aa3b, v67
	v_exp_f32_e32 v92, v92
	v_exp_f32_e32 v93, v93
	v_exp_f32_e32 v94, v94
	v_exp_f32_e32 v95, v95
	v_exp_f32_e32 v100, v100
	v_exp_f32_e32 v101, v101
	v_exp_f32_e32 v102, v102
	v_exp_f32_e32 v103, v103
	v_sub_f32_e32 v96, 1.0, v96
	v_sub_f32_e32 v97, 1.0, v97
	v_sub_f32_e32 v98, 1.0, v98
	v_sub_f32_e32 v99, 1.0, v99
	v_mul_f32_e32 v96, v96, v92
	v_mul_f32_e32 v97, v97, v93
	v_mul_f32_e32 v98, v98, v94
	v_mul_f32_e32 v99, v99, v95
	v_lshlrev_b32_e32 v92, 16, v14
	v_and_b32_e32 v93, 0xffff0000, v14
	v_lshlrev_b32_e32 v94, 16, v15
	v_and_b32_e32 v95, 0xffff0000, v15
	v_mul_f32_e32 v92, v92, v100
	v_mul_f32_e32 v93, v93, v101
	v_mul_f32_e32 v94, v94, v102
	v_mul_f32_e32 v95, v95, v103
	v_cvt_pk_bf16_f32 v117, v117, v96
	v_cvt_pk_bf16_f32 v133, v133, v97
	v_cvt_pk_bf16_f32 v167, v167, v98
	v_cvt_pk_bf16_f32 v183, v183, v99
	v_cvt_pk_bf16_f32 v92, v92, v93
	v_cvt_pk_bf16_f32 v93, v94, v95
	v_cvt_pk_bf16_f32 v96, v96, v97
	v_cvt_pk_bf16_f32 v97, v98, v99
	global_store_dwordx2 v112, v[92:93], s[2:3]
	global_store_dwordx2 v114, v[96:97], s[2:3]
	s_add_u32 s2, s2, 0x400
	s_addc_u32 s3, s3, 0
	v_lshlrev_b32_e32 v92, 16, v16
	v_and_b32_e32 v93, 0xffff0000, v16
	v_lshlrev_b32_e32 v94, 16, v17
	v_and_b32_e32 v95, 0xffff0000, v17
	v_mul_f32_e32 v92, 0xbfb8aa3b, v92
	v_mul_f32_e32 v93, 0xbfb8aa3b, v93
	v_mul_f32_e32 v94, 0xbfb8aa3b, v94
	v_mul_f32_e32 v95, 0xbfb8aa3b, v95
	v_exp_f32_e32 v92, v92
	v_exp_f32_e32 v93, v93
	v_exp_f32_e32 v94, v94
	v_exp_f32_e32 v95, v95
	v_add_f32_e32 v92, 1.0, v92
	v_add_f32_e32 v93, 1.0, v93
	v_add_f32_e32 v94, 1.0, v94
	v_add_f32_e32 v95, 1.0, v95
	v_rcp_f32_e32 v92, v92
	v_rcp_f32_e32 v93, v93
	v_rcp_f32_e32 v94, v94
	v_rcp_f32_e32 v95, v95
	v_fma_f32 v96, v72, v92, v68
	v_fma_f32 v97, v73, v93, v69
	v_fma_f32 v98, v74, v94, v70
	v_fma_f32 v99, v75, v95, v71
	v_cmp_gt_f32_e64 s[22:23], s30, v96
	v_cmp_gt_f32_e64 s[24:25], s30, v97
	v_cmp_gt_f32_e64 s[26:27], s30, v98
	v_cmp_gt_f32_e64 s[28:29], s30, v99
	v_cndmask_b32_e64 v92, 0, 32, s[22:23]
	v_cndmask_b32_e64 v93, 0, 32, s[24:25]
	v_cndmask_b32_e64 v94, 0, 32, s[26:27]
	v_cndmask_b32_e64 v95, 0, 32, s[28:29]
	v_ldexp_f32 v92, v96, v92
	v_ldexp_f32 v93, v97, v93
	v_ldexp_f32 v94, v98, v94
	v_ldexp_f32 v95, v99, v95
	v_log_f32_e32 v92, v92
	v_log_f32_e32 v93, v93
	v_log_f32_e32 v94, v94
	v_log_f32_e32 v95, v95
	v_mul_f32_e32 v100, 0x3f317217, v92
	v_mul_f32_e32 v101, 0x3f317217, v93
	v_mul_f32_e32 v102, 0x3f317217, v94
	v_mul_f32_e32 v103, 0x3f317217, v95
	v_fma_f32 v100, v92, s31, -v100
; DEV u16 f2bf(float f) { return (u16)(pack2(f, f) & 0xffffu); }
; DEV float bf2f(u16 h) { return __uint_as_float(((unsigned)h) << 16); }
; DEV float sigmoid_f(float x) { return __builtin_amdgcn_rcpf(1.f + __expf(-x)); }
; DEV void phase_p15(const Params& p, int g) {
;     ...
;     for (int j8 = 0; j8 < 8; ++j8) {
;       const int st = j8 % 3;
;       if (j8 < 6) { P15_LOAD((j8 + 2) % 3, j8 + 2); }
; #pragma unroll
;       for (int cc = 0; cc < 2; ++cc) {
;         const int c = tid + 256 * cc;
;         unsigned kb[8];
; #pragma unroll
;         for (int e = 0; e < 8; ++e) {
;           const int jj = j8 * 8 + e;
;           const int j = dir ? 63 - jj : jj;
;           const size_t tok = (size_t)cidx * 64 + j;
;           const float f = lb[cc] + (1.f - lb[cc]) * sigmoid_f(bf2f(xr[st][cc][e]));
;           G[cc] += __logf(f);
;           const float eg = __expf(G[cc]), ig = __expf(-G[cc]);
;           Qp[tok * 512 + c] = f2bf(bf2f(qr[st][cc][e]) * eg);
;           const u16 kk = f2bf((1.f - f) * ig);
;           Kp[tok * 512 + c] = kk;
;           kb[e] = kk;
;         }
;         const int s0 = dir ? 56 - 8 * j8 : 8 * j8;
;         uint4 w;
;         w.x = dir ? (kb[7] | (kb[6] << 16)) : (kb[0] | (kb[1] << 16));
;         w.y = dir ? (kb[5] | (kb[4] << 16)) : (kb[2] | (kb[3] << 16));
;         w.z = dir ? (kb[3] | (kb[2] << 16)) : (kb[4] | (kb[5] << 16));
;         w.w = dir ? (kb[1] | (kb[0] << 16)) : (kb[6] | (kb[7] << 16));
;         *(uint4*)(KT + (((size_t)cidx * 2 + dir) * 512 + c) * 64 + s0) = w;
;       }
	v_fma_f32 v101, v93, s31, -v101
	v_fma_f32 v102, v94, s31, -v102
	v_fma_f32 v103, v95, s31, -v103
	v_fmac_f32_e32 v100, 0x3377d1cf, v92
	v_fmac_f32_e32 v101, 0x3377d1cf, v93
	v_fmac_f32_e32 v102, 0x3377d1cf, v94
	v_fmac_f32_e32 v103, 0x3377d1cf, v95
	v_fmac_f32_e32 v100, 0x3f317217, v92
	v_fmac_f32_e32 v101, 0x3f317217, v93
	v_fmac_f32_e32 v102, 0x3f317217, v94
	v_fmac_f32_e32 v103, 0x3f317217, v95
	v_cmp_lt_f32_e64 vcc, |v92|, s34
	v_cndmask_b32_e32 v92, v92, v100, vcc
	v_cmp_lt_f32_e64 vcc, |v93|, s34
	v_cndmask_b32_e32 v93, v93, v101, vcc
	v_cmp_lt_f32_e64 vcc, |v94|, s34
	v_cndmask_b32_e32 v94, v94, v102, vcc
	v_cmp_lt_f32_e64 vcc, |v95|, s34
	v_cndmask_b32_e32 v95, v95, v103, vcc
	v_cndmask_b32_e64 v100, 0, v213, s[22:23]
	v_cndmask_b32_e64 v101, 0, v213, s[24:25]
	v_cndmask_b32_e64 v102, 0, v213, s[26:27]
	v_cndmask_b32_e64 v103, 0, v213, s[28:29]
	v_sub_f32_e32 v92, v92, v100
	v_sub_f32_e32 v93, v93, v101
	v_sub_f32_e32 v94, v94, v102
	v_sub_f32_e32 v95, v95, v103
	v_add_f32_e32 v64, v64, v92
	v_add_f32_e32 v65, v65, v93
	v_add_f32_e32 v66, v66, v94
	v_add_f32_e32 v67, v67, v95
	v_mul_f32_e32 v92, 0xbfb8aa3b, v64
	v_mul_f32_e32 v93, 0xbfb8aa3b, v65
	v_mul_f32_e32 v94, 0xbfb8aa3b, v66
	v_mul_f32_e32 v95, 0xbfb8aa3b, v67
	v_mul_f32_e32 v100, 0x3fb8aa3b, v64
	v_mul_f32_e32 v101, 0x3fb8aa3b, v65
	v_mul_f32_e32 v102, 0x3fb8aa3b, v66
	v_mul_f32_e32 v103, 0x3fb8aa3b, v67
	v_exp_f32_e32 v92, v92
	v_exp_f32_e32 v93, v93
	v_exp_f32_e32 v94, v94
	v_exp_f32_e32 v95, v95
	v_exp_f32_e32 v100, v100
	v_exp_f32_e32 v101, v101
	v_exp_f32_e32 v102, v102
	v_exp_f32_e32 v103, v103
	v_sub_f32_e32 v96, 1.0, v96
	v_sub_f32_e32 v97, 1.0, v97
	v_sub_f32_e32 v98, 1.0, v98
	v_sub_f32_e32 v99, 1.0, v99
	v_mul_f32_e32 v96, v96, v92
	v_mul_f32_e32 v97, v97, v93
	v_mul_f32_e32 v98, v98, v94
	v_mul_f32_e32 v99, v99, v95
	v_lshlrev_b32_e32 v92, 16, v18
	v_and_b32_e32 v93, 0xffff0000, v18
	v_lshlrev_b32_e32 v94, 16, v19
	v_and_b32_e32 v95, 0xffff0000, v19
	v_mul_f32_e32 v92, v92, v100
	v_mul_f32_e32 v93, v93, v101
	v_mul_f32_e32 v94, v94, v102
	v_mul_f32_e32 v95, v95, v103
	v_mov_b32_e32 v118, v96
	v_mov_b32_e32 v134, v97
	v_mov_b32_e32 v168, v98
	v_mov_b32_e32 v184, v99
	v_cvt_pk_bf16_f32 v92, v92, v93
	v_cvt_pk_bf16_f32 v93, v94, v95
	v_cvt_pk_bf16_f32 v96, v96, v97
	v_cvt_pk_bf16_f32 v97, v98, v99
	global_store_dwordx2 v112, v[92:93], s[2:3]
	global_store_dwordx2 v114, v[96:97], s[2:3]
	s_add_u32 s2, s2, 0x400
	s_addc_u32 s3, s3, 0
	v_lshlrev_b32_e32 v92, 16, v20
	v_and_b32_e32 v93, 0xffff0000, v20
	v_lshlrev_b32_e32 v94, 16, v21
	v_and_b32_e32 v95, 0xffff0000, v21
	v_mul_f32_e32 v92, 0xbfb8aa3b, v92
	v_mul_f32_e32 v93, 0xbfb8aa3b, v93
	v_mul_f32_e32 v94, 0xbfb8aa3b, v94
	v_mul_f32_e32 v95, 0xbfb8aa3b, v95
	v_exp_f32_e32 v92, v92
	v_exp_f32_e32 v93, v93
	v_exp_f32_e32 v94, v94
	v_exp_f32_e32 v95, v95
	v_add_f32_e32 v92, 1.0, v92
	v_add_f32_e32 v93, 1.0, v93
	v_add_f32_e32 v94, 1.0, v94
	v_add_f32_e32 v95, 1.0, v95
	v_rcp_f32_e32 v92, v92
	v_rcp_f32_e32 v93, v93
	v_rcp_f32_e32 v94, v94
	v_rcp_f32_e32 v95, v95
	v_fma_f32 v96, v72, v92, v68
	v_fma_f32 v97, v73, v93, v69
	v_fma_f32 v98, v74, v94, v70
	v_fma_f32 v99, v75, v95, v71
	v_cmp_gt_f32_e64 s[22:23], s30, v96
	v_cmp_gt_f32_e64 s[24:25], s30, v97
	v_cmp_gt_f32_e64 s[26:27], s30, v98
	v_cmp_gt_f32_e64 s[28:29], s30, v99
	v_cndmask_b32_e64 v92, 0, 32, s[22:23]
	v_cndmask_b32_e64 v93, 0, 32, s[24:25]
	v_cndmask_b32_e64 v94, 0, 32, s[26:27]
	v_cndmask_b32_e64 v95, 0, 32, s[28:29]
	v_ldexp_f32 v92, v96, v92
	v_ldexp_f32 v93, v97, v93
	v_ldexp_f32 v94, v98, v94
	v_ldexp_f32 v95, v99, v95
	v_log_f32_e32 v92, v92
	v_log_f32_e32 v93, v93
	v_log_f32_e32 v94, v94
	v_log_f32_e32 v95, v95
	v_mul_f32_e32 v100, 0x3f317217, v92
	v_mul_f32_e32 v101, 0x3f317217, v93
	v_mul_f32_e32 v102, 0x3f317217, v94
	v_mul_f32_e32 v103, 0x3f317217, v95
	v_fma_f32 v100, v92, s31, -v100
	v_fma_f32 v101, v93, s31, -v101
	v_fma_f32 v102, v94, s31, -v102
	v_fma_f32 v103, v95, s31, -v103
	v_fmac_f32_e32 v100, 0x3377d1cf, v92
	v_fmac_f32_e32 v101, 0x3377d1cf, v93
	v_fmac_f32_e32 v102, 0x3377d1cf, v94
	v_fmac_f32_e32 v103, 0x3377d1cf, v95
	v_fmac_f32_e32 v100, 0x3f317217, v92
	v_fmac_f32_e32 v101, 0x3f317217, v93
	v_fmac_f32_e32 v102, 0x3f317217, v94
	v_fmac_f32_e32 v103, 0x3f317217, v95
	v_cmp_lt_f32_e64 vcc, |v92|, s34
	v_cndmask_b32_e32 v92, v92, v100, vcc
	v_cmp_lt_f32_e64 vcc, |v93|, s34
	v_cndmask_b32_e32 v93, v93, v101, vcc
	v_cmp_lt_f32_e64 vcc, |v94|, s34
	v_cndmask_b32_e32 v94, v94, v102, vcc
	v_cmp_lt_f32_e64 vcc, |v95|, s34
	v_cndmask_b32_e32 v95, v95, v103, vcc
	v_cndmask_b32_e64 v100, 0, v213, s[22:23]
	v_cndmask_b32_e64 v101, 0, v213, s[24:25]
	v_cndmask_b32_e64 v102, 0, v213, s[26:27]
	v_cndmask_b32_e64 v103, 0, v213, s[28:29]
	v_sub_f32_e32 v92, v92, v100
	v_sub_f32_e32 v93, v93, v101
	v_sub_f32_e32 v94, v94, v102
	v_sub_f32_e32 v95, v95, v103
	v_add_f32_e32 v64, v64, v92
	v_add_f32_e32 v65, v65, v93
	v_add_f32_e32 v66, v66, v94
	v_add_f32_e32 v67, v67, v95
	v_mul_f32_e32 v92, 0xbfb8aa3b, v64
	v_mul_f32_e32 v93, 0xbfb8aa3b, v65
	v_mul_f32_e32 v94, 0xbfb8aa3b, v66
	v_mul_f32_e32 v95, 0xbfb8aa3b, v67
	v_mul_f32_e32 v100, 0x3fb8aa3b, v64
	v_mul_f32_e32 v101, 0x3fb8aa3b, v65
	v_mul_f32_e32 v102, 0x3fb8aa3b, v66
	v_mul_f32_e32 v103, 0x3fb8aa3b, v67
	v_exp_f32_e32 v92, v92
	v_exp_f32_e32 v93, v93
	v_exp_f32_e32 v94, v94
	v_exp_f32_e32 v95, v95
	v_exp_f32_e32 v100, v100
	v_exp_f32_e32 v101, v101
	v_exp_f32_e32 v102, v102
	v_exp_f32_e32 v103, v103
	v_sub_f32_e32 v96, 1.0, v96
	v_sub_f32_e32 v97, 1.0, v97
	v_sub_f32_e32 v98, 1.0, v98
	v_sub_f32_e32 v99, 1.0, v99
	v_mul_f32_e32 v96, v96, v92
	v_mul_f32_e32 v97, v97, v93
	v_mul_f32_e32 v98, v98, v94
; DEV u16 f2bf(float f) { return (u16)(pack2(f, f) & 0xffffu); }
; DEV float bf2f(u16 h) { return __uint_as_float(((unsigned)h) << 16); }
; DEV float sigmoid_f(float x) { return __builtin_amdgcn_rcpf(1.f + __expf(-x)); }
; DEV void phase_p15(const Params& p, int g) {
;     ...
;     for (int j8 = 0; j8 < 8; ++j8) {
;       const int st = j8 % 3;
;       if (j8 < 6) { P15_LOAD((j8 + 2) % 3, j8 + 2); }
; #pragma unroll
;       for (int cc = 0; cc < 2; ++cc) {
;         const int c = tid + 256 * cc;
;         unsigned kb[8];
; #pragma unroll
;         for (int e = 0; e < 8; ++e) {
;           const int jj = j8 * 8 + e;
;           const int j = dir ? 63 - jj : jj;
;           const size_t tok = (size_t)cidx * 64 + j;
;           const float f = lb[cc] + (1.f - lb[cc]) * sigmoid_f(bf2f(xr[st][cc][e]));
;           G[cc] += __logf(f);
;           const float eg = __expf(G[cc]), ig = __expf(-G[cc]);
;           Qp[tok * 512 + c] = f2bf(bf2f(qr[st][cc][e]) * eg);
;           const u16 kk = f2bf((1.f - f) * ig);
;           Kp[tok * 512 + c] = kk;
;           kb[e] = kk;
;         }
;         const int s0 = dir ? 56 - 8 * j8 : 8 * j8;
;         uint4 w;
;         w.x = dir ? (kb[7] | (kb[6] << 16)) : (kb[0] | (kb[1] << 16));
;         w.y = dir ? (kb[5] | (kb[4] << 16)) : (kb[2] | (kb[3] << 16));
;         w.z = dir ? (kb[3] | (kb[2] << 16)) : (kb[4] | (kb[5] << 16));
;         w.w = dir ? (kb[1] | (kb[0] << 16)) : (kb[6] | (kb[7] << 16));
;         *(uint4*)(KT + (((size_t)cidx * 2 + dir) * 512 + c) * 64 + s0) = w;
;       }
	v_mul_f32_e32 v99, v99, v95
	v_lshlrev_b32_e32 v92, 16, v22
	v_and_b32_e32 v93, 0xffff0000, v22
	v_lshlrev_b32_e32 v94, 16, v23
	v_and_b32_e32 v95, 0xffff0000, v23
	v_mul_f32_e32 v92, v92, v100
	v_mul_f32_e32 v93, v93, v101
	v_mul_f32_e32 v94, v94, v102
	v_mul_f32_e32 v95, v95, v103
	v_cvt_pk_bf16_f32 v118, v118, v96
	v_cvt_pk_bf16_f32 v134, v134, v97
	v_cvt_pk_bf16_f32 v168, v168, v98
	v_cvt_pk_bf16_f32 v184, v184, v99
	v_cvt_pk_bf16_f32 v92, v92, v93
	v_cvt_pk_bf16_f32 v93, v94, v95
	v_cvt_pk_bf16_f32 v96, v96, v97
	v_cvt_pk_bf16_f32 v97, v98, v99
	global_store_dwordx2 v112, v[92:93], s[2:3]
	global_store_dwordx2 v114, v[96:97], s[2:3]
	s_add_u32 s2, s2, 0x400
	s_addc_u32 s3, s3, 0
	v_lshlrev_b32_e32 v92, 16, v24
	v_and_b32_e32 v93, 0xffff0000, v24
	v_lshlrev_b32_e32 v94, 16, v25
	v_and_b32_e32 v95, 0xffff0000, v25
	v_mul_f32_e32 v92, 0xbfb8aa3b, v92
	v_mul_f32_e32 v93, 0xbfb8aa3b, v93
	v_mul_f32_e32 v94, 0xbfb8aa3b, v94
	v_mul_f32_e32 v95, 0xbfb8aa3b, v95
	v_exp_f32_e32 v92, v92
	v_exp_f32_e32 v93, v93
	v_exp_f32_e32 v94, v94
	v_exp_f32_e32 v95, v95
	v_add_f32_e32 v92, 1.0, v92
	v_add_f32_e32 v93, 1.0, v93
	v_add_f32_e32 v94, 1.0, v94
	v_add_f32_e32 v95, 1.0, v95
	v_rcp_f32_e32 v92, v92
	v_rcp_f32_e32 v93, v93
	v_rcp_f32_e32 v94, v94
	v_rcp_f32_e32 v95, v95
	v_fma_f32 v96, v72, v92, v68
	v_fma_f32 v97, v73, v93, v69
	v_fma_f32 v98, v74, v94, v70
	v_fma_f32 v99, v75, v95, v71
	v_cmp_gt_f32_e64 s[22:23], s30, v96
	v_cmp_gt_f32_e64 s[24:25], s30, v97
	v_cmp_gt_f32_e64 s[26:27], s30, v98
	v_cmp_gt_f32_e64 s[28:29], s30, v99
	v_cndmask_b32_e64 v92, 0, 32, s[22:23]
	v_cndmask_b32_e64 v93, 0, 32, s[24:25]
	v_cndmask_b32_e64 v94, 0, 32, s[26:27]
	v_cndmask_b32_e64 v95, 0, 32, s[28:29]
	v_ldexp_f32 v92, v96, v92
	v_ldexp_f32 v93, v97, v93
	v_ldexp_f32 v94, v98, v94
	v_ldexp_f32 v95, v99, v95
	v_log_f32_e32 v92, v92
	v_log_f32_e32 v93, v93
	v_log_f32_e32 v94, v94
	v_log_f32_e32 v95, v95
	v_mul_f32_e32 v100, 0x3f317217, v92
	v_mul_f32_e32 v101, 0x3f317217, v93
	v_mul_f32_e32 v102, 0x3f317217, v94
	v_mul_f32_e32 v103, 0x3f317217, v95
	v_fma_f32 v100, v92, s31, -v100
	v_fma_f32 v101, v93, s31, -v101
	v_fma_f32 v102, v94, s31, -v102
	v_fma_f32 v103, v95, s31, -v103
	v_fmac_f32_e32 v100, 0x3377d1cf, v92
	v_fmac_f32_e32 v101, 0x3377d1cf, v93
	v_fmac_f32_e32 v102, 0x3377d1cf, v94
	v_fmac_f32_e32 v103, 0x3377d1cf, v95
	v_fmac_f32_e32 v100, 0x3f317217, v92
	v_fmac_f32_e32 v101, 0x3f317217, v93
	v_fmac_f32_e32 v102, 0x3f317217, v94
	v_fmac_f32_e32 v103, 0x3f317217, v95
	v_cmp_lt_f32_e64 vcc, |v92|, s34
	v_cndmask_b32_e32 v92, v92, v100, vcc
	v_cmp_lt_f32_e64 vcc, |v93|, s34
	v_cndmask_b32_e32 v93, v93, v101, vcc
	v_cmp_lt_f32_e64 vcc, |v94|, s34
	v_cndmask_b32_e32 v94, v94, v102, vcc
	v_cmp_lt_f32_e64 vcc, |v95|, s34
	v_cndmask_b32_e32 v95, v95, v103, vcc
	v_cndmask_b32_e64 v100, 0, v213, s[22:23]
	v_cndmask_b32_e64 v101, 0, v213, s[24:25]
	v_cndmask_b32_e64 v102, 0, v213, s[26:27]
	v_cndmask_b32_e64 v103, 0, v213, s[28:29]
	v_sub_f32_e32 v92, v92, v100
	v_sub_f32_e32 v93, v93, v101
	v_sub_f32_e32 v94, v94, v102
	v_sub_f32_e32 v95, v95, v103
	v_add_f32_e32 v64, v64, v92
	v_add_f32_e32 v65, v65, v93
	v_add_f32_e32 v66, v66, v94
	v_add_f32_e32 v67, v67, v95
	v_mul_f32_e32 v92, 0xbfb8aa3b, v64
	v_mul_f32_e32 v93, 0xbfb8aa3b, v65
	v_mul_f32_e32 v94, 0xbfb8aa3b, v66
	v_mul_f32_e32 v95, 0xbfb8aa3b, v67
	v_mul_f32_e32 v100, 0x3fb8aa3b, v64
	v_mul_f32_e32 v101, 0x3fb8aa3b, v65
	v_mul_f32_e32 v102, 0x3fb8aa3b, v66
	v_mul_f32_e32 v103, 0x3fb8aa3b, v67
	v_exp_f32_e32 v92, v92
	v_exp_f32_e32 v93, v93
	v_exp_f32_e32 v94, v94
	v_exp_f32_e32 v95, v95
	v_exp_f32_e32 v100, v100
	v_exp_f32_e32 v101, v101
	v_exp_f32_e32 v102, v102
	v_exp_f32_e32 v103, v103
	v_sub_f32_e32 v96, 1.0, v96
	v_sub_f32_e32 v97, 1.0, v97
	v_sub_f32_e32 v98, 1.0, v98
	v_sub_f32_e32 v99, 1.0, v99
	v_mul_f32_e32 v96, v96, v92
	v_mul_f32_e32 v97, v97, v93
	v_mul_f32_e32 v98, v98, v94
	v_mul_f32_e32 v99, v99, v95
	v_lshlrev_b32_e32 v92, 16, v26
	v_and_b32_e32 v93, 0xffff0000, v26
	v_lshlrev_b32_e32 v94, 16, v27
	v_and_b32_e32 v95, 0xffff0000, v27
	v_mul_f32_e32 v92, v92, v100
	v_mul_f32_e32 v93, v93, v101
	v_mul_f32_e32 v94, v94, v102
	v_mul_f32_e32 v95, v95, v103
	v_mov_b32_e32 v119, v96
	v_mov_b32_e32 v135, v97
	v_mov_b32_e32 v169, v98
	v_mov_b32_e32 v185, v99
	v_cvt_pk_bf16_f32 v92, v92, v93
	v_cvt_pk_bf16_f32 v93, v94, v95
	v_cvt_pk_bf16_f32 v96, v96, v97
	v_cvt_pk_bf16_f32 v97, v98, v99
	global_store_dwordx2 v112, v[92:93], s[2:3]
	global_store_dwordx2 v114, v[96:97], s[2:3]
	s_add_u32 s2, s2, 0x400
	s_addc_u32 s3, s3, 0
	v_lshlrev_b32_e32 v92, 16, v28
	v_and_b32_e32 v93, 0xffff0000, v28
	v_lshlrev_b32_e32 v94, 16, v29
	v_and_b32_e32 v95, 0xffff0000, v29
	v_mul_f32_e32 v92, 0xbfb8aa3b, v92
	v_mul_f32_e32 v93, 0xbfb8aa3b, v93
	v_mul_f32_e32 v94, 0xbfb8aa3b, v94
	v_mul_f32_e32 v95, 0xbfb8aa3b, v95
	v_exp_f32_e32 v92, v92
	v_exp_f32_e32 v93, v93
	v_exp_f32_e32 v94, v94
	v_exp_f32_e32 v95, v95
	v_add_f32_e32 v92, 1.0, v92
	v_add_f32_e32 v93, 1.0, v93
	v_add_f32_e32 v94, 1.0, v94
	v_add_f32_e32 v95, 1.0, v95
	v_rcp_f32_e32 v92, v92
	v_rcp_f32_e32 v93, v93
	v_rcp_f32_e32 v94, v94
	v_rcp_f32_e32 v95, v95
	v_fma_f32 v96, v72, v92, v68
	v_fma_f32 v97, v73, v93, v69
	v_fma_f32 v98, v74, v94, v70
	v_fma_f32 v99, v75, v95, v71
	v_cmp_gt_f32_e64 s[22:23], s30, v96
	v_cmp_gt_f32_e64 s[24:25], s30, v97
	v_cmp_gt_f32_e64 s[26:27], s30, v98
	v_cmp_gt_f32_e64 s[28:29], s30, v99
	v_cndmask_b32_e64 v92, 0, 32, s[22:23]
	v_cndmask_b32_e64 v93, 0, 32, s[24:25]
	v_cndmask_b32_e64 v94, 0, 32, s[26:27]
	v_cndmask_b32_e64 v95, 0, 32, s[28:29]
	v_ldexp_f32 v92, v96, v92
	v_ldexp_f32 v93, v97, v93
	v_ldexp_f32 v94, v98, v94
; DEV u16 f2bf(float f) { return (u16)(pack2(f, f) & 0xffffu); }
; DEV float bf2f(u16 h) { return __uint_as_float(((unsigned)h) << 16); }
; DEV float sigmoid_f(float x) { return __builtin_amdgcn_rcpf(1.f + __expf(-x)); }
; DEV void phase_p15(const Params& p, int g) {
;     ...
;     P15_LOAD(0, 0);
;     P15_LOAD(1, 1);
; #pragma unroll
;     for (int j8 = 0; j8 < 8; ++j8) {
;       const int st = j8 % 3;
;       if (j8 < 6) { P15_LOAD((j8 + 2) % 3, j8 + 2); }
; #pragma unroll
;       for (int cc = 0; cc < 2; ++cc) {
;         const int c = tid + 256 * cc;
;         unsigned kb[8];
; #pragma unroll
;         for (int e = 0; e < 8; ++e) {
;           const int jj = j8 * 8 + e;
;           const int j = dir ? 63 - jj : jj;
;           const size_t tok = (size_t)cidx * 64 + j;
;           const float f = lb[cc] + (1.f - lb[cc]) * sigmoid_f(bf2f(xr[st][cc][e]));
;           G[cc] += __logf(f);
;           const float eg = __expf(G[cc]), ig = __expf(-G[cc]);
;           Qp[tok * 512 + c] = f2bf(bf2f(qr[st][cc][e]) * eg);
;           const u16 kk = f2bf((1.f - f) * ig);
;           Kp[tok * 512 + c] = kk;
;           kb[e] = kk;
;         }
;         const int s0 = dir ? 56 - 8 * j8 : 8 * j8;
;         uint4 w;
;         w.x = dir ? (kb[7] | (kb[6] << 16)) : (kb[0] | (kb[1] << 16));
;         w.y = dir ? (kb[5] | (kb[4] << 16)) : (kb[2] | (kb[3] << 16));
;         w.z = dir ? (kb[3] | (kb[2] << 16)) : (kb[4] | (kb[5] << 16));
;         w.w = dir ? (kb[1] | (kb[0] << 16)) : (kb[6] | (kb[7] << 16));
;         *(uint4*)(KT + (((size_t)cidx * 2 + dir) * 512 + c) * 64 + s0) = w;
;       }
	v_ldexp_f32 v95, v99, v95
	v_log_f32_e32 v92, v92
	v_log_f32_e32 v93, v93
	v_log_f32_e32 v94, v94
	v_log_f32_e32 v95, v95
	v_mul_f32_e32 v100, 0x3f317217, v92
	v_mul_f32_e32 v101, 0x3f317217, v93
	v_mul_f32_e32 v102, 0x3f317217, v94
	v_mul_f32_e32 v103, 0x3f317217, v95
	v_fma_f32 v100, v92, s31, -v100
	v_fma_f32 v101, v93, s31, -v101
	v_fma_f32 v102, v94, s31, -v102
	v_fma_f32 v103, v95, s31, -v103
	v_fmac_f32_e32 v100, 0x3377d1cf, v92
	v_fmac_f32_e32 v101, 0x3377d1cf, v93
	v_fmac_f32_e32 v102, 0x3377d1cf, v94
	v_fmac_f32_e32 v103, 0x3377d1cf, v95
	v_fmac_f32_e32 v100, 0x3f317217, v92
	v_fmac_f32_e32 v101, 0x3f317217, v93
	v_fmac_f32_e32 v102, 0x3f317217, v94
	v_fmac_f32_e32 v103, 0x3f317217, v95
	v_cmp_lt_f32_e64 vcc, |v92|, s34
	v_cndmask_b32_e32 v92, v92, v100, vcc
	v_cmp_lt_f32_e64 vcc, |v93|, s34
	v_cndmask_b32_e32 v93, v93, v101, vcc
	v_cmp_lt_f32_e64 vcc, |v94|, s34
	v_cndmask_b32_e32 v94, v94, v102, vcc
	v_cmp_lt_f32_e64 vcc, |v95|, s34
	v_cndmask_b32_e32 v95, v95, v103, vcc
	v_cndmask_b32_e64 v100, 0, v213, s[22:23]
	v_cndmask_b32_e64 v101, 0, v213, s[24:25]
	v_cndmask_b32_e64 v102, 0, v213, s[26:27]
	v_cndmask_b32_e64 v103, 0, v213, s[28:29]
	v_sub_f32_e32 v92, v92, v100
	v_sub_f32_e32 v93, v93, v101
	v_sub_f32_e32 v94, v94, v102
	v_sub_f32_e32 v95, v95, v103
	v_add_f32_e32 v64, v64, v92
	v_add_f32_e32 v65, v65, v93
	v_add_f32_e32 v66, v66, v94
	v_add_f32_e32 v67, v67, v95
	v_mul_f32_e32 v92, 0xbfb8aa3b, v64
	v_mul_f32_e32 v93, 0xbfb8aa3b, v65
	v_mul_f32_e32 v94, 0xbfb8aa3b, v66
	v_mul_f32_e32 v95, 0xbfb8aa3b, v67
	v_mul_f32_e32 v100, 0x3fb8aa3b, v64
	v_mul_f32_e32 v101, 0x3fb8aa3b, v65
	v_mul_f32_e32 v102, 0x3fb8aa3b, v66
	v_mul_f32_e32 v103, 0x3fb8aa3b, v67
	v_exp_f32_e32 v92, v92
	v_exp_f32_e32 v93, v93
	v_exp_f32_e32 v94, v94
	v_exp_f32_e32 v95, v95
	v_exp_f32_e32 v100, v100
	v_exp_f32_e32 v101, v101
	v_exp_f32_e32 v102, v102
	v_exp_f32_e32 v103, v103
	v_sub_f32_e32 v96, 1.0, v96
	v_sub_f32_e32 v97, 1.0, v97
	v_sub_f32_e32 v98, 1.0, v98
	v_sub_f32_e32 v99, 1.0, v99
	v_mul_f32_e32 v96, v96, v92
	v_mul_f32_e32 v97, v97, v93
	v_mul_f32_e32 v98, v98, v94
	v_mul_f32_e32 v99, v99, v95
	v_lshlrev_b32_e32 v92, 16, v30
	v_and_b32_e32 v93, 0xffff0000, v30
	v_lshlrev_b32_e32 v94, 16, v31
	v_and_b32_e32 v95, 0xffff0000, v31
	v_mul_f32_e32 v92, v92, v100
	v_mul_f32_e32 v93, v93, v101
	v_mul_f32_e32 v94, v94, v102
	v_mul_f32_e32 v95, v95, v103
	v_cvt_pk_bf16_f32 v119, v119, v96
	v_cvt_pk_bf16_f32 v135, v135, v97
	v_cvt_pk_bf16_f32 v169, v169, v98
	v_cvt_pk_bf16_f32 v185, v185, v99
	v_cvt_pk_bf16_f32 v92, v92, v93
	v_cvt_pk_bf16_f32 v93, v94, v95
	v_cvt_pk_bf16_f32 v96, v96, v97
	v_cvt_pk_bf16_f32 v97, v98, v99
	global_store_dwordx2 v112, v[92:93], s[2:3]
	global_store_dwordx2 v114, v[96:97], s[2:3]
	s_add_u32 s2, s2, 0x400
	s_addc_u32 s3, s3, 0
	global_load_dwordx2 v[0:1], v113, s[0:1]
	global_load_dwordx2 v[2:3], v112, s[0:1]
	s_add_u32 s0, s0, 0x1400
	s_addc_u32 s1, s1, 0
	global_load_dwordx2 v[4:5], v113, s[0:1]
	global_load_dwordx2 v[6:7], v112, s[0:1]
	s_add_u32 s0, s0, 0x1400
	s_addc_u32 s1, s1, 0
	global_load_dwordx2 v[8:9], v113, s[0:1]
	global_load_dwordx2 v[10:11], v112, s[0:1]
	s_add_u32 s0, s0, 0x1400
	s_addc_u32 s1, s1, 0
	global_load_dwordx2 v[12:13], v113, s[0:1]
	global_load_dwordx2 v[14:15], v112, s[0:1]
	s_add_u32 s0, s0, 0x1400
	s_addc_u32 s1, s1, 0
	global_load_dwordx2 v[16:17], v113, s[0:1]
	global_load_dwordx2 v[18:19], v112, s[0:1]
	s_add_u32 s0, s0, 0x1400
	s_addc_u32 s1, s1, 0
	global_load_dwordx2 v[20:21], v113, s[0:1]
	global_load_dwordx2 v[22:23], v112, s[0:1]
	s_add_u32 s0, s0, 0x1400
	s_addc_u32 s1, s1, 0
	global_load_dwordx2 v[24:25], v113, s[0:1]
	global_load_dwordx2 v[26:27], v112, s[0:1]
	s_add_u32 s0, s0, 0x1400
	s_addc_u32 s1, s1, 0
	global_load_dwordx2 v[28:29], v113, s[0:1]
	global_load_dwordx2 v[30:31], v112, s[0:1]
	s_add_u32 s0, s0, 0x1400
	s_addc_u32 s1, s1, 0
	s_waitcnt vmcnt(32)
	v_lshlrev_b32_e32 v92, 16, v32
	v_and_b32_e32 v93, 0xffff0000, v32
	v_lshlrev_b32_e32 v94, 16, v33
	v_and_b32_e32 v95, 0xffff0000, v33
	v_mul_f32_e32 v92, 0xbfb8aa3b, v92
	v_mul_f32_e32 v93, 0xbfb8aa3b, v93
	v_mul_f32_e32 v94, 0xbfb8aa3b, v94
	v_mul_f32_e32 v95, 0xbfb8aa3b, v95
	v_exp_f32_e32 v92, v92
	v_exp_f32_e32 v93, v93
	v_exp_f32_e32 v94, v94
	v_exp_f32_e32 v95, v95
	v_add_f32_e32 v92, 1.0, v92
	v_add_f32_e32 v93, 1.0, v93
	v_add_f32_e32 v94, 1.0, v94
	v_add_f32_e32 v95, 1.0, v95
	v_rcp_f32_e32 v92, v92
	v_rcp_f32_e32 v93, v93
	v_rcp_f32_e32 v94, v94
	v_rcp_f32_e32 v95, v95
	v_fma_f32 v96, v72, v92, v68
	v_fma_f32 v97, v73, v93, v69
	v_fma_f32 v98, v74, v94, v70
	v_fma_f32 v99, v75, v95, v71
	v_cmp_gt_f32_e64 s[22:23], s30, v96
	v_cmp_gt_f32_e64 s[24:25], s30, v97
	v_cmp_gt_f32_e64 s[26:27], s30, v98
	v_cmp_gt_f32_e64 s[28:29], s30, v99
	v_cndmask_b32_e64 v92, 0, 32, s[22:23]
	v_cndmask_b32_e64 v93, 0, 32, s[24:25]
	v_cndmask_b32_e64 v94, 0, 32, s[26:27]
	v_cndmask_b32_e64 v95, 0, 32, s[28:29]
	v_ldexp_f32 v92, v96, v92
	v_ldexp_f32 v93, v97, v93
	v_ldexp_f32 v94, v98, v94
	v_ldexp_f32 v95, v99, v95
	v_log_f32_e32 v92, v92
	v_log_f32_e32 v93, v93
	v_log_f32_e32 v94, v94
	v_log_f32_e32 v95, v95
	v_mul_f32_e32 v100, 0x3f317217, v92
	v_mul_f32_e32 v101, 0x3f317217, v93
	v_mul_f32_e32 v102, 0x3f317217, v94
	v_mul_f32_e32 v103, 0x3f317217, v95
	v_fma_f32 v100, v92, s31, -v100
	v_fma_f32 v101, v93, s31, -v101
	v_fma_f32 v102, v94, s31, -v102
	v_fma_f32 v103, v95, s31, -v103
	v_fmac_f32_e32 v100, 0x3377d1cf, v92
	v_fmac_f32_e32 v101, 0x3377d1cf, v93
	v_fmac_f32_e32 v102, 0x3377d1cf, v94
	v_fmac_f32_e32 v103, 0x3377d1cf, v95
	v_fmac_f32_e32 v100, 0x3f317217, v92
	v_fmac_f32_e32 v101, 0x3f317217, v93
; DEV u16 f2bf(float f) { return (u16)(pack2(f, f) & 0xffffu); }
; DEV float bf2f(u16 h) { return __uint_as_float(((unsigned)h) << 16); }
; DEV float sigmoid_f(float x) { return __builtin_amdgcn_rcpf(1.f + __expf(-x)); }
; DEV void phase_p15(const Params& p, int g) {
;     ...
;           const float f = lb[cc] + (1.f - lb[cc]) * sigmoid_f(bf2f(xr[st][cc][e]));
;           G[cc] += __logf(f);
;           const float eg = __expf(G[cc]), ig = __expf(-G[cc]);
;           Qp[tok * 512 + c] = f2bf(bf2f(qr[st][cc][e]) * eg);
;           const u16 kk = f2bf((1.f - f) * ig);
;           Kp[tok * 512 + c] = kk;
;           kb[e] = kk;
;         }
;         const int s0 = dir ? 56 - 8 * j8 : 8 * j8;
;         uint4 w;
;         w.x = dir ? (kb[7] | (kb[6] << 16)) : (kb[0] | (kb[1] << 16));
;         w.y = dir ? (kb[5] | (kb[4] << 16)) : (kb[2] | (kb[3] << 16));
;         w.z = dir ? (kb[3] | (kb[2] << 16)) : (kb[4] | (kb[5] << 16));
;         w.w = dir ? (kb[1] | (kb[0] << 16)) : (kb[6] | (kb[7] << 16));
;         *(uint4*)(KT + (((size_t)cidx * 2 + dir) * 512 + c) * 64 + s0) = w;
	v_fmac_f32_e32 v102, 0x3f317217, v94
	v_fmac_f32_e32 v103, 0x3f317217, v95
	v_cmp_lt_f32_e64 vcc, |v92|, s34
	v_cndmask_b32_e32 v92, v92, v100, vcc
	v_cmp_lt_f32_e64 vcc, |v93|, s34
	v_cndmask_b32_e32 v93, v93, v101, vcc
	v_cmp_lt_f32_e64 vcc, |v94|, s34
	v_cndmask_b32_e32 v94, v94, v102, vcc
	v_cmp_lt_f32_e64 vcc, |v95|, s34
	v_cndmask_b32_e32 v95, v95, v103, vcc
	v_cndmask_b32_e64 v100, 0, v213, s[22:23]
	v_cndmask_b32_e64 v101, 0, v213, s[24:25]
	v_cndmask_b32_e64 v102, 0, v213, s[26:27]
	v_cndmask_b32_e64 v103, 0, v213, s[28:29]
	v_sub_f32_e32 v92, v92, v100
	v_sub_f32_e32 v93, v93, v101
	v_sub_f32_e32 v94, v94, v102
	v_sub_f32_e32 v95, v95, v103
	v_add_f32_e32 v64, v64, v92
	v_add_f32_e32 v65, v65, v93
	v_add_f32_e32 v66, v66, v94
	v_add_f32_e32 v67, v67, v95
	v_mul_f32_e32 v92, 0xbfb8aa3b, v64
	v_mul_f32_e32 v93, 0xbfb8aa3b, v65
	v_mul_f32_e32 v94, 0xbfb8aa3b, v66
	v_mul_f32_e32 v95, 0xbfb8aa3b, v67
	v_mul_f32_e32 v100, 0x3fb8aa3b, v64
	v_mul_f32_e32 v101, 0x3fb8aa3b, v65
	v_mul_f32_e32 v102, 0x3fb8aa3b, v66
	v_mul_f32_e32 v103, 0x3fb8aa3b, v67
	v_exp_f32_e32 v92, v92
	v_exp_f32_e32 v93, v93
	v_exp_f32_e32 v94, v94
	v_exp_f32_e32 v95, v95
	v_exp_f32_e32 v100, v100
	v_exp_f32_e32 v101, v101
	v_exp_f32_e32 v102, v102
	v_exp_f32_e32 v103, v103
	v_sub_f32_e32 v96, 1.0, v96
	v_sub_f32_e32 v97, 1.0, v97
	v_sub_f32_e32 v98, 1.0, v98
	v_sub_f32_e32 v99, 1.0, v99
	v_mul_f32_e32 v96, v96, v92
	v_mul_f32_e32 v97, v97, v93
	v_mul_f32_e32 v98, v98, v94
	v_mul_f32_e32 v99, v99, v95
	v_lshlrev_b32_e32 v92, 16, v34
	v_and_b32_e32 v93, 0xffff0000, v34
	v_lshlrev_b32_e32 v94, 16, v35
	v_and_b32_e32 v95, 0xffff0000, v35
	v_mul_f32_e32 v92, v92, v100
	v_mul_f32_e32 v93, v93, v101
	v_mul_f32_e32 v94, v94, v102
	v_mul_f32_e32 v95, v95, v103
	v_mov_b32_e32 v120, v96
	v_mov_b32_e32 v136, v97
	v_mov_b32_e32 v170, v98
	v_mov_b32_e32 v186, v99
	v_cvt_pk_bf16_f32 v92, v92, v93
	v_cvt_pk_bf16_f32 v93, v94, v95
	v_cvt_pk_bf16_f32 v96, v96, v97
	v_cvt_pk_bf16_f32 v97, v98, v99
	global_store_dwordx2 v112, v[92:93], s[2:3]
	global_store_dwordx2 v114, v[96:97], s[2:3]
	s_add_u32 s2, s2, 0x400
	s_addc_u32 s3, s3, 0
	v_lshlrev_b32_e32 v92, 16, v36
	v_and_b32_e32 v93, 0xffff0000, v36
	v_lshlrev_b32_e32 v94, 16, v37
	v_and_b32_e32 v95, 0xffff0000, v37
	v_mul_f32_e32 v92, 0xbfb8aa3b, v92
	v_mul_f32_e32 v93, 0xbfb8aa3b, v93
	v_mul_f32_e32 v94, 0xbfb8aa3b, v94
	v_mul_f32_e32 v95, 0xbfb8aa3b, v95
	v_exp_f32_e32 v92, v92
	v_exp_f32_e32 v93, v93
	v_exp_f32_e32 v94, v94
	v_exp_f32_e32 v95, v95
	v_add_f32_e32 v92, 1.0, v92
	v_add_f32_e32 v93, 1.0, v93
	v_add_f32_e32 v94, 1.0, v94
	v_add_f32_e32 v95, 1.0, v95
	v_rcp_f32_e32 v92, v92
	v_rcp_f32_e32 v93, v93
	v_rcp_f32_e32 v94, v94
	v_rcp_f32_e32 v95, v95
	v_fma_f32 v96, v72, v92, v68
	v_fma_f32 v97, v73, v93, v69
	v_fma_f32 v98, v74, v94, v70
	v_fma_f32 v99, v75, v95, v71
	v_cmp_gt_f32_e64 s[22:23], s30, v96
	v_cmp_gt_f32_e64 s[24:25], s30, v97
	v_cmp_gt_f32_e64 s[26:27], s30, v98
	v_cmp_gt_f32_e64 s[28:29], s30, v99
	v_cndmask_b32_e64 v92, 0, 32, s[22:23]
	v_cndmask_b32_e64 v93, 0, 32, s[24:25]
	v_cndmask_b32_e64 v94, 0, 32, s[26:27]
	v_cndmask_b32_e64 v95, 0, 32, s[28:29]
	v_ldexp_f32 v92, v96, v92
	v_ldexp_f32 v93, v97, v93
	v_ldexp_f32 v94, v98, v94
	v_ldexp_f32 v95, v99, v95
	v_log_f32_e32 v92, v92
	v_log_f32_e32 v93, v93
	v_log_f32_e32 v94, v94
	v_log_f32_e32 v95, v95
	v_mul_f32_e32 v100, 0x3f317217, v92
	v_mul_f32_e32 v101, 0x3f317217, v93
	v_mul_f32_e32 v102, 0x3f317217, v94
	v_mul_f32_e32 v103, 0x3f317217, v95
	v_fma_f32 v100, v92, s31, -v100
	v_fma_f32 v101, v93, s31, -v101
	v_fma_f32 v102, v94, s31, -v102
	v_fma_f32 v103, v95, s31, -v103
	v_fmac_f32_e32 v100, 0x3377d1cf, v92
	v_fmac_f32_e32 v101, 0x3377d1cf, v93
	v_fmac_f32_e32 v102, 0x3377d1cf, v94
	v_fmac_f32_e32 v103, 0x3377d1cf, v95
	v_fmac_f32_e32 v100, 0x3f317217, v92
	v_fmac_f32_e32 v101, 0x3f317217, v93
	v_fmac_f32_e32 v102, 0x3f317217, v94
	v_fmac_f32_e32 v103, 0x3f317217, v95
	v_cmp_lt_f32_e64 vcc, |v92|, s34
	v_cndmask_b32_e32 v92, v92, v100, vcc
	v_cmp_lt_f32_e64 vcc, |v93|, s34
	v_cndmask_b32_e32 v93, v93, v101, vcc
	v_cmp_lt_f32_e64 vcc, |v94|, s34
	v_cndmask_b32_e32 v94, v94, v102, vcc
	v_cmp_lt_f32_e64 vcc, |v95|, s34
	v_cndmask_b32_e32 v95, v95, v103, vcc
	v_cndmask_b32_e64 v100, 0, v213, s[22:23]
	v_cndmask_b32_e64 v101, 0, v213, s[24:25]
	v_cndmask_b32_e64 v102, 0, v213, s[26:27]
	v_cndmask_b32_e64 v103, 0, v213, s[28:29]
	v_sub_f32_e32 v92, v92, v100
	v_sub_f32_e32 v93, v93, v101
	v_sub_f32_e32 v94, v94, v102
	v_sub_f32_e32 v95, v95, v103
	v_add_f32_e32 v64, v64, v92
	v_add_f32_e32 v65, v65, v93
	v_add_f32_e32 v66, v66, v94
	v_add_f32_e32 v67, v67, v95
	v_mul_f32_e32 v92, 0xbfb8aa3b, v64
	v_mul_f32_e32 v93, 0xbfb8aa3b, v65
	v_mul_f32_e32 v94, 0xbfb8aa3b, v66
	v_mul_f32_e32 v95, 0xbfb8aa3b, v67
	v_mul_f32_e32 v100, 0x3fb8aa3b, v64
	v_mul_f32_e32 v101, 0x3fb8aa3b, v65
	v_mul_f32_e32 v102, 0x3fb8aa3b, v66
	v_mul_f32_e32 v103, 0x3fb8aa3b, v67
	v_exp_f32_e32 v92, v92
	v_exp_f32_e32 v93, v93
	v_exp_f32_e32 v94, v94
	v_exp_f32_e32 v95, v95
	v_exp_f32_e32 v100, v100
	v_exp_f32_e32 v101, v101
	v_exp_f32_e32 v102, v102
	v_exp_f32_e32 v103, v103
	v_sub_f32_e32 v96, 1.0, v96
	v_sub_f32_e32 v97, 1.0, v97
	v_sub_f32_e32 v98, 1.0, v98
	v_sub_f32_e32 v99, 1.0, v99
	v_mul_f32_e32 v96, v96, v92
	v_mul_f32_e32 v97, v97, v93
	v_mul_f32_e32 v98, v98, v94
	v_mul_f32_e32 v99, v99, v95
	v_lshlrev_b32_e32 v92, 16, v38
	v_and_b32_e32 v93, 0xffff0000, v38
	v_lshlrev_b32_e32 v94, 16, v39
	v_and_b32_e32 v95, 0xffff0000, v39
	v_mul_f32_e32 v92, v92, v100
	v_mul_f32_e32 v93, v93, v101
	v_mul_f32_e32 v94, v94, v102
	v_mul_f32_e32 v95, v95, v103
	v_cvt_pk_bf16_f32 v120, v120, v96
; DEV u16 f2bf(float f) { return (u16)(pack2(f, f) & 0xffffu); }
; DEV float bf2f(u16 h) { return __uint_as_float(((unsigned)h) << 16); }
; DEV float sigmoid_f(float x) { return __builtin_amdgcn_rcpf(1.f + __expf(-x)); }
; DEV void phase_p15(const Params& p, int g) {
;     ...
;           const float f = lb[cc] + (1.f - lb[cc]) * sigmoid_f(bf2f(xr[st][cc][e]));
;           G[cc] += __logf(f);
;           const float eg = __expf(G[cc]), ig = __expf(-G[cc]);
;           Qp[tok * 512 + c] = f2bf(bf2f(qr[st][cc][e]) * eg);
;           const u16 kk = f2bf((1.f - f) * ig);
;           Kp[tok * 512 + c] = kk;
;           kb[e] = kk;
;         }
;         const int s0 = dir ? 56 - 8 * j8 : 8 * j8;
;         uint4 w;
;         w.x = dir ? (kb[7] | (kb[6] << 16)) : (kb[0] | (kb[1] << 16));
;         w.y = dir ? (kb[5] | (kb[4] << 16)) : (kb[2] | (kb[3] << 16));
;         w.z = dir ? (kb[3] | (kb[2] << 16)) : (kb[4] | (kb[5] << 16));
;         w.w = dir ? (kb[1] | (kb[0] << 16)) : (kb[6] | (kb[7] << 16));
;         *(uint4*)(KT + (((size_t)cidx * 2 + dir) * 512 + c) * 64 + s0) = w;
	v_cvt_pk_bf16_f32 v136, v136, v97
	v_cvt_pk_bf16_f32 v170, v170, v98
	v_cvt_pk_bf16_f32 v186, v186, v99
	v_cvt_pk_bf16_f32 v92, v92, v93
	v_cvt_pk_bf16_f32 v93, v94, v95
	v_cvt_pk_bf16_f32 v96, v96, v97
	v_cvt_pk_bf16_f32 v97, v98, v99
	global_store_dwordx2 v112, v[92:93], s[2:3]
	global_store_dwordx2 v114, v[96:97], s[2:3]
	s_add_u32 s2, s2, 0x400
	s_addc_u32 s3, s3, 0
	v_lshlrev_b32_e32 v92, 16, v40
	v_and_b32_e32 v93, 0xffff0000, v40
	v_lshlrev_b32_e32 v94, 16, v41
	v_and_b32_e32 v95, 0xffff0000, v41
	v_mul_f32_e32 v92, 0xbfb8aa3b, v92
	v_mul_f32_e32 v93, 0xbfb8aa3b, v93
	v_mul_f32_e32 v94, 0xbfb8aa3b, v94
	v_mul_f32_e32 v95, 0xbfb8aa3b, v95
	v_exp_f32_e32 v92, v92
	v_exp_f32_e32 v93, v93
	v_exp_f32_e32 v94, v94
	v_exp_f32_e32 v95, v95
	v_add_f32_e32 v92, 1.0, v92
	v_add_f32_e32 v93, 1.0, v93
	v_add_f32_e32 v94, 1.0, v94
	v_add_f32_e32 v95, 1.0, v95
	v_rcp_f32_e32 v92, v92
	v_rcp_f32_e32 v93, v93
	v_rcp_f32_e32 v94, v94
	v_rcp_f32_e32 v95, v95
	v_fma_f32 v96, v72, v92, v68
	v_fma_f32 v97, v73, v93, v69
	v_fma_f32 v98, v74, v94, v70
	v_fma_f32 v99, v75, v95, v71
	v_cmp_gt_f32_e64 s[22:23], s30, v96
	v_cmp_gt_f32_e64 s[24:25], s30, v97
	v_cmp_gt_f32_e64 s[26:27], s30, v98
	v_cmp_gt_f32_e64 s[28:29], s30, v99
	v_cndmask_b32_e64 v92, 0, 32, s[22:23]
	v_cndmask_b32_e64 v93, 0, 32, s[24:25]
	v_cndmask_b32_e64 v94, 0, 32, s[26:27]
	v_cndmask_b32_e64 v95, 0, 32, s[28:29]
	v_ldexp_f32 v92, v96, v92
	v_ldexp_f32 v93, v97, v93
	v_ldexp_f32 v94, v98, v94
	v_ldexp_f32 v95, v99, v95
	v_log_f32_e32 v92, v92
	v_log_f32_e32 v93, v93
	v_log_f32_e32 v94, v94
	v_log_f32_e32 v95, v95
	v_mul_f32_e32 v100, 0x3f317217, v92
	v_mul_f32_e32 v101, 0x3f317217, v93
	v_mul_f32_e32 v102, 0x3f317217, v94
	v_mul_f32_e32 v103, 0x3f317217, v95
	v_fma_f32 v100, v92, s31, -v100
	v_fma_f32 v101, v93, s31, -v101
	v_fma_f32 v102, v94, s31, -v102
	v_fma_f32 v103, v95, s31, -v103
	v_fmac_f32_e32 v100, 0x3377d1cf, v92
	v_fmac_f32_e32 v101, 0x3377d1cf, v93
	v_fmac_f32_e32 v102, 0x3377d1cf, v94
	v_fmac_f32_e32 v103, 0x3377d1cf, v95
	v_fmac_f32_e32 v100, 0x3f317217, v92
	v_fmac_f32_e32 v101, 0x3f317217, v93
	v_fmac_f32_e32 v102, 0x3f317217, v94
	v_fmac_f32_e32 v103, 0x3f317217, v95
	v_cmp_lt_f32_e64 vcc, |v92|, s34
	v_cndmask_b32_e32 v92, v92, v100, vcc
	v_cmp_lt_f32_e64 vcc, |v93|, s34
	v_cndmask_b32_e32 v93, v93, v101, vcc
	v_cmp_lt_f32_e64 vcc, |v94|, s34
	v_cndmask_b32_e32 v94, v94, v102, vcc
	v_cmp_lt_f32_e64 vcc, |v95|, s34
	v_cndmask_b32_e32 v95, v95, v103, vcc
	v_cndmask_b32_e64 v100, 0, v213, s[22:23]
	v_cndmask_b32_e64 v101, 0, v213, s[24:25]
	v_cndmask_b32_e64 v102, 0, v213, s[26:27]
	v_cndmask_b32_e64 v103, 0, v213, s[28:29]
	v_sub_f32_e32 v92, v92, v100
	v_sub_f32_e32 v93, v93, v101
	v_sub_f32_e32 v94, v94, v102
	v_sub_f32_e32 v95, v95, v103
	v_add_f32_e32 v64, v64, v92
	v_add_f32_e32 v65, v65, v93
	v_add_f32_e32 v66, v66, v94
	v_add_f32_e32 v67, v67, v95
	v_mul_f32_e32 v92, 0xbfb8aa3b, v64
	v_mul_f32_e32 v93, 0xbfb8aa3b, v65
	v_mul_f32_e32 v94, 0xbfb8aa3b, v66
	v_mul_f32_e32 v95, 0xbfb8aa3b, v67
	v_mul_f32_e32 v100, 0x3fb8aa3b, v64
	v_mul_f32_e32 v101, 0x3fb8aa3b, v65
	v_mul_f32_e32 v102, 0x3fb8aa3b, v66
	v_mul_f32_e32 v103, 0x3fb8aa3b, v67
	v_exp_f32_e32 v92, v92
	v_exp_f32_e32 v93, v93
	v_exp_f32_e32 v94, v94
	v_exp_f32_e32 v95, v95
	v_exp_f32_e32 v100, v100
	v_exp_f32_e32 v101, v101
	v_exp_f32_e32 v102, v102
	v_exp_f32_e32 v103, v103
	v_sub_f32_e32 v96, 1.0, v96
	v_sub_f32_e32 v97, 1.0, v97
	v_sub_f32_e32 v98, 1.0, v98
	v_sub_f32_e32 v99, 1.0, v99
	v_mul_f32_e32 v96, v96, v92
	v_mul_f32_e32 v97, v97, v93
	v_mul_f32_e32 v98, v98, v94
	v_mul_f32_e32 v99, v99, v95
	v_lshlrev_b32_e32 v92, 16, v42
	v_and_b32_e32 v93, 0xffff0000, v42
	v_lshlrev_b32_e32 v94, 16, v43
	v_and_b32_e32 v95, 0xffff0000, v43
	v_mul_f32_e32 v92, v92, v100
	v_mul_f32_e32 v93, v93, v101
	v_mul_f32_e32 v94, v94, v102
	v_mul_f32_e32 v95, v95, v103
	v_mov_b32_e32 v121, v96
	v_mov_b32_e32 v137, v97
	v_mov_b32_e32 v171, v98
	v_mov_b32_e32 v187, v99
	v_cvt_pk_bf16_f32 v92, v92, v93
	v_cvt_pk_bf16_f32 v93, v94, v95
	v_cvt_pk_bf16_f32 v96, v96, v97
	v_cvt_pk_bf16_f32 v97, v98, v99
	global_store_dwordx2 v112, v[92:93], s[2:3]
	global_store_dwordx2 v114, v[96:97], s[2:3]
	s_add_u32 s2, s2, 0x400
	s_addc_u32 s3, s3, 0
	v_lshlrev_b32_e32 v92, 16, v44
	v_and_b32_e32 v93, 0xffff0000, v44
	v_lshlrev_b32_e32 v94, 16, v45
	v_and_b32_e32 v95, 0xffff0000, v45
	v_mul_f32_e32 v92, 0xbfb8aa3b, v92
	v_mul_f32_e32 v93, 0xbfb8aa3b, v93
	v_mul_f32_e32 v94, 0xbfb8aa3b, v94
	v_mul_f32_e32 v95, 0xbfb8aa3b, v95
	v_exp_f32_e32 v92, v92
	v_exp_f32_e32 v93, v93
	v_exp_f32_e32 v94, v94
	v_exp_f32_e32 v95, v95
	v_add_f32_e32 v92, 1.0, v92
	v_add_f32_e32 v93, 1.0, v93
	v_add_f32_e32 v94, 1.0, v94
	v_add_f32_e32 v95, 1.0, v95
	v_rcp_f32_e32 v92, v92
	v_rcp_f32_e32 v93, v93
	v_rcp_f32_e32 v94, v94
	v_rcp_f32_e32 v95, v95
	v_fma_f32 v96, v72, v92, v68
	v_fma_f32 v97, v73, v93, v69
	v_fma_f32 v98, v74, v94, v70
	v_fma_f32 v99, v75, v95, v71
	v_cmp_gt_f32_e64 s[22:23], s30, v96
	v_cmp_gt_f32_e64 s[24:25], s30, v97
	v_cmp_gt_f32_e64 s[26:27], s30, v98
	v_cmp_gt_f32_e64 s[28:29], s30, v99
	v_cndmask_b32_e64 v92, 0, 32, s[22:23]
	v_cndmask_b32_e64 v93, 0, 32, s[24:25]
	v_cndmask_b32_e64 v94, 0, 32, s[26:27]
	v_cndmask_b32_e64 v95, 0, 32, s[28:29]
	v_ldexp_f32 v92, v96, v92
	v_ldexp_f32 v93, v97, v93
	v_ldexp_f32 v94, v98, v94
	v_ldexp_f32 v95, v99, v95
	v_log_f32_e32 v92, v92
	v_log_f32_e32 v93, v93
	v_log_f32_e32 v94, v94
	v_log_f32_e32 v95, v95
	v_mul_f32_e32 v100, 0x3f317217, v92
	v_mul_f32_e32 v101, 0x3f317217, v93
	v_mul_f32_e32 v102, 0x3f317217, v94
	v_mul_f32_e32 v103, 0x3f317217, v95
	v_fma_f32 v100, v92, s31, -v100
; DEV u16 f2bf(float f) { return (u16)(pack2(f, f) & 0xffffu); }
; DEV float bf2f(u16 h) { return __uint_as_float(((unsigned)h) << 16); }
; DEV float sigmoid_f(float x) { return __builtin_amdgcn_rcpf(1.f + __expf(-x)); }
; DEV void phase_p15(const Params& p, int g) {
;     ...
;           const float f = lb[cc] + (1.f - lb[cc]) * sigmoid_f(bf2f(xr[st][cc][e]));
;           G[cc] += __logf(f);
;           const float eg = __expf(G[cc]), ig = __expf(-G[cc]);
;           Qp[tok * 512 + c] = f2bf(bf2f(qr[st][cc][e]) * eg);
;           const u16 kk = f2bf((1.f - f) * ig);
;           Kp[tok * 512 + c] = kk;
;           kb[e] = kk;
;         }
;         const int s0 = dir ? 56 - 8 * j8 : 8 * j8;
;         uint4 w;
;         w.x = dir ? (kb[7] | (kb[6] << 16)) : (kb[0] | (kb[1] << 16));
;         w.y = dir ? (kb[5] | (kb[4] << 16)) : (kb[2] | (kb[3] << 16));
;         w.z = dir ? (kb[3] | (kb[2] << 16)) : (kb[4] | (kb[5] << 16));
;         w.w = dir ? (kb[1] | (kb[0] << 16)) : (kb[6] | (kb[7] << 16));
;         *(uint4*)(KT + (((size_t)cidx * 2 + dir) * 512 + c) * 64 + s0) = w;
	v_fma_f32 v101, v93, s31, -v101
	v_fma_f32 v102, v94, s31, -v102
	v_fma_f32 v103, v95, s31, -v103
	v_fmac_f32_e32 v100, 0x3377d1cf, v92
	v_fmac_f32_e32 v101, 0x3377d1cf, v93
	v_fmac_f32_e32 v102, 0x3377d1cf, v94
	v_fmac_f32_e32 v103, 0x3377d1cf, v95
	v_fmac_f32_e32 v100, 0x3f317217, v92
	v_fmac_f32_e32 v101, 0x3f317217, v93
	v_fmac_f32_e32 v102, 0x3f317217, v94
	v_fmac_f32_e32 v103, 0x3f317217, v95
	v_cmp_lt_f32_e64 vcc, |v92|, s34
	v_cndmask_b32_e32 v92, v92, v100, vcc
	v_cmp_lt_f32_e64 vcc, |v93|, s34
	v_cndmask_b32_e32 v93, v93, v101, vcc
	v_cmp_lt_f32_e64 vcc, |v94|, s34
	v_cndmask_b32_e32 v94, v94, v102, vcc
	v_cmp_lt_f32_e64 vcc, |v95|, s34
	v_cndmask_b32_e32 v95, v95, v103, vcc
	v_cndmask_b32_e64 v100, 0, v213, s[22:23]
	v_cndmask_b32_e64 v101, 0, v213, s[24:25]
	v_cndmask_b32_e64 v102, 0, v213, s[26:27]
	v_cndmask_b32_e64 v103, 0, v213, s[28:29]
	v_sub_f32_e32 v92, v92, v100
	v_sub_f32_e32 v93, v93, v101
	v_sub_f32_e32 v94, v94, v102
	v_sub_f32_e32 v95, v95, v103
	v_add_f32_e32 v64, v64, v92
	v_add_f32_e32 v65, v65, v93
	v_add_f32_e32 v66, v66, v94
	v_add_f32_e32 v67, v67, v95
	v_mul_f32_e32 v92, 0xbfb8aa3b, v64
	v_mul_f32_e32 v93, 0xbfb8aa3b, v65
	v_mul_f32_e32 v94, 0xbfb8aa3b, v66
	v_mul_f32_e32 v95, 0xbfb8aa3b, v67
	v_mul_f32_e32 v100, 0x3fb8aa3b, v64
	v_mul_f32_e32 v101, 0x3fb8aa3b, v65
	v_mul_f32_e32 v102, 0x3fb8aa3b, v66
	v_mul_f32_e32 v103, 0x3fb8aa3b, v67
	v_exp_f32_e32 v92, v92
	v_exp_f32_e32 v93, v93
	v_exp_f32_e32 v94, v94
	v_exp_f32_e32 v95, v95
	v_exp_f32_e32 v100, v100
	v_exp_f32_e32 v101, v101
	v_exp_f32_e32 v102, v102
	v_exp_f32_e32 v103, v103
	v_sub_f32_e32 v96, 1.0, v96
	v_sub_f32_e32 v97, 1.0, v97
	v_sub_f32_e32 v98, 1.0, v98
	v_sub_f32_e32 v99, 1.0, v99
	v_mul_f32_e32 v96, v96, v92
	v_mul_f32_e32 v97, v97, v93
	v_mul_f32_e32 v98, v98, v94
	v_mul_f32_e32 v99, v99, v95
	v_lshlrev_b32_e32 v92, 16, v46
	v_and_b32_e32 v93, 0xffff0000, v46
	v_lshlrev_b32_e32 v94, 16, v47
	v_and_b32_e32 v95, 0xffff0000, v47
	v_mul_f32_e32 v92, v92, v100
	v_mul_f32_e32 v93, v93, v101
	v_mul_f32_e32 v94, v94, v102
	v_mul_f32_e32 v95, v95, v103
	v_cvt_pk_bf16_f32 v121, v121, v96
	v_cvt_pk_bf16_f32 v137, v137, v97
	v_cvt_pk_bf16_f32 v171, v171, v98
	v_cvt_pk_bf16_f32 v187, v187, v99
	v_cvt_pk_bf16_f32 v92, v92, v93
	v_cvt_pk_bf16_f32 v93, v94, v95
	v_cvt_pk_bf16_f32 v96, v96, v97
	v_cvt_pk_bf16_f32 v97, v98, v99
	global_store_dwordx2 v112, v[92:93], s[2:3]
	global_store_dwordx2 v114, v[96:97], s[2:3]
	s_add_u32 s2, s2, 0x400
	s_addc_u32 s3, s3, 0
	v_lshlrev_b32_e32 v92, 16, v48
	v_and_b32_e32 v93, 0xffff0000, v48
	v_lshlrev_b32_e32 v94, 16, v49
	v_and_b32_e32 v95, 0xffff0000, v49
	v_mul_f32_e32 v92, 0xbfb8aa3b, v92
	v_mul_f32_e32 v93, 0xbfb8aa3b, v93
	v_mul_f32_e32 v94, 0xbfb8aa3b, v94
	v_mul_f32_e32 v95, 0xbfb8aa3b, v95
	v_exp_f32_e32 v92, v92
	v_exp_f32_e32 v93, v93
	v_exp_f32_e32 v94, v94
	v_exp_f32_e32 v95, v95
	v_add_f32_e32 v92, 1.0, v92
	v_add_f32_e32 v93, 1.0, v93
	v_add_f32_e32 v94, 1.0, v94
	v_add_f32_e32 v95, 1.0, v95
	v_rcp_f32_e32 v92, v92
	v_rcp_f32_e32 v93, v93
	v_rcp_f32_e32 v94, v94
	v_rcp_f32_e32 v95, v95
	v_fma_f32 v96, v72, v92, v68
	v_fma_f32 v97, v73, v93, v69
	v_fma_f32 v98, v74, v94, v70
	v_fma_f32 v99, v75, v95, v71
	v_cmp_gt_f32_e64 s[22:23], s30, v96
	v_cmp_gt_f32_e64 s[24:25], s30, v97
	v_cmp_gt_f32_e64 s[26:27], s30, v98
	v_cmp_gt_f32_e64 s[28:29], s30, v99
	v_cndmask_b32_e64 v92, 0, 32, s[22:23]
	v_cndmask_b32_e64 v93, 0, 32, s[24:25]
	v_cndmask_b32_e64 v94, 0, 32, s[26:27]
	v_cndmask_b32_e64 v95, 0, 32, s[28:29]
	v_ldexp_f32 v92, v96, v92
	v_ldexp_f32 v93, v97, v93
	v_ldexp_f32 v94, v98, v94
	v_ldexp_f32 v95, v99, v95
	v_log_f32_e32 v92, v92
	v_log_f32_e32 v93, v93
	v_log_f32_e32 v94, v94
	v_log_f32_e32 v95, v95
	v_mul_f32_e32 v100, 0x3f317217, v92
	v_mul_f32_e32 v101, 0x3f317217, v93
	v_mul_f32_e32 v102, 0x3f317217, v94
	v_mul_f32_e32 v103, 0x3f317217, v95
	v_fma_f32 v100, v92, s31, -v100
	v_fma_f32 v101, v93, s31, -v101
	v_fma_f32 v102, v94, s31, -v102
	v_fma_f32 v103, v95, s31, -v103
	v_fmac_f32_e32 v100, 0x3377d1cf, v92
	v_fmac_f32_e32 v101, 0x3377d1cf, v93
	v_fmac_f32_e32 v102, 0x3377d1cf, v94
	v_fmac_f32_e32 v103, 0x3377d1cf, v95
	v_fmac_f32_e32 v100, 0x3f317217, v92
	v_fmac_f32_e32 v101, 0x3f317217, v93
	v_fmac_f32_e32 v102, 0x3f317217, v94
	v_fmac_f32_e32 v103, 0x3f317217, v95
	v_cmp_lt_f32_e64 vcc, |v92|, s34
	v_cndmask_b32_e32 v92, v92, v100, vcc
	v_cmp_lt_f32_e64 vcc, |v93|, s34
	v_cndmask_b32_e32 v93, v93, v101, vcc
	v_cmp_lt_f32_e64 vcc, |v94|, s34
	v_cndmask_b32_e32 v94, v94, v102, vcc
	v_cmp_lt_f32_e64 vcc, |v95|, s34
	v_cndmask_b32_e32 v95, v95, v103, vcc
	v_cndmask_b32_e64 v100, 0, v213, s[22:23]
	v_cndmask_b32_e64 v101, 0, v213, s[24:25]
	v_cndmask_b32_e64 v102, 0, v213, s[26:27]
	v_cndmask_b32_e64 v103, 0, v213, s[28:29]
	v_sub_f32_e32 v92, v92, v100
	v_sub_f32_e32 v93, v93, v101
	v_sub_f32_e32 v94, v94, v102
	v_sub_f32_e32 v95, v95, v103
	v_add_f32_e32 v64, v64, v92
	v_add_f32_e32 v65, v65, v93
	v_add_f32_e32 v66, v66, v94
	v_add_f32_e32 v67, v67, v95
	v_mul_f32_e32 v92, 0xbfb8aa3b, v64
	v_mul_f32_e32 v93, 0xbfb8aa3b, v65
	v_mul_f32_e32 v94, 0xbfb8aa3b, v66
	v_mul_f32_e32 v95, 0xbfb8aa3b, v67
	v_mul_f32_e32 v100, 0x3fb8aa3b, v64
	v_mul_f32_e32 v101, 0x3fb8aa3b, v65
	v_mul_f32_e32 v102, 0x3fb8aa3b, v66
	v_mul_f32_e32 v103, 0x3fb8aa3b, v67
	v_exp_f32_e32 v92, v92
	v_exp_f32_e32 v93, v93
	v_exp_f32_e32 v94, v94
	v_exp_f32_e32 v95, v95
	v_exp_f32_e32 v100, v100
	v_exp_f32_e32 v101, v101
	v_exp_f32_e32 v102, v102
	v_exp_f32_e32 v103, v103
	v_sub_f32_e32 v96, 1.0, v96
	v_sub_f32_e32 v97, 1.0, v97
	v_sub_f32_e32 v98, 1.0, v98
	v_sub_f32_e32 v99, 1.0, v99
	v_mul_f32_e32 v96, v96, v92
; DEV u16 f2bf(float f) { return (u16)(pack2(f, f) & 0xffffu); }
; DEV float bf2f(u16 h) { return __uint_as_float(((unsigned)h) << 16); }
; DEV float sigmoid_f(float x) { return __builtin_amdgcn_rcpf(1.f + __expf(-x)); }
; DEV void phase_p15(const Params& p, int g) {
;     ...
;           const float f = lb[cc] + (1.f - lb[cc]) * sigmoid_f(bf2f(xr[st][cc][e]));
;           G[cc] += __logf(f);
;           const float eg = __expf(G[cc]), ig = __expf(-G[cc]);
;           Qp[tok * 512 + c] = f2bf(bf2f(qr[st][cc][e]) * eg);
;           const u16 kk = f2bf((1.f - f) * ig);
;           Kp[tok * 512 + c] = kk;
;           kb[e] = kk;
;         }
;         const int s0 = dir ? 56 - 8 * j8 : 8 * j8;
;         uint4 w;
;         w.x = dir ? (kb[7] | (kb[6] << 16)) : (kb[0] | (kb[1] << 16));
;         w.y = dir ? (kb[5] | (kb[4] << 16)) : (kb[2] | (kb[3] << 16));
;         w.z = dir ? (kb[3] | (kb[2] << 16)) : (kb[4] | (kb[5] << 16));
;         w.w = dir ? (kb[1] | (kb[0] << 16)) : (kb[6] | (kb[7] << 16));
;         *(uint4*)(KT + (((size_t)cidx * 2 + dir) * 512 + c) * 64 + s0) = w;
	v_mul_f32_e32 v97, v97, v93
	v_mul_f32_e32 v98, v98, v94
	v_mul_f32_e32 v99, v99, v95
	v_lshlrev_b32_e32 v92, 16, v50
	v_and_b32_e32 v93, 0xffff0000, v50
	v_lshlrev_b32_e32 v94, 16, v51
	v_and_b32_e32 v95, 0xffff0000, v51
	v_mul_f32_e32 v92, v92, v100
	v_mul_f32_e32 v93, v93, v101
	v_mul_f32_e32 v94, v94, v102
	v_mul_f32_e32 v95, v95, v103
	v_mov_b32_e32 v122, v96
	v_mov_b32_e32 v138, v97
	v_mov_b32_e32 v172, v98
	v_mov_b32_e32 v188, v99
	v_cvt_pk_bf16_f32 v92, v92, v93
	v_cvt_pk_bf16_f32 v93, v94, v95
	v_cvt_pk_bf16_f32 v96, v96, v97
	v_cvt_pk_bf16_f32 v97, v98, v99
	global_store_dwordx2 v112, v[92:93], s[2:3]
	global_store_dwordx2 v114, v[96:97], s[2:3]
	s_add_u32 s2, s2, 0x400
	s_addc_u32 s3, s3, 0
	v_lshlrev_b32_e32 v92, 16, v52
	v_and_b32_e32 v93, 0xffff0000, v52
	v_lshlrev_b32_e32 v94, 16, v53
	v_and_b32_e32 v95, 0xffff0000, v53
	v_mul_f32_e32 v92, 0xbfb8aa3b, v92
	v_mul_f32_e32 v93, 0xbfb8aa3b, v93
	v_mul_f32_e32 v94, 0xbfb8aa3b, v94
	v_mul_f32_e32 v95, 0xbfb8aa3b, v95
	v_exp_f32_e32 v92, v92
	v_exp_f32_e32 v93, v93
	v_exp_f32_e32 v94, v94
	v_exp_f32_e32 v95, v95
	v_add_f32_e32 v92, 1.0, v92
	v_add_f32_e32 v93, 1.0, v93
	v_add_f32_e32 v94, 1.0, v94
	v_add_f32_e32 v95, 1.0, v95
	v_rcp_f32_e32 v92, v92
	v_rcp_f32_e32 v93, v93
	v_rcp_f32_e32 v94, v94
	v_rcp_f32_e32 v95, v95
	v_fma_f32 v96, v72, v92, v68
	v_fma_f32 v97, v73, v93, v69
	v_fma_f32 v98, v74, v94, v70
	v_fma_f32 v99, v75, v95, v71
	v_cmp_gt_f32_e64 s[22:23], s30, v96
	v_cmp_gt_f32_e64 s[24:25], s30, v97
	v_cmp_gt_f32_e64 s[26:27], s30, v98
	v_cmp_gt_f32_e64 s[28:29], s30, v99
	v_cndmask_b32_e64 v92, 0, 32, s[22:23]
	v_cndmask_b32_e64 v93, 0, 32, s[24:25]
	v_cndmask_b32_e64 v94, 0, 32, s[26:27]
	v_cndmask_b32_e64 v95, 0, 32, s[28:29]
	v_ldexp_f32 v92, v96, v92
	v_ldexp_f32 v93, v97, v93
	v_ldexp_f32 v94, v98, v94
	v_ldexp_f32 v95, v99, v95
	v_log_f32_e32 v92, v92
	v_log_f32_e32 v93, v93
	v_log_f32_e32 v94, v94
	v_log_f32_e32 v95, v95
	v_mul_f32_e32 v100, 0x3f317217, v92
	v_mul_f32_e32 v101, 0x3f317217, v93
	v_mul_f32_e32 v102, 0x3f317217, v94
	v_mul_f32_e32 v103, 0x3f317217, v95
	v_fma_f32 v100, v92, s31, -v100
	v_fma_f32 v101, v93, s31, -v101
	v_fma_f32 v102, v94, s31, -v102
	v_fma_f32 v103, v95, s31, -v103
	v_fmac_f32_e32 v100, 0x3377d1cf, v92
	v_fmac_f32_e32 v101, 0x3377d1cf, v93
	v_fmac_f32_e32 v102, 0x3377d1cf, v94
	v_fmac_f32_e32 v103, 0x3377d1cf, v95
	v_fmac_f32_e32 v100, 0x3f317217, v92
	v_fmac_f32_e32 v101, 0x3f317217, v93
	v_fmac_f32_e32 v102, 0x3f317217, v94
	v_fmac_f32_e32 v103, 0x3f317217, v95
	v_cmp_lt_f32_e64 vcc, |v92|, s34
	v_cndmask_b32_e32 v92, v92, v100, vcc
	v_cmp_lt_f32_e64 vcc, |v93|, s34
	v_cndmask_b32_e32 v93, v93, v101, vcc
	v_cmp_lt_f32_e64 vcc, |v94|, s34
	v_cndmask_b32_e32 v94, v94, v102, vcc
	v_cmp_lt_f32_e64 vcc, |v95|, s34
	v_cndmask_b32_e32 v95, v95, v103, vcc
	v_cndmask_b32_e64 v100, 0, v213, s[22:23]
	v_cndmask_b32_e64 v101, 0, v213, s[24:25]
	v_cndmask_b32_e64 v102, 0, v213, s[26:27]
	v_cndmask_b32_e64 v103, 0, v213, s[28:29]
	v_sub_f32_e32 v92, v92, v100
	v_sub_f32_e32 v93, v93, v101
	v_sub_f32_e32 v94, v94, v102
	v_sub_f32_e32 v95, v95, v103
	v_add_f32_e32 v64, v64, v92
	v_add_f32_e32 v65, v65, v93
	v_add_f32_e32 v66, v66, v94
	v_add_f32_e32 v67, v67, v95
	v_mul_f32_e32 v92, 0xbfb8aa3b, v64
	v_mul_f32_e32 v93, 0xbfb8aa3b, v65
	v_mul_f32_e32 v94, 0xbfb8aa3b, v66
	v_mul_f32_e32 v95, 0xbfb8aa3b, v67
	v_mul_f32_e32 v100, 0x3fb8aa3b, v64
	v_mul_f32_e32 v101, 0x3fb8aa3b, v65
	v_mul_f32_e32 v102, 0x3fb8aa3b, v66
	v_mul_f32_e32 v103, 0x3fb8aa3b, v67
	v_exp_f32_e32 v92, v92
	v_exp_f32_e32 v93, v93
	v_exp_f32_e32 v94, v94
	v_exp_f32_e32 v95, v95
	v_exp_f32_e32 v100, v100
	v_exp_f32_e32 v101, v101
	v_exp_f32_e32 v102, v102
	v_exp_f32_e32 v103, v103
	v_sub_f32_e32 v96, 1.0, v96
	v_sub_f32_e32 v97, 1.0, v97
	v_sub_f32_e32 v98, 1.0, v98
	v_sub_f32_e32 v99, 1.0, v99
	v_mul_f32_e32 v96, v96, v92
	v_mul_f32_e32 v97, v97, v93
	v_mul_f32_e32 v98, v98, v94
	v_mul_f32_e32 v99, v99, v95
	v_lshlrev_b32_e32 v92, 16, v54
	v_and_b32_e32 v93, 0xffff0000, v54
	v_lshlrev_b32_e32 v94, 16, v55
	v_and_b32_e32 v95, 0xffff0000, v55
	v_mul_f32_e32 v92, v92, v100
	v_mul_f32_e32 v93, v93, v101
	v_mul_f32_e32 v94, v94, v102
	v_mul_f32_e32 v95, v95, v103
	v_cvt_pk_bf16_f32 v122, v122, v96
	v_cvt_pk_bf16_f32 v138, v138, v97
	v_cvt_pk_bf16_f32 v172, v172, v98
	v_cvt_pk_bf16_f32 v188, v188, v99
	v_cvt_pk_bf16_f32 v92, v92, v93
	v_cvt_pk_bf16_f32 v93, v94, v95
	v_cvt_pk_bf16_f32 v96, v96, v97
	v_cvt_pk_bf16_f32 v97, v98, v99
	global_store_dwordx2 v112, v[92:93], s[2:3]
	global_store_dwordx2 v114, v[96:97], s[2:3]
	s_add_u32 s2, s2, 0x400
	s_addc_u32 s3, s3, 0
	v_lshlrev_b32_e32 v92, 16, v56
	v_and_b32_e32 v93, 0xffff0000, v56
	v_lshlrev_b32_e32 v94, 16, v57
	v_and_b32_e32 v95, 0xffff0000, v57
	v_mul_f32_e32 v92, 0xbfb8aa3b, v92
	v_mul_f32_e32 v93, 0xbfb8aa3b, v93
	v_mul_f32_e32 v94, 0xbfb8aa3b, v94
	v_mul_f32_e32 v95, 0xbfb8aa3b, v95
	v_exp_f32_e32 v92, v92
	v_exp_f32_e32 v93, v93
	v_exp_f32_e32 v94, v94
	v_exp_f32_e32 v95, v95
	v_add_f32_e32 v92, 1.0, v92
	v_add_f32_e32 v93, 1.0, v93
	v_add_f32_e32 v94, 1.0, v94
	v_add_f32_e32 v95, 1.0, v95
	v_rcp_f32_e32 v92, v92
	v_rcp_f32_e32 v93, v93
	v_rcp_f32_e32 v94, v94
	v_rcp_f32_e32 v95, v95
	v_fma_f32 v96, v72, v92, v68
	v_fma_f32 v97, v73, v93, v69
	v_fma_f32 v98, v74, v94, v70
	v_fma_f32 v99, v75, v95, v71
	v_cmp_gt_f32_e64 s[22:23], s30, v96
	v_cmp_gt_f32_e64 s[24:25], s30, v97
	v_cmp_gt_f32_e64 s[26:27], s30, v98
	v_cmp_gt_f32_e64 s[28:29], s30, v99
	v_cndmask_b32_e64 v92, 0, 32, s[22:23]
	v_cndmask_b32_e64 v93, 0, 32, s[24:25]
	v_cndmask_b32_e64 v94, 0, 32, s[26:27]
	v_cndmask_b32_e64 v95, 0, 32, s[28:29]
	v_ldexp_f32 v92, v96, v92
; DEV u16 f2bf(float f) { return (u16)(pack2(f, f) & 0xffffu); }
; DEV float bf2f(u16 h) { return __uint_as_float(((unsigned)h) << 16); }
; DEV float sigmoid_f(float x) { return __builtin_amdgcn_rcpf(1.f + __expf(-x)); }
; DEV void phase_p15(const Params& p, int g) {
;     ...
;           const float f = lb[cc] + (1.f - lb[cc]) * sigmoid_f(bf2f(xr[st][cc][e]));
;           G[cc] += __logf(f);
;           const float eg = __expf(G[cc]), ig = __expf(-G[cc]);
;           Qp[tok * 512 + c] = f2bf(bf2f(qr[st][cc][e]) * eg);
;           const u16 kk = f2bf((1.f - f) * ig);
;           Kp[tok * 512 + c] = kk;
;           kb[e] = kk;
;         }
;         const int s0 = dir ? 56 - 8 * j8 : 8 * j8;
;         uint4 w;
;         w.x = dir ? (kb[7] | (kb[6] << 16)) : (kb[0] | (kb[1] << 16));
;         w.y = dir ? (kb[5] | (kb[4] << 16)) : (kb[2] | (kb[3] << 16));
;         w.z = dir ? (kb[3] | (kb[2] << 16)) : (kb[4] | (kb[5] << 16));
;         w.w = dir ? (kb[1] | (kb[0] << 16)) : (kb[6] | (kb[7] << 16));
;         *(uint4*)(KT + (((size_t)cidx * 2 + dir) * 512 + c) * 64 + s0) = w;
	v_ldexp_f32 v93, v97, v93
	v_ldexp_f32 v94, v98, v94
	v_ldexp_f32 v95, v99, v95
	v_log_f32_e32 v92, v92
	v_log_f32_e32 v93, v93
	v_log_f32_e32 v94, v94
	v_log_f32_e32 v95, v95
	v_mul_f32_e32 v100, 0x3f317217, v92
	v_mul_f32_e32 v101, 0x3f317217, v93
	v_mul_f32_e32 v102, 0x3f317217, v94
	v_mul_f32_e32 v103, 0x3f317217, v95
	v_fma_f32 v100, v92, s31, -v100
	v_fma_f32 v101, v93, s31, -v101
	v_fma_f32 v102, v94, s31, -v102
	v_fma_f32 v103, v95, s31, -v103
	v_fmac_f32_e32 v100, 0x3377d1cf, v92
	v_fmac_f32_e32 v101, 0x3377d1cf, v93
	v_fmac_f32_e32 v102, 0x3377d1cf, v94
	v_fmac_f32_e32 v103, 0x3377d1cf, v95
	v_fmac_f32_e32 v100, 0x3f317217, v92
	v_fmac_f32_e32 v101, 0x3f317217, v93
	v_fmac_f32_e32 v102, 0x3f317217, v94
	v_fmac_f32_e32 v103, 0x3f317217, v95
	v_cmp_lt_f32_e64 vcc, |v92|, s34
	v_cndmask_b32_e32 v92, v92, v100, vcc
	v_cmp_lt_f32_e64 vcc, |v93|, s34
	v_cndmask_b32_e32 v93, v93, v101, vcc
	v_cmp_lt_f32_e64 vcc, |v94|, s34
	v_cndmask_b32_e32 v94, v94, v102, vcc
	v_cmp_lt_f32_e64 vcc, |v95|, s34
	v_cndmask_b32_e32 v95, v95, v103, vcc
	v_cndmask_b32_e64 v100, 0, v213, s[22:23]
	v_cndmask_b32_e64 v101, 0, v213, s[24:25]
	v_cndmask_b32_e64 v102, 0, v213, s[26:27]
	v_cndmask_b32_e64 v103, 0, v213, s[28:29]
	v_sub_f32_e32 v92, v92, v100
	v_sub_f32_e32 v93, v93, v101
	v_sub_f32_e32 v94, v94, v102
	v_sub_f32_e32 v95, v95, v103
	v_add_f32_e32 v64, v64, v92
	v_add_f32_e32 v65, v65, v93
	v_add_f32_e32 v66, v66, v94
	v_add_f32_e32 v67, v67, v95
	v_mul_f32_e32 v92, 0xbfb8aa3b, v64
	v_mul_f32_e32 v93, 0xbfb8aa3b, v65
	v_mul_f32_e32 v94, 0xbfb8aa3b, v66
	v_mul_f32_e32 v95, 0xbfb8aa3b, v67
	v_mul_f32_e32 v100, 0x3fb8aa3b, v64
	v_mul_f32_e32 v101, 0x3fb8aa3b, v65
	v_mul_f32_e32 v102, 0x3fb8aa3b, v66
	v_mul_f32_e32 v103, 0x3fb8aa3b, v67
	v_exp_f32_e32 v92, v92
	v_exp_f32_e32 v93, v93
	v_exp_f32_e32 v94, v94
	v_exp_f32_e32 v95, v95
	v_exp_f32_e32 v100, v100
	v_exp_f32_e32 v101, v101
	v_exp_f32_e32 v102, v102
	v_exp_f32_e32 v103, v103
	v_sub_f32_e32 v96, 1.0, v96
	v_sub_f32_e32 v97, 1.0, v97
	v_sub_f32_e32 v98, 1.0, v98
	v_sub_f32_e32 v99, 1.0, v99
	v_mul_f32_e32 v96, v96, v92
	v_mul_f32_e32 v97, v97, v93
	v_mul_f32_e32 v98, v98, v94
	v_mul_f32_e32 v99, v99, v95
	v_lshlrev_b32_e32 v92, 16, v58
	v_and_b32_e32 v93, 0xffff0000, v58
	v_lshlrev_b32_e32 v94, 16, v59
	v_and_b32_e32 v95, 0xffff0000, v59
	v_mul_f32_e32 v92, v92, v100
	v_mul_f32_e32 v93, v93, v101
	v_mul_f32_e32 v94, v94, v102
	v_mul_f32_e32 v95, v95, v103
	v_mov_b32_e32 v123, v96
	v_mov_b32_e32 v139, v97
	v_mov_b32_e32 v173, v98
	v_mov_b32_e32 v189, v99
	v_cvt_pk_bf16_f32 v92, v92, v93
	v_cvt_pk_bf16_f32 v93, v94, v95
	v_cvt_pk_bf16_f32 v96, v96, v97
	v_cvt_pk_bf16_f32 v97, v98, v99
	global_store_dwordx2 v112, v[92:93], s[2:3]
	global_store_dwordx2 v114, v[96:97], s[2:3]
	s_add_u32 s2, s2, 0x400
	s_addc_u32 s3, s3, 0
	v_lshlrev_b32_e32 v92, 16, v60
	v_and_b32_e32 v93, 0xffff0000, v60
	v_lshlrev_b32_e32 v94, 16, v61
	v_and_b32_e32 v95, 0xffff0000, v61
	v_mul_f32_e32 v92, 0xbfb8aa3b, v92
	v_mul_f32_e32 v93, 0xbfb8aa3b, v93
	v_mul_f32_e32 v94, 0xbfb8aa3b, v94
	v_mul_f32_e32 v95, 0xbfb8aa3b, v95
	v_exp_f32_e32 v92, v92
	v_exp_f32_e32 v93, v93
	v_exp_f32_e32 v94, v94
	v_exp_f32_e32 v95, v95
	v_add_f32_e32 v92, 1.0, v92
	v_add_f32_e32 v93, 1.0, v93
	v_add_f32_e32 v94, 1.0, v94
	v_add_f32_e32 v95, 1.0, v95
	v_rcp_f32_e32 v92, v92
	v_rcp_f32_e32 v93, v93
	v_rcp_f32_e32 v94, v94
	v_rcp_f32_e32 v95, v95
	v_fma_f32 v96, v72, v92, v68
	v_fma_f32 v97, v73, v93, v69
	v_fma_f32 v98, v74, v94, v70
	v_fma_f32 v99, v75, v95, v71
	v_cmp_gt_f32_e64 s[22:23], s30, v96
	v_cmp_gt_f32_e64 s[24:25], s30, v97
	v_cmp_gt_f32_e64 s[26:27], s30, v98
	v_cmp_gt_f32_e64 s[28:29], s30, v99
	v_cndmask_b32_e64 v92, 0, 32, s[22:23]
	v_cndmask_b32_e64 v93, 0, 32, s[24:25]
	v_cndmask_b32_e64 v94, 0, 32, s[26:27]
	v_cndmask_b32_e64 v95, 0, 32, s[28:29]
	v_ldexp_f32 v92, v96, v92
	v_ldexp_f32 v93, v97, v93
	v_ldexp_f32 v94, v98, v94
	v_ldexp_f32 v95, v99, v95
	v_log_f32_e32 v92, v92
	v_log_f32_e32 v93, v93
	v_log_f32_e32 v94, v94
	v_log_f32_e32 v95, v95
	v_mul_f32_e32 v100, 0x3f317217, v92
	v_mul_f32_e32 v101, 0x3f317217, v93
	v_mul_f32_e32 v102, 0x3f317217, v94
	v_mul_f32_e32 v103, 0x3f317217, v95
	v_fma_f32 v100, v92, s31, -v100
	v_fma_f32 v101, v93, s31, -v101
	v_fma_f32 v102, v94, s31, -v102
	v_fma_f32 v103, v95, s31, -v103
	v_fmac_f32_e32 v100, 0x3377d1cf, v92
	v_fmac_f32_e32 v101, 0x3377d1cf, v93
	v_fmac_f32_e32 v102, 0x3377d1cf, v94
	v_fmac_f32_e32 v103, 0x3377d1cf, v95
	v_fmac_f32_e32 v100, 0x3f317217, v92
	v_fmac_f32_e32 v101, 0x3f317217, v93
	v_fmac_f32_e32 v102, 0x3f317217, v94
	v_fmac_f32_e32 v103, 0x3f317217, v95
	v_cmp_lt_f32_e64 vcc, |v92|, s34
	v_cndmask_b32_e32 v92, v92, v100, vcc
	v_cmp_lt_f32_e64 vcc, |v93|, s34
	v_cndmask_b32_e32 v93, v93, v101, vcc
	v_cmp_lt_f32_e64 vcc, |v94|, s34
	v_cndmask_b32_e32 v94, v94, v102, vcc
	v_cmp_lt_f32_e64 vcc, |v95|, s34
	v_cndmask_b32_e32 v95, v95, v103, vcc
	v_cndmask_b32_e64 v100, 0, v213, s[22:23]
	v_cndmask_b32_e64 v101, 0, v213, s[24:25]
	v_cndmask_b32_e64 v102, 0, v213, s[26:27]
	v_cndmask_b32_e64 v103, 0, v213, s[28:29]
	v_sub_f32_e32 v92, v92, v100
	v_sub_f32_e32 v93, v93, v101
	v_sub_f32_e32 v94, v94, v102
	v_sub_f32_e32 v95, v95, v103
	v_add_f32_e32 v64, v64, v92
	v_add_f32_e32 v65, v65, v93
	v_add_f32_e32 v66, v66, v94
	v_add_f32_e32 v67, v67, v95
	v_mul_f32_e32 v92, 0xbfb8aa3b, v64
	v_mul_f32_e32 v93, 0xbfb8aa3b, v65
	v_mul_f32_e32 v94, 0xbfb8aa3b, v66
	v_mul_f32_e32 v95, 0xbfb8aa3b, v67
	v_mul_f32_e32 v100, 0x3fb8aa3b, v64
	v_mul_f32_e32 v101, 0x3fb8aa3b, v65
	v_mul_f32_e32 v102, 0x3fb8aa3b, v66
	v_mul_f32_e32 v103, 0x3fb8aa3b, v67
	v_exp_f32_e32 v92, v92
; DEV u16 f2bf(float f) { return (u16)(pack2(f, f) & 0xffffu); }
; DEV float bf2f(u16 h) { return __uint_as_float(((unsigned)h) << 16); }
; DEV float sigmoid_f(float x) { return __builtin_amdgcn_rcpf(1.f + __expf(-x)); }
; DEV void phase_p15(const Params& p, int g) {
;     ...
;           const float f = lb[cc] + (1.f - lb[cc]) * sigmoid_f(bf2f(xr[st][cc][e]));
;           G[cc] += __logf(f);
;           const float eg = __expf(G[cc]), ig = __expf(-G[cc]);
;           Qp[tok * 512 + c] = f2bf(bf2f(qr[st][cc][e]) * eg);
;           const u16 kk = f2bf((1.f - f) * ig);
;           Kp[tok * 512 + c] = kk;
;           kb[e] = kk;
;         }
;         const int s0 = dir ? 56 - 8 * j8 : 8 * j8;
;         uint4 w;
;         w.x = dir ? (kb[7] | (kb[6] << 16)) : (kb[0] | (kb[1] << 16));
;         w.y = dir ? (kb[5] | (kb[4] << 16)) : (kb[2] | (kb[3] << 16));
;         w.z = dir ? (kb[3] | (kb[2] << 16)) : (kb[4] | (kb[5] << 16));
;         w.w = dir ? (kb[1] | (kb[0] << 16)) : (kb[6] | (kb[7] << 16));
;         *(uint4*)(KT + (((size_t)cidx * 2 + dir) * 512 + c) * 64 + s0) = w;
	v_exp_f32_e32 v93, v93
	v_exp_f32_e32 v94, v94
	v_exp_f32_e32 v95, v95
	v_exp_f32_e32 v100, v100
	v_exp_f32_e32 v101, v101
	v_exp_f32_e32 v102, v102
	v_exp_f32_e32 v103, v103
	v_sub_f32_e32 v96, 1.0, v96
	v_sub_f32_e32 v97, 1.0, v97
	v_sub_f32_e32 v98, 1.0, v98
	v_sub_f32_e32 v99, 1.0, v99
	v_mul_f32_e32 v96, v96, v92
	v_mul_f32_e32 v97, v97, v93
	v_mul_f32_e32 v98, v98, v94
	v_mul_f32_e32 v99, v99, v95
	v_lshlrev_b32_e32 v92, 16, v62
	v_and_b32_e32 v93, 0xffff0000, v62
	v_lshlrev_b32_e32 v94, 16, v63
	v_and_b32_e32 v95, 0xffff0000, v63
	v_mul_f32_e32 v92, v92, v100
	v_mul_f32_e32 v93, v93, v101
	v_mul_f32_e32 v94, v94, v102
	v_mul_f32_e32 v95, v95, v103
	v_cvt_pk_bf16_f32 v123, v123, v96
	v_cvt_pk_bf16_f32 v139, v139, v97
	v_cvt_pk_bf16_f32 v173, v173, v98
	v_cvt_pk_bf16_f32 v189, v189, v99
	v_cvt_pk_bf16_f32 v92, v92, v93
	v_cvt_pk_bf16_f32 v93, v94, v95
	v_cvt_pk_bf16_f32 v96, v96, v97
	v_cvt_pk_bf16_f32 v97, v98, v99
	global_store_dwordx2 v112, v[92:93], s[2:3]
	global_store_dwordx2 v114, v[96:97], s[2:3]
	s_add_u32 s2, s2, 0x400
	s_addc_u32 s3, s3, 0
	global_load_dwordx2 v[32:33], v113, s[0:1]
	global_load_dwordx2 v[34:35], v112, s[0:1]
	s_add_u32 s0, s0, 0x1400
	s_addc_u32 s1, s1, 0
	global_load_dwordx2 v[36:37], v113, s[0:1]
	global_load_dwordx2 v[38:39], v112, s[0:1]
	s_add_u32 s0, s0, 0x1400
	s_addc_u32 s1, s1, 0
	global_load_dwordx2 v[40:41], v113, s[0:1]
	global_load_dwordx2 v[42:43], v112, s[0:1]
	s_add_u32 s0, s0, 0x1400
	s_addc_u32 s1, s1, 0
	global_load_dwordx2 v[44:45], v113, s[0:1]
	global_load_dwordx2 v[46:47], v112, s[0:1]
	s_add_u32 s0, s0, 0x1400
	s_addc_u32 s1, s1, 0
	global_load_dwordx2 v[48:49], v113, s[0:1]
	global_load_dwordx2 v[50:51], v112, s[0:1]
	s_add_u32 s0, s0, 0x1400
	s_addc_u32 s1, s1, 0
	global_load_dwordx2 v[52:53], v113, s[0:1]
	global_load_dwordx2 v[54:55], v112, s[0:1]
	s_add_u32 s0, s0, 0x1400
	s_addc_u32 s1, s1, 0
	global_load_dwordx2 v[56:57], v113, s[0:1]
	global_load_dwordx2 v[58:59], v112, s[0:1]
	s_add_u32 s0, s0, 0x1400
	s_addc_u32 s1, s1, 0
	global_load_dwordx2 v[60:61], v113, s[0:1]
	global_load_dwordx2 v[62:63], v112, s[0:1]
	s_add_u32 s0, s0, 0x1400
	s_addc_u32 s1, s1, 0
	s_waitcnt vmcnt(32)
	v_lshlrev_b32_e32 v92, 16, v0
	v_and_b32_e32 v93, 0xffff0000, v0
	v_lshlrev_b32_e32 v94, 16, v1
	v_and_b32_e32 v95, 0xffff0000, v1
	v_mul_f32_e32 v92, 0xbfb8aa3b, v92
	v_mul_f32_e32 v93, 0xbfb8aa3b, v93
	v_mul_f32_e32 v94, 0xbfb8aa3b, v94
	v_mul_f32_e32 v95, 0xbfb8aa3b, v95
	v_exp_f32_e32 v92, v92
	v_exp_f32_e32 v93, v93
	v_exp_f32_e32 v94, v94
	v_exp_f32_e32 v95, v95
	v_add_f32_e32 v92, 1.0, v92
	v_add_f32_e32 v93, 1.0, v93
	v_add_f32_e32 v94, 1.0, v94
	v_add_f32_e32 v95, 1.0, v95
	v_rcp_f32_e32 v92, v92
	v_rcp_f32_e32 v93, v93
	v_rcp_f32_e32 v94, v94
	v_rcp_f32_e32 v95, v95
	v_fma_f32 v96, v72, v92, v68
	v_fma_f32 v97, v73, v93, v69
	v_fma_f32 v98, v74, v94, v70
	v_fma_f32 v99, v75, v95, v71
	v_cmp_gt_f32_e64 s[22:23], s30, v96
	v_cmp_gt_f32_e64 s[24:25], s30, v97
	v_cmp_gt_f32_e64 s[26:27], s30, v98
	v_cmp_gt_f32_e64 s[28:29], s30, v99
	v_cndmask_b32_e64 v92, 0, 32, s[22:23]
	v_cndmask_b32_e64 v93, 0, 32, s[24:25]
	v_cndmask_b32_e64 v94, 0, 32, s[26:27]
	v_cndmask_b32_e64 v95, 0, 32, s[28:29]
	v_ldexp_f32 v92, v96, v92
	v_ldexp_f32 v93, v97, v93
	v_ldexp_f32 v94, v98, v94
	v_ldexp_f32 v95, v99, v95
	v_log_f32_e32 v92, v92
	v_log_f32_e32 v93, v93
	v_log_f32_e32 v94, v94
	v_log_f32_e32 v95, v95
	v_mul_f32_e32 v100, 0x3f317217, v92
	v_mul_f32_e32 v101, 0x3f317217, v93
	v_mul_f32_e32 v102, 0x3f317217, v94
	v_mul_f32_e32 v103, 0x3f317217, v95
	v_fma_f32 v100, v92, s31, -v100
	v_fma_f32 v101, v93, s31, -v101
	v_fma_f32 v102, v94, s31, -v102
	v_fma_f32 v103, v95, s31, -v103
	v_fmac_f32_e32 v100, 0x3377d1cf, v92
	v_fmac_f32_e32 v101, 0x3377d1cf, v93
	v_fmac_f32_e32 v102, 0x3377d1cf, v94
	v_fmac_f32_e32 v103, 0x3377d1cf, v95
	v_fmac_f32_e32 v100, 0x3f317217, v92
	v_fmac_f32_e32 v101, 0x3f317217, v93
	v_fmac_f32_e32 v102, 0x3f317217, v94
	v_fmac_f32_e32 v103, 0x3f317217, v95
	v_cmp_lt_f32_e64 vcc, |v92|, s34
	v_cndmask_b32_e32 v92, v92, v100, vcc
	v_cmp_lt_f32_e64 vcc, |v93|, s34
	v_cndmask_b32_e32 v93, v93, v101, vcc
	v_cmp_lt_f32_e64 vcc, |v94|, s34
	v_cndmask_b32_e32 v94, v94, v102, vcc
	v_cmp_lt_f32_e64 vcc, |v95|, s34
	v_cndmask_b32_e32 v95, v95, v103, vcc
	v_cndmask_b32_e64 v100, 0, v213, s[22:23]
	v_cndmask_b32_e64 v101, 0, v213, s[24:25]
	v_cndmask_b32_e64 v102, 0, v213, s[26:27]
	v_cndmask_b32_e64 v103, 0, v213, s[28:29]
	v_sub_f32_e32 v92, v92, v100
	v_sub_f32_e32 v93, v93, v101
	v_sub_f32_e32 v94, v94, v102
	v_sub_f32_e32 v95, v95, v103
	v_add_f32_e32 v64, v64, v92
	v_add_f32_e32 v65, v65, v93
	v_add_f32_e32 v66, v66, v94
	v_add_f32_e32 v67, v67, v95
	v_mul_f32_e32 v92, 0xbfb8aa3b, v64
	v_mul_f32_e32 v93, 0xbfb8aa3b, v65
	v_mul_f32_e32 v94, 0xbfb8aa3b, v66
	v_mul_f32_e32 v95, 0xbfb8aa3b, v67
	v_mul_f32_e32 v100, 0x3fb8aa3b, v64
	v_mul_f32_e32 v101, 0x3fb8aa3b, v65
	v_mul_f32_e32 v102, 0x3fb8aa3b, v66
	v_mul_f32_e32 v103, 0x3fb8aa3b, v67
	v_exp_f32_e32 v92, v92
	v_exp_f32_e32 v93, v93
	v_exp_f32_e32 v94, v94
	v_exp_f32_e32 v95, v95
	v_exp_f32_e32 v100, v100
	v_exp_f32_e32 v101, v101
	v_exp_f32_e32 v102, v102
	v_exp_f32_e32 v103, v103
	v_sub_f32_e32 v96, 1.0, v96
	v_sub_f32_e32 v97, 1.0, v97
	v_sub_f32_e32 v98, 1.0, v98
	v_sub_f32_e32 v99, 1.0, v99
	v_mul_f32_e32 v96, v96, v92
	v_mul_f32_e32 v97, v97, v93
	v_mul_f32_e32 v98, v98, v94
	v_mul_f32_e32 v99, v99, v95
	v_lshlrev_b32_e32 v92, 16, v2
	v_and_b32_e32 v93, 0xffff0000, v2
	v_lshlrev_b32_e32 v94, 16, v3
	v_and_b32_e32 v95, 0xffff0000, v3
	v_mul_f32_e32 v92, v92, v100
	v_mul_f32_e32 v93, v93, v101
	v_mul_f32_e32 v94, v94, v102
; DEV u16 f2bf(float f) { return (u16)(pack2(f, f) & 0xffffu); }
; DEV float bf2f(u16 h) { return __uint_as_float(((unsigned)h) << 16); }
; DEV float sigmoid_f(float x) { return __builtin_amdgcn_rcpf(1.f + __expf(-x)); }
; DEV void phase_p15(const Params& p, int g) {
;     ...
;           const float f = lb[cc] + (1.f - lb[cc]) * sigmoid_f(bf2f(xr[st][cc][e]));
;           G[cc] += __logf(f);
;           const float eg = __expf(G[cc]), ig = __expf(-G[cc]);
;           Qp[tok * 512 + c] = f2bf(bf2f(qr[st][cc][e]) * eg);
;           const u16 kk = f2bf((1.f - f) * ig);
;           Kp[tok * 512 + c] = kk;
;           kb[e] = kk;
;         }
;         const int s0 = dir ? 56 - 8 * j8 : 8 * j8;
;         uint4 w;
;         w.x = dir ? (kb[7] | (kb[6] << 16)) : (kb[0] | (kb[1] << 16));
;         w.y = dir ? (kb[5] | (kb[4] << 16)) : (kb[2] | (kb[3] << 16));
;         w.z = dir ? (kb[3] | (kb[2] << 16)) : (kb[4] | (kb[5] << 16));
;         w.w = dir ? (kb[1] | (kb[0] << 16)) : (kb[6] | (kb[7] << 16));
;         *(uint4*)(KT + (((size_t)cidx * 2 + dir) * 512 + c) * 64 + s0) = w;
	v_mul_f32_e32 v95, v95, v103
	v_mov_b32_e32 v124, v96
	v_mov_b32_e32 v140, v97
	v_mov_b32_e32 v174, v98
	v_mov_b32_e32 v190, v99
	v_cvt_pk_bf16_f32 v92, v92, v93
	v_cvt_pk_bf16_f32 v93, v94, v95
	v_cvt_pk_bf16_f32 v96, v96, v97
	v_cvt_pk_bf16_f32 v97, v98, v99
	global_store_dwordx2 v112, v[92:93], s[2:3]
	global_store_dwordx2 v114, v[96:97], s[2:3]
	s_add_u32 s2, s2, 0x400
	s_addc_u32 s3, s3, 0
	v_lshlrev_b32_e32 v92, 16, v4
	v_and_b32_e32 v93, 0xffff0000, v4
	v_lshlrev_b32_e32 v94, 16, v5
	v_and_b32_e32 v95, 0xffff0000, v5
	v_mul_f32_e32 v92, 0xbfb8aa3b, v92
	v_mul_f32_e32 v93, 0xbfb8aa3b, v93
	v_mul_f32_e32 v94, 0xbfb8aa3b, v94
	v_mul_f32_e32 v95, 0xbfb8aa3b, v95
	v_exp_f32_e32 v92, v92
	v_exp_f32_e32 v93, v93
	v_exp_f32_e32 v94, v94
	v_exp_f32_e32 v95, v95
	v_add_f32_e32 v92, 1.0, v92
	v_add_f32_e32 v93, 1.0, v93
	v_add_f32_e32 v94, 1.0, v94
	v_add_f32_e32 v95, 1.0, v95
	v_rcp_f32_e32 v92, v92
	v_rcp_f32_e32 v93, v93
	v_rcp_f32_e32 v94, v94
	v_rcp_f32_e32 v95, v95
	v_fma_f32 v96, v72, v92, v68
	v_fma_f32 v97, v73, v93, v69
	v_fma_f32 v98, v74, v94, v70
	v_fma_f32 v99, v75, v95, v71
	v_cmp_gt_f32_e64 s[22:23], s30, v96
	v_cmp_gt_f32_e64 s[24:25], s30, v97
	v_cmp_gt_f32_e64 s[26:27], s30, v98
	v_cmp_gt_f32_e64 s[28:29], s30, v99
	v_cndmask_b32_e64 v92, 0, 32, s[22:23]
	v_cndmask_b32_e64 v93, 0, 32, s[24:25]
	v_cndmask_b32_e64 v94, 0, 32, s[26:27]
	v_cndmask_b32_e64 v95, 0, 32, s[28:29]
	v_ldexp_f32 v92, v96, v92
	v_ldexp_f32 v93, v97, v93
	v_ldexp_f32 v94, v98, v94
	v_ldexp_f32 v95, v99, v95
	v_log_f32_e32 v92, v92
	v_log_f32_e32 v93, v93
	v_log_f32_e32 v94, v94
	v_log_f32_e32 v95, v95
	v_mul_f32_e32 v100, 0x3f317217, v92
	v_mul_f32_e32 v101, 0x3f317217, v93
	v_mul_f32_e32 v102, 0x3f317217, v94
	v_mul_f32_e32 v103, 0x3f317217, v95
	v_fma_f32 v100, v92, s31, -v100
	v_fma_f32 v101, v93, s31, -v101
	v_fma_f32 v102, v94, s31, -v102
	v_fma_f32 v103, v95, s31, -v103
	v_fmac_f32_e32 v100, 0x3377d1cf, v92
	v_fmac_f32_e32 v101, 0x3377d1cf, v93
	v_fmac_f32_e32 v102, 0x3377d1cf, v94
	v_fmac_f32_e32 v103, 0x3377d1cf, v95
	v_fmac_f32_e32 v100, 0x3f317217, v92
	v_fmac_f32_e32 v101, 0x3f317217, v93
	v_fmac_f32_e32 v102, 0x3f317217, v94
	v_fmac_f32_e32 v103, 0x3f317217, v95
	v_cmp_lt_f32_e64 vcc, |v92|, s34
	v_cndmask_b32_e32 v92, v92, v100, vcc
	v_cmp_lt_f32_e64 vcc, |v93|, s34
	v_cndmask_b32_e32 v93, v93, v101, vcc
	v_cmp_lt_f32_e64 vcc, |v94|, s34
	v_cndmask_b32_e32 v94, v94, v102, vcc
	v_cmp_lt_f32_e64 vcc, |v95|, s34
	v_cndmask_b32_e32 v95, v95, v103, vcc
	v_cndmask_b32_e64 v100, 0, v213, s[22:23]
	v_cndmask_b32_e64 v101, 0, v213, s[24:25]
	v_cndmask_b32_e64 v102, 0, v213, s[26:27]
	v_cndmask_b32_e64 v103, 0, v213, s[28:29]
	v_sub_f32_e32 v92, v92, v100
	v_sub_f32_e32 v93, v93, v101
	v_sub_f32_e32 v94, v94, v102
	v_sub_f32_e32 v95, v95, v103
	v_add_f32_e32 v64, v64, v92
	v_add_f32_e32 v65, v65, v93
	v_add_f32_e32 v66, v66, v94
	v_add_f32_e32 v67, v67, v95
	v_mul_f32_e32 v92, 0xbfb8aa3b, v64
	v_mul_f32_e32 v93, 0xbfb8aa3b, v65
	v_mul_f32_e32 v94, 0xbfb8aa3b, v66
	v_mul_f32_e32 v95, 0xbfb8aa3b, v67
	v_mul_f32_e32 v100, 0x3fb8aa3b, v64
	v_mul_f32_e32 v101, 0x3fb8aa3b, v65
	v_mul_f32_e32 v102, 0x3fb8aa3b, v66
	v_mul_f32_e32 v103, 0x3fb8aa3b, v67
	v_exp_f32_e32 v92, v92
	v_exp_f32_e32 v93, v93
	v_exp_f32_e32 v94, v94
	v_exp_f32_e32 v95, v95
	v_exp_f32_e32 v100, v100
	v_exp_f32_e32 v101, v101
	v_exp_f32_e32 v102, v102
	v_exp_f32_e32 v103, v103
	v_sub_f32_e32 v96, 1.0, v96
	v_sub_f32_e32 v97, 1.0, v97
	v_sub_f32_e32 v98, 1.0, v98
	v_sub_f32_e32 v99, 1.0, v99
	v_mul_f32_e32 v96, v96, v92
	v_mul_f32_e32 v97, v97, v93
	v_mul_f32_e32 v98, v98, v94
	v_mul_f32_e32 v99, v99, v95
	v_lshlrev_b32_e32 v92, 16, v6
	v_and_b32_e32 v93, 0xffff0000, v6
	v_lshlrev_b32_e32 v94, 16, v7
	v_and_b32_e32 v95, 0xffff0000, v7
	v_mul_f32_e32 v92, v92, v100
	v_mul_f32_e32 v93, v93, v101
	v_mul_f32_e32 v94, v94, v102
	v_mul_f32_e32 v95, v95, v103
	v_cvt_pk_bf16_f32 v124, v124, v96
	v_cvt_pk_bf16_f32 v140, v140, v97
	v_cvt_pk_bf16_f32 v174, v174, v98
	v_cvt_pk_bf16_f32 v190, v190, v99
	v_cvt_pk_bf16_f32 v92, v92, v93
	v_cvt_pk_bf16_f32 v93, v94, v95
	v_cvt_pk_bf16_f32 v96, v96, v97
	v_cvt_pk_bf16_f32 v97, v98, v99
	global_store_dwordx2 v112, v[92:93], s[2:3]
	global_store_dwordx2 v114, v[96:97], s[2:3]
	s_add_u32 s2, s2, 0x400
	s_addc_u32 s3, s3, 0
	v_lshlrev_b32_e32 v92, 16, v8
	v_and_b32_e32 v93, 0xffff0000, v8
	v_lshlrev_b32_e32 v94, 16, v9
	v_and_b32_e32 v95, 0xffff0000, v9
	v_mul_f32_e32 v92, 0xbfb8aa3b, v92
	v_mul_f32_e32 v93, 0xbfb8aa3b, v93
	v_mul_f32_e32 v94, 0xbfb8aa3b, v94
	v_mul_f32_e32 v95, 0xbfb8aa3b, v95
	v_exp_f32_e32 v92, v92
	v_exp_f32_e32 v93, v93
	v_exp_f32_e32 v94, v94
	v_exp_f32_e32 v95, v95
	v_add_f32_e32 v92, 1.0, v92
	v_add_f32_e32 v93, 1.0, v93
	v_add_f32_e32 v94, 1.0, v94
	v_add_f32_e32 v95, 1.0, v95
	v_rcp_f32_e32 v92, v92
	v_rcp_f32_e32 v93, v93
	v_rcp_f32_e32 v94, v94
	v_rcp_f32_e32 v95, v95
	v_fma_f32 v96, v72, v92, v68
	v_fma_f32 v97, v73, v93, v69
	v_fma_f32 v98, v74, v94, v70
	v_fma_f32 v99, v75, v95, v71
	v_cmp_gt_f32_e64 s[22:23], s30, v96
	v_cmp_gt_f32_e64 s[24:25], s30, v97
	v_cmp_gt_f32_e64 s[26:27], s30, v98
	v_cmp_gt_f32_e64 s[28:29], s30, v99
	v_cndmask_b32_e64 v92, 0, 32, s[22:23]
	v_cndmask_b32_e64 v93, 0, 32, s[24:25]
	v_cndmask_b32_e64 v94, 0, 32, s[26:27]
	v_cndmask_b32_e64 v95, 0, 32, s[28:29]
	v_ldexp_f32 v92, v96, v92
	v_ldexp_f32 v93, v97, v93
	v_ldexp_f32 v94, v98, v94
	v_ldexp_f32 v95, v99, v95
	v_log_f32_e32 v92, v92
	v_log_f32_e32 v93, v93
	v_log_f32_e32 v94, v94
	v_log_f32_e32 v95, v95
	v_mul_f32_e32 v100, 0x3f317217, v92
	v_mul_f32_e32 v101, 0x3f317217, v93
	v_mul_f32_e32 v102, 0x3f317217, v94
	v_mul_f32_e32 v103, 0x3f317217, v95
; DEV u16 f2bf(float f) { return (u16)(pack2(f, f) & 0xffffu); }
; DEV float bf2f(u16 h) { return __uint_as_float(((unsigned)h) << 16); }
; DEV float sigmoid_f(float x) { return __builtin_amdgcn_rcpf(1.f + __expf(-x)); }
; DEV void phase_p15(const Params& p, int g) {
;     ...
;           const float f = lb[cc] + (1.f - lb[cc]) * sigmoid_f(bf2f(xr[st][cc][e]));
;           G[cc] += __logf(f);
;           const float eg = __expf(G[cc]), ig = __expf(-G[cc]);
;           Qp[tok * 512 + c] = f2bf(bf2f(qr[st][cc][e]) * eg);
;           const u16 kk = f2bf((1.f - f) * ig);
;           Kp[tok * 512 + c] = kk;
;           kb[e] = kk;
;         }
;         const int s0 = dir ? 56 - 8 * j8 : 8 * j8;
;         uint4 w;
;         w.x = dir ? (kb[7] | (kb[6] << 16)) : (kb[0] | (kb[1] << 16));
;         w.y = dir ? (kb[5] | (kb[4] << 16)) : (kb[2] | (kb[3] << 16));
;         w.z = dir ? (kb[3] | (kb[2] << 16)) : (kb[4] | (kb[5] << 16));
;         w.w = dir ? (kb[1] | (kb[0] << 16)) : (kb[6] | (kb[7] << 16));
;         *(uint4*)(KT + (((size_t)cidx * 2 + dir) * 512 + c) * 64 + s0) = w;
	v_fma_f32 v100, v92, s31, -v100
	v_fma_f32 v101, v93, s31, -v101
	v_fma_f32 v102, v94, s31, -v102
	v_fma_f32 v103, v95, s31, -v103
	v_fmac_f32_e32 v100, 0x3377d1cf, v92
	v_fmac_f32_e32 v101, 0x3377d1cf, v93
	v_fmac_f32_e32 v102, 0x3377d1cf, v94
	v_fmac_f32_e32 v103, 0x3377d1cf, v95
	v_fmac_f32_e32 v100, 0x3f317217, v92
	v_fmac_f32_e32 v101, 0x3f317217, v93
	v_fmac_f32_e32 v102, 0x3f317217, v94
	v_fmac_f32_e32 v103, 0x3f317217, v95
	v_cmp_lt_f32_e64 vcc, |v92|, s34
	v_cndmask_b32_e32 v92, v92, v100, vcc
	v_cmp_lt_f32_e64 vcc, |v93|, s34
	v_cndmask_b32_e32 v93, v93, v101, vcc
	v_cmp_lt_f32_e64 vcc, |v94|, s34
	v_cndmask_b32_e32 v94, v94, v102, vcc
	v_cmp_lt_f32_e64 vcc, |v95|, s34
	v_cndmask_b32_e32 v95, v95, v103, vcc
	v_cndmask_b32_e64 v100, 0, v213, s[22:23]
	v_cndmask_b32_e64 v101, 0, v213, s[24:25]
	v_cndmask_b32_e64 v102, 0, v213, s[26:27]
	v_cndmask_b32_e64 v103, 0, v213, s[28:29]
	v_sub_f32_e32 v92, v92, v100
	v_sub_f32_e32 v93, v93, v101
	v_sub_f32_e32 v94, v94, v102
	v_sub_f32_e32 v95, v95, v103
	v_add_f32_e32 v64, v64, v92
	v_add_f32_e32 v65, v65, v93
	v_add_f32_e32 v66, v66, v94
	v_add_f32_e32 v67, v67, v95
	v_mul_f32_e32 v92, 0xbfb8aa3b, v64
	v_mul_f32_e32 v93, 0xbfb8aa3b, v65
	v_mul_f32_e32 v94, 0xbfb8aa3b, v66
	v_mul_f32_e32 v95, 0xbfb8aa3b, v67
	v_mul_f32_e32 v100, 0x3fb8aa3b, v64
	v_mul_f32_e32 v101, 0x3fb8aa3b, v65
	v_mul_f32_e32 v102, 0x3fb8aa3b, v66
	v_mul_f32_e32 v103, 0x3fb8aa3b, v67
	v_exp_f32_e32 v92, v92
	v_exp_f32_e32 v93, v93
	v_exp_f32_e32 v94, v94
	v_exp_f32_e32 v95, v95
	v_exp_f32_e32 v100, v100
	v_exp_f32_e32 v101, v101
	v_exp_f32_e32 v102, v102
	v_exp_f32_e32 v103, v103
	v_sub_f32_e32 v96, 1.0, v96
	v_sub_f32_e32 v97, 1.0, v97
	v_sub_f32_e32 v98, 1.0, v98
	v_sub_f32_e32 v99, 1.0, v99
	v_mul_f32_e32 v96, v96, v92
	v_mul_f32_e32 v97, v97, v93
	v_mul_f32_e32 v98, v98, v94
	v_mul_f32_e32 v99, v99, v95
	v_lshlrev_b32_e32 v92, 16, v10
	v_and_b32_e32 v93, 0xffff0000, v10
	v_lshlrev_b32_e32 v94, 16, v11
	v_and_b32_e32 v95, 0xffff0000, v11
	v_mul_f32_e32 v92, v92, v100
	v_mul_f32_e32 v93, v93, v101
	v_mul_f32_e32 v94, v94, v102
	v_mul_f32_e32 v95, v95, v103
	v_mov_b32_e32 v125, v96
	v_mov_b32_e32 v141, v97
	v_mov_b32_e32 v175, v98
	v_mov_b32_e32 v191, v99
	v_cvt_pk_bf16_f32 v92, v92, v93
	v_cvt_pk_bf16_f32 v93, v94, v95
	v_cvt_pk_bf16_f32 v96, v96, v97
	v_cvt_pk_bf16_f32 v97, v98, v99
	global_store_dwordx2 v112, v[92:93], s[2:3]
	global_store_dwordx2 v114, v[96:97], s[2:3]
	s_add_u32 s2, s2, 0x400
	s_addc_u32 s3, s3, 0
	v_lshlrev_b32_e32 v92, 16, v12
	v_and_b32_e32 v93, 0xffff0000, v12
	v_lshlrev_b32_e32 v94, 16, v13
	v_and_b32_e32 v95, 0xffff0000, v13
	v_mul_f32_e32 v92, 0xbfb8aa3b, v92
	v_mul_f32_e32 v93, 0xbfb8aa3b, v93
	v_mul_f32_e32 v94, 0xbfb8aa3b, v94
	v_mul_f32_e32 v95, 0xbfb8aa3b, v95
	v_exp_f32_e32 v92, v92
	v_exp_f32_e32 v93, v93
	v_exp_f32_e32 v94, v94
	v_exp_f32_e32 v95, v95
	v_add_f32_e32 v92, 1.0, v92
	v_add_f32_e32 v93, 1.0, v93
	v_add_f32_e32 v94, 1.0, v94
	v_add_f32_e32 v95, 1.0, v95
	v_rcp_f32_e32 v92, v92
	v_rcp_f32_e32 v93, v93
	v_rcp_f32_e32 v94, v94
	v_rcp_f32_e32 v95, v95
	v_fma_f32 v96, v72, v92, v68
	v_fma_f32 v97, v73, v93, v69
	v_fma_f32 v98, v74, v94, v70
	v_fma_f32 v99, v75, v95, v71
	v_cmp_gt_f32_e64 s[22:23], s30, v96
	v_cmp_gt_f32_e64 s[24:25], s30, v97
	v_cmp_gt_f32_e64 s[26:27], s30, v98
	v_cmp_gt_f32_e64 s[28:29], s30, v99
	v_cndmask_b32_e64 v92, 0, 32, s[22:23]
	v_cndmask_b32_e64 v93, 0, 32, s[24:25]
	v_cndmask_b32_e64 v94, 0, 32, s[26:27]
	v_cndmask_b32_e64 v95, 0, 32, s[28:29]
	v_ldexp_f32 v92, v96, v92
	v_ldexp_f32 v93, v97, v93
	v_ldexp_f32 v94, v98, v94
	v_ldexp_f32 v95, v99, v95
	v_log_f32_e32 v92, v92
	v_log_f32_e32 v93, v93
	v_log_f32_e32 v94, v94
	v_log_f32_e32 v95, v95
	v_mul_f32_e32 v100, 0x3f317217, v92
	v_mul_f32_e32 v101, 0x3f317217, v93
	v_mul_f32_e32 v102, 0x3f317217, v94
	v_mul_f32_e32 v103, 0x3f317217, v95
	v_fma_f32 v100, v92, s31, -v100
	v_fma_f32 v101, v93, s31, -v101
	v_fma_f32 v102, v94, s31, -v102
	v_fma_f32 v103, v95, s31, -v103
	v_fmac_f32_e32 v100, 0x3377d1cf, v92
	v_fmac_f32_e32 v101, 0x3377d1cf, v93
	v_fmac_f32_e32 v102, 0x3377d1cf, v94
	v_fmac_f32_e32 v103, 0x3377d1cf, v95
	v_fmac_f32_e32 v100, 0x3f317217, v92
	v_fmac_f32_e32 v101, 0x3f317217, v93
	v_fmac_f32_e32 v102, 0x3f317217, v94
	v_fmac_f32_e32 v103, 0x3f317217, v95
	v_cmp_lt_f32_e64 vcc, |v92|, s34
	v_cndmask_b32_e32 v92, v92, v100, vcc
	v_cmp_lt_f32_e64 vcc, |v93|, s34
	v_cndmask_b32_e32 v93, v93, v101, vcc
	v_cmp_lt_f32_e64 vcc, |v94|, s34
	v_cndmask_b32_e32 v94, v94, v102, vcc
	v_cmp_lt_f32_e64 vcc, |v95|, s34
	v_cndmask_b32_e32 v95, v95, v103, vcc
	v_cndmask_b32_e64 v100, 0, v213, s[22:23]
	v_cndmask_b32_e64 v101, 0, v213, s[24:25]
	v_cndmask_b32_e64 v102, 0, v213, s[26:27]
	v_cndmask_b32_e64 v103, 0, v213, s[28:29]
	v_sub_f32_e32 v92, v92, v100
	v_sub_f32_e32 v93, v93, v101
	v_sub_f32_e32 v94, v94, v102
	v_sub_f32_e32 v95, v95, v103
	v_add_f32_e32 v64, v64, v92
	v_add_f32_e32 v65, v65, v93
	v_add_f32_e32 v66, v66, v94
	v_add_f32_e32 v67, v67, v95
	v_mul_f32_e32 v92, 0xbfb8aa3b, v64
	v_mul_f32_e32 v93, 0xbfb8aa3b, v65
	v_mul_f32_e32 v94, 0xbfb8aa3b, v66
	v_mul_f32_e32 v95, 0xbfb8aa3b, v67
	v_mul_f32_e32 v100, 0x3fb8aa3b, v64
	v_mul_f32_e32 v101, 0x3fb8aa3b, v65
	v_mul_f32_e32 v102, 0x3fb8aa3b, v66
	v_mul_f32_e32 v103, 0x3fb8aa3b, v67
	v_exp_f32_e32 v92, v92
	v_exp_f32_e32 v93, v93
	v_exp_f32_e32 v94, v94
	v_exp_f32_e32 v95, v95
	v_exp_f32_e32 v100, v100
	v_exp_f32_e32 v101, v101
	v_exp_f32_e32 v102, v102
	v_exp_f32_e32 v103, v103
	v_sub_f32_e32 v96, 1.0, v96
	v_sub_f32_e32 v97, 1.0, v97
	v_sub_f32_e32 v98, 1.0, v98
	v_sub_f32_e32 v99, 1.0, v99
	v_mul_f32_e32 v96, v96, v92
; DEV u16 f2bf(float f) { return (u16)(pack2(f, f) & 0xffffu); }
; DEV float bf2f(u16 h) { return __uint_as_float(((unsigned)h) << 16); }
; DEV float sigmoid_f(float x) { return __builtin_amdgcn_rcpf(1.f + __expf(-x)); }
; DEV void phase_p15(const Params& p, int g) {
;     ...
;           const float f = lb[cc] + (1.f - lb[cc]) * sigmoid_f(bf2f(xr[st][cc][e]));
;           G[cc] += __logf(f);
;           const float eg = __expf(G[cc]), ig = __expf(-G[cc]);
;           Qp[tok * 512 + c] = f2bf(bf2f(qr[st][cc][e]) * eg);
;           const u16 kk = f2bf((1.f - f) * ig);
;           Kp[tok * 512 + c] = kk;
;           kb[e] = kk;
;         }
;         const int s0 = dir ? 56 - 8 * j8 : 8 * j8;
;         uint4 w;
;         w.x = dir ? (kb[7] | (kb[6] << 16)) : (kb[0] | (kb[1] << 16));
;         w.y = dir ? (kb[5] | (kb[4] << 16)) : (kb[2] | (kb[3] << 16));
;         w.z = dir ? (kb[3] | (kb[2] << 16)) : (kb[4] | (kb[5] << 16));
;         w.w = dir ? (kb[1] | (kb[0] << 16)) : (kb[6] | (kb[7] << 16));
;         *(uint4*)(KT + (((size_t)cidx * 2 + dir) * 512 + c) * 64 + s0) = w;
	v_mul_f32_e32 v97, v97, v93
	v_mul_f32_e32 v98, v98, v94
	v_mul_f32_e32 v99, v99, v95
	v_lshlrev_b32_e32 v92, 16, v14
	v_and_b32_e32 v93, 0xffff0000, v14
	v_lshlrev_b32_e32 v94, 16, v15
	v_and_b32_e32 v95, 0xffff0000, v15
	v_mul_f32_e32 v92, v92, v100
	v_mul_f32_e32 v93, v93, v101
	v_mul_f32_e32 v94, v94, v102
	v_mul_f32_e32 v95, v95, v103
	v_cvt_pk_bf16_f32 v125, v125, v96
	v_cvt_pk_bf16_f32 v141, v141, v97
	v_cvt_pk_bf16_f32 v175, v175, v98
	v_cvt_pk_bf16_f32 v191, v191, v99
	v_cvt_pk_bf16_f32 v92, v92, v93
	v_cvt_pk_bf16_f32 v93, v94, v95
	v_cvt_pk_bf16_f32 v96, v96, v97
	v_cvt_pk_bf16_f32 v97, v98, v99
	global_store_dwordx2 v112, v[92:93], s[2:3]
	global_store_dwordx2 v114, v[96:97], s[2:3]
	s_add_u32 s2, s2, 0x400
	s_addc_u32 s3, s3, 0
	v_lshlrev_b32_e32 v92, 16, v16
	v_and_b32_e32 v93, 0xffff0000, v16
	v_lshlrev_b32_e32 v94, 16, v17
	v_and_b32_e32 v95, 0xffff0000, v17
	v_mul_f32_e32 v92, 0xbfb8aa3b, v92
	v_mul_f32_e32 v93, 0xbfb8aa3b, v93
	v_mul_f32_e32 v94, 0xbfb8aa3b, v94
	v_mul_f32_e32 v95, 0xbfb8aa3b, v95
	v_exp_f32_e32 v92, v92
	v_exp_f32_e32 v93, v93
	v_exp_f32_e32 v94, v94
	v_exp_f32_e32 v95, v95
	v_add_f32_e32 v92, 1.0, v92
	v_add_f32_e32 v93, 1.0, v93
	v_add_f32_e32 v94, 1.0, v94
	v_add_f32_e32 v95, 1.0, v95
	v_rcp_f32_e32 v92, v92
	v_rcp_f32_e32 v93, v93
	v_rcp_f32_e32 v94, v94
	v_rcp_f32_e32 v95, v95
	v_fma_f32 v96, v72, v92, v68
	v_fma_f32 v97, v73, v93, v69
	v_fma_f32 v98, v74, v94, v70
	v_fma_f32 v99, v75, v95, v71
	v_cmp_gt_f32_e64 s[22:23], s30, v96
	v_cmp_gt_f32_e64 s[24:25], s30, v97
	v_cmp_gt_f32_e64 s[26:27], s30, v98
	v_cmp_gt_f32_e64 s[28:29], s30, v99
	v_cndmask_b32_e64 v92, 0, 32, s[22:23]
	v_cndmask_b32_e64 v93, 0, 32, s[24:25]
	v_cndmask_b32_e64 v94, 0, 32, s[26:27]
	v_cndmask_b32_e64 v95, 0, 32, s[28:29]
	v_ldexp_f32 v92, v96, v92
	v_ldexp_f32 v93, v97, v93
	v_ldexp_f32 v94, v98, v94
	v_ldexp_f32 v95, v99, v95
	v_log_f32_e32 v92, v92
	v_log_f32_e32 v93, v93
	v_log_f32_e32 v94, v94
	v_log_f32_e32 v95, v95
	v_mul_f32_e32 v100, 0x3f317217, v92
	v_mul_f32_e32 v101, 0x3f317217, v93
	v_mul_f32_e32 v102, 0x3f317217, v94
	v_mul_f32_e32 v103, 0x3f317217, v95
	v_fma_f32 v100, v92, s31, -v100
	v_fma_f32 v101, v93, s31, -v101
	v_fma_f32 v102, v94, s31, -v102
	v_fma_f32 v103, v95, s31, -v103
	v_fmac_f32_e32 v100, 0x3377d1cf, v92
	v_fmac_f32_e32 v101, 0x3377d1cf, v93
	v_fmac_f32_e32 v102, 0x3377d1cf, v94
	v_fmac_f32_e32 v103, 0x3377d1cf, v95
	v_fmac_f32_e32 v100, 0x3f317217, v92
	v_fmac_f32_e32 v101, 0x3f317217, v93
	v_fmac_f32_e32 v102, 0x3f317217, v94
	v_fmac_f32_e32 v103, 0x3f317217, v95
	v_cmp_lt_f32_e64 vcc, |v92|, s34
	v_cndmask_b32_e32 v92, v92, v100, vcc
	v_cmp_lt_f32_e64 vcc, |v93|, s34
	v_cndmask_b32_e32 v93, v93, v101, vcc
	v_cmp_lt_f32_e64 vcc, |v94|, s34
	v_cndmask_b32_e32 v94, v94, v102, vcc
	v_cmp_lt_f32_e64 vcc, |v95|, s34
	v_cndmask_b32_e32 v95, v95, v103, vcc
	v_cndmask_b32_e64 v100, 0, v213, s[22:23]
	v_cndmask_b32_e64 v101, 0, v213, s[24:25]
	v_cndmask_b32_e64 v102, 0, v213, s[26:27]
	v_cndmask_b32_e64 v103, 0, v213, s[28:29]
	v_sub_f32_e32 v92, v92, v100
	v_sub_f32_e32 v93, v93, v101
	v_sub_f32_e32 v94, v94, v102
	v_sub_f32_e32 v95, v95, v103
	v_add_f32_e32 v64, v64, v92
	v_add_f32_e32 v65, v65, v93
	v_add_f32_e32 v66, v66, v94
	v_add_f32_e32 v67, v67, v95
	v_mul_f32_e32 v92, 0xbfb8aa3b, v64
	v_mul_f32_e32 v93, 0xbfb8aa3b, v65
	v_mul_f32_e32 v94, 0xbfb8aa3b, v66
	v_mul_f32_e32 v95, 0xbfb8aa3b, v67
	v_mul_f32_e32 v100, 0x3fb8aa3b, v64
	v_mul_f32_e32 v101, 0x3fb8aa3b, v65
	v_mul_f32_e32 v102, 0x3fb8aa3b, v66
	v_mul_f32_e32 v103, 0x3fb8aa3b, v67
	v_exp_f32_e32 v92, v92
	v_exp_f32_e32 v93, v93
	v_exp_f32_e32 v94, v94
	v_exp_f32_e32 v95, v95
	v_exp_f32_e32 v100, v100
	v_exp_f32_e32 v101, v101
	v_exp_f32_e32 v102, v102
	v_exp_f32_e32 v103, v103
	v_sub_f32_e32 v96, 1.0, v96
	v_sub_f32_e32 v97, 1.0, v97
	v_sub_f32_e32 v98, 1.0, v98
	v_sub_f32_e32 v99, 1.0, v99
	v_mul_f32_e32 v96, v96, v92
	v_mul_f32_e32 v97, v97, v93
	v_mul_f32_e32 v98, v98, v94
	v_mul_f32_e32 v99, v99, v95
	v_lshlrev_b32_e32 v92, 16, v18
	v_and_b32_e32 v93, 0xffff0000, v18
	v_lshlrev_b32_e32 v94, 16, v19
	v_and_b32_e32 v95, 0xffff0000, v19
	v_mul_f32_e32 v92, v92, v100
	v_mul_f32_e32 v93, v93, v101
	v_mul_f32_e32 v94, v94, v102
	v_mul_f32_e32 v95, v95, v103
	v_mov_b32_e32 v126, v96
	v_mov_b32_e32 v142, v97
	v_mov_b32_e32 v176, v98
	v_mov_b32_e32 v192, v99
	v_cvt_pk_bf16_f32 v92, v92, v93
	v_cvt_pk_bf16_f32 v93, v94, v95
	v_cvt_pk_bf16_f32 v96, v96, v97
	v_cvt_pk_bf16_f32 v97, v98, v99
	global_store_dwordx2 v112, v[92:93], s[2:3]
	global_store_dwordx2 v114, v[96:97], s[2:3]
	s_add_u32 s2, s2, 0x400
	s_addc_u32 s3, s3, 0
	v_lshlrev_b32_e32 v92, 16, v20
	v_and_b32_e32 v93, 0xffff0000, v20
	v_lshlrev_b32_e32 v94, 16, v21
	v_and_b32_e32 v95, 0xffff0000, v21
	v_mul_f32_e32 v92, 0xbfb8aa3b, v92
	v_mul_f32_e32 v93, 0xbfb8aa3b, v93
	v_mul_f32_e32 v94, 0xbfb8aa3b, v94
	v_mul_f32_e32 v95, 0xbfb8aa3b, v95
	v_exp_f32_e32 v92, v92
	v_exp_f32_e32 v93, v93
	v_exp_f32_e32 v94, v94
	v_exp_f32_e32 v95, v95
	v_add_f32_e32 v92, 1.0, v92
	v_add_f32_e32 v93, 1.0, v93
	v_add_f32_e32 v94, 1.0, v94
	v_add_f32_e32 v95, 1.0, v95
	v_rcp_f32_e32 v92, v92
	v_rcp_f32_e32 v93, v93
	v_rcp_f32_e32 v94, v94
	v_rcp_f32_e32 v95, v95
	v_fma_f32 v96, v72, v92, v68
	v_fma_f32 v97, v73, v93, v69
	v_fma_f32 v98, v74, v94, v70
	v_fma_f32 v99, v75, v95, v71
	v_cmp_gt_f32_e64 s[22:23], s30, v96
	v_cmp_gt_f32_e64 s[24:25], s30, v97
	v_cmp_gt_f32_e64 s[26:27], s30, v98
	v_cmp_gt_f32_e64 s[28:29], s30, v99
	v_cndmask_b32_e64 v92, 0, 32, s[22:23]
	v_cndmask_b32_e64 v93, 0, 32, s[24:25]
	v_cndmask_b32_e64 v94, 0, 32, s[26:27]
	v_cndmask_b32_e64 v95, 0, 32, s[28:29]
	v_ldexp_f32 v92, v96, v92
; DEV u16 f2bf(float f) { return (u16)(pack2(f, f) & 0xffffu); }
; DEV float bf2f(u16 h) { return __uint_as_float(((unsigned)h) << 16); }
; DEV float sigmoid_f(float x) { return __builtin_amdgcn_rcpf(1.f + __expf(-x)); }
; DEV void phase_p15(const Params& p, int g) {
;     ...
;           const float f = lb[cc] + (1.f - lb[cc]) * sigmoid_f(bf2f(xr[st][cc][e]));
;           G[cc] += __logf(f);
;           const float eg = __expf(G[cc]), ig = __expf(-G[cc]);
;           Qp[tok * 512 + c] = f2bf(bf2f(qr[st][cc][e]) * eg);
;           const u16 kk = f2bf((1.f - f) * ig);
;           Kp[tok * 512 + c] = kk;
;           kb[e] = kk;
;         }
;         const int s0 = dir ? 56 - 8 * j8 : 8 * j8;
;         uint4 w;
;         w.x = dir ? (kb[7] | (kb[6] << 16)) : (kb[0] | (kb[1] << 16));
;         w.y = dir ? (kb[5] | (kb[4] << 16)) : (kb[2] | (kb[3] << 16));
;         w.z = dir ? (kb[3] | (kb[2] << 16)) : (kb[4] | (kb[5] << 16));
;         w.w = dir ? (kb[1] | (kb[0] << 16)) : (kb[6] | (kb[7] << 16));
;         *(uint4*)(KT + (((size_t)cidx * 2 + dir) * 512 + c) * 64 + s0) = w;
	v_ldexp_f32 v93, v97, v93
	v_ldexp_f32 v94, v98, v94
	v_ldexp_f32 v95, v99, v95
	v_log_f32_e32 v92, v92
	v_log_f32_e32 v93, v93
	v_log_f32_e32 v94, v94
	v_log_f32_e32 v95, v95
	v_mul_f32_e32 v100, 0x3f317217, v92
	v_mul_f32_e32 v101, 0x3f317217, v93
	v_mul_f32_e32 v102, 0x3f317217, v94
	v_mul_f32_e32 v103, 0x3f317217, v95
	v_fma_f32 v100, v92, s31, -v100
	v_fma_f32 v101, v93, s31, -v101
	v_fma_f32 v102, v94, s31, -v102
	v_fma_f32 v103, v95, s31, -v103
	v_fmac_f32_e32 v100, 0x3377d1cf, v92
	v_fmac_f32_e32 v101, 0x3377d1cf, v93
	v_fmac_f32_e32 v102, 0x3377d1cf, v94
	v_fmac_f32_e32 v103, 0x3377d1cf, v95
	v_fmac_f32_e32 v100, 0x3f317217, v92
	v_fmac_f32_e32 v101, 0x3f317217, v93
	v_fmac_f32_e32 v102, 0x3f317217, v94
	v_fmac_f32_e32 v103, 0x3f317217, v95
	v_cmp_lt_f32_e64 vcc, |v92|, s34
	v_cndmask_b32_e32 v92, v92, v100, vcc
	v_cmp_lt_f32_e64 vcc, |v93|, s34
	v_cndmask_b32_e32 v93, v93, v101, vcc
	v_cmp_lt_f32_e64 vcc, |v94|, s34
	v_cndmask_b32_e32 v94, v94, v102, vcc
	v_cmp_lt_f32_e64 vcc, |v95|, s34
	v_cndmask_b32_e32 v95, v95, v103, vcc
	v_cndmask_b32_e64 v100, 0, v213, s[22:23]
	v_cndmask_b32_e64 v101, 0, v213, s[24:25]
	v_cndmask_b32_e64 v102, 0, v213, s[26:27]
	v_cndmask_b32_e64 v103, 0, v213, s[28:29]
	v_sub_f32_e32 v92, v92, v100
	v_sub_f32_e32 v93, v93, v101
	v_sub_f32_e32 v94, v94, v102
	v_sub_f32_e32 v95, v95, v103
	v_add_f32_e32 v64, v64, v92
	v_add_f32_e32 v65, v65, v93
	v_add_f32_e32 v66, v66, v94
	v_add_f32_e32 v67, v67, v95
	v_mul_f32_e32 v92, 0xbfb8aa3b, v64
	v_mul_f32_e32 v93, 0xbfb8aa3b, v65
	v_mul_f32_e32 v94, 0xbfb8aa3b, v66
	v_mul_f32_e32 v95, 0xbfb8aa3b, v67
	v_mul_f32_e32 v100, 0x3fb8aa3b, v64
	v_mul_f32_e32 v101, 0x3fb8aa3b, v65
	v_mul_f32_e32 v102, 0x3fb8aa3b, v66
	v_mul_f32_e32 v103, 0x3fb8aa3b, v67
	v_exp_f32_e32 v92, v92
	v_exp_f32_e32 v93, v93
	v_exp_f32_e32 v94, v94
	v_exp_f32_e32 v95, v95
	v_exp_f32_e32 v100, v100
	v_exp_f32_e32 v101, v101
	v_exp_f32_e32 v102, v102
	v_exp_f32_e32 v103, v103
	v_sub_f32_e32 v96, 1.0, v96
	v_sub_f32_e32 v97, 1.0, v97
	v_sub_f32_e32 v98, 1.0, v98
	v_sub_f32_e32 v99, 1.0, v99
	v_mul_f32_e32 v96, v96, v92
	v_mul_f32_e32 v97, v97, v93
	v_mul_f32_e32 v98, v98, v94
	v_mul_f32_e32 v99, v99, v95
	v_lshlrev_b32_e32 v92, 16, v22
	v_and_b32_e32 v93, 0xffff0000, v22
	v_lshlrev_b32_e32 v94, 16, v23
	v_and_b32_e32 v95, 0xffff0000, v23
	v_mul_f32_e32 v92, v92, v100
	v_mul_f32_e32 v93, v93, v101
	v_mul_f32_e32 v94, v94, v102
	v_mul_f32_e32 v95, v95, v103
	v_cvt_pk_bf16_f32 v126, v126, v96
	v_cvt_pk_bf16_f32 v142, v142, v97
	v_cvt_pk_bf16_f32 v176, v176, v98
	v_cvt_pk_bf16_f32 v192, v192, v99
	v_cvt_pk_bf16_f32 v92, v92, v93
	v_cvt_pk_bf16_f32 v93, v94, v95
	v_cvt_pk_bf16_f32 v96, v96, v97
	v_cvt_pk_bf16_f32 v97, v98, v99
	global_store_dwordx2 v112, v[92:93], s[2:3]
	global_store_dwordx2 v114, v[96:97], s[2:3]
	s_add_u32 s2, s2, 0x400
	s_addc_u32 s3, s3, 0
	v_lshlrev_b32_e32 v92, 16, v24
	v_and_b32_e32 v93, 0xffff0000, v24
	v_lshlrev_b32_e32 v94, 16, v25
	v_and_b32_e32 v95, 0xffff0000, v25
	v_mul_f32_e32 v92, 0xbfb8aa3b, v92
	v_mul_f32_e32 v93, 0xbfb8aa3b, v93
	v_mul_f32_e32 v94, 0xbfb8aa3b, v94
	v_mul_f32_e32 v95, 0xbfb8aa3b, v95
	v_exp_f32_e32 v92, v92
	v_exp_f32_e32 v93, v93
	v_exp_f32_e32 v94, v94
	v_exp_f32_e32 v95, v95
	v_add_f32_e32 v92, 1.0, v92
	v_add_f32_e32 v93, 1.0, v93
	v_add_f32_e32 v94, 1.0, v94
	v_add_f32_e32 v95, 1.0, v95
	v_rcp_f32_e32 v92, v92
	v_rcp_f32_e32 v93, v93
	v_rcp_f32_e32 v94, v94
	v_rcp_f32_e32 v95, v95
	v_fma_f32 v96, v72, v92, v68
	v_fma_f32 v97, v73, v93, v69
	v_fma_f32 v98, v74, v94, v70
	v_fma_f32 v99, v75, v95, v71
	v_cmp_gt_f32_e64 s[22:23], s30, v96
	v_cmp_gt_f32_e64 s[24:25], s30, v97
	v_cmp_gt_f32_e64 s[26:27], s30, v98
	v_cmp_gt_f32_e64 s[28:29], s30, v99
	v_cndmask_b32_e64 v92, 0, 32, s[22:23]
	v_cndmask_b32_e64 v93, 0, 32, s[24:25]
	v_cndmask_b32_e64 v94, 0, 32, s[26:27]
	v_cndmask_b32_e64 v95, 0, 32, s[28:29]
	v_ldexp_f32 v92, v96, v92
	v_ldexp_f32 v93, v97, v93
	v_ldexp_f32 v94, v98, v94
	v_ldexp_f32 v95, v99, v95
	v_log_f32_e32 v92, v92
	v_log_f32_e32 v93, v93
	v_log_f32_e32 v94, v94
	v_log_f32_e32 v95, v95
	v_mul_f32_e32 v100, 0x3f317217, v92
	v_mul_f32_e32 v101, 0x3f317217, v93
	v_mul_f32_e32 v102, 0x3f317217, v94
	v_mul_f32_e32 v103, 0x3f317217, v95
	v_fma_f32 v100, v92, s31, -v100
	v_fma_f32 v101, v93, s31, -v101
	v_fma_f32 v102, v94, s31, -v102
	v_fma_f32 v103, v95, s31, -v103
	v_fmac_f32_e32 v100, 0x3377d1cf, v92
	v_fmac_f32_e32 v101, 0x3377d1cf, v93
	v_fmac_f32_e32 v102, 0x3377d1cf, v94
	v_fmac_f32_e32 v103, 0x3377d1cf, v95
	v_fmac_f32_e32 v100, 0x3f317217, v92
	v_fmac_f32_e32 v101, 0x3f317217, v93
	v_fmac_f32_e32 v102, 0x3f317217, v94
	v_fmac_f32_e32 v103, 0x3f317217, v95
	v_cmp_lt_f32_e64 vcc, |v92|, s34
	v_cndmask_b32_e32 v92, v92, v100, vcc
	v_cmp_lt_f32_e64 vcc, |v93|, s34
	v_cndmask_b32_e32 v93, v93, v101, vcc
	v_cmp_lt_f32_e64 vcc, |v94|, s34
	v_cndmask_b32_e32 v94, v94, v102, vcc
	v_cmp_lt_f32_e64 vcc, |v95|, s34
	v_cndmask_b32_e32 v95, v95, v103, vcc
	v_cndmask_b32_e64 v100, 0, v213, s[22:23]
	v_cndmask_b32_e64 v101, 0, v213, s[24:25]
	v_cndmask_b32_e64 v102, 0, v213, s[26:27]
	v_cndmask_b32_e64 v103, 0, v213, s[28:29]
	v_sub_f32_e32 v92, v92, v100
	v_sub_f32_e32 v93, v93, v101
	v_sub_f32_e32 v94, v94, v102
	v_sub_f32_e32 v95, v95, v103
	v_add_f32_e32 v64, v64, v92
	v_add_f32_e32 v65, v65, v93
	v_add_f32_e32 v66, v66, v94
	v_add_f32_e32 v67, v67, v95
	v_mul_f32_e32 v92, 0xbfb8aa3b, v64
	v_mul_f32_e32 v93, 0xbfb8aa3b, v65
	v_mul_f32_e32 v94, 0xbfb8aa3b, v66
	v_mul_f32_e32 v95, 0xbfb8aa3b, v67
	v_mul_f32_e32 v100, 0x3fb8aa3b, v64
	v_mul_f32_e32 v101, 0x3fb8aa3b, v65
	v_mul_f32_e32 v102, 0x3fb8aa3b, v66
	v_mul_f32_e32 v103, 0x3fb8aa3b, v67
; DEV u16 f2bf(float f) { return (u16)(pack2(f, f) & 0xffffu); }
; DEV float bf2f(u16 h) { return __uint_as_float(((unsigned)h) << 16); }
; DEV float sigmoid_f(float x) { return __builtin_amdgcn_rcpf(1.f + __expf(-x)); }
; DEV void phase_p15(const Params& p, int g) {
;     ...
;           const float f = lb[cc] + (1.f - lb[cc]) * sigmoid_f(bf2f(xr[st][cc][e]));
;           G[cc] += __logf(f);
;           const float eg = __expf(G[cc]), ig = __expf(-G[cc]);
;           Qp[tok * 512 + c] = f2bf(bf2f(qr[st][cc][e]) * eg);
;           const u16 kk = f2bf((1.f - f) * ig);
;           Kp[tok * 512 + c] = kk;
;           kb[e] = kk;
;         }
;         const int s0 = dir ? 56 - 8 * j8 : 8 * j8;
;         uint4 w;
;         w.x = dir ? (kb[7] | (kb[6] << 16)) : (kb[0] | (kb[1] << 16));
;         w.y = dir ? (kb[5] | (kb[4] << 16)) : (kb[2] | (kb[3] << 16));
;         w.z = dir ? (kb[3] | (kb[2] << 16)) : (kb[4] | (kb[5] << 16));
;         w.w = dir ? (kb[1] | (kb[0] << 16)) : (kb[6] | (kb[7] << 16));
;         *(uint4*)(KT + (((size_t)cidx * 2 + dir) * 512 + c) * 64 + s0) = w;
	v_exp_f32_e32 v92, v92
	v_exp_f32_e32 v93, v93
	v_exp_f32_e32 v94, v94
	v_exp_f32_e32 v95, v95
	v_exp_f32_e32 v100, v100
	v_exp_f32_e32 v101, v101
	v_exp_f32_e32 v102, v102
	v_exp_f32_e32 v103, v103
	v_sub_f32_e32 v96, 1.0, v96
	v_sub_f32_e32 v97, 1.0, v97
	v_sub_f32_e32 v98, 1.0, v98
	v_sub_f32_e32 v99, 1.0, v99
	v_mul_f32_e32 v96, v96, v92
	v_mul_f32_e32 v97, v97, v93
	v_mul_f32_e32 v98, v98, v94
	v_mul_f32_e32 v99, v99, v95
	v_lshlrev_b32_e32 v92, 16, v26
	v_and_b32_e32 v93, 0xffff0000, v26
	v_lshlrev_b32_e32 v94, 16, v27
	v_and_b32_e32 v95, 0xffff0000, v27
	v_mul_f32_e32 v92, v92, v100
	v_mul_f32_e32 v93, v93, v101
	v_mul_f32_e32 v94, v94, v102
	v_mul_f32_e32 v95, v95, v103
	v_mov_b32_e32 v127, v96
	v_mov_b32_e32 v143, v97
	v_mov_b32_e32 v177, v98
	v_mov_b32_e32 v193, v99
	v_cvt_pk_bf16_f32 v92, v92, v93
	v_cvt_pk_bf16_f32 v93, v94, v95
	v_cvt_pk_bf16_f32 v96, v96, v97
	v_cvt_pk_bf16_f32 v97, v98, v99
	global_store_dwordx2 v112, v[92:93], s[2:3]
	global_store_dwordx2 v114, v[96:97], s[2:3]
	s_add_u32 s2, s2, 0x400
	s_addc_u32 s3, s3, 0
	v_lshlrev_b32_e32 v92, 16, v28
	v_and_b32_e32 v93, 0xffff0000, v28
	v_lshlrev_b32_e32 v94, 16, v29
	v_and_b32_e32 v95, 0xffff0000, v29
	v_mul_f32_e32 v92, 0xbfb8aa3b, v92
	v_mul_f32_e32 v93, 0xbfb8aa3b, v93
	v_mul_f32_e32 v94, 0xbfb8aa3b, v94
	v_mul_f32_e32 v95, 0xbfb8aa3b, v95
	v_exp_f32_e32 v92, v92
	v_exp_f32_e32 v93, v93
	v_exp_f32_e32 v94, v94
	v_exp_f32_e32 v95, v95
	v_add_f32_e32 v92, 1.0, v92
	v_add_f32_e32 v93, 1.0, v93
	v_add_f32_e32 v94, 1.0, v94
	v_add_f32_e32 v95, 1.0, v95
	v_rcp_f32_e32 v92, v92
	v_rcp_f32_e32 v93, v93
	v_rcp_f32_e32 v94, v94
	v_rcp_f32_e32 v95, v95
	v_fma_f32 v96, v72, v92, v68
	v_fma_f32 v97, v73, v93, v69
	v_fma_f32 v98, v74, v94, v70
	v_fma_f32 v99, v75, v95, v71
	v_cmp_gt_f32_e64 s[22:23], s30, v96
	v_cmp_gt_f32_e64 s[24:25], s30, v97
	v_cmp_gt_f32_e64 s[26:27], s30, v98
	v_cmp_gt_f32_e64 s[28:29], s30, v99
	v_cndmask_b32_e64 v92, 0, 32, s[22:23]
	v_cndmask_b32_e64 v93, 0, 32, s[24:25]
	v_cndmask_b32_e64 v94, 0, 32, s[26:27]
	v_cndmask_b32_e64 v95, 0, 32, s[28:29]
	v_ldexp_f32 v92, v96, v92
	v_ldexp_f32 v93, v97, v93
	v_ldexp_f32 v94, v98, v94
	v_ldexp_f32 v95, v99, v95
	v_log_f32_e32 v92, v92
	v_log_f32_e32 v93, v93
	v_log_f32_e32 v94, v94
	v_log_f32_e32 v95, v95
	v_mul_f32_e32 v100, 0x3f317217, v92
	v_mul_f32_e32 v101, 0x3f317217, v93
	v_mul_f32_e32 v102, 0x3f317217, v94
	v_mul_f32_e32 v103, 0x3f317217, v95
	v_fma_f32 v100, v92, s31, -v100
	v_fma_f32 v101, v93, s31, -v101
	v_fma_f32 v102, v94, s31, -v102
	v_fma_f32 v103, v95, s31, -v103
	v_fmac_f32_e32 v100, 0x3377d1cf, v92
	v_fmac_f32_e32 v101, 0x3377d1cf, v93
	v_fmac_f32_e32 v102, 0x3377d1cf, v94
	v_fmac_f32_e32 v103, 0x3377d1cf, v95
	v_fmac_f32_e32 v100, 0x3f317217, v92
	v_fmac_f32_e32 v101, 0x3f317217, v93
	v_fmac_f32_e32 v102, 0x3f317217, v94
	v_fmac_f32_e32 v103, 0x3f317217, v95
	v_cmp_lt_f32_e64 vcc, |v92|, s34
	v_cndmask_b32_e32 v92, v92, v100, vcc
	v_cmp_lt_f32_e64 vcc, |v93|, s34
	v_cndmask_b32_e32 v93, v93, v101, vcc
	v_cmp_lt_f32_e64 vcc, |v94|, s34
	v_cndmask_b32_e32 v94, v94, v102, vcc
	v_cmp_lt_f32_e64 vcc, |v95|, s34
	v_cndmask_b32_e32 v95, v95, v103, vcc
	v_cndmask_b32_e64 v100, 0, v213, s[22:23]
	v_cndmask_b32_e64 v101, 0, v213, s[24:25]
	v_cndmask_b32_e64 v102, 0, v213, s[26:27]
	v_cndmask_b32_e64 v103, 0, v213, s[28:29]
	v_sub_f32_e32 v92, v92, v100
	v_sub_f32_e32 v93, v93, v101
	v_sub_f32_e32 v94, v94, v102
	v_sub_f32_e32 v95, v95, v103
	v_add_f32_e32 v64, v64, v92
	v_add_f32_e32 v65, v65, v93
	v_add_f32_e32 v66, v66, v94
	v_add_f32_e32 v67, v67, v95
	v_mul_f32_e32 v92, 0xbfb8aa3b, v64
	v_mul_f32_e32 v93, 0xbfb8aa3b, v65
	v_mul_f32_e32 v94, 0xbfb8aa3b, v66
	v_mul_f32_e32 v95, 0xbfb8aa3b, v67
	v_mul_f32_e32 v100, 0x3fb8aa3b, v64
	v_mul_f32_e32 v101, 0x3fb8aa3b, v65
	v_mul_f32_e32 v102, 0x3fb8aa3b, v66
	v_mul_f32_e32 v103, 0x3fb8aa3b, v67
	v_exp_f32_e32 v92, v92
	v_exp_f32_e32 v93, v93
	v_exp_f32_e32 v94, v94
	v_exp_f32_e32 v95, v95
	v_exp_f32_e32 v100, v100
	v_exp_f32_e32 v101, v101
	v_exp_f32_e32 v102, v102
	v_exp_f32_e32 v103, v103
	v_sub_f32_e32 v96, 1.0, v96
	v_sub_f32_e32 v97, 1.0, v97
	v_sub_f32_e32 v98, 1.0, v98
	v_sub_f32_e32 v99, 1.0, v99
	v_mul_f32_e32 v96, v96, v92
	v_mul_f32_e32 v97, v97, v93
	v_mul_f32_e32 v98, v98, v94
	v_mul_f32_e32 v99, v99, v95
	v_lshlrev_b32_e32 v92, 16, v30
	v_and_b32_e32 v93, 0xffff0000, v30
	v_lshlrev_b32_e32 v94, 16, v31
	v_and_b32_e32 v95, 0xffff0000, v31
	v_mul_f32_e32 v92, v92, v100
	v_mul_f32_e32 v93, v93, v101
	v_mul_f32_e32 v94, v94, v102
	v_mul_f32_e32 v95, v95, v103
	v_cvt_pk_bf16_f32 v127, v127, v96
	v_cvt_pk_bf16_f32 v143, v143, v97
	v_cvt_pk_bf16_f32 v177, v177, v98
	v_cvt_pk_bf16_f32 v193, v193, v99
	v_cvt_pk_bf16_f32 v92, v92, v93
	v_cvt_pk_bf16_f32 v93, v94, v95
	v_cvt_pk_bf16_f32 v96, v96, v97
	v_cvt_pk_bf16_f32 v97, v98, v99
	global_store_dwordx2 v112, v[92:93], s[2:3]
	global_store_dwordx2 v114, v[96:97], s[2:3]
	s_add_u32 s2, s2, 0x400
	s_addc_u32 s3, s3, 0
	global_load_dwordx2 v[0:1], v113, s[0:1]
	global_load_dwordx2 v[2:3], v112, s[0:1]
	s_add_u32 s0, s0, 0x1400
	s_addc_u32 s1, s1, 0
	global_load_dwordx2 v[4:5], v113, s[0:1]
	global_load_dwordx2 v[6:7], v112, s[0:1]
	s_add_u32 s0, s0, 0x1400
	s_addc_u32 s1, s1, 0
	global_load_dwordx2 v[8:9], v113, s[0:1]
	global_load_dwordx2 v[10:11], v112, s[0:1]
	s_add_u32 s0, s0, 0x1400
	s_addc_u32 s1, s1, 0
	global_load_dwordx2 v[12:13], v113, s[0:1]
	global_load_dwordx2 v[14:15], v112, s[0:1]
	s_add_u32 s0, s0, 0x1400
	s_addc_u32 s1, s1, 0
	global_load_dwordx2 v[16:17], v113, s[0:1]
	global_load_dwordx2 v[18:19], v112, s[0:1]
	s_add_u32 s0, s0, 0x1400
	s_addc_u32 s1, s1, 0
	global_load_dwordx2 v[20:21], v113, s[0:1]
	global_load_dwordx2 v[22:23], v112, s[0:1]
	s_add_u32 s0, s0, 0x1400
	s_addc_u32 s1, s1, 0
	global_load_dwordx2 v[24:25], v113, s[0:1]
	global_load_dwordx2 v[26:27], v112, s[0:1]
	s_add_u32 s0, s0, 0x1400
	s_addc_u32 s1, s1, 0
	global_load_dwordx2 v[28:29], v113, s[0:1]
	global_load_dwordx2 v[30:31], v112, s[0:1]
	s_add_u32 s0, s0, 0x1400
	s_addc_u32 s1, s1, 0
	s_waitcnt vmcnt(32)
; DEV u16 f2bf(float f) { return (u16)(pack2(f, f) & 0xffffu); }
; DEV float bf2f(u16 h) { return __uint_as_float(((unsigned)h) << 16); }
; DEV float sigmoid_f(float x) { return __builtin_amdgcn_rcpf(1.f + __expf(-x)); }
; DEV void phase_p15(const Params& p, int g) {
;     ...
;           const float f = lb[cc] + (1.f - lb[cc]) * sigmoid_f(bf2f(xr[st][cc][e]));
;           G[cc] += __logf(f);
;           const float eg = __expf(G[cc]), ig = __expf(-G[cc]);
;           Qp[tok * 512 + c] = f2bf(bf2f(qr[st][cc][e]) * eg);
;           const u16 kk = f2bf((1.f - f) * ig);
;           Kp[tok * 512 + c] = kk;
;           kb[e] = kk;
;         }
;         const int s0 = dir ? 56 - 8 * j8 : 8 * j8;
;         uint4 w;
;         w.x = dir ? (kb[7] | (kb[6] << 16)) : (kb[0] | (kb[1] << 16));
;         w.y = dir ? (kb[5] | (kb[4] << 16)) : (kb[2] | (kb[3] << 16));
;         w.z = dir ? (kb[3] | (kb[2] << 16)) : (kb[4] | (kb[5] << 16));
;         w.w = dir ? (kb[1] | (kb[0] << 16)) : (kb[6] | (kb[7] << 16));
;         *(uint4*)(KT + (((size_t)cidx * 2 + dir) * 512 + c) * 64 + s0) = w;
	v_lshlrev_b32_e32 v92, 16, v32
	v_and_b32_e32 v93, 0xffff0000, v32
	v_lshlrev_b32_e32 v94, 16, v33
	v_and_b32_e32 v95, 0xffff0000, v33
	v_mul_f32_e32 v92, 0xbfb8aa3b, v92
	v_mul_f32_e32 v93, 0xbfb8aa3b, v93
	v_mul_f32_e32 v94, 0xbfb8aa3b, v94
	v_mul_f32_e32 v95, 0xbfb8aa3b, v95
	v_exp_f32_e32 v92, v92
	v_exp_f32_e32 v93, v93
	v_exp_f32_e32 v94, v94
	v_exp_f32_e32 v95, v95
	v_add_f32_e32 v92, 1.0, v92
	v_add_f32_e32 v93, 1.0, v93
	v_add_f32_e32 v94, 1.0, v94
	v_add_f32_e32 v95, 1.0, v95
	v_rcp_f32_e32 v92, v92
	v_rcp_f32_e32 v93, v93
	v_rcp_f32_e32 v94, v94
	v_rcp_f32_e32 v95, v95
	v_fma_f32 v96, v72, v92, v68
	v_fma_f32 v97, v73, v93, v69
	v_fma_f32 v98, v74, v94, v70
	v_fma_f32 v99, v75, v95, v71
	v_cmp_gt_f32_e64 s[22:23], s30, v96
	v_cmp_gt_f32_e64 s[24:25], s30, v97
	v_cmp_gt_f32_e64 s[26:27], s30, v98
	v_cmp_gt_f32_e64 s[28:29], s30, v99
	v_cndmask_b32_e64 v92, 0, 32, s[22:23]
	v_cndmask_b32_e64 v93, 0, 32, s[24:25]
	v_cndmask_b32_e64 v94, 0, 32, s[26:27]
	v_cndmask_b32_e64 v95, 0, 32, s[28:29]
	v_ldexp_f32 v92, v96, v92
	v_ldexp_f32 v93, v97, v93
	v_ldexp_f32 v94, v98, v94
	v_ldexp_f32 v95, v99, v95
	v_log_f32_e32 v92, v92
	v_log_f32_e32 v93, v93
	v_log_f32_e32 v94, v94
	v_log_f32_e32 v95, v95
	v_mul_f32_e32 v100, 0x3f317217, v92
	v_mul_f32_e32 v101, 0x3f317217, v93
	v_mul_f32_e32 v102, 0x3f317217, v94
	v_mul_f32_e32 v103, 0x3f317217, v95
	v_fma_f32 v100, v92, s31, -v100
	v_fma_f32 v101, v93, s31, -v101
	v_fma_f32 v102, v94, s31, -v102
	v_fma_f32 v103, v95, s31, -v103
	v_fmac_f32_e32 v100, 0x3377d1cf, v92
	v_fmac_f32_e32 v101, 0x3377d1cf, v93
	v_fmac_f32_e32 v102, 0x3377d1cf, v94
	v_fmac_f32_e32 v103, 0x3377d1cf, v95
	v_fmac_f32_e32 v100, 0x3f317217, v92
	v_fmac_f32_e32 v101, 0x3f317217, v93
	v_fmac_f32_e32 v102, 0x3f317217, v94
	v_fmac_f32_e32 v103, 0x3f317217, v95
	v_cmp_lt_f32_e64 vcc, |v92|, s34
	v_cndmask_b32_e32 v92, v92, v100, vcc
	v_cmp_lt_f32_e64 vcc, |v93|, s34
	v_cndmask_b32_e32 v93, v93, v101, vcc
	v_cmp_lt_f32_e64 vcc, |v94|, s34
	v_cndmask_b32_e32 v94, v94, v102, vcc
	v_cmp_lt_f32_e64 vcc, |v95|, s34
	v_cndmask_b32_e32 v95, v95, v103, vcc
	v_cndmask_b32_e64 v100, 0, v213, s[22:23]
	v_cndmask_b32_e64 v101, 0, v213, s[24:25]
	v_cndmask_b32_e64 v102, 0, v213, s[26:27]
	v_cndmask_b32_e64 v103, 0, v213, s[28:29]
	v_sub_f32_e32 v92, v92, v100
	v_sub_f32_e32 v93, v93, v101
	v_sub_f32_e32 v94, v94, v102
	v_sub_f32_e32 v95, v95, v103
	v_add_f32_e32 v64, v64, v92
	v_add_f32_e32 v65, v65, v93
	v_add_f32_e32 v66, v66, v94
	v_add_f32_e32 v67, v67, v95
	v_mul_f32_e32 v92, 0xbfb8aa3b, v64
	v_mul_f32_e32 v93, 0xbfb8aa3b, v65
	v_mul_f32_e32 v94, 0xbfb8aa3b, v66
	v_mul_f32_e32 v95, 0xbfb8aa3b, v67
	v_mul_f32_e32 v100, 0x3fb8aa3b, v64
	v_mul_f32_e32 v101, 0x3fb8aa3b, v65
	v_mul_f32_e32 v102, 0x3fb8aa3b, v66
	v_mul_f32_e32 v103, 0x3fb8aa3b, v67
	v_exp_f32_e32 v92, v92
	v_exp_f32_e32 v93, v93
	v_exp_f32_e32 v94, v94
	v_exp_f32_e32 v95, v95
	v_exp_f32_e32 v100, v100
	v_exp_f32_e32 v101, v101
	v_exp_f32_e32 v102, v102
	v_exp_f32_e32 v103, v103
	v_sub_f32_e32 v96, 1.0, v96
	v_sub_f32_e32 v97, 1.0, v97
	v_sub_f32_e32 v98, 1.0, v98
	v_sub_f32_e32 v99, 1.0, v99
	v_mul_f32_e32 v96, v96, v92
	v_mul_f32_e32 v97, v97, v93
	v_mul_f32_e32 v98, v98, v94
	v_mul_f32_e32 v99, v99, v95
	v_lshlrev_b32_e32 v92, 16, v34
	v_and_b32_e32 v93, 0xffff0000, v34
	v_lshlrev_b32_e32 v94, 16, v35
	v_and_b32_e32 v95, 0xffff0000, v35
	v_mul_f32_e32 v92, v92, v100
	v_mul_f32_e32 v93, v93, v101
	v_mul_f32_e32 v94, v94, v102
	v_mul_f32_e32 v95, v95, v103
	v_mov_b32_e32 v128, v96
	v_mov_b32_e32 v144, v97
	v_mov_b32_e32 v178, v98
	v_mov_b32_e32 v194, v99
	v_cvt_pk_bf16_f32 v92, v92, v93
	v_cvt_pk_bf16_f32 v93, v94, v95
	v_cvt_pk_bf16_f32 v96, v96, v97
	v_cvt_pk_bf16_f32 v97, v98, v99
	global_store_dwordx2 v112, v[92:93], s[2:3]
	global_store_dwordx2 v114, v[96:97], s[2:3]
	s_add_u32 s2, s2, 0x400
	s_addc_u32 s3, s3, 0
	v_lshlrev_b32_e32 v92, 16, v36
	v_and_b32_e32 v93, 0xffff0000, v36
	v_lshlrev_b32_e32 v94, 16, v37
	v_and_b32_e32 v95, 0xffff0000, v37
	v_mul_f32_e32 v92, 0xbfb8aa3b, v92
	v_mul_f32_e32 v93, 0xbfb8aa3b, v93
	v_mul_f32_e32 v94, 0xbfb8aa3b, v94
	v_mul_f32_e32 v95, 0xbfb8aa3b, v95
	v_exp_f32_e32 v92, v92
	v_exp_f32_e32 v93, v93
	v_exp_f32_e32 v94, v94
	v_exp_f32_e32 v95, v95
	v_add_f32_e32 v92, 1.0, v92
	v_add_f32_e32 v93, 1.0, v93
	v_add_f32_e32 v94, 1.0, v94
	v_add_f32_e32 v95, 1.0, v95
	v_rcp_f32_e32 v92, v92
	v_rcp_f32_e32 v93, v93
	v_rcp_f32_e32 v94, v94
	v_rcp_f32_e32 v95, v95
	v_fma_f32 v96, v72, v92, v68
	v_fma_f32 v97, v73, v93, v69
	v_fma_f32 v98, v74, v94, v70
	v_fma_f32 v99, v75, v95, v71
	v_cmp_gt_f32_e64 s[22:23], s30, v96
	v_cmp_gt_f32_e64 s[24:25], s30, v97
	v_cmp_gt_f32_e64 s[26:27], s30, v98
	v_cmp_gt_f32_e64 s[28:29], s30, v99
	v_cndmask_b32_e64 v92, 0, 32, s[22:23]
	v_cndmask_b32_e64 v93, 0, 32, s[24:25]
	v_cndmask_b32_e64 v94, 0, 32, s[26:27]
	v_cndmask_b32_e64 v95, 0, 32, s[28:29]
	v_ldexp_f32 v92, v96, v92
	v_ldexp_f32 v93, v97, v93
	v_ldexp_f32 v94, v98, v94
	v_ldexp_f32 v95, v99, v95
	v_log_f32_e32 v92, v92
	v_log_f32_e32 v93, v93
	v_log_f32_e32 v94, v94
	v_log_f32_e32 v95, v95
	v_mul_f32_e32 v100, 0x3f317217, v92
	v_mul_f32_e32 v101, 0x3f317217, v93
	v_mul_f32_e32 v102, 0x3f317217, v94
	v_mul_f32_e32 v103, 0x3f317217, v95
	v_fma_f32 v100, v92, s31, -v100
	v_fma_f32 v101, v93, s31, -v101
	v_fma_f32 v102, v94, s31, -v102
	v_fma_f32 v103, v95, s31, -v103
	v_fmac_f32_e32 v100, 0x3377d1cf, v92
	v_fmac_f32_e32 v101, 0x3377d1cf, v93
	v_fmac_f32_e32 v102, 0x3377d1cf, v94
	v_fmac_f32_e32 v103, 0x3377d1cf, v95
	v_fmac_f32_e32 v100, 0x3f317217, v92
	v_fmac_f32_e32 v101, 0x3f317217, v93
	v_fmac_f32_e32 v102, 0x3f317217, v94
	v_fmac_f32_e32 v103, 0x3f317217, v95
; DEV u16 f2bf(float f) { return (u16)(pack2(f, f) & 0xffffu); }
; DEV float bf2f(u16 h) { return __uint_as_float(((unsigned)h) << 16); }
; DEV float sigmoid_f(float x) { return __builtin_amdgcn_rcpf(1.f + __expf(-x)); }
; DEV void phase_p15(const Params& p, int g) {
;     ...
;           const float f = lb[cc] + (1.f - lb[cc]) * sigmoid_f(bf2f(xr[st][cc][e]));
;           G[cc] += __logf(f);
;           const float eg = __expf(G[cc]), ig = __expf(-G[cc]);
;           Qp[tok * 512 + c] = f2bf(bf2f(qr[st][cc][e]) * eg);
;           const u16 kk = f2bf((1.f - f) * ig);
;           Kp[tok * 512 + c] = kk;
;           kb[e] = kk;
;         }
;         const int s0 = dir ? 56 - 8 * j8 : 8 * j8;
;         uint4 w;
;         w.x = dir ? (kb[7] | (kb[6] << 16)) : (kb[0] | (kb[1] << 16));
;         w.y = dir ? (kb[5] | (kb[4] << 16)) : (kb[2] | (kb[3] << 16));
;         w.z = dir ? (kb[3] | (kb[2] << 16)) : (kb[4] | (kb[5] << 16));
;         w.w = dir ? (kb[1] | (kb[0] << 16)) : (kb[6] | (kb[7] << 16));
;         *(uint4*)(KT + (((size_t)cidx * 2 + dir) * 512 + c) * 64 + s0) = w;
	v_cmp_lt_f32_e64 vcc, |v92|, s34
	v_cndmask_b32_e32 v92, v92, v100, vcc
	v_cmp_lt_f32_e64 vcc, |v93|, s34
	v_cndmask_b32_e32 v93, v93, v101, vcc
	v_cmp_lt_f32_e64 vcc, |v94|, s34
	v_cndmask_b32_e32 v94, v94, v102, vcc
	v_cmp_lt_f32_e64 vcc, |v95|, s34
	v_cndmask_b32_e32 v95, v95, v103, vcc
	v_cndmask_b32_e64 v100, 0, v213, s[22:23]
	v_cndmask_b32_e64 v101, 0, v213, s[24:25]
	v_cndmask_b32_e64 v102, 0, v213, s[26:27]
	v_cndmask_b32_e64 v103, 0, v213, s[28:29]
	v_sub_f32_e32 v92, v92, v100
	v_sub_f32_e32 v93, v93, v101
	v_sub_f32_e32 v94, v94, v102
	v_sub_f32_e32 v95, v95, v103
	v_add_f32_e32 v64, v64, v92
	v_add_f32_e32 v65, v65, v93
	v_add_f32_e32 v66, v66, v94
	v_add_f32_e32 v67, v67, v95
	v_mul_f32_e32 v92, 0xbfb8aa3b, v64
	v_mul_f32_e32 v93, 0xbfb8aa3b, v65
	v_mul_f32_e32 v94, 0xbfb8aa3b, v66
	v_mul_f32_e32 v95, 0xbfb8aa3b, v67
	v_mul_f32_e32 v100, 0x3fb8aa3b, v64
	v_mul_f32_e32 v101, 0x3fb8aa3b, v65
	v_mul_f32_e32 v102, 0x3fb8aa3b, v66
	v_mul_f32_e32 v103, 0x3fb8aa3b, v67
	v_exp_f32_e32 v92, v92
	v_exp_f32_e32 v93, v93
	v_exp_f32_e32 v94, v94
	v_exp_f32_e32 v95, v95
	v_exp_f32_e32 v100, v100
	v_exp_f32_e32 v101, v101
	v_exp_f32_e32 v102, v102
	v_exp_f32_e32 v103, v103
	v_sub_f32_e32 v96, 1.0, v96
	v_sub_f32_e32 v97, 1.0, v97
	v_sub_f32_e32 v98, 1.0, v98
	v_sub_f32_e32 v99, 1.0, v99
	v_mul_f32_e32 v96, v96, v92
	v_mul_f32_e32 v97, v97, v93
	v_mul_f32_e32 v98, v98, v94
	v_mul_f32_e32 v99, v99, v95
	v_lshlrev_b32_e32 v92, 16, v38
	v_and_b32_e32 v93, 0xffff0000, v38
	v_lshlrev_b32_e32 v94, 16, v39
	v_and_b32_e32 v95, 0xffff0000, v39
	v_mul_f32_e32 v92, v92, v100
	v_mul_f32_e32 v93, v93, v101
	v_mul_f32_e32 v94, v94, v102
	v_mul_f32_e32 v95, v95, v103
	v_cvt_pk_bf16_f32 v128, v128, v96
	v_cvt_pk_bf16_f32 v144, v144, v97
	v_cvt_pk_bf16_f32 v178, v178, v98
	v_cvt_pk_bf16_f32 v194, v194, v99
	v_cvt_pk_bf16_f32 v92, v92, v93
	v_cvt_pk_bf16_f32 v93, v94, v95
	v_cvt_pk_bf16_f32 v96, v96, v97
	v_cvt_pk_bf16_f32 v97, v98, v99
	global_store_dwordx2 v112, v[92:93], s[2:3]
	global_store_dwordx2 v114, v[96:97], s[2:3]
	s_add_u32 s2, s2, 0x400
	s_addc_u32 s3, s3, 0
	v_lshlrev_b32_e32 v92, 16, v40
	v_and_b32_e32 v93, 0xffff0000, v40
	v_lshlrev_b32_e32 v94, 16, v41
	v_and_b32_e32 v95, 0xffff0000, v41
	v_mul_f32_e32 v92, 0xbfb8aa3b, v92
	v_mul_f32_e32 v93, 0xbfb8aa3b, v93
	v_mul_f32_e32 v94, 0xbfb8aa3b, v94
	v_mul_f32_e32 v95, 0xbfb8aa3b, v95
	v_exp_f32_e32 v92, v92
	v_exp_f32_e32 v93, v93
	v_exp_f32_e32 v94, v94
	v_exp_f32_e32 v95, v95
	v_add_f32_e32 v92, 1.0, v92
	v_add_f32_e32 v93, 1.0, v93
	v_add_f32_e32 v94, 1.0, v94
	v_add_f32_e32 v95, 1.0, v95
	v_rcp_f32_e32 v92, v92
	v_rcp_f32_e32 v93, v93
	v_rcp_f32_e32 v94, v94
	v_rcp_f32_e32 v95, v95
	v_fma_f32 v96, v72, v92, v68
	v_fma_f32 v97, v73, v93, v69
	v_fma_f32 v98, v74, v94, v70
	v_fma_f32 v99, v75, v95, v71
	v_cmp_gt_f32_e64 s[22:23], s30, v96
	v_cmp_gt_f32_e64 s[24:25], s30, v97
	v_cmp_gt_f32_e64 s[26:27], s30, v98
	v_cmp_gt_f32_e64 s[28:29], s30, v99
	v_cndmask_b32_e64 v92, 0, 32, s[22:23]
	v_cndmask_b32_e64 v93, 0, 32, s[24:25]
	v_cndmask_b32_e64 v94, 0, 32, s[26:27]
	v_cndmask_b32_e64 v95, 0, 32, s[28:29]
	v_ldexp_f32 v92, v96, v92
	v_ldexp_f32 v93, v97, v93
	v_ldexp_f32 v94, v98, v94
	v_ldexp_f32 v95, v99, v95
	v_log_f32_e32 v92, v92
	v_log_f32_e32 v93, v93
	v_log_f32_e32 v94, v94
	v_log_f32_e32 v95, v95
	v_mul_f32_e32 v100, 0x3f317217, v92
	v_mul_f32_e32 v101, 0x3f317217, v93
	v_mul_f32_e32 v102, 0x3f317217, v94
	v_mul_f32_e32 v103, 0x3f317217, v95
	v_fma_f32 v100, v92, s31, -v100
	v_fma_f32 v101, v93, s31, -v101
	v_fma_f32 v102, v94, s31, -v102
	v_fma_f32 v103, v95, s31, -v103
	v_fmac_f32_e32 v100, 0x3377d1cf, v92
	v_fmac_f32_e32 v101, 0x3377d1cf, v93
	v_fmac_f32_e32 v102, 0x3377d1cf, v94
	v_fmac_f32_e32 v103, 0x3377d1cf, v95
	v_fmac_f32_e32 v100, 0x3f317217, v92
	v_fmac_f32_e32 v101, 0x3f317217, v93
	v_fmac_f32_e32 v102, 0x3f317217, v94
	v_fmac_f32_e32 v103, 0x3f317217, v95
	v_cmp_lt_f32_e64 vcc, |v92|, s34
	v_cndmask_b32_e32 v92, v92, v100, vcc
	v_cmp_lt_f32_e64 vcc, |v93|, s34
	v_cndmask_b32_e32 v93, v93, v101, vcc
	v_cmp_lt_f32_e64 vcc, |v94|, s34
	v_cndmask_b32_e32 v94, v94, v102, vcc
	v_cmp_lt_f32_e64 vcc, |v95|, s34
	v_cndmask_b32_e32 v95, v95, v103, vcc
	v_cndmask_b32_e64 v100, 0, v213, s[22:23]
	v_cndmask_b32_e64 v101, 0, v213, s[24:25]
	v_cndmask_b32_e64 v102, 0, v213, s[26:27]
	v_cndmask_b32_e64 v103, 0, v213, s[28:29]
	v_sub_f32_e32 v92, v92, v100
	v_sub_f32_e32 v93, v93, v101
	v_sub_f32_e32 v94, v94, v102
	v_sub_f32_e32 v95, v95, v103
	v_add_f32_e32 v64, v64, v92
	v_add_f32_e32 v65, v65, v93
	v_add_f32_e32 v66, v66, v94
	v_add_f32_e32 v67, v67, v95
	v_mul_f32_e32 v92, 0xbfb8aa3b, v64
	v_mul_f32_e32 v93, 0xbfb8aa3b, v65
	v_mul_f32_e32 v94, 0xbfb8aa3b, v66
	v_mul_f32_e32 v95, 0xbfb8aa3b, v67
	v_mul_f32_e32 v100, 0x3fb8aa3b, v64
	v_mul_f32_e32 v101, 0x3fb8aa3b, v65
	v_mul_f32_e32 v102, 0x3fb8aa3b, v66
	v_mul_f32_e32 v103, 0x3fb8aa3b, v67
	v_exp_f32_e32 v92, v92
	v_exp_f32_e32 v93, v93
	v_exp_f32_e32 v94, v94
	v_exp_f32_e32 v95, v95
	v_exp_f32_e32 v100, v100
	v_exp_f32_e32 v101, v101
	v_exp_f32_e32 v102, v102
	v_exp_f32_e32 v103, v103
	v_sub_f32_e32 v96, 1.0, v96
	v_sub_f32_e32 v97, 1.0, v97
	v_sub_f32_e32 v98, 1.0, v98
	v_sub_f32_e32 v99, 1.0, v99
	v_mul_f32_e32 v96, v96, v92
	v_mul_f32_e32 v97, v97, v93
	v_mul_f32_e32 v98, v98, v94
	v_mul_f32_e32 v99, v99, v95
	v_lshlrev_b32_e32 v92, 16, v42
	v_and_b32_e32 v93, 0xffff0000, v42
	v_lshlrev_b32_e32 v94, 16, v43
	v_and_b32_e32 v95, 0xffff0000, v43
	v_mul_f32_e32 v92, v92, v100
	v_mul_f32_e32 v93, v93, v101
	v_mul_f32_e32 v94, v94, v102
	v_mul_f32_e32 v95, v95, v103
	v_mov_b32_e32 v129, v96
	v_mov_b32_e32 v145, v97
	v_mov_b32_e32 v179, v98
; DEV u16 f2bf(float f) { return (u16)(pack2(f, f) & 0xffffu); }
; DEV float bf2f(u16 h) { return __uint_as_float(((unsigned)h) << 16); }
; DEV float sigmoid_f(float x) { return __builtin_amdgcn_rcpf(1.f + __expf(-x)); }
; DEV void phase_p15(const Params& p, int g) {
;     ...
;           const float f = lb[cc] + (1.f - lb[cc]) * sigmoid_f(bf2f(xr[st][cc][e]));
;           G[cc] += __logf(f);
;           const float eg = __expf(G[cc]), ig = __expf(-G[cc]);
;           Qp[tok * 512 + c] = f2bf(bf2f(qr[st][cc][e]) * eg);
;           const u16 kk = f2bf((1.f - f) * ig);
;           Kp[tok * 512 + c] = kk;
;           kb[e] = kk;
;         }
;         const int s0 = dir ? 56 - 8 * j8 : 8 * j8;
;         uint4 w;
;         w.x = dir ? (kb[7] | (kb[6] << 16)) : (kb[0] | (kb[1] << 16));
;         w.y = dir ? (kb[5] | (kb[4] << 16)) : (kb[2] | (kb[3] << 16));
;         w.z = dir ? (kb[3] | (kb[2] << 16)) : (kb[4] | (kb[5] << 16));
;         w.w = dir ? (kb[1] | (kb[0] << 16)) : (kb[6] | (kb[7] << 16));
;         *(uint4*)(KT + (((size_t)cidx * 2 + dir) * 512 + c) * 64 + s0) = w;
	v_mov_b32_e32 v195, v99
	v_cvt_pk_bf16_f32 v92, v92, v93
	v_cvt_pk_bf16_f32 v93, v94, v95
	v_cvt_pk_bf16_f32 v96, v96, v97
	v_cvt_pk_bf16_f32 v97, v98, v99
	global_store_dwordx2 v112, v[92:93], s[2:3]
	global_store_dwordx2 v114, v[96:97], s[2:3]
	s_add_u32 s2, s2, 0x400
	s_addc_u32 s3, s3, 0
	v_lshlrev_b32_e32 v92, 16, v44
	v_and_b32_e32 v93, 0xffff0000, v44
	v_lshlrev_b32_e32 v94, 16, v45
	v_and_b32_e32 v95, 0xffff0000, v45
	v_mul_f32_e32 v92, 0xbfb8aa3b, v92
	v_mul_f32_e32 v93, 0xbfb8aa3b, v93
	v_mul_f32_e32 v94, 0xbfb8aa3b, v94
	v_mul_f32_e32 v95, 0xbfb8aa3b, v95
	v_exp_f32_e32 v92, v92
	v_exp_f32_e32 v93, v93
	v_exp_f32_e32 v94, v94
	v_exp_f32_e32 v95, v95
	v_add_f32_e32 v92, 1.0, v92
	v_add_f32_e32 v93, 1.0, v93
	v_add_f32_e32 v94, 1.0, v94
	v_add_f32_e32 v95, 1.0, v95
	v_rcp_f32_e32 v92, v92
	v_rcp_f32_e32 v93, v93
	v_rcp_f32_e32 v94, v94
	v_rcp_f32_e32 v95, v95
	v_fma_f32 v96, v72, v92, v68
	v_fma_f32 v97, v73, v93, v69
	v_fma_f32 v98, v74, v94, v70
	v_fma_f32 v99, v75, v95, v71
	v_cmp_gt_f32_e64 s[22:23], s30, v96
	v_cmp_gt_f32_e64 s[24:25], s30, v97
	v_cmp_gt_f32_e64 s[26:27], s30, v98
	v_cmp_gt_f32_e64 s[28:29], s30, v99
	v_cndmask_b32_e64 v92, 0, 32, s[22:23]
	v_cndmask_b32_e64 v93, 0, 32, s[24:25]
	v_cndmask_b32_e64 v94, 0, 32, s[26:27]
	v_cndmask_b32_e64 v95, 0, 32, s[28:29]
	v_ldexp_f32 v92, v96, v92
	v_ldexp_f32 v93, v97, v93
	v_ldexp_f32 v94, v98, v94
	v_ldexp_f32 v95, v99, v95
	v_log_f32_e32 v92, v92
	v_log_f32_e32 v93, v93
	v_log_f32_e32 v94, v94
	v_log_f32_e32 v95, v95
	v_mul_f32_e32 v100, 0x3f317217, v92
	v_mul_f32_e32 v101, 0x3f317217, v93
	v_mul_f32_e32 v102, 0x3f317217, v94
	v_mul_f32_e32 v103, 0x3f317217, v95
	v_fma_f32 v100, v92, s31, -v100
	v_fma_f32 v101, v93, s31, -v101
	v_fma_f32 v102, v94, s31, -v102
	v_fma_f32 v103, v95, s31, -v103
	v_fmac_f32_e32 v100, 0x3377d1cf, v92
	v_fmac_f32_e32 v101, 0x3377d1cf, v93
	v_fmac_f32_e32 v102, 0x3377d1cf, v94
	v_fmac_f32_e32 v103, 0x3377d1cf, v95
	v_fmac_f32_e32 v100, 0x3f317217, v92
	v_fmac_f32_e32 v101, 0x3f317217, v93
	v_fmac_f32_e32 v102, 0x3f317217, v94
	v_fmac_f32_e32 v103, 0x3f317217, v95
	v_cmp_lt_f32_e64 vcc, |v92|, s34
	v_cndmask_b32_e32 v92, v92, v100, vcc
	v_cmp_lt_f32_e64 vcc, |v93|, s34
	v_cndmask_b32_e32 v93, v93, v101, vcc
	v_cmp_lt_f32_e64 vcc, |v94|, s34
	v_cndmask_b32_e32 v94, v94, v102, vcc
	v_cmp_lt_f32_e64 vcc, |v95|, s34
	v_cndmask_b32_e32 v95, v95, v103, vcc
	v_cndmask_b32_e64 v100, 0, v213, s[22:23]
	v_cndmask_b32_e64 v101, 0, v213, s[24:25]
	v_cndmask_b32_e64 v102, 0, v213, s[26:27]
	v_cndmask_b32_e64 v103, 0, v213, s[28:29]
	v_sub_f32_e32 v92, v92, v100
	v_sub_f32_e32 v93, v93, v101
	v_sub_f32_e32 v94, v94, v102
	v_sub_f32_e32 v95, v95, v103
	v_add_f32_e32 v64, v64, v92
	v_add_f32_e32 v65, v65, v93
	v_add_f32_e32 v66, v66, v94
	v_add_f32_e32 v67, v67, v95
	v_mul_f32_e32 v92, 0xbfb8aa3b, v64
	v_mul_f32_e32 v93, 0xbfb8aa3b, v65
	v_mul_f32_e32 v94, 0xbfb8aa3b, v66
	v_mul_f32_e32 v95, 0xbfb8aa3b, v67
	v_mul_f32_e32 v100, 0x3fb8aa3b, v64
	v_mul_f32_e32 v101, 0x3fb8aa3b, v65
	v_mul_f32_e32 v102, 0x3fb8aa3b, v66
	v_mul_f32_e32 v103, 0x3fb8aa3b, v67
	v_exp_f32_e32 v92, v92
	v_exp_f32_e32 v93, v93
	v_exp_f32_e32 v94, v94
	v_exp_f32_e32 v95, v95
	v_exp_f32_e32 v100, v100
	v_exp_f32_e32 v101, v101
	v_exp_f32_e32 v102, v102
	v_exp_f32_e32 v103, v103
	v_sub_f32_e32 v96, 1.0, v96
	v_sub_f32_e32 v97, 1.0, v97
	v_sub_f32_e32 v98, 1.0, v98
	v_sub_f32_e32 v99, 1.0, v99
	v_mul_f32_e32 v96, v96, v92
	v_mul_f32_e32 v97, v97, v93
	v_mul_f32_e32 v98, v98, v94
	v_mul_f32_e32 v99, v99, v95
	v_lshlrev_b32_e32 v92, 16, v46
	v_and_b32_e32 v93, 0xffff0000, v46
	v_lshlrev_b32_e32 v94, 16, v47
	v_and_b32_e32 v95, 0xffff0000, v47
	v_mul_f32_e32 v92, v92, v100
	v_mul_f32_e32 v93, v93, v101
	v_mul_f32_e32 v94, v94, v102
	v_mul_f32_e32 v95, v95, v103
	v_cvt_pk_bf16_f32 v129, v129, v96
	v_cvt_pk_bf16_f32 v145, v145, v97
	v_cvt_pk_bf16_f32 v179, v179, v98
	v_cvt_pk_bf16_f32 v195, v195, v99
	v_cvt_pk_bf16_f32 v92, v92, v93
	v_cvt_pk_bf16_f32 v93, v94, v95
	v_cvt_pk_bf16_f32 v96, v96, v97
	v_cvt_pk_bf16_f32 v97, v98, v99
	global_store_dwordx2 v112, v[92:93], s[2:3]
	global_store_dwordx2 v114, v[96:97], s[2:3]
	s_add_u32 s2, s2, 0x400
	s_addc_u32 s3, s3, 0
	v_lshlrev_b32_e32 v92, 16, v48
	v_and_b32_e32 v93, 0xffff0000, v48
	v_lshlrev_b32_e32 v94, 16, v49
	v_and_b32_e32 v95, 0xffff0000, v49
	v_mul_f32_e32 v92, 0xbfb8aa3b, v92
	v_mul_f32_e32 v93, 0xbfb8aa3b, v93
	v_mul_f32_e32 v94, 0xbfb8aa3b, v94
	v_mul_f32_e32 v95, 0xbfb8aa3b, v95
	v_exp_f32_e32 v92, v92
	v_exp_f32_e32 v93, v93
	v_exp_f32_e32 v94, v94
	v_exp_f32_e32 v95, v95
	v_add_f32_e32 v92, 1.0, v92
	v_add_f32_e32 v93, 1.0, v93
	v_add_f32_e32 v94, 1.0, v94
	v_add_f32_e32 v95, 1.0, v95
	v_rcp_f32_e32 v92, v92
	v_rcp_f32_e32 v93, v93
	v_rcp_f32_e32 v94, v94
	v_rcp_f32_e32 v95, v95
	v_fma_f32 v96, v72, v92, v68
	v_fma_f32 v97, v73, v93, v69
	v_fma_f32 v98, v74, v94, v70
	v_fma_f32 v99, v75, v95, v71
	v_cmp_gt_f32_e64 s[22:23], s30, v96
	v_cmp_gt_f32_e64 s[24:25], s30, v97
	v_cmp_gt_f32_e64 s[26:27], s30, v98
	v_cmp_gt_f32_e64 s[28:29], s30, v99
	v_cndmask_b32_e64 v92, 0, 32, s[22:23]
	v_cndmask_b32_e64 v93, 0, 32, s[24:25]
	v_cndmask_b32_e64 v94, 0, 32, s[26:27]
	v_cndmask_b32_e64 v95, 0, 32, s[28:29]
	v_ldexp_f32 v92, v96, v92
	v_ldexp_f32 v93, v97, v93
	v_ldexp_f32 v94, v98, v94
	v_ldexp_f32 v95, v99, v95
	v_log_f32_e32 v92, v92
	v_log_f32_e32 v93, v93
	v_log_f32_e32 v94, v94
	v_log_f32_e32 v95, v95
	v_mul_f32_e32 v100, 0x3f317217, v92
	v_mul_f32_e32 v101, 0x3f317217, v93
	v_mul_f32_e32 v102, 0x3f317217, v94
	v_mul_f32_e32 v103, 0x3f317217, v95
	v_fma_f32 v100, v92, s31, -v100
	v_fma_f32 v101, v93, s31, -v101
	v_fma_f32 v102, v94, s31, -v102
; DEV u16 f2bf(float f) { return (u16)(pack2(f, f) & 0xffffu); }
; DEV float bf2f(u16 h) { return __uint_as_float(((unsigned)h) << 16); }
; DEV float sigmoid_f(float x) { return __builtin_amdgcn_rcpf(1.f + __expf(-x)); }
; DEV void phase_p15(const Params& p, int g) {
;     ...
;           const float f = lb[cc] + (1.f - lb[cc]) * sigmoid_f(bf2f(xr[st][cc][e]));
;           G[cc] += __logf(f);
;           const float eg = __expf(G[cc]), ig = __expf(-G[cc]);
;           Qp[tok * 512 + c] = f2bf(bf2f(qr[st][cc][e]) * eg);
;           const u16 kk = f2bf((1.f - f) * ig);
;           Kp[tok * 512 + c] = kk;
;           kb[e] = kk;
;         }
;         const int s0 = dir ? 56 - 8 * j8 : 8 * j8;
;         uint4 w;
;         w.x = dir ? (kb[7] | (kb[6] << 16)) : (kb[0] | (kb[1] << 16));
;         w.y = dir ? (kb[5] | (kb[4] << 16)) : (kb[2] | (kb[3] << 16));
;         w.z = dir ? (kb[3] | (kb[2] << 16)) : (kb[4] | (kb[5] << 16));
;         w.w = dir ? (kb[1] | (kb[0] << 16)) : (kb[6] | (kb[7] << 16));
;         *(uint4*)(KT + (((size_t)cidx * 2 + dir) * 512 + c) * 64 + s0) = w;
	v_fma_f32 v103, v95, s31, -v103
	v_fmac_f32_e32 v100, 0x3377d1cf, v92
	v_fmac_f32_e32 v101, 0x3377d1cf, v93
	v_fmac_f32_e32 v102, 0x3377d1cf, v94
	v_fmac_f32_e32 v103, 0x3377d1cf, v95
	v_fmac_f32_e32 v100, 0x3f317217, v92
	v_fmac_f32_e32 v101, 0x3f317217, v93
	v_fmac_f32_e32 v102, 0x3f317217, v94
	v_fmac_f32_e32 v103, 0x3f317217, v95
	v_cmp_lt_f32_e64 vcc, |v92|, s34
	v_cndmask_b32_e32 v92, v92, v100, vcc
	v_cmp_lt_f32_e64 vcc, |v93|, s34
	v_cndmask_b32_e32 v93, v93, v101, vcc
	v_cmp_lt_f32_e64 vcc, |v94|, s34
	v_cndmask_b32_e32 v94, v94, v102, vcc
	v_cmp_lt_f32_e64 vcc, |v95|, s34
	v_cndmask_b32_e32 v95, v95, v103, vcc
	v_cndmask_b32_e64 v100, 0, v213, s[22:23]
	v_cndmask_b32_e64 v101, 0, v213, s[24:25]
	v_cndmask_b32_e64 v102, 0, v213, s[26:27]
	v_cndmask_b32_e64 v103, 0, v213, s[28:29]
	v_sub_f32_e32 v92, v92, v100
	v_sub_f32_e32 v93, v93, v101
	v_sub_f32_e32 v94, v94, v102
	v_sub_f32_e32 v95, v95, v103
	v_add_f32_e32 v64, v64, v92
	v_add_f32_e32 v65, v65, v93
	v_add_f32_e32 v66, v66, v94
	v_add_f32_e32 v67, v67, v95
	v_mul_f32_e32 v92, 0xbfb8aa3b, v64
	v_mul_f32_e32 v93, 0xbfb8aa3b, v65
	v_mul_f32_e32 v94, 0xbfb8aa3b, v66
	v_mul_f32_e32 v95, 0xbfb8aa3b, v67
	v_mul_f32_e32 v100, 0x3fb8aa3b, v64
	v_mul_f32_e32 v101, 0x3fb8aa3b, v65
	v_mul_f32_e32 v102, 0x3fb8aa3b, v66
	v_mul_f32_e32 v103, 0x3fb8aa3b, v67
	v_exp_f32_e32 v92, v92
	v_exp_f32_e32 v93, v93
	v_exp_f32_e32 v94, v94
	v_exp_f32_e32 v95, v95
	v_exp_f32_e32 v100, v100
	v_exp_f32_e32 v101, v101
	v_exp_f32_e32 v102, v102
	v_exp_f32_e32 v103, v103
	v_sub_f32_e32 v96, 1.0, v96
	v_sub_f32_e32 v97, 1.0, v97
	v_sub_f32_e32 v98, 1.0, v98
	v_sub_f32_e32 v99, 1.0, v99
	v_mul_f32_e32 v96, v96, v92
	v_mul_f32_e32 v97, v97, v93
	v_mul_f32_e32 v98, v98, v94
	v_mul_f32_e32 v99, v99, v95
	v_lshlrev_b32_e32 v92, 16, v50
	v_and_b32_e32 v93, 0xffff0000, v50
	v_lshlrev_b32_e32 v94, 16, v51
	v_and_b32_e32 v95, 0xffff0000, v51
	v_mul_f32_e32 v92, v92, v100
	v_mul_f32_e32 v93, v93, v101
	v_mul_f32_e32 v94, v94, v102
	v_mul_f32_e32 v95, v95, v103
	v_mov_b32_e32 v130, v96
	v_mov_b32_e32 v146, v97
	v_mov_b32_e32 v180, v98
	v_mov_b32_e32 v196, v99
	v_cvt_pk_bf16_f32 v92, v92, v93
	v_cvt_pk_bf16_f32 v93, v94, v95
	v_cvt_pk_bf16_f32 v96, v96, v97
	v_cvt_pk_bf16_f32 v97, v98, v99
	global_store_dwordx2 v112, v[92:93], s[2:3]
	global_store_dwordx2 v114, v[96:97], s[2:3]
	s_add_u32 s2, s2, 0x400
	s_addc_u32 s3, s3, 0
	v_lshlrev_b32_e32 v92, 16, v52
	v_and_b32_e32 v93, 0xffff0000, v52
	v_lshlrev_b32_e32 v94, 16, v53
	v_and_b32_e32 v95, 0xffff0000, v53
	v_mul_f32_e32 v92, 0xbfb8aa3b, v92
	v_mul_f32_e32 v93, 0xbfb8aa3b, v93
	v_mul_f32_e32 v94, 0xbfb8aa3b, v94
	v_mul_f32_e32 v95, 0xbfb8aa3b, v95
	v_exp_f32_e32 v92, v92
	v_exp_f32_e32 v93, v93
	v_exp_f32_e32 v94, v94
	v_exp_f32_e32 v95, v95
	v_add_f32_e32 v92, 1.0, v92
	v_add_f32_e32 v93, 1.0, v93
	v_add_f32_e32 v94, 1.0, v94
	v_add_f32_e32 v95, 1.0, v95
	v_rcp_f32_e32 v92, v92
	v_rcp_f32_e32 v93, v93
	v_rcp_f32_e32 v94, v94
	v_rcp_f32_e32 v95, v95
	v_fma_f32 v96, v72, v92, v68
	v_fma_f32 v97, v73, v93, v69
	v_fma_f32 v98, v74, v94, v70
	v_fma_f32 v99, v75, v95, v71
	v_cmp_gt_f32_e64 s[22:23], s30, v96
	v_cmp_gt_f32_e64 s[24:25], s30, v97
	v_cmp_gt_f32_e64 s[26:27], s30, v98
	v_cmp_gt_f32_e64 s[28:29], s30, v99
	v_cndmask_b32_e64 v92, 0, 32, s[22:23]
	v_cndmask_b32_e64 v93, 0, 32, s[24:25]
	v_cndmask_b32_e64 v94, 0, 32, s[26:27]
	v_cndmask_b32_e64 v95, 0, 32, s[28:29]
	v_ldexp_f32 v92, v96, v92
	v_ldexp_f32 v93, v97, v93
	v_ldexp_f32 v94, v98, v94
	v_ldexp_f32 v95, v99, v95
	v_log_f32_e32 v92, v92
	v_log_f32_e32 v93, v93
	v_log_f32_e32 v94, v94
	v_log_f32_e32 v95, v95
	v_mul_f32_e32 v100, 0x3f317217, v92
	v_mul_f32_e32 v101, 0x3f317217, v93
	v_mul_f32_e32 v102, 0x3f317217, v94
	v_mul_f32_e32 v103, 0x3f317217, v95
	v_fma_f32 v100, v92, s31, -v100
	v_fma_f32 v101, v93, s31, -v101
	v_fma_f32 v102, v94, s31, -v102
	v_fma_f32 v103, v95, s31, -v103
	v_fmac_f32_e32 v100, 0x3377d1cf, v92
	v_fmac_f32_e32 v101, 0x3377d1cf, v93
	v_fmac_f32_e32 v102, 0x3377d1cf, v94
	v_fmac_f32_e32 v103, 0x3377d1cf, v95
	v_fmac_f32_e32 v100, 0x3f317217, v92
	v_fmac_f32_e32 v101, 0x3f317217, v93
	v_fmac_f32_e32 v102, 0x3f317217, v94
	v_fmac_f32_e32 v103, 0x3f317217, v95
	v_cmp_lt_f32_e64 vcc, |v92|, s34
	v_cndmask_b32_e32 v92, v92, v100, vcc
	v_cmp_lt_f32_e64 vcc, |v93|, s34
	v_cndmask_b32_e32 v93, v93, v101, vcc
	v_cmp_lt_f32_e64 vcc, |v94|, s34
	v_cndmask_b32_e32 v94, v94, v102, vcc
	v_cmp_lt_f32_e64 vcc, |v95|, s34
	v_cndmask_b32_e32 v95, v95, v103, vcc
	v_cndmask_b32_e64 v100, 0, v213, s[22:23]
	v_cndmask_b32_e64 v101, 0, v213, s[24:25]
	v_cndmask_b32_e64 v102, 0, v213, s[26:27]
	v_cndmask_b32_e64 v103, 0, v213, s[28:29]
	v_sub_f32_e32 v92, v92, v100
	v_sub_f32_e32 v93, v93, v101
	v_sub_f32_e32 v94, v94, v102
	v_sub_f32_e32 v95, v95, v103
	v_add_f32_e32 v64, v64, v92
	v_add_f32_e32 v65, v65, v93
	v_add_f32_e32 v66, v66, v94
	v_add_f32_e32 v67, v67, v95
	v_mul_f32_e32 v92, 0xbfb8aa3b, v64
	v_mul_f32_e32 v93, 0xbfb8aa3b, v65
	v_mul_f32_e32 v94, 0xbfb8aa3b, v66
	v_mul_f32_e32 v95, 0xbfb8aa3b, v67
	v_mul_f32_e32 v100, 0x3fb8aa3b, v64
	v_mul_f32_e32 v101, 0x3fb8aa3b, v65
	v_mul_f32_e32 v102, 0x3fb8aa3b, v66
	v_mul_f32_e32 v103, 0x3fb8aa3b, v67
	v_exp_f32_e32 v92, v92
	v_exp_f32_e32 v93, v93
	v_exp_f32_e32 v94, v94
	v_exp_f32_e32 v95, v95
	v_exp_f32_e32 v100, v100
	v_exp_f32_e32 v101, v101
	v_exp_f32_e32 v102, v102
	v_exp_f32_e32 v103, v103
	v_sub_f32_e32 v96, 1.0, v96
	v_sub_f32_e32 v97, 1.0, v97
	v_sub_f32_e32 v98, 1.0, v98
	v_sub_f32_e32 v99, 1.0, v99
	v_mul_f32_e32 v96, v96, v92
	v_mul_f32_e32 v97, v97, v93
	v_mul_f32_e32 v98, v98, v94
	v_mul_f32_e32 v99, v99, v95
	v_lshlrev_b32_e32 v92, 16, v54
; DEV u16 f2bf(float f) { return (u16)(pack2(f, f) & 0xffffu); }
; DEV float bf2f(u16 h) { return __uint_as_float(((unsigned)h) << 16); }
; DEV float sigmoid_f(float x) { return __builtin_amdgcn_rcpf(1.f + __expf(-x)); }
; DEV void phase_p15(const Params& p, int g) {
;     ...
;           const float f = lb[cc] + (1.f - lb[cc]) * sigmoid_f(bf2f(xr[st][cc][e]));
;           G[cc] += __logf(f);
;           const float eg = __expf(G[cc]), ig = __expf(-G[cc]);
;           Qp[tok * 512 + c] = f2bf(bf2f(qr[st][cc][e]) * eg);
;           const u16 kk = f2bf((1.f - f) * ig);
;           Kp[tok * 512 + c] = kk;
;           kb[e] = kk;
;         }
;         const int s0 = dir ? 56 - 8 * j8 : 8 * j8;
;         uint4 w;
;         w.x = dir ? (kb[7] | (kb[6] << 16)) : (kb[0] | (kb[1] << 16));
;         w.y = dir ? (kb[5] | (kb[4] << 16)) : (kb[2] | (kb[3] << 16));
;         w.z = dir ? (kb[3] | (kb[2] << 16)) : (kb[4] | (kb[5] << 16));
;         w.w = dir ? (kb[1] | (kb[0] << 16)) : (kb[6] | (kb[7] << 16));
;         *(uint4*)(KT + (((size_t)cidx * 2 + dir) * 512 + c) * 64 + s0) = w;
	v_and_b32_e32 v93, 0xffff0000, v54
	v_lshlrev_b32_e32 v94, 16, v55
	v_and_b32_e32 v95, 0xffff0000, v55
	v_mul_f32_e32 v92, v92, v100
	v_mul_f32_e32 v93, v93, v101
	v_mul_f32_e32 v94, v94, v102
	v_mul_f32_e32 v95, v95, v103
	v_cvt_pk_bf16_f32 v130, v130, v96
	v_cvt_pk_bf16_f32 v146, v146, v97
	v_cvt_pk_bf16_f32 v180, v180, v98
	v_cvt_pk_bf16_f32 v196, v196, v99
	v_cvt_pk_bf16_f32 v92, v92, v93
	v_cvt_pk_bf16_f32 v93, v94, v95
	v_cvt_pk_bf16_f32 v96, v96, v97
	v_cvt_pk_bf16_f32 v97, v98, v99
	global_store_dwordx2 v112, v[92:93], s[2:3]
	global_store_dwordx2 v114, v[96:97], s[2:3]
	s_add_u32 s2, s2, 0x400
	s_addc_u32 s3, s3, 0
	v_lshlrev_b32_e32 v92, 16, v56
	v_and_b32_e32 v93, 0xffff0000, v56
	v_lshlrev_b32_e32 v94, 16, v57
	v_and_b32_e32 v95, 0xffff0000, v57
	v_mul_f32_e32 v92, 0xbfb8aa3b, v92
	v_mul_f32_e32 v93, 0xbfb8aa3b, v93
	v_mul_f32_e32 v94, 0xbfb8aa3b, v94
	v_mul_f32_e32 v95, 0xbfb8aa3b, v95
	v_exp_f32_e32 v92, v92
	v_exp_f32_e32 v93, v93
	v_exp_f32_e32 v94, v94
	v_exp_f32_e32 v95, v95
	v_add_f32_e32 v92, 1.0, v92
	v_add_f32_e32 v93, 1.0, v93
	v_add_f32_e32 v94, 1.0, v94
	v_add_f32_e32 v95, 1.0, v95
	v_rcp_f32_e32 v92, v92
	v_rcp_f32_e32 v93, v93
	v_rcp_f32_e32 v94, v94
	v_rcp_f32_e32 v95, v95
	v_fma_f32 v96, v72, v92, v68
	v_fma_f32 v97, v73, v93, v69
	v_fma_f32 v98, v74, v94, v70
	v_fma_f32 v99, v75, v95, v71
	v_cmp_gt_f32_e64 s[22:23], s30, v96
	v_cmp_gt_f32_e64 s[24:25], s30, v97
	v_cmp_gt_f32_e64 s[26:27], s30, v98
	v_cmp_gt_f32_e64 s[28:29], s30, v99
	v_cndmask_b32_e64 v92, 0, 32, s[22:23]
	v_cndmask_b32_e64 v93, 0, 32, s[24:25]
	v_cndmask_b32_e64 v94, 0, 32, s[26:27]
	v_cndmask_b32_e64 v95, 0, 32, s[28:29]
	v_ldexp_f32 v92, v96, v92
	v_ldexp_f32 v93, v97, v93
	v_ldexp_f32 v94, v98, v94
	v_ldexp_f32 v95, v99, v95
	v_log_f32_e32 v92, v92
	v_log_f32_e32 v93, v93
	v_log_f32_e32 v94, v94
	v_log_f32_e32 v95, v95
	v_mul_f32_e32 v100, 0x3f317217, v92
	v_mul_f32_e32 v101, 0x3f317217, v93
	v_mul_f32_e32 v102, 0x3f317217, v94
	v_mul_f32_e32 v103, 0x3f317217, v95
	v_fma_f32 v100, v92, s31, -v100
	v_fma_f32 v101, v93, s31, -v101
	v_fma_f32 v102, v94, s31, -v102
	v_fma_f32 v103, v95, s31, -v103
	v_fmac_f32_e32 v100, 0x3377d1cf, v92
	v_fmac_f32_e32 v101, 0x3377d1cf, v93
	v_fmac_f32_e32 v102, 0x3377d1cf, v94
	v_fmac_f32_e32 v103, 0x3377d1cf, v95
	v_fmac_f32_e32 v100, 0x3f317217, v92
	v_fmac_f32_e32 v101, 0x3f317217, v93
	v_fmac_f32_e32 v102, 0x3f317217, v94
	v_fmac_f32_e32 v103, 0x3f317217, v95
	v_cmp_lt_f32_e64 vcc, |v92|, s34
	v_cndmask_b32_e32 v92, v92, v100, vcc
	v_cmp_lt_f32_e64 vcc, |v93|, s34
	v_cndmask_b32_e32 v93, v93, v101, vcc
	v_cmp_lt_f32_e64 vcc, |v94|, s34
	v_cndmask_b32_e32 v94, v94, v102, vcc
	v_cmp_lt_f32_e64 vcc, |v95|, s34
	v_cndmask_b32_e32 v95, v95, v103, vcc
	v_cndmask_b32_e64 v100, 0, v213, s[22:23]
	v_cndmask_b32_e64 v101, 0, v213, s[24:25]
	v_cndmask_b32_e64 v102, 0, v213, s[26:27]
	v_cndmask_b32_e64 v103, 0, v213, s[28:29]
	v_sub_f32_e32 v92, v92, v100
	v_sub_f32_e32 v93, v93, v101
	v_sub_f32_e32 v94, v94, v102
	v_sub_f32_e32 v95, v95, v103
	v_add_f32_e32 v64, v64, v92
	v_add_f32_e32 v65, v65, v93
	v_add_f32_e32 v66, v66, v94
	v_add_f32_e32 v67, v67, v95
	v_mul_f32_e32 v92, 0xbfb8aa3b, v64
	v_mul_f32_e32 v93, 0xbfb8aa3b, v65
	v_mul_f32_e32 v94, 0xbfb8aa3b, v66
	v_mul_f32_e32 v95, 0xbfb8aa3b, v67
	v_mul_f32_e32 v100, 0x3fb8aa3b, v64
	v_mul_f32_e32 v101, 0x3fb8aa3b, v65
	v_mul_f32_e32 v102, 0x3fb8aa3b, v66
	v_mul_f32_e32 v103, 0x3fb8aa3b, v67
	v_exp_f32_e32 v92, v92
	v_exp_f32_e32 v93, v93
	v_exp_f32_e32 v94, v94
	v_exp_f32_e32 v95, v95
	v_exp_f32_e32 v100, v100
	v_exp_f32_e32 v101, v101
	v_exp_f32_e32 v102, v102
	v_exp_f32_e32 v103, v103
	v_sub_f32_e32 v96, 1.0, v96
	v_sub_f32_e32 v97, 1.0, v97
	v_sub_f32_e32 v98, 1.0, v98
	v_sub_f32_e32 v99, 1.0, v99
	v_mul_f32_e32 v96, v96, v92
	v_mul_f32_e32 v97, v97, v93
	v_mul_f32_e32 v98, v98, v94
	v_mul_f32_e32 v99, v99, v95
	v_lshlrev_b32_e32 v92, 16, v58
	v_and_b32_e32 v93, 0xffff0000, v58
	v_lshlrev_b32_e32 v94, 16, v59
	v_and_b32_e32 v95, 0xffff0000, v59
	v_mul_f32_e32 v92, v92, v100
	v_mul_f32_e32 v93, v93, v101
	v_mul_f32_e32 v94, v94, v102
	v_mul_f32_e32 v95, v95, v103
	v_mov_b32_e32 v131, v96
	v_mov_b32_e32 v147, v97
	v_mov_b32_e32 v181, v98
	v_mov_b32_e32 v197, v99
	v_cvt_pk_bf16_f32 v92, v92, v93
	v_cvt_pk_bf16_f32 v93, v94, v95
	v_cvt_pk_bf16_f32 v96, v96, v97
	v_cvt_pk_bf16_f32 v97, v98, v99
	global_store_dwordx2 v112, v[92:93], s[2:3]
	global_store_dwordx2 v114, v[96:97], s[2:3]
	s_add_u32 s2, s2, 0x400
	s_addc_u32 s3, s3, 0
	v_lshlrev_b32_e32 v92, 16, v60
	v_and_b32_e32 v93, 0xffff0000, v60
	v_lshlrev_b32_e32 v94, 16, v61
	v_and_b32_e32 v95, 0xffff0000, v61
	v_mul_f32_e32 v92, 0xbfb8aa3b, v92
	v_mul_f32_e32 v93, 0xbfb8aa3b, v93
	v_mul_f32_e32 v94, 0xbfb8aa3b, v94
	v_mul_f32_e32 v95, 0xbfb8aa3b, v95
	v_exp_f32_e32 v92, v92
	v_exp_f32_e32 v93, v93
	v_exp_f32_e32 v94, v94
	v_exp_f32_e32 v95, v95
	v_add_f32_e32 v92, 1.0, v92
	v_add_f32_e32 v93, 1.0, v93
	v_add_f32_e32 v94, 1.0, v94
	v_add_f32_e32 v95, 1.0, v95
	v_rcp_f32_e32 v92, v92
	v_rcp_f32_e32 v93, v93
	v_rcp_f32_e32 v94, v94
	v_rcp_f32_e32 v95, v95
	v_fma_f32 v96, v72, v92, v68
	v_fma_f32 v97, v73, v93, v69
	v_fma_f32 v98, v74, v94, v70
	v_fma_f32 v99, v75, v95, v71
	v_cmp_gt_f32_e64 s[22:23], s30, v96
	v_cmp_gt_f32_e64 s[24:25], s30, v97
	v_cmp_gt_f32_e64 s[26:27], s30, v98
	v_cmp_gt_f32_e64 s[28:29], s30, v99
	v_cndmask_b32_e64 v92, 0, 32, s[22:23]
	v_cndmask_b32_e64 v93, 0, 32, s[24:25]
	v_cndmask_b32_e64 v94, 0, 32, s[26:27]
	v_cndmask_b32_e64 v95, 0, 32, s[28:29]
	v_ldexp_f32 v92, v96, v92
	v_ldexp_f32 v93, v97, v93
	v_ldexp_f32 v94, v98, v94
	v_ldexp_f32 v95, v99, v95
	v_log_f32_e32 v92, v92
; DEV u16 f2bf(float f) { return (u16)(pack2(f, f) & 0xffffu); }
; DEV float bf2f(u16 h) { return __uint_as_float(((unsigned)h) << 16); }
; DEV float sigmoid_f(float x) { return __builtin_amdgcn_rcpf(1.f + __expf(-x)); }
; DEV void phase_p15(const Params& p, int g) {
;     ...
;           const float f = lb[cc] + (1.f - lb[cc]) * sigmoid_f(bf2f(xr[st][cc][e]));
;           G[cc] += __logf(f);
;           const float eg = __expf(G[cc]), ig = __expf(-G[cc]);
;           Qp[tok * 512 + c] = f2bf(bf2f(qr[st][cc][e]) * eg);
;           const u16 kk = f2bf((1.f - f) * ig);
;           Kp[tok * 512 + c] = kk;
;           kb[e] = kk;
;         }
;         const int s0 = dir ? 56 - 8 * j8 : 8 * j8;
;         uint4 w;
;         w.x = dir ? (kb[7] | (kb[6] << 16)) : (kb[0] | (kb[1] << 16));
;         w.y = dir ? (kb[5] | (kb[4] << 16)) : (kb[2] | (kb[3] << 16));
;         w.z = dir ? (kb[3] | (kb[2] << 16)) : (kb[4] | (kb[5] << 16));
;         w.w = dir ? (kb[1] | (kb[0] << 16)) : (kb[6] | (kb[7] << 16));
;         *(uint4*)(KT + (((size_t)cidx * 2 + dir) * 512 + c) * 64 + s0) = w;
	v_log_f32_e32 v93, v93
	v_log_f32_e32 v94, v94
	v_log_f32_e32 v95, v95
	v_mul_f32_e32 v100, 0x3f317217, v92
	v_mul_f32_e32 v101, 0x3f317217, v93
	v_mul_f32_e32 v102, 0x3f317217, v94
	v_mul_f32_e32 v103, 0x3f317217, v95
	v_fma_f32 v100, v92, s31, -v100
	v_fma_f32 v101, v93, s31, -v101
	v_fma_f32 v102, v94, s31, -v102
	v_fma_f32 v103, v95, s31, -v103
	v_fmac_f32_e32 v100, 0x3377d1cf, v92
	v_fmac_f32_e32 v101, 0x3377d1cf, v93
	v_fmac_f32_e32 v102, 0x3377d1cf, v94
	v_fmac_f32_e32 v103, 0x3377d1cf, v95
	v_fmac_f32_e32 v100, 0x3f317217, v92
	v_fmac_f32_e32 v101, 0x3f317217, v93
	v_fmac_f32_e32 v102, 0x3f317217, v94
	v_fmac_f32_e32 v103, 0x3f317217, v95
	v_cmp_lt_f32_e64 vcc, |v92|, s34
	v_cndmask_b32_e32 v92, v92, v100, vcc
	v_cmp_lt_f32_e64 vcc, |v93|, s34
	v_cndmask_b32_e32 v93, v93, v101, vcc
	v_cmp_lt_f32_e64 vcc, |v94|, s34
	v_cndmask_b32_e32 v94, v94, v102, vcc
	v_cmp_lt_f32_e64 vcc, |v95|, s34
	v_cndmask_b32_e32 v95, v95, v103, vcc
	v_cndmask_b32_e64 v100, 0, v213, s[22:23]
	v_cndmask_b32_e64 v101, 0, v213, s[24:25]
	v_cndmask_b32_e64 v102, 0, v213, s[26:27]
	v_cndmask_b32_e64 v103, 0, v213, s[28:29]
	v_sub_f32_e32 v92, v92, v100
	v_sub_f32_e32 v93, v93, v101
	v_sub_f32_e32 v94, v94, v102
	v_sub_f32_e32 v95, v95, v103
	v_add_f32_e32 v64, v64, v92
	v_add_f32_e32 v65, v65, v93
	v_add_f32_e32 v66, v66, v94
	v_add_f32_e32 v67, v67, v95
	v_mul_f32_e32 v92, 0xbfb8aa3b, v64
	v_mul_f32_e32 v93, 0xbfb8aa3b, v65
	v_mul_f32_e32 v94, 0xbfb8aa3b, v66
	v_mul_f32_e32 v95, 0xbfb8aa3b, v67
	v_mul_f32_e32 v100, 0x3fb8aa3b, v64
	v_mul_f32_e32 v101, 0x3fb8aa3b, v65
	v_mul_f32_e32 v102, 0x3fb8aa3b, v66
	v_mul_f32_e32 v103, 0x3fb8aa3b, v67
	v_exp_f32_e32 v92, v92
	v_exp_f32_e32 v93, v93
	v_exp_f32_e32 v94, v94
	v_exp_f32_e32 v95, v95
	v_exp_f32_e32 v100, v100
	v_exp_f32_e32 v101, v101
	v_exp_f32_e32 v102, v102
	v_exp_f32_e32 v103, v103
	v_sub_f32_e32 v96, 1.0, v96
	v_sub_f32_e32 v97, 1.0, v97
	v_sub_f32_e32 v98, 1.0, v98
	v_sub_f32_e32 v99, 1.0, v99
	v_mul_f32_e32 v96, v96, v92
	v_mul_f32_e32 v97, v97, v93
	v_mul_f32_e32 v98, v98, v94
	v_mul_f32_e32 v99, v99, v95
	v_lshlrev_b32_e32 v92, 16, v62
	v_and_b32_e32 v93, 0xffff0000, v62
	v_lshlrev_b32_e32 v94, 16, v63
	v_and_b32_e32 v95, 0xffff0000, v63
	v_mul_f32_e32 v92, v92, v100
	v_mul_f32_e32 v93, v93, v101
	v_mul_f32_e32 v94, v94, v102
	v_mul_f32_e32 v95, v95, v103
	v_cvt_pk_bf16_f32 v131, v131, v96
	v_cvt_pk_bf16_f32 v147, v147, v97
	v_cvt_pk_bf16_f32 v181, v181, v98
	v_cvt_pk_bf16_f32 v197, v197, v99
	v_cvt_pk_bf16_f32 v92, v92, v93
	v_cvt_pk_bf16_f32 v93, v94, v95
	v_cvt_pk_bf16_f32 v96, v96, v97
	v_cvt_pk_bf16_f32 v97, v98, v99
	global_store_dwordx2 v112, v[92:93], s[2:3]
	global_store_dwordx2 v114, v[96:97], s[2:3]
	s_add_u32 s2, s2, 0x400
	s_addc_u32 s3, s3, 0
	global_load_dwordx2 v[32:33], v113, s[0:1]
	global_load_dwordx2 v[34:35], v112, s[0:1]
	s_add_u32 s0, s0, 0x1400
	s_addc_u32 s1, s1, 0
	global_load_dwordx2 v[36:37], v113, s[0:1]
	global_load_dwordx2 v[38:39], v112, s[0:1]
	s_add_u32 s0, s0, 0x1400
	s_addc_u32 s1, s1, 0
	global_load_dwordx2 v[40:41], v113, s[0:1]
	global_load_dwordx2 v[42:43], v112, s[0:1]
	s_add_u32 s0, s0, 0x1400
	s_addc_u32 s1, s1, 0
	global_load_dwordx2 v[44:45], v113, s[0:1]
	global_load_dwordx2 v[46:47], v112, s[0:1]
	s_add_u32 s0, s0, 0x1400
	s_addc_u32 s1, s1, 0
	global_load_dwordx2 v[48:49], v113, s[0:1]
	global_load_dwordx2 v[50:51], v112, s[0:1]
	s_add_u32 s0, s0, 0x1400
	s_addc_u32 s1, s1, 0
	global_load_dwordx2 v[52:53], v113, s[0:1]
	global_load_dwordx2 v[54:55], v112, s[0:1]
	s_add_u32 s0, s0, 0x1400
	s_addc_u32 s1, s1, 0
	global_load_dwordx2 v[56:57], v113, s[0:1]
	global_load_dwordx2 v[58:59], v112, s[0:1]
	s_add_u32 s0, s0, 0x1400
	s_addc_u32 s1, s1, 0
	global_load_dwordx2 v[60:61], v113, s[0:1]
	global_load_dwordx2 v[62:63], v112, s[0:1]
	s_add_u32 s0, s0, 0x1400
	s_addc_u32 s1, s1, 0
	s_cmp_eq_u32 s35, 0
	s_cbranch_scc0 .Lp15_d0_nopark
	v_mov_b32_e32 v148, v116
	v_mov_b32_e32 v149, v117
	v_mov_b32_e32 v150, v118
	v_mov_b32_e32 v151, v119
	v_mov_b32_e32 v152, v120
	v_mov_b32_e32 v153, v121
	v_mov_b32_e32 v154, v122
	v_mov_b32_e32 v155, v123
	v_mov_b32_e32 v156, v124
	v_mov_b32_e32 v157, v125
	v_mov_b32_e32 v158, v126
	v_mov_b32_e32 v159, v127
	v_mov_b32_e32 v198, v128
	v_mov_b32_e32 v199, v129
	v_mov_b32_e32 v200, v130
	v_mov_b32_e32 v201, v131
	v_mov_b32_e32 v222, v132
	v_mov_b32_e32 v223, v133
	v_mov_b32_e32 v224, v134
	v_mov_b32_e32 v225, v135
	v_mov_b32_e32 v226, v136
	v_mov_b32_e32 v227, v137
	v_mov_b32_e32 v228, v138
	v_mov_b32_e32 v229, v139
	v_mov_b32_e32 v230, v140
	v_mov_b32_e32 v231, v141
	v_mov_b32_e32 v232, v142
	v_mov_b32_e32 v233, v143
	v_mov_b32_e32 v234, v144
	v_mov_b32_e32 v235, v145
	v_mov_b32_e32 v236, v146
	v_mov_b32_e32 v237, v147
	v_mov_b32_e32 v238, v166
	v_mov_b32_e32 v239, v167
	v_mov_b32_e32 v240, v168
	v_mov_b32_e32 v241, v169
	v_mov_b32_e32 v242, v170
	v_mov_b32_e32 v243, v171
	v_mov_b32_e32 v244, v172
	v_mov_b32_e32 v245, v173
	v_mov_b32_e32 v76, v174
	v_mov_b32_e32 v77, v175
	v_mov_b32_e32 v78, v176
	v_mov_b32_e32 v79, v177
	v_mov_b32_e32 v80, v178
	v_mov_b32_e32 v81, v179
	v_mov_b32_e32 v82, v180
	v_mov_b32_e32 v83, v181
	v_mov_b32_e32 v84, v182
	v_mov_b32_e32 v85, v183
	v_mov_b32_e32 v86, v184
	v_mov_b32_e32 v87, v185
	v_mov_b32_e32 v88, v186
	v_mov_b32_e32 v89, v187
	v_mov_b32_e32 v90, v188
	v_mov_b32_e32 v91, v189
	v_mov_b32_e32 v104, v190
	v_mov_b32_e32 v105, v191
	v_mov_b32_e32 v106, v192
	v_mov_b32_e32 v107, v193
	v_mov_b32_e32 v108, v194
	v_mov_b32_e32 v109, v195
	v_mov_b32_e32 v110, v196
	v_mov_b32_e32 v111, v197
; DEV void phase_p15(const Params& p, int g) {
;     ...
;         const int s0 = dir ? 56 - 8 * j8 : 8 * j8;
;         uint4 w;
;         w.x = dir ? (kb[7] | (kb[6] << 16)) : (kb[0] | (kb[1] << 16));
;         w.y = dir ? (kb[5] | (kb[4] << 16)) : (kb[2] | (kb[3] << 16));
;         w.z = dir ? (kb[3] | (kb[2] << 16)) : (kb[4] | (kb[5] << 16));
;         w.w = dir ? (kb[1] | (kb[0] << 16)) : (kb[6] | (kb[7] << 16));
;         *(uint4*)(KT + (((size_t)cidx * 2 + dir) * 512 + c) * 64 + s0) = w;
.Lp15_d0_nopark:
	s_add_u32 s35, s35, 1
	s_cmp_lt_u32 s35, 2
	s_cbranch_scc1 .Lp15_d0_loop
	global_store_dwordx4 v115, v[148:151], s[4:5]
	global_store_dwordx4 v115, v[152:155], s[4:5] offset:16
	global_store_dwordx4 v115, v[156:159], s[4:5] offset:32
	global_store_dwordx4 v115, v[198:201], s[4:5] offset:48
	global_store_dwordx4 v115, v[116:119], s[4:5] offset:64
	global_store_dwordx4 v115, v[120:123], s[4:5] offset:80
	global_store_dwordx4 v115, v[124:127], s[4:5] offset:96
	global_store_dwordx4 v115, v[128:131], s[4:5] offset:112
	global_store_dwordx4 v115, v[222:225], s[4:5] offset:128
	global_store_dwordx4 v115, v[226:229], s[4:5] offset:144
	global_store_dwordx4 v115, v[230:233], s[4:5] offset:160
	global_store_dwordx4 v115, v[234:237], s[4:5] offset:176
	global_store_dwordx4 v115, v[132:135], s[4:5] offset:192
	global_store_dwordx4 v115, v[136:139], s[4:5] offset:208
	global_store_dwordx4 v115, v[140:143], s[4:5] offset:224
	global_store_dwordx4 v115, v[144:147], s[4:5] offset:240
	global_store_dwordx4 v115, v[238:241], s[4:5] offset:256
	global_store_dwordx4 v115, v[242:245], s[4:5] offset:272
	global_store_dwordx4 v115, v[76:79], s[4:5] offset:288
	global_store_dwordx4 v115, v[80:83], s[4:5] offset:304
	global_store_dwordx4 v115, v[166:169], s[4:5] offset:320
	global_store_dwordx4 v115, v[170:173], s[4:5] offset:336
	global_store_dwordx4 v115, v[174:177], s[4:5] offset:352
	global_store_dwordx4 v115, v[178:181], s[4:5] offset:368
	global_store_dwordx4 v115, v[84:87], s[4:5] offset:384
	global_store_dwordx4 v115, v[88:91], s[4:5] offset:400
	global_store_dwordx4 v115, v[104:107], s[4:5] offset:416
	global_store_dwordx4 v115, v[108:111], s[4:5] offset:432
	global_store_dwordx4 v115, v[182:185], s[4:5] offset:448
	global_store_dwordx4 v115, v[186:189], s[4:5] offset:464
	global_store_dwordx4 v115, v[190:193], s[4:5] offset:480
	global_store_dwordx4 v115, v[194:197], s[4:5] offset:496
	s_branch .Lp15_done

; DEV u16 f2bf(float f) { return (u16)(pack2(f, f) & 0xffffu); }
; DEV float bf2f(u16 h) { return __uint_as_float(((unsigned)h) << 16); }
; DEV float sigmoid_f(float x) { return __builtin_amdgcn_rcpf(1.f + __expf(-x)); }
; DEV void phase_p15(const Params& p, int g) {
;     ...
;           const float f = lb[cc] + (1.f - lb[cc]) * sigmoid_f(bf2f(xr[st][cc][e]));
;           G[cc] += __logf(f);
;           const float eg = __expf(G[cc]), ig = __expf(-G[cc]);
;           Qp[tok * 512 + c] = f2bf(bf2f(qr[st][cc][e]) * eg);
;           const u16 kk = f2bf((1.f - f) * ig);
;           Kp[tok * 512 + c] = kk;
;           kb[e] = kk;
;         }
;         const int s0 = dir ? 56 - 8 * j8 : 8 * j8;
;         uint4 w;
;         w.x = dir ? (kb[7] | (kb[6] << 16)) : (kb[0] | (kb[1] << 16));
;         w.y = dir ? (kb[5] | (kb[4] << 16)) : (kb[2] | (kb[3] << 16));
;         w.z = dir ? (kb[3] | (kb[2] << 16)) : (kb[4] | (kb[5] << 16));
;         w.w = dir ? (kb[1] | (kb[0] << 16)) : (kb[6] | (kb[7] << 16));
;         *(uint4*)(KT + (((size_t)cidx * 2 + dir) * 512 + c) * 64 + s0) = w;
.Lp15_d1_loop:
	s_waitcnt vmcnt(32)
	v_lshlrev_b32_e32 v92, 16, v0
	v_and_b32_e32 v93, 0xffff0000, v0
	v_lshlrev_b32_e32 v94, 16, v1
	v_and_b32_e32 v95, 0xffff0000, v1
	v_mul_f32_e32 v92, 0xbfb8aa3b, v92
	v_mul_f32_e32 v93, 0xbfb8aa3b, v93
	v_mul_f32_e32 v94, 0xbfb8aa3b, v94
	v_mul_f32_e32 v95, 0xbfb8aa3b, v95
	v_exp_f32_e32 v92, v92
	v_exp_f32_e32 v93, v93
	v_exp_f32_e32 v94, v94
	v_exp_f32_e32 v95, v95
	v_add_f32_e32 v92, 1.0, v92
	v_add_f32_e32 v93, 1.0, v93
	v_add_f32_e32 v94, 1.0, v94
	v_add_f32_e32 v95, 1.0, v95
	v_rcp_f32_e32 v92, v92
	v_rcp_f32_e32 v93, v93
	v_rcp_f32_e32 v94, v94
	v_rcp_f32_e32 v95, v95
	v_fma_f32 v96, v72, v92, v68
	v_fma_f32 v97, v73, v93, v69
	v_fma_f32 v98, v74, v94, v70
	v_fma_f32 v99, v75, v95, v71
	v_cmp_gt_f32_e64 s[22:23], s30, v96
	v_cmp_gt_f32_e64 s[24:25], s30, v97
	v_cmp_gt_f32_e64 s[26:27], s30, v98
	v_cmp_gt_f32_e64 s[28:29], s30, v99
	v_cndmask_b32_e64 v92, 0, 32, s[22:23]
	v_cndmask_b32_e64 v93, 0, 32, s[24:25]
	v_cndmask_b32_e64 v94, 0, 32, s[26:27]
	v_cndmask_b32_e64 v95, 0, 32, s[28:29]
	v_ldexp_f32 v92, v96, v92
	v_ldexp_f32 v93, v97, v93
	v_ldexp_f32 v94, v98, v94
	v_ldexp_f32 v95, v99, v95
	v_log_f32_e32 v92, v92
	v_log_f32_e32 v93, v93
	v_log_f32_e32 v94, v94
	v_log_f32_e32 v95, v95
	v_mul_f32_e32 v100, 0x3f317217, v92
	v_mul_f32_e32 v101, 0x3f317217, v93
	v_mul_f32_e32 v102, 0x3f317217, v94
	v_mul_f32_e32 v103, 0x3f317217, v95
	v_fma_f32 v100, v92, s31, -v100
	v_fma_f32 v101, v93, s31, -v101
	v_fma_f32 v102, v94, s31, -v102
	v_fma_f32 v103, v95, s31, -v103
	v_fmac_f32_e32 v100, 0x3377d1cf, v92
	v_fmac_f32_e32 v101, 0x3377d1cf, v93
	v_fmac_f32_e32 v102, 0x3377d1cf, v94
	v_fmac_f32_e32 v103, 0x3377d1cf, v95
	v_fmac_f32_e32 v100, 0x3f317217, v92
	v_fmac_f32_e32 v101, 0x3f317217, v93
	v_fmac_f32_e32 v102, 0x3f317217, v94
	v_fmac_f32_e32 v103, 0x3f317217, v95
	v_cmp_lt_f32_e64 vcc, |v92|, s34
	v_cndmask_b32_e32 v92, v92, v100, vcc
	v_cmp_lt_f32_e64 vcc, |v93|, s34
	v_cndmask_b32_e32 v93, v93, v101, vcc
	v_cmp_lt_f32_e64 vcc, |v94|, s34
	v_cndmask_b32_e32 v94, v94, v102, vcc
	v_cmp_lt_f32_e64 vcc, |v95|, s34
	v_cndmask_b32_e32 v95, v95, v103, vcc
	v_cndmask_b32_e64 v100, 0, v213, s[22:23]
	v_cndmask_b32_e64 v101, 0, v213, s[24:25]
	v_cndmask_b32_e64 v102, 0, v213, s[26:27]
	v_cndmask_b32_e64 v103, 0, v213, s[28:29]
	v_sub_f32_e32 v92, v92, v100
	v_sub_f32_e32 v93, v93, v101
	v_sub_f32_e32 v94, v94, v102
	v_sub_f32_e32 v95, v95, v103
	v_add_f32_e32 v64, v64, v92
	v_add_f32_e32 v65, v65, v93
	v_add_f32_e32 v66, v66, v94
	v_add_f32_e32 v67, v67, v95
	v_mul_f32_e32 v92, 0xbfb8aa3b, v64
	v_mul_f32_e32 v93, 0xbfb8aa3b, v65
	v_mul_f32_e32 v94, 0xbfb8aa3b, v66
	v_mul_f32_e32 v95, 0xbfb8aa3b, v67
	v_mul_f32_e32 v100, 0x3fb8aa3b, v64
	v_mul_f32_e32 v101, 0x3fb8aa3b, v65
	v_mul_f32_e32 v102, 0x3fb8aa3b, v66
	v_mul_f32_e32 v103, 0x3fb8aa3b, v67
	v_exp_f32_e32 v92, v92
	v_exp_f32_e32 v93, v93
	v_exp_f32_e32 v94, v94
	v_exp_f32_e32 v95, v95
	v_exp_f32_e32 v100, v100
	v_exp_f32_e32 v101, v101
	v_exp_f32_e32 v102, v102
	v_exp_f32_e32 v103, v103
	v_sub_f32_e32 v96, 1.0, v96
	v_sub_f32_e32 v97, 1.0, v97
	v_sub_f32_e32 v98, 1.0, v98
	v_sub_f32_e32 v99, 1.0, v99
	v_mul_f32_e32 v96, v96, v92
	v_mul_f32_e32 v97, v97, v93
	v_mul_f32_e32 v98, v98, v94
	v_mul_f32_e32 v99, v99, v95
	v_lshlrev_b32_e32 v92, 16, v2
	v_and_b32_e32 v93, 0xffff0000, v2
	v_lshlrev_b32_e32 v94, 16, v3
	v_and_b32_e32 v95, 0xffff0000, v3
	v_mul_f32_e32 v92, v92, v100
	v_mul_f32_e32 v93, v93, v101
	v_mul_f32_e32 v94, v94, v102
	v_mul_f32_e32 v95, v95, v103
	v_mov_b32_e32 v131, v96
	v_mov_b32_e32 v147, v97
	v_mov_b32_e32 v181, v98
	v_mov_b32_e32 v197, v99
	v_cvt_pk_bf16_f32 v92, v92, v93
	v_cvt_pk_bf16_f32 v93, v94, v95
	v_cvt_pk_bf16_f32 v96, v96, v97
	v_cvt_pk_bf16_f32 v97, v98, v99
	global_store_dwordx2 v112, v[92:93], s[2:3]
	global_store_dwordx2 v114, v[96:97], s[2:3]
	s_sub_u32 s2, s2, 0x400
	s_subb_u32 s3, s3, 0
	v_lshlrev_b32_e32 v92, 16, v4
	v_and_b32_e32 v93, 0xffff0000, v4
	v_lshlrev_b32_e32 v94, 16, v5
	v_and_b32_e32 v95, 0xffff0000, v5
	v_mul_f32_e32 v92, 0xbfb8aa3b, v92
	v_mul_f32_e32 v93, 0xbfb8aa3b, v93
	v_mul_f32_e32 v94, 0xbfb8aa3b, v94
	v_mul_f32_e32 v95, 0xbfb8aa3b, v95
	v_exp_f32_e32 v92, v92
	v_exp_f32_e32 v93, v93
	v_exp_f32_e32 v94, v94
	v_exp_f32_e32 v95, v95
	v_add_f32_e32 v92, 1.0, v92
	v_add_f32_e32 v93, 1.0, v93
	v_add_f32_e32 v94, 1.0, v94
	v_add_f32_e32 v95, 1.0, v95
	v_rcp_f32_e32 v92, v92
	v_rcp_f32_e32 v93, v93
	v_rcp_f32_e32 v94, v94
	v_rcp_f32_e32 v95, v95
	v_fma_f32 v96, v72, v92, v68
	v_fma_f32 v97, v73, v93, v69
	v_fma_f32 v98, v74, v94, v70
	v_fma_f32 v99, v75, v95, v71
	v_cmp_gt_f32_e64 s[22:23], s30, v96
	v_cmp_gt_f32_e64 s[24:25], s30, v97
	v_cmp_gt_f32_e64 s[26:27], s30, v98
	v_cmp_gt_f32_e64 s[28:29], s30, v99
	v_cndmask_b32_e64 v92, 0, 32, s[22:23]
	v_cndmask_b32_e64 v93, 0, 32, s[24:25]
	v_cndmask_b32_e64 v94, 0, 32, s[26:27]
	v_cndmask_b32_e64 v95, 0, 32, s[28:29]
	v_ldexp_f32 v92, v96, v92
	v_ldexp_f32 v93, v97, v93
	v_ldexp_f32 v94, v98, v94
	v_ldexp_f32 v95, v99, v95
	v_log_f32_e32 v92, v92
	v_log_f32_e32 v93, v93
	v_log_f32_e32 v94, v94
	v_log_f32_e32 v95, v95
	v_mul_f32_e32 v100, 0x3f317217, v92
	v_mul_f32_e32 v101, 0x3f317217, v93
	v_mul_f32_e32 v102, 0x3f317217, v94
	v_mul_f32_e32 v103, 0x3f317217, v95
	v_fma_f32 v100, v92, s31, -v100
	v_fma_f32 v101, v93, s31, -v101
	v_fma_f32 v102, v94, s31, -v102
	v_fma_f32 v103, v95, s31, -v103
	v_fmac_f32_e32 v100, 0x3377d1cf, v92
	v_fmac_f32_e32 v101, 0x3377d1cf, v93
	v_fmac_f32_e32 v102, 0x3377d1cf, v94
	v_fmac_f32_e32 v103, 0x3377d1cf, v95
	v_fmac_f32_e32 v100, 0x3f317217, v92
	v_fmac_f32_e32 v101, 0x3f317217, v93
	v_fmac_f32_e32 v102, 0x3f317217, v94
; DEV u16 f2bf(float f) { return (u16)(pack2(f, f) & 0xffffu); }
; DEV float bf2f(u16 h) { return __uint_as_float(((unsigned)h) << 16); }
; DEV float sigmoid_f(float x) { return __builtin_amdgcn_rcpf(1.f + __expf(-x)); }
; DEV void phase_p15(const Params& p, int g) {
;     ...
;           const float f = lb[cc] + (1.f - lb[cc]) * sigmoid_f(bf2f(xr[st][cc][e]));
;           G[cc] += __logf(f);
;           const float eg = __expf(G[cc]), ig = __expf(-G[cc]);
;           Qp[tok * 512 + c] = f2bf(bf2f(qr[st][cc][e]) * eg);
;           const u16 kk = f2bf((1.f - f) * ig);
;           Kp[tok * 512 + c] = kk;
;           kb[e] = kk;
;         }
;         const int s0 = dir ? 56 - 8 * j8 : 8 * j8;
;         uint4 w;
;         w.x = dir ? (kb[7] | (kb[6] << 16)) : (kb[0] | (kb[1] << 16));
;         w.y = dir ? (kb[5] | (kb[4] << 16)) : (kb[2] | (kb[3] << 16));
;         w.z = dir ? (kb[3] | (kb[2] << 16)) : (kb[4] | (kb[5] << 16));
;         w.w = dir ? (kb[1] | (kb[0] << 16)) : (kb[6] | (kb[7] << 16));
;         *(uint4*)(KT + (((size_t)cidx * 2 + dir) * 512 + c) * 64 + s0) = w;
	v_fmac_f32_e32 v103, 0x3f317217, v95
	v_cmp_lt_f32_e64 vcc, |v92|, s34
	v_cndmask_b32_e32 v92, v92, v100, vcc
	v_cmp_lt_f32_e64 vcc, |v93|, s34
	v_cndmask_b32_e32 v93, v93, v101, vcc
	v_cmp_lt_f32_e64 vcc, |v94|, s34
	v_cndmask_b32_e32 v94, v94, v102, vcc
	v_cmp_lt_f32_e64 vcc, |v95|, s34
	v_cndmask_b32_e32 v95, v95, v103, vcc
	v_cndmask_b32_e64 v100, 0, v213, s[22:23]
	v_cndmask_b32_e64 v101, 0, v213, s[24:25]
	v_cndmask_b32_e64 v102, 0, v213, s[26:27]
	v_cndmask_b32_e64 v103, 0, v213, s[28:29]
	v_sub_f32_e32 v92, v92, v100
	v_sub_f32_e32 v93, v93, v101
	v_sub_f32_e32 v94, v94, v102
	v_sub_f32_e32 v95, v95, v103
	v_add_f32_e32 v64, v64, v92
	v_add_f32_e32 v65, v65, v93
	v_add_f32_e32 v66, v66, v94
	v_add_f32_e32 v67, v67, v95
	v_mul_f32_e32 v92, 0xbfb8aa3b, v64
	v_mul_f32_e32 v93, 0xbfb8aa3b, v65
	v_mul_f32_e32 v94, 0xbfb8aa3b, v66
	v_mul_f32_e32 v95, 0xbfb8aa3b, v67
	v_mul_f32_e32 v100, 0x3fb8aa3b, v64
	v_mul_f32_e32 v101, 0x3fb8aa3b, v65
	v_mul_f32_e32 v102, 0x3fb8aa3b, v66
	v_mul_f32_e32 v103, 0x3fb8aa3b, v67
	v_exp_f32_e32 v92, v92
	v_exp_f32_e32 v93, v93
	v_exp_f32_e32 v94, v94
	v_exp_f32_e32 v95, v95
	v_exp_f32_e32 v100, v100
	v_exp_f32_e32 v101, v101
	v_exp_f32_e32 v102, v102
	v_exp_f32_e32 v103, v103
	v_sub_f32_e32 v96, 1.0, v96
	v_sub_f32_e32 v97, 1.0, v97
	v_sub_f32_e32 v98, 1.0, v98
	v_sub_f32_e32 v99, 1.0, v99
	v_mul_f32_e32 v96, v96, v92
	v_mul_f32_e32 v97, v97, v93
	v_mul_f32_e32 v98, v98, v94
	v_mul_f32_e32 v99, v99, v95
	v_lshlrev_b32_e32 v92, 16, v6
	v_and_b32_e32 v93, 0xffff0000, v6
	v_lshlrev_b32_e32 v94, 16, v7
	v_and_b32_e32 v95, 0xffff0000, v7
	v_mul_f32_e32 v92, v92, v100
	v_mul_f32_e32 v93, v93, v101
	v_mul_f32_e32 v94, v94, v102
	v_mul_f32_e32 v95, v95, v103
	v_cvt_pk_bf16_f32 v131, v96, v131
	v_cvt_pk_bf16_f32 v147, v97, v147
	v_cvt_pk_bf16_f32 v181, v98, v181
	v_cvt_pk_bf16_f32 v197, v99, v197
	v_cvt_pk_bf16_f32 v92, v92, v93
	v_cvt_pk_bf16_f32 v93, v94, v95
	v_cvt_pk_bf16_f32 v96, v96, v97
	v_cvt_pk_bf16_f32 v97, v98, v99
	global_store_dwordx2 v112, v[92:93], s[2:3]
	global_store_dwordx2 v114, v[96:97], s[2:3]
	s_sub_u32 s2, s2, 0x400
	s_subb_u32 s3, s3, 0
	v_lshlrev_b32_e32 v92, 16, v8
	v_and_b32_e32 v93, 0xffff0000, v8
	v_lshlrev_b32_e32 v94, 16, v9
	v_and_b32_e32 v95, 0xffff0000, v9
	v_mul_f32_e32 v92, 0xbfb8aa3b, v92
	v_mul_f32_e32 v93, 0xbfb8aa3b, v93
	v_mul_f32_e32 v94, 0xbfb8aa3b, v94
	v_mul_f32_e32 v95, 0xbfb8aa3b, v95
	v_exp_f32_e32 v92, v92
	v_exp_f32_e32 v93, v93
	v_exp_f32_e32 v94, v94
	v_exp_f32_e32 v95, v95
	v_add_f32_e32 v92, 1.0, v92
	v_add_f32_e32 v93, 1.0, v93
	v_add_f32_e32 v94, 1.0, v94
	v_add_f32_e32 v95, 1.0, v95
	v_rcp_f32_e32 v92, v92
	v_rcp_f32_e32 v93, v93
	v_rcp_f32_e32 v94, v94
	v_rcp_f32_e32 v95, v95
	v_fma_f32 v96, v72, v92, v68
	v_fma_f32 v97, v73, v93, v69
	v_fma_f32 v98, v74, v94, v70
	v_fma_f32 v99, v75, v95, v71
	v_cmp_gt_f32_e64 s[22:23], s30, v96
	v_cmp_gt_f32_e64 s[24:25], s30, v97
	v_cmp_gt_f32_e64 s[26:27], s30, v98
	v_cmp_gt_f32_e64 s[28:29], s30, v99
	v_cndmask_b32_e64 v92, 0, 32, s[22:23]
	v_cndmask_b32_e64 v93, 0, 32, s[24:25]
	v_cndmask_b32_e64 v94, 0, 32, s[26:27]
	v_cndmask_b32_e64 v95, 0, 32, s[28:29]
	v_ldexp_f32 v92, v96, v92
	v_ldexp_f32 v93, v97, v93
	v_ldexp_f32 v94, v98, v94
	v_ldexp_f32 v95, v99, v95
	v_log_f32_e32 v92, v92
	v_log_f32_e32 v93, v93
	v_log_f32_e32 v94, v94
	v_log_f32_e32 v95, v95
	v_mul_f32_e32 v100, 0x3f317217, v92
	v_mul_f32_e32 v101, 0x3f317217, v93
	v_mul_f32_e32 v102, 0x3f317217, v94
	v_mul_f32_e32 v103, 0x3f317217, v95
	v_fma_f32 v100, v92, s31, -v100
	v_fma_f32 v101, v93, s31, -v101
	v_fma_f32 v102, v94, s31, -v102
	v_fma_f32 v103, v95, s31, -v103
	v_fmac_f32_e32 v100, 0x3377d1cf, v92
	v_fmac_f32_e32 v101, 0x3377d1cf, v93
	v_fmac_f32_e32 v102, 0x3377d1cf, v94
	v_fmac_f32_e32 v103, 0x3377d1cf, v95
	v_fmac_f32_e32 v100, 0x3f317217, v92
	v_fmac_f32_e32 v101, 0x3f317217, v93
	v_fmac_f32_e32 v102, 0x3f317217, v94
	v_fmac_f32_e32 v103, 0x3f317217, v95
	v_cmp_lt_f32_e64 vcc, |v92|, s34
	v_cndmask_b32_e32 v92, v92, v100, vcc
	v_cmp_lt_f32_e64 vcc, |v93|, s34
	v_cndmask_b32_e32 v93, v93, v101, vcc
	v_cmp_lt_f32_e64 vcc, |v94|, s34
	v_cndmask_b32_e32 v94, v94, v102, vcc
	v_cmp_lt_f32_e64 vcc, |v95|, s34
	v_cndmask_b32_e32 v95, v95, v103, vcc
	v_cndmask_b32_e64 v100, 0, v213, s[22:23]
	v_cndmask_b32_e64 v101, 0, v213, s[24:25]
	v_cndmask_b32_e64 v102, 0, v213, s[26:27]
	v_cndmask_b32_e64 v103, 0, v213, s[28:29]
	v_sub_f32_e32 v92, v92, v100
	v_sub_f32_e32 v93, v93, v101
	v_sub_f32_e32 v94, v94, v102
	v_sub_f32_e32 v95, v95, v103
	v_add_f32_e32 v64, v64, v92
	v_add_f32_e32 v65, v65, v93
	v_add_f32_e32 v66, v66, v94
	v_add_f32_e32 v67, v67, v95
	v_mul_f32_e32 v92, 0xbfb8aa3b, v64
	v_mul_f32_e32 v93, 0xbfb8aa3b, v65
	v_mul_f32_e32 v94, 0xbfb8aa3b, v66
	v_mul_f32_e32 v95, 0xbfb8aa3b, v67
	v_mul_f32_e32 v100, 0x3fb8aa3b, v64
	v_mul_f32_e32 v101, 0x3fb8aa3b, v65
	v_mul_f32_e32 v102, 0x3fb8aa3b, v66
	v_mul_f32_e32 v103, 0x3fb8aa3b, v67
	v_exp_f32_e32 v92, v92
	v_exp_f32_e32 v93, v93
	v_exp_f32_e32 v94, v94
	v_exp_f32_e32 v95, v95
	v_exp_f32_e32 v100, v100
	v_exp_f32_e32 v101, v101
	v_exp_f32_e32 v102, v102
	v_exp_f32_e32 v103, v103
	v_sub_f32_e32 v96, 1.0, v96
	v_sub_f32_e32 v97, 1.0, v97
	v_sub_f32_e32 v98, 1.0, v98
	v_sub_f32_e32 v99, 1.0, v99
	v_mul_f32_e32 v96, v96, v92
	v_mul_f32_e32 v97, v97, v93
	v_mul_f32_e32 v98, v98, v94
	v_mul_f32_e32 v99, v99, v95
	v_lshlrev_b32_e32 v92, 16, v10
	v_and_b32_e32 v93, 0xffff0000, v10
	v_lshlrev_b32_e32 v94, 16, v11
	v_and_b32_e32 v95, 0xffff0000, v11
	v_mul_f32_e32 v92, v92, v100
	v_mul_f32_e32 v93, v93, v101
	v_mul_f32_e32 v94, v94, v102
	v_mul_f32_e32 v95, v95, v103
	v_mov_b32_e32 v130, v96
; DEV u16 f2bf(float f) { return (u16)(pack2(f, f) & 0xffffu); }
; DEV float bf2f(u16 h) { return __uint_as_float(((unsigned)h) << 16); }
; DEV float sigmoid_f(float x) { return __builtin_amdgcn_rcpf(1.f + __expf(-x)); }
; DEV void phase_p15(const Params& p, int g) {
;     ...
;         for (int e = 0; e < 8; ++e) {
;           const int jj = j8 * 8 + e;
;           const int j = dir ? 63 - jj : jj;
;           const size_t tok = (size_t)cidx * 64 + j;
;           const float f = lb[cc] + (1.f - lb[cc]) * sigmoid_f(bf2f(xr[st][cc][e]));
;           G[cc] += __logf(f);
;           const float eg = __expf(G[cc]), ig = __expf(-G[cc]);
;           Qp[tok * 512 + c] = f2bf(bf2f(qr[st][cc][e]) * eg);
;           const u16 kk = f2bf((1.f - f) * ig);
;           Kp[tok * 512 + c] = kk;
;           kb[e] = kk;
;         }
;         const int s0 = dir ? 56 - 8 * j8 : 8 * j8;
;         uint4 w;
;         w.x = dir ? (kb[7] | (kb[6] << 16)) : (kb[0] | (kb[1] << 16));
;         w.y = dir ? (kb[5] | (kb[4] << 16)) : (kb[2] | (kb[3] << 16));
;         w.z = dir ? (kb[3] | (kb[2] << 16)) : (kb[4] | (kb[5] << 16));
;         w.w = dir ? (kb[1] | (kb[0] << 16)) : (kb[6] | (kb[7] << 16));
;         *(uint4*)(KT + (((size_t)cidx * 2 + dir) * 512 + c) * 64 + s0) = w;
	v_mov_b32_e32 v146, v97
	v_mov_b32_e32 v180, v98
	v_mov_b32_e32 v196, v99
	v_cvt_pk_bf16_f32 v92, v92, v93
	v_cvt_pk_bf16_f32 v93, v94, v95
	v_cvt_pk_bf16_f32 v96, v96, v97
	v_cvt_pk_bf16_f32 v97, v98, v99
	global_store_dwordx2 v112, v[92:93], s[2:3]
	global_store_dwordx2 v114, v[96:97], s[2:3]
	s_sub_u32 s2, s2, 0x400
	s_subb_u32 s3, s3, 0
	v_lshlrev_b32_e32 v92, 16, v12
	v_and_b32_e32 v93, 0xffff0000, v12
	v_lshlrev_b32_e32 v94, 16, v13
	v_and_b32_e32 v95, 0xffff0000, v13
	v_mul_f32_e32 v92, 0xbfb8aa3b, v92
	v_mul_f32_e32 v93, 0xbfb8aa3b, v93
	v_mul_f32_e32 v94, 0xbfb8aa3b, v94
	v_mul_f32_e32 v95, 0xbfb8aa3b, v95
	v_exp_f32_e32 v92, v92
	v_exp_f32_e32 v93, v93
	v_exp_f32_e32 v94, v94
	v_exp_f32_e32 v95, v95
	v_add_f32_e32 v92, 1.0, v92
	v_add_f32_e32 v93, 1.0, v93
	v_add_f32_e32 v94, 1.0, v94
	v_add_f32_e32 v95, 1.0, v95
	v_rcp_f32_e32 v92, v92
	v_rcp_f32_e32 v93, v93
	v_rcp_f32_e32 v94, v94
	v_rcp_f32_e32 v95, v95
	v_fma_f32 v96, v72, v92, v68
	v_fma_f32 v97, v73, v93, v69
	v_fma_f32 v98, v74, v94, v70
	v_fma_f32 v99, v75, v95, v71
	v_cmp_gt_f32_e64 s[22:23], s30, v96
	v_cmp_gt_f32_e64 s[24:25], s30, v97
	v_cmp_gt_f32_e64 s[26:27], s30, v98
	v_cmp_gt_f32_e64 s[28:29], s30, v99
	v_cndmask_b32_e64 v92, 0, 32, s[22:23]
	v_cndmask_b32_e64 v93, 0, 32, s[24:25]
	v_cndmask_b32_e64 v94, 0, 32, s[26:27]
	v_cndmask_b32_e64 v95, 0, 32, s[28:29]
	v_ldexp_f32 v92, v96, v92
	v_ldexp_f32 v93, v97, v93
	v_ldexp_f32 v94, v98, v94
	v_ldexp_f32 v95, v99, v95
	v_log_f32_e32 v92, v92
	v_log_f32_e32 v93, v93
	v_log_f32_e32 v94, v94
	v_log_f32_e32 v95, v95
	v_mul_f32_e32 v100, 0x3f317217, v92
	v_mul_f32_e32 v101, 0x3f317217, v93
	v_mul_f32_e32 v102, 0x3f317217, v94
	v_mul_f32_e32 v103, 0x3f317217, v95
	v_fma_f32 v100, v92, s31, -v100
	v_fma_f32 v101, v93, s31, -v101
	v_fma_f32 v102, v94, s31, -v102
	v_fma_f32 v103, v95, s31, -v103
	v_fmac_f32_e32 v100, 0x3377d1cf, v92
	v_fmac_f32_e32 v101, 0x3377d1cf, v93
	v_fmac_f32_e32 v102, 0x3377d1cf, v94
	v_fmac_f32_e32 v103, 0x3377d1cf, v95
	v_fmac_f32_e32 v100, 0x3f317217, v92
	v_fmac_f32_e32 v101, 0x3f317217, v93
	v_fmac_f32_e32 v102, 0x3f317217, v94
	v_fmac_f32_e32 v103, 0x3f317217, v95
	v_cmp_lt_f32_e64 vcc, |v92|, s34
	v_cndmask_b32_e32 v92, v92, v100, vcc
	v_cmp_lt_f32_e64 vcc, |v93|, s34
	v_cndmask_b32_e32 v93, v93, v101, vcc
	v_cmp_lt_f32_e64 vcc, |v94|, s34
	v_cndmask_b32_e32 v94, v94, v102, vcc
	v_cmp_lt_f32_e64 vcc, |v95|, s34
	v_cndmask_b32_e32 v95, v95, v103, vcc
	v_cndmask_b32_e64 v100, 0, v213, s[22:23]
	v_cndmask_b32_e64 v101, 0, v213, s[24:25]
	v_cndmask_b32_e64 v102, 0, v213, s[26:27]
	v_cndmask_b32_e64 v103, 0, v213, s[28:29]
	v_sub_f32_e32 v92, v92, v100
	v_sub_f32_e32 v93, v93, v101
	v_sub_f32_e32 v94, v94, v102
	v_sub_f32_e32 v95, v95, v103
	v_add_f32_e32 v64, v64, v92
	v_add_f32_e32 v65, v65, v93
	v_add_f32_e32 v66, v66, v94
	v_add_f32_e32 v67, v67, v95
	v_mul_f32_e32 v92, 0xbfb8aa3b, v64
	v_mul_f32_e32 v93, 0xbfb8aa3b, v65
	v_mul_f32_e32 v94, 0xbfb8aa3b, v66
	v_mul_f32_e32 v95, 0xbfb8aa3b, v67
	v_mul_f32_e32 v100, 0x3fb8aa3b, v64
	v_mul_f32_e32 v101, 0x3fb8aa3b, v65
	v_mul_f32_e32 v102, 0x3fb8aa3b, v66
	v_mul_f32_e32 v103, 0x3fb8aa3b, v67
	v_exp_f32_e32 v92, v92
	v_exp_f32_e32 v93, v93
	v_exp_f32_e32 v94, v94
	v_exp_f32_e32 v95, v95
	v_exp_f32_e32 v100, v100
	v_exp_f32_e32 v101, v101
	v_exp_f32_e32 v102, v102
	v_exp_f32_e32 v103, v103
	v_sub_f32_e32 v96, 1.0, v96
	v_sub_f32_e32 v97, 1.0, v97
	v_sub_f32_e32 v98, 1.0, v98
	v_sub_f32_e32 v99, 1.0, v99
	v_mul_f32_e32 v96, v96, v92
	v_mul_f32_e32 v97, v97, v93
	v_mul_f32_e32 v98, v98, v94
	v_mul_f32_e32 v99, v99, v95
	v_lshlrev_b32_e32 v92, 16, v14
	v_and_b32_e32 v93, 0xffff0000, v14
	v_lshlrev_b32_e32 v94, 16, v15
	v_and_b32_e32 v95, 0xffff0000, v15
	v_mul_f32_e32 v92, v92, v100
	v_mul_f32_e32 v93, v93, v101
	v_mul_f32_e32 v94, v94, v102
	v_mul_f32_e32 v95, v95, v103
	v_cvt_pk_bf16_f32 v130, v96, v130
	v_cvt_pk_bf16_f32 v146, v97, v146
	v_cvt_pk_bf16_f32 v180, v98, v180
	v_cvt_pk_bf16_f32 v196, v99, v196
	v_cvt_pk_bf16_f32 v92, v92, v93
	v_cvt_pk_bf16_f32 v93, v94, v95
	v_cvt_pk_bf16_f32 v96, v96, v97
	v_cvt_pk_bf16_f32 v97, v98, v99
	global_store_dwordx2 v112, v[92:93], s[2:3]
	global_store_dwordx2 v114, v[96:97], s[2:3]
	s_sub_u32 s2, s2, 0x400
	s_subb_u32 s3, s3, 0
	v_lshlrev_b32_e32 v92, 16, v16
	v_and_b32_e32 v93, 0xffff0000, v16
	v_lshlrev_b32_e32 v94, 16, v17
	v_and_b32_e32 v95, 0xffff0000, v17
	v_mul_f32_e32 v92, 0xbfb8aa3b, v92
	v_mul_f32_e32 v93, 0xbfb8aa3b, v93
	v_mul_f32_e32 v94, 0xbfb8aa3b, v94
	v_mul_f32_e32 v95, 0xbfb8aa3b, v95
	v_exp_f32_e32 v92, v92
	v_exp_f32_e32 v93, v93
	v_exp_f32_e32 v94, v94
	v_exp_f32_e32 v95, v95
	v_add_f32_e32 v92, 1.0, v92
	v_add_f32_e32 v93, 1.0, v93
	v_add_f32_e32 v94, 1.0, v94
	v_add_f32_e32 v95, 1.0, v95
	v_rcp_f32_e32 v92, v92
	v_rcp_f32_e32 v93, v93
	v_rcp_f32_e32 v94, v94
	v_rcp_f32_e32 v95, v95
	v_fma_f32 v96, v72, v92, v68
	v_fma_f32 v97, v73, v93, v69
	v_fma_f32 v98, v74, v94, v70
	v_fma_f32 v99, v75, v95, v71
	v_cmp_gt_f32_e64 s[22:23], s30, v96
	v_cmp_gt_f32_e64 s[24:25], s30, v97
	v_cmp_gt_f32_e64 s[26:27], s30, v98
	v_cmp_gt_f32_e64 s[28:29], s30, v99
	v_cndmask_b32_e64 v92, 0, 32, s[22:23]
	v_cndmask_b32_e64 v93, 0, 32, s[24:25]
	v_cndmask_b32_e64 v94, 0, 32, s[26:27]
	v_cndmask_b32_e64 v95, 0, 32, s[28:29]
	v_ldexp_f32 v92, v96, v92
	v_ldexp_f32 v93, v97, v93
	v_ldexp_f32 v94, v98, v94
	v_ldexp_f32 v95, v99, v95
	v_log_f32_e32 v92, v92
	v_log_f32_e32 v93, v93
	v_log_f32_e32 v94, v94
	v_log_f32_e32 v95, v95
	v_mul_f32_e32 v100, 0x3f317217, v92
	v_mul_f32_e32 v101, 0x3f317217, v93
	v_mul_f32_e32 v102, 0x3f317217, v94
	v_mul_f32_e32 v103, 0x3f317217, v95
	v_fma_f32 v100, v92, s31, -v100
; DEV u16 f2bf(float f) { return (u16)(pack2(f, f) & 0xffffu); }
; DEV float bf2f(u16 h) { return __uint_as_float(((unsigned)h) << 16); }
; DEV float sigmoid_f(float x) { return __builtin_amdgcn_rcpf(1.f + __expf(-x)); }
; DEV void phase_p15(const Params& p, int g) {
;     ...
;         for (int e = 0; e < 8; ++e) {
;           const int jj = j8 * 8 + e;
;           const int j = dir ? 63 - jj : jj;
;           const size_t tok = (size_t)cidx * 64 + j;
;           const float f = lb[cc] + (1.f - lb[cc]) * sigmoid_f(bf2f(xr[st][cc][e]));
;           G[cc] += __logf(f);
;           const float eg = __expf(G[cc]), ig = __expf(-G[cc]);
;           Qp[tok * 512 + c] = f2bf(bf2f(qr[st][cc][e]) * eg);
;           const u16 kk = f2bf((1.f - f) * ig);
;           Kp[tok * 512 + c] = kk;
;           kb[e] = kk;
;         }
;         const int s0 = dir ? 56 - 8 * j8 : 8 * j8;
;         uint4 w;
;         w.x = dir ? (kb[7] | (kb[6] << 16)) : (kb[0] | (kb[1] << 16));
;         w.y = dir ? (kb[5] | (kb[4] << 16)) : (kb[2] | (kb[3] << 16));
;         w.z = dir ? (kb[3] | (kb[2] << 16)) : (kb[4] | (kb[5] << 16));
;         w.w = dir ? (kb[1] | (kb[0] << 16)) : (kb[6] | (kb[7] << 16));
;         *(uint4*)(KT + (((size_t)cidx * 2 + dir) * 512 + c) * 64 + s0) = w;
	v_fma_f32 v101, v93, s31, -v101
	v_fma_f32 v102, v94, s31, -v102
	v_fma_f32 v103, v95, s31, -v103
	v_fmac_f32_e32 v100, 0x3377d1cf, v92
	v_fmac_f32_e32 v101, 0x3377d1cf, v93
	v_fmac_f32_e32 v102, 0x3377d1cf, v94
	v_fmac_f32_e32 v103, 0x3377d1cf, v95
	v_fmac_f32_e32 v100, 0x3f317217, v92
	v_fmac_f32_e32 v101, 0x3f317217, v93
	v_fmac_f32_e32 v102, 0x3f317217, v94
	v_fmac_f32_e32 v103, 0x3f317217, v95
	v_cmp_lt_f32_e64 vcc, |v92|, s34
	v_cndmask_b32_e32 v92, v92, v100, vcc
	v_cmp_lt_f32_e64 vcc, |v93|, s34
	v_cndmask_b32_e32 v93, v93, v101, vcc
	v_cmp_lt_f32_e64 vcc, |v94|, s34
	v_cndmask_b32_e32 v94, v94, v102, vcc
	v_cmp_lt_f32_e64 vcc, |v95|, s34
	v_cndmask_b32_e32 v95, v95, v103, vcc
	v_cndmask_b32_e64 v100, 0, v213, s[22:23]
	v_cndmask_b32_e64 v101, 0, v213, s[24:25]
	v_cndmask_b32_e64 v102, 0, v213, s[26:27]
	v_cndmask_b32_e64 v103, 0, v213, s[28:29]
	v_sub_f32_e32 v92, v92, v100
	v_sub_f32_e32 v93, v93, v101
	v_sub_f32_e32 v94, v94, v102
	v_sub_f32_e32 v95, v95, v103
	v_add_f32_e32 v64, v64, v92
	v_add_f32_e32 v65, v65, v93
	v_add_f32_e32 v66, v66, v94
	v_add_f32_e32 v67, v67, v95
	v_mul_f32_e32 v92, 0xbfb8aa3b, v64
	v_mul_f32_e32 v93, 0xbfb8aa3b, v65
	v_mul_f32_e32 v94, 0xbfb8aa3b, v66
	v_mul_f32_e32 v95, 0xbfb8aa3b, v67
	v_mul_f32_e32 v100, 0x3fb8aa3b, v64
	v_mul_f32_e32 v101, 0x3fb8aa3b, v65
	v_mul_f32_e32 v102, 0x3fb8aa3b, v66
	v_mul_f32_e32 v103, 0x3fb8aa3b, v67
	v_exp_f32_e32 v92, v92
	v_exp_f32_e32 v93, v93
	v_exp_f32_e32 v94, v94
	v_exp_f32_e32 v95, v95
	v_exp_f32_e32 v100, v100
	v_exp_f32_e32 v101, v101
	v_exp_f32_e32 v102, v102
	v_exp_f32_e32 v103, v103
	v_sub_f32_e32 v96, 1.0, v96
	v_sub_f32_e32 v97, 1.0, v97
	v_sub_f32_e32 v98, 1.0, v98
	v_sub_f32_e32 v99, 1.0, v99
	v_mul_f32_e32 v96, v96, v92
	v_mul_f32_e32 v97, v97, v93
	v_mul_f32_e32 v98, v98, v94
	v_mul_f32_e32 v99, v99, v95
	v_lshlrev_b32_e32 v92, 16, v18
	v_and_b32_e32 v93, 0xffff0000, v18
	v_lshlrev_b32_e32 v94, 16, v19
	v_and_b32_e32 v95, 0xffff0000, v19
	v_mul_f32_e32 v92, v92, v100
	v_mul_f32_e32 v93, v93, v101
	v_mul_f32_e32 v94, v94, v102
	v_mul_f32_e32 v95, v95, v103
	v_mov_b32_e32 v129, v96
	v_mov_b32_e32 v145, v97
	v_mov_b32_e32 v179, v98
	v_mov_b32_e32 v195, v99
	v_cvt_pk_bf16_f32 v92, v92, v93
	v_cvt_pk_bf16_f32 v93, v94, v95
	v_cvt_pk_bf16_f32 v96, v96, v97
	v_cvt_pk_bf16_f32 v97, v98, v99
	global_store_dwordx2 v112, v[92:93], s[2:3]
	global_store_dwordx2 v114, v[96:97], s[2:3]
	s_sub_u32 s2, s2, 0x400
	s_subb_u32 s3, s3, 0
	v_lshlrev_b32_e32 v92, 16, v20
	v_and_b32_e32 v93, 0xffff0000, v20
	v_lshlrev_b32_e32 v94, 16, v21
	v_and_b32_e32 v95, 0xffff0000, v21
	v_mul_f32_e32 v92, 0xbfb8aa3b, v92
	v_mul_f32_e32 v93, 0xbfb8aa3b, v93
	v_mul_f32_e32 v94, 0xbfb8aa3b, v94
	v_mul_f32_e32 v95, 0xbfb8aa3b, v95
	v_exp_f32_e32 v92, v92
	v_exp_f32_e32 v93, v93
	v_exp_f32_e32 v94, v94
	v_exp_f32_e32 v95, v95
	v_add_f32_e32 v92, 1.0, v92
	v_add_f32_e32 v93, 1.0, v93
	v_add_f32_e32 v94, 1.0, v94
	v_add_f32_e32 v95, 1.0, v95
	v_rcp_f32_e32 v92, v92
	v_rcp_f32_e32 v93, v93
	v_rcp_f32_e32 v94, v94
	v_rcp_f32_e32 v95, v95
	v_fma_f32 v96, v72, v92, v68
	v_fma_f32 v97, v73, v93, v69
	v_fma_f32 v98, v74, v94, v70
	v_fma_f32 v99, v75, v95, v71
	v_cmp_gt_f32_e64 s[22:23], s30, v96
	v_cmp_gt_f32_e64 s[24:25], s30, v97
	v_cmp_gt_f32_e64 s[26:27], s30, v98
	v_cmp_gt_f32_e64 s[28:29], s30, v99
	v_cndmask_b32_e64 v92, 0, 32, s[22:23]
	v_cndmask_b32_e64 v93, 0, 32, s[24:25]
	v_cndmask_b32_e64 v94, 0, 32, s[26:27]
	v_cndmask_b32_e64 v95, 0, 32, s[28:29]
	v_ldexp_f32 v92, v96, v92
	v_ldexp_f32 v93, v97, v93
	v_ldexp_f32 v94, v98, v94
	v_ldexp_f32 v95, v99, v95
	v_log_f32_e32 v92, v92
	v_log_f32_e32 v93, v93
	v_log_f32_e32 v94, v94
	v_log_f32_e32 v95, v95
	v_mul_f32_e32 v100, 0x3f317217, v92
	v_mul_f32_e32 v101, 0x3f317217, v93
	v_mul_f32_e32 v102, 0x3f317217, v94
	v_mul_f32_e32 v103, 0x3f317217, v95
	v_fma_f32 v100, v92, s31, -v100
	v_fma_f32 v101, v93, s31, -v101
	v_fma_f32 v102, v94, s31, -v102
	v_fma_f32 v103, v95, s31, -v103
	v_fmac_f32_e32 v100, 0x3377d1cf, v92
	v_fmac_f32_e32 v101, 0x3377d1cf, v93
	v_fmac_f32_e32 v102, 0x3377d1cf, v94
	v_fmac_f32_e32 v103, 0x3377d1cf, v95
	v_fmac_f32_e32 v100, 0x3f317217, v92
	v_fmac_f32_e32 v101, 0x3f317217, v93
	v_fmac_f32_e32 v102, 0x3f317217, v94
	v_fmac_f32_e32 v103, 0x3f317217, v95
	v_cmp_lt_f32_e64 vcc, |v92|, s34
	v_cndmask_b32_e32 v92, v92, v100, vcc
	v_cmp_lt_f32_e64 vcc, |v93|, s34
	v_cndmask_b32_e32 v93, v93, v101, vcc
	v_cmp_lt_f32_e64 vcc, |v94|, s34
	v_cndmask_b32_e32 v94, v94, v102, vcc
	v_cmp_lt_f32_e64 vcc, |v95|, s34
	v_cndmask_b32_e32 v95, v95, v103, vcc
	v_cndmask_b32_e64 v100, 0, v213, s[22:23]
	v_cndmask_b32_e64 v101, 0, v213, s[24:25]
	v_cndmask_b32_e64 v102, 0, v213, s[26:27]
	v_cndmask_b32_e64 v103, 0, v213, s[28:29]
	v_sub_f32_e32 v92, v92, v100
	v_sub_f32_e32 v93, v93, v101
	v_sub_f32_e32 v94, v94, v102
	v_sub_f32_e32 v95, v95, v103
	v_add_f32_e32 v64, v64, v92
	v_add_f32_e32 v65, v65, v93
	v_add_f32_e32 v66, v66, v94
	v_add_f32_e32 v67, v67, v95
	v_mul_f32_e32 v92, 0xbfb8aa3b, v64
	v_mul_f32_e32 v93, 0xbfb8aa3b, v65
	v_mul_f32_e32 v94, 0xbfb8aa3b, v66
	v_mul_f32_e32 v95, 0xbfb8aa3b, v67
	v_mul_f32_e32 v100, 0x3fb8aa3b, v64
	v_mul_f32_e32 v101, 0x3fb8aa3b, v65
	v_mul_f32_e32 v102, 0x3fb8aa3b, v66
	v_mul_f32_e32 v103, 0x3fb8aa3b, v67
	v_exp_f32_e32 v92, v92
	v_exp_f32_e32 v93, v93
	v_exp_f32_e32 v94, v94
	v_exp_f32_e32 v95, v95
	v_exp_f32_e32 v100, v100
	v_exp_f32_e32 v101, v101
	v_exp_f32_e32 v102, v102
	v_exp_f32_e32 v103, v103
	v_sub_f32_e32 v96, 1.0, v96
	v_sub_f32_e32 v97, 1.0, v97
	v_sub_f32_e32 v98, 1.0, v98
	v_sub_f32_e32 v99, 1.0, v99
	v_mul_f32_e32 v96, v96, v92
	v_mul_f32_e32 v97, v97, v93
	v_mul_f32_e32 v98, v98, v94
; DEV u16 f2bf(float f) { return (u16)(pack2(f, f) & 0xffffu); }
; DEV float bf2f(u16 h) { return __uint_as_float(((unsigned)h) << 16); }
; DEV float sigmoid_f(float x) { return __builtin_amdgcn_rcpf(1.f + __expf(-x)); }
; DEV void phase_p15(const Params& p, int g) {
;     ...
;         for (int e = 0; e < 8; ++e) {
;           const int jj = j8 * 8 + e;
;           const int j = dir ? 63 - jj : jj;
;           const size_t tok = (size_t)cidx * 64 + j;
;           const float f = lb[cc] + (1.f - lb[cc]) * sigmoid_f(bf2f(xr[st][cc][e]));
;           G[cc] += __logf(f);
;           const float eg = __expf(G[cc]), ig = __expf(-G[cc]);
;           Qp[tok * 512 + c] = f2bf(bf2f(qr[st][cc][e]) * eg);
;           const u16 kk = f2bf((1.f - f) * ig);
;           Kp[tok * 512 + c] = kk;
;           kb[e] = kk;
;         }
;         const int s0 = dir ? 56 - 8 * j8 : 8 * j8;
;         uint4 w;
;         w.x = dir ? (kb[7] | (kb[6] << 16)) : (kb[0] | (kb[1] << 16));
;         w.y = dir ? (kb[5] | (kb[4] << 16)) : (kb[2] | (kb[3] << 16));
;         w.z = dir ? (kb[3] | (kb[2] << 16)) : (kb[4] | (kb[5] << 16));
;         w.w = dir ? (kb[1] | (kb[0] << 16)) : (kb[6] | (kb[7] << 16));
;         *(uint4*)(KT + (((size_t)cidx * 2 + dir) * 512 + c) * 64 + s0) = w;
	v_mul_f32_e32 v99, v99, v95
	v_lshlrev_b32_e32 v92, 16, v22
	v_and_b32_e32 v93, 0xffff0000, v22
	v_lshlrev_b32_e32 v94, 16, v23
	v_and_b32_e32 v95, 0xffff0000, v23
	v_mul_f32_e32 v92, v92, v100
	v_mul_f32_e32 v93, v93, v101
	v_mul_f32_e32 v94, v94, v102
	v_mul_f32_e32 v95, v95, v103
	v_cvt_pk_bf16_f32 v129, v96, v129
	v_cvt_pk_bf16_f32 v145, v97, v145
	v_cvt_pk_bf16_f32 v179, v98, v179
	v_cvt_pk_bf16_f32 v195, v99, v195
	v_cvt_pk_bf16_f32 v92, v92, v93
	v_cvt_pk_bf16_f32 v93, v94, v95
	v_cvt_pk_bf16_f32 v96, v96, v97
	v_cvt_pk_bf16_f32 v97, v98, v99
	global_store_dwordx2 v112, v[92:93], s[2:3]
	global_store_dwordx2 v114, v[96:97], s[2:3]
	s_sub_u32 s2, s2, 0x400
	s_subb_u32 s3, s3, 0
	v_lshlrev_b32_e32 v92, 16, v24
	v_and_b32_e32 v93, 0xffff0000, v24
	v_lshlrev_b32_e32 v94, 16, v25
	v_and_b32_e32 v95, 0xffff0000, v25
	v_mul_f32_e32 v92, 0xbfb8aa3b, v92
	v_mul_f32_e32 v93, 0xbfb8aa3b, v93
	v_mul_f32_e32 v94, 0xbfb8aa3b, v94
	v_mul_f32_e32 v95, 0xbfb8aa3b, v95
	v_exp_f32_e32 v92, v92
	v_exp_f32_e32 v93, v93
	v_exp_f32_e32 v94, v94
	v_exp_f32_e32 v95, v95
	v_add_f32_e32 v92, 1.0, v92
	v_add_f32_e32 v93, 1.0, v93
	v_add_f32_e32 v94, 1.0, v94
	v_add_f32_e32 v95, 1.0, v95
	v_rcp_f32_e32 v92, v92
	v_rcp_f32_e32 v93, v93
	v_rcp_f32_e32 v94, v94
	v_rcp_f32_e32 v95, v95
	v_fma_f32 v96, v72, v92, v68
	v_fma_f32 v97, v73, v93, v69
	v_fma_f32 v98, v74, v94, v70
	v_fma_f32 v99, v75, v95, v71
	v_cmp_gt_f32_e64 s[22:23], s30, v96
	v_cmp_gt_f32_e64 s[24:25], s30, v97
	v_cmp_gt_f32_e64 s[26:27], s30, v98
	v_cmp_gt_f32_e64 s[28:29], s30, v99
	v_cndmask_b32_e64 v92, 0, 32, s[22:23]
	v_cndmask_b32_e64 v93, 0, 32, s[24:25]
	v_cndmask_b32_e64 v94, 0, 32, s[26:27]
	v_cndmask_b32_e64 v95, 0, 32, s[28:29]
	v_ldexp_f32 v92, v96, v92
	v_ldexp_f32 v93, v97, v93
	v_ldexp_f32 v94, v98, v94
	v_ldexp_f32 v95, v99, v95
	v_log_f32_e32 v92, v92
	v_log_f32_e32 v93, v93
	v_log_f32_e32 v94, v94
	v_log_f32_e32 v95, v95
	v_mul_f32_e32 v100, 0x3f317217, v92
	v_mul_f32_e32 v101, 0x3f317217, v93
	v_mul_f32_e32 v102, 0x3f317217, v94
	v_mul_f32_e32 v103, 0x3f317217, v95
	v_fma_f32 v100, v92, s31, -v100
	v_fma_f32 v101, v93, s31, -v101
	v_fma_f32 v102, v94, s31, -v102
	v_fma_f32 v103, v95, s31, -v103
	v_fmac_f32_e32 v100, 0x3377d1cf, v92
	v_fmac_f32_e32 v101, 0x3377d1cf, v93
	v_fmac_f32_e32 v102, 0x3377d1cf, v94
	v_fmac_f32_e32 v103, 0x3377d1cf, v95
	v_fmac_f32_e32 v100, 0x3f317217, v92
	v_fmac_f32_e32 v101, 0x3f317217, v93
	v_fmac_f32_e32 v102, 0x3f317217, v94
	v_fmac_f32_e32 v103, 0x3f317217, v95
	v_cmp_lt_f32_e64 vcc, |v92|, s34
	v_cndmask_b32_e32 v92, v92, v100, vcc
	v_cmp_lt_f32_e64 vcc, |v93|, s34
	v_cndmask_b32_e32 v93, v93, v101, vcc
	v_cmp_lt_f32_e64 vcc, |v94|, s34
	v_cndmask_b32_e32 v94, v94, v102, vcc
	v_cmp_lt_f32_e64 vcc, |v95|, s34
	v_cndmask_b32_e32 v95, v95, v103, vcc
	v_cndmask_b32_e64 v100, 0, v213, s[22:23]
	v_cndmask_b32_e64 v101, 0, v213, s[24:25]
	v_cndmask_b32_e64 v102, 0, v213, s[26:27]
	v_cndmask_b32_e64 v103, 0, v213, s[28:29]
	v_sub_f32_e32 v92, v92, v100
	v_sub_f32_e32 v93, v93, v101
	v_sub_f32_e32 v94, v94, v102
	v_sub_f32_e32 v95, v95, v103
	v_add_f32_e32 v64, v64, v92
	v_add_f32_e32 v65, v65, v93
	v_add_f32_e32 v66, v66, v94
	v_add_f32_e32 v67, v67, v95
	v_mul_f32_e32 v92, 0xbfb8aa3b, v64
	v_mul_f32_e32 v93, 0xbfb8aa3b, v65
	v_mul_f32_e32 v94, 0xbfb8aa3b, v66
	v_mul_f32_e32 v95, 0xbfb8aa3b, v67
	v_mul_f32_e32 v100, 0x3fb8aa3b, v64
	v_mul_f32_e32 v101, 0x3fb8aa3b, v65
	v_mul_f32_e32 v102, 0x3fb8aa3b, v66
	v_mul_f32_e32 v103, 0x3fb8aa3b, v67
	v_exp_f32_e32 v92, v92
	v_exp_f32_e32 v93, v93
	v_exp_f32_e32 v94, v94
	v_exp_f32_e32 v95, v95
	v_exp_f32_e32 v100, v100
	v_exp_f32_e32 v101, v101
	v_exp_f32_e32 v102, v102
	v_exp_f32_e32 v103, v103
	v_sub_f32_e32 v96, 1.0, v96
	v_sub_f32_e32 v97, 1.0, v97
	v_sub_f32_e32 v98, 1.0, v98
	v_sub_f32_e32 v99, 1.0, v99
	v_mul_f32_e32 v96, v96, v92
	v_mul_f32_e32 v97, v97, v93
	v_mul_f32_e32 v98, v98, v94
	v_mul_f32_e32 v99, v99, v95
	v_lshlrev_b32_e32 v92, 16, v26
	v_and_b32_e32 v93, 0xffff0000, v26
	v_lshlrev_b32_e32 v94, 16, v27
	v_and_b32_e32 v95, 0xffff0000, v27
	v_mul_f32_e32 v92, v92, v100
	v_mul_f32_e32 v93, v93, v101
	v_mul_f32_e32 v94, v94, v102
	v_mul_f32_e32 v95, v95, v103
	v_mov_b32_e32 v128, v96
	v_mov_b32_e32 v144, v97
	v_mov_b32_e32 v178, v98
	v_mov_b32_e32 v194, v99
	v_cvt_pk_bf16_f32 v92, v92, v93
	v_cvt_pk_bf16_f32 v93, v94, v95
	v_cvt_pk_bf16_f32 v96, v96, v97
	v_cvt_pk_bf16_f32 v97, v98, v99
	global_store_dwordx2 v112, v[92:93], s[2:3]
	global_store_dwordx2 v114, v[96:97], s[2:3]
	s_sub_u32 s2, s2, 0x400
	s_subb_u32 s3, s3, 0
	v_lshlrev_b32_e32 v92, 16, v28
	v_and_b32_e32 v93, 0xffff0000, v28
	v_lshlrev_b32_e32 v94, 16, v29
	v_and_b32_e32 v95, 0xffff0000, v29
	v_mul_f32_e32 v92, 0xbfb8aa3b, v92
	v_mul_f32_e32 v93, 0xbfb8aa3b, v93
	v_mul_f32_e32 v94, 0xbfb8aa3b, v94
	v_mul_f32_e32 v95, 0xbfb8aa3b, v95
	v_exp_f32_e32 v92, v92
	v_exp_f32_e32 v93, v93
	v_exp_f32_e32 v94, v94
	v_exp_f32_e32 v95, v95
	v_add_f32_e32 v92, 1.0, v92
	v_add_f32_e32 v93, 1.0, v93
	v_add_f32_e32 v94, 1.0, v94
	v_add_f32_e32 v95, 1.0, v95
	v_rcp_f32_e32 v92, v92
	v_rcp_f32_e32 v93, v93
	v_rcp_f32_e32 v94, v94
	v_rcp_f32_e32 v95, v95
	v_fma_f32 v96, v72, v92, v68
	v_fma_f32 v97, v73, v93, v69
	v_fma_f32 v98, v74, v94, v70
	v_fma_f32 v99, v75, v95, v71
	v_cmp_gt_f32_e64 s[22:23], s30, v96
	v_cmp_gt_f32_e64 s[24:25], s30, v97
	v_cmp_gt_f32_e64 s[26:27], s30, v98
	v_cmp_gt_f32_e64 s[28:29], s30, v99
	v_cndmask_b32_e64 v92, 0, 32, s[22:23]
	v_cndmask_b32_e64 v93, 0, 32, s[24:25]
	v_cndmask_b32_e64 v94, 0, 32, s[26:27]
	v_cndmask_b32_e64 v95, 0, 32, s[28:29]
	v_ldexp_f32 v92, v96, v92
	v_ldexp_f32 v93, v97, v93
	v_ldexp_f32 v94, v98, v94
; DEV u16 f2bf(float f) { return (u16)(pack2(f, f) & 0xffffu); }
; DEV float bf2f(u16 h) { return __uint_as_float(((unsigned)h) << 16); }
; DEV float sigmoid_f(float x) { return __builtin_amdgcn_rcpf(1.f + __expf(-x)); }
; DEV void phase_p15(const Params& p, int g) {
;     ...
;         for (int e = 0; e < 8; ++e) {
;           const int jj = j8 * 8 + e;
;           const int j = dir ? 63 - jj : jj;
;           const size_t tok = (size_t)cidx * 64 + j;
;           const float f = lb[cc] + (1.f - lb[cc]) * sigmoid_f(bf2f(xr[st][cc][e]));
;           G[cc] += __logf(f);
;           const float eg = __expf(G[cc]), ig = __expf(-G[cc]);
;           Qp[tok * 512 + c] = f2bf(bf2f(qr[st][cc][e]) * eg);
;           const u16 kk = f2bf((1.f - f) * ig);
;           Kp[tok * 512 + c] = kk;
;           kb[e] = kk;
;         }
;         const int s0 = dir ? 56 - 8 * j8 : 8 * j8;
;         uint4 w;
;         w.x = dir ? (kb[7] | (kb[6] << 16)) : (kb[0] | (kb[1] << 16));
;         w.y = dir ? (kb[5] | (kb[4] << 16)) : (kb[2] | (kb[3] << 16));
;         w.z = dir ? (kb[3] | (kb[2] << 16)) : (kb[4] | (kb[5] << 16));
;         w.w = dir ? (kb[1] | (kb[0] << 16)) : (kb[6] | (kb[7] << 16));
;         *(uint4*)(KT + (((size_t)cidx * 2 + dir) * 512 + c) * 64 + s0) = w;
	v_ldexp_f32 v95, v99, v95
	v_log_f32_e32 v92, v92
	v_log_f32_e32 v93, v93
	v_log_f32_e32 v94, v94
	v_log_f32_e32 v95, v95
	v_mul_f32_e32 v100, 0x3f317217, v92
	v_mul_f32_e32 v101, 0x3f317217, v93
	v_mul_f32_e32 v102, 0x3f317217, v94
	v_mul_f32_e32 v103, 0x3f317217, v95
	v_fma_f32 v100, v92, s31, -v100
	v_fma_f32 v101, v93, s31, -v101
	v_fma_f32 v102, v94, s31, -v102
	v_fma_f32 v103, v95, s31, -v103
	v_fmac_f32_e32 v100, 0x3377d1cf, v92
	v_fmac_f32_e32 v101, 0x3377d1cf, v93
	v_fmac_f32_e32 v102, 0x3377d1cf, v94
	v_fmac_f32_e32 v103, 0x3377d1cf, v95
	v_fmac_f32_e32 v100, 0x3f317217, v92
	v_fmac_f32_e32 v101, 0x3f317217, v93
	v_fmac_f32_e32 v102, 0x3f317217, v94
	v_fmac_f32_e32 v103, 0x3f317217, v95
	v_cmp_lt_f32_e64 vcc, |v92|, s34
	v_cndmask_b32_e32 v92, v92, v100, vcc
	v_cmp_lt_f32_e64 vcc, |v93|, s34
	v_cndmask_b32_e32 v93, v93, v101, vcc
	v_cmp_lt_f32_e64 vcc, |v94|, s34
	v_cndmask_b32_e32 v94, v94, v102, vcc
	v_cmp_lt_f32_e64 vcc, |v95|, s34
	v_cndmask_b32_e32 v95, v95, v103, vcc
	v_cndmask_b32_e64 v100, 0, v213, s[22:23]
	v_cndmask_b32_e64 v101, 0, v213, s[24:25]
	v_cndmask_b32_e64 v102, 0, v213, s[26:27]
	v_cndmask_b32_e64 v103, 0, v213, s[28:29]
	v_sub_f32_e32 v92, v92, v100
	v_sub_f32_e32 v93, v93, v101
	v_sub_f32_e32 v94, v94, v102
	v_sub_f32_e32 v95, v95, v103
	v_add_f32_e32 v64, v64, v92
	v_add_f32_e32 v65, v65, v93
	v_add_f32_e32 v66, v66, v94
	v_add_f32_e32 v67, v67, v95
	v_mul_f32_e32 v92, 0xbfb8aa3b, v64
	v_mul_f32_e32 v93, 0xbfb8aa3b, v65
	v_mul_f32_e32 v94, 0xbfb8aa3b, v66
	v_mul_f32_e32 v95, 0xbfb8aa3b, v67
	v_mul_f32_e32 v100, 0x3fb8aa3b, v64
	v_mul_f32_e32 v101, 0x3fb8aa3b, v65
	v_mul_f32_e32 v102, 0x3fb8aa3b, v66
	v_mul_f32_e32 v103, 0x3fb8aa3b, v67
	v_exp_f32_e32 v92, v92
	v_exp_f32_e32 v93, v93
	v_exp_f32_e32 v94, v94
	v_exp_f32_e32 v95, v95
	v_exp_f32_e32 v100, v100
	v_exp_f32_e32 v101, v101
	v_exp_f32_e32 v102, v102
	v_exp_f32_e32 v103, v103
	v_sub_f32_e32 v96, 1.0, v96
	v_sub_f32_e32 v97, 1.0, v97
	v_sub_f32_e32 v98, 1.0, v98
	v_sub_f32_e32 v99, 1.0, v99
	v_mul_f32_e32 v96, v96, v92
	v_mul_f32_e32 v97, v97, v93
	v_mul_f32_e32 v98, v98, v94
	v_mul_f32_e32 v99, v99, v95
	v_lshlrev_b32_e32 v92, 16, v30
	v_and_b32_e32 v93, 0xffff0000, v30
	v_lshlrev_b32_e32 v94, 16, v31
	v_and_b32_e32 v95, 0xffff0000, v31
	v_mul_f32_e32 v92, v92, v100
	v_mul_f32_e32 v93, v93, v101
	v_mul_f32_e32 v94, v94, v102
	v_mul_f32_e32 v95, v95, v103
	v_cvt_pk_bf16_f32 v128, v96, v128
	v_cvt_pk_bf16_f32 v144, v97, v144
	v_cvt_pk_bf16_f32 v178, v98, v178
	v_cvt_pk_bf16_f32 v194, v99, v194
	v_cvt_pk_bf16_f32 v92, v92, v93
	v_cvt_pk_bf16_f32 v93, v94, v95
	v_cvt_pk_bf16_f32 v96, v96, v97
	v_cvt_pk_bf16_f32 v97, v98, v99
	global_store_dwordx2 v112, v[92:93], s[2:3]
	global_store_dwordx2 v114, v[96:97], s[2:3]
	s_sub_u32 s2, s2, 0x400
	s_subb_u32 s3, s3, 0
	global_load_dwordx2 v[0:1], v113, s[0:1]
	global_load_dwordx2 v[2:3], v112, s[0:1]
	s_sub_u32 s0, s0, 0x1400
	s_subb_u32 s1, s1, 0
	global_load_dwordx2 v[4:5], v113, s[0:1]
	global_load_dwordx2 v[6:7], v112, s[0:1]
	s_sub_u32 s0, s0, 0x1400
	s_subb_u32 s1, s1, 0
	global_load_dwordx2 v[8:9], v113, s[0:1]
	global_load_dwordx2 v[10:11], v112, s[0:1]
	s_sub_u32 s0, s0, 0x1400
	s_subb_u32 s1, s1, 0
	global_load_dwordx2 v[12:13], v113, s[0:1]
	global_load_dwordx2 v[14:15], v112, s[0:1]
	s_sub_u32 s0, s0, 0x1400
	s_subb_u32 s1, s1, 0
	global_load_dwordx2 v[16:17], v113, s[0:1]
	global_load_dwordx2 v[18:19], v112, s[0:1]
	s_sub_u32 s0, s0, 0x1400
	s_subb_u32 s1, s1, 0
	global_load_dwordx2 v[20:21], v113, s[0:1]
	global_load_dwordx2 v[22:23], v112, s[0:1]
	s_sub_u32 s0, s0, 0x1400
	s_subb_u32 s1, s1, 0
	global_load_dwordx2 v[24:25], v113, s[0:1]
	global_load_dwordx2 v[26:27], v112, s[0:1]
	s_sub_u32 s0, s0, 0x1400
	s_subb_u32 s1, s1, 0
	global_load_dwordx2 v[28:29], v113, s[0:1]
	global_load_dwordx2 v[30:31], v112, s[0:1]
	s_sub_u32 s0, s0, 0x1400
	s_subb_u32 s1, s1, 0
	s_waitcnt vmcnt(32)
	v_lshlrev_b32_e32 v92, 16, v32
	v_and_b32_e32 v93, 0xffff0000, v32
	v_lshlrev_b32_e32 v94, 16, v33
	v_and_b32_e32 v95, 0xffff0000, v33
	v_mul_f32_e32 v92, 0xbfb8aa3b, v92
	v_mul_f32_e32 v93, 0xbfb8aa3b, v93
	v_mul_f32_e32 v94, 0xbfb8aa3b, v94
	v_mul_f32_e32 v95, 0xbfb8aa3b, v95
	v_exp_f32_e32 v92, v92
	v_exp_f32_e32 v93, v93
	v_exp_f32_e32 v94, v94
	v_exp_f32_e32 v95, v95
	v_add_f32_e32 v92, 1.0, v92
	v_add_f32_e32 v93, 1.0, v93
	v_add_f32_e32 v94, 1.0, v94
	v_add_f32_e32 v95, 1.0, v95
	v_rcp_f32_e32 v92, v92
	v_rcp_f32_e32 v93, v93
	v_rcp_f32_e32 v94, v94
	v_rcp_f32_e32 v95, v95
	v_fma_f32 v96, v72, v92, v68
	v_fma_f32 v97, v73, v93, v69
	v_fma_f32 v98, v74, v94, v70
	v_fma_f32 v99, v75, v95, v71
	v_cmp_gt_f32_e64 s[22:23], s30, v96
	v_cmp_gt_f32_e64 s[24:25], s30, v97
	v_cmp_gt_f32_e64 s[26:27], s30, v98
	v_cmp_gt_f32_e64 s[28:29], s30, v99
	v_cndmask_b32_e64 v92, 0, 32, s[22:23]
	v_cndmask_b32_e64 v93, 0, 32, s[24:25]
	v_cndmask_b32_e64 v94, 0, 32, s[26:27]
	v_cndmask_b32_e64 v95, 0, 32, s[28:29]
	v_ldexp_f32 v92, v96, v92
	v_ldexp_f32 v93, v97, v93
	v_ldexp_f32 v94, v98, v94
	v_ldexp_f32 v95, v99, v95
	v_log_f32_e32 v92, v92
	v_log_f32_e32 v93, v93
	v_log_f32_e32 v94, v94
	v_log_f32_e32 v95, v95
	v_mul_f32_e32 v100, 0x3f317217, v92
	v_mul_f32_e32 v101, 0x3f317217, v93
	v_mul_f32_e32 v102, 0x3f317217, v94
	v_mul_f32_e32 v103, 0x3f317217, v95
	v_fma_f32 v100, v92, s31, -v100
	v_fma_f32 v101, v93, s31, -v101
	v_fma_f32 v102, v94, s31, -v102
	v_fma_f32 v103, v95, s31, -v103
	v_fmac_f32_e32 v100, 0x3377d1cf, v92
	v_fmac_f32_e32 v101, 0x3377d1cf, v93
	v_fmac_f32_e32 v102, 0x3377d1cf, v94
	v_fmac_f32_e32 v103, 0x3377d1cf, v95
	v_fmac_f32_e32 v100, 0x3f317217, v92
	v_fmac_f32_e32 v101, 0x3f317217, v93
; DEV u16 f2bf(float f) { return (u16)(pack2(f, f) & 0xffffu); }
; DEV float bf2f(u16 h) { return __uint_as_float(((unsigned)h) << 16); }
; DEV float sigmoid_f(float x) { return __builtin_amdgcn_rcpf(1.f + __expf(-x)); }
; DEV void phase_p15(const Params& p, int g) {
;     ...
;         for (int e = 0; e < 8; ++e) {
;           const int jj = j8 * 8 + e;
;           const int j = dir ? 63 - jj : jj;
;           const size_t tok = (size_t)cidx * 64 + j;
;           const float f = lb[cc] + (1.f - lb[cc]) * sigmoid_f(bf2f(xr[st][cc][e]));
;           G[cc] += __logf(f);
;           const float eg = __expf(G[cc]), ig = __expf(-G[cc]);
;           Qp[tok * 512 + c] = f2bf(bf2f(qr[st][cc][e]) * eg);
;           const u16 kk = f2bf((1.f - f) * ig);
;           Kp[tok * 512 + c] = kk;
;           kb[e] = kk;
;         }
;         const int s0 = dir ? 56 - 8 * j8 : 8 * j8;
;         uint4 w;
;         w.x = dir ? (kb[7] | (kb[6] << 16)) : (kb[0] | (kb[1] << 16));
;         w.y = dir ? (kb[5] | (kb[4] << 16)) : (kb[2] | (kb[3] << 16));
;         w.z = dir ? (kb[3] | (kb[2] << 16)) : (kb[4] | (kb[5] << 16));
;         w.w = dir ? (kb[1] | (kb[0] << 16)) : (kb[6] | (kb[7] << 16));
;         *(uint4*)(KT + (((size_t)cidx * 2 + dir) * 512 + c) * 64 + s0) = w;
	v_fmac_f32_e32 v102, 0x3f317217, v94
	v_fmac_f32_e32 v103, 0x3f317217, v95
	v_cmp_lt_f32_e64 vcc, |v92|, s34
	v_cndmask_b32_e32 v92, v92, v100, vcc
	v_cmp_lt_f32_e64 vcc, |v93|, s34
	v_cndmask_b32_e32 v93, v93, v101, vcc
	v_cmp_lt_f32_e64 vcc, |v94|, s34
	v_cndmask_b32_e32 v94, v94, v102, vcc
	v_cmp_lt_f32_e64 vcc, |v95|, s34
	v_cndmask_b32_e32 v95, v95, v103, vcc
	v_cndmask_b32_e64 v100, 0, v213, s[22:23]
	v_cndmask_b32_e64 v101, 0, v213, s[24:25]
	v_cndmask_b32_e64 v102, 0, v213, s[26:27]
	v_cndmask_b32_e64 v103, 0, v213, s[28:29]
	v_sub_f32_e32 v92, v92, v100
	v_sub_f32_e32 v93, v93, v101
	v_sub_f32_e32 v94, v94, v102
	v_sub_f32_e32 v95, v95, v103
	v_add_f32_e32 v64, v64, v92
	v_add_f32_e32 v65, v65, v93
	v_add_f32_e32 v66, v66, v94
	v_add_f32_e32 v67, v67, v95
	v_mul_f32_e32 v92, 0xbfb8aa3b, v64
	v_mul_f32_e32 v93, 0xbfb8aa3b, v65
	v_mul_f32_e32 v94, 0xbfb8aa3b, v66
	v_mul_f32_e32 v95, 0xbfb8aa3b, v67
	v_mul_f32_e32 v100, 0x3fb8aa3b, v64
	v_mul_f32_e32 v101, 0x3fb8aa3b, v65
	v_mul_f32_e32 v102, 0x3fb8aa3b, v66
	v_mul_f32_e32 v103, 0x3fb8aa3b, v67
	v_exp_f32_e32 v92, v92
	v_exp_f32_e32 v93, v93
	v_exp_f32_e32 v94, v94
	v_exp_f32_e32 v95, v95
	v_exp_f32_e32 v100, v100
	v_exp_f32_e32 v101, v101
	v_exp_f32_e32 v102, v102
	v_exp_f32_e32 v103, v103
	v_sub_f32_e32 v96, 1.0, v96
	v_sub_f32_e32 v97, 1.0, v97
	v_sub_f32_e32 v98, 1.0, v98
	v_sub_f32_e32 v99, 1.0, v99
	v_mul_f32_e32 v96, v96, v92
	v_mul_f32_e32 v97, v97, v93
	v_mul_f32_e32 v98, v98, v94
	v_mul_f32_e32 v99, v99, v95
	v_lshlrev_b32_e32 v92, 16, v34
	v_and_b32_e32 v93, 0xffff0000, v34
	v_lshlrev_b32_e32 v94, 16, v35
	v_and_b32_e32 v95, 0xffff0000, v35
	v_mul_f32_e32 v92, v92, v100
	v_mul_f32_e32 v93, v93, v101
	v_mul_f32_e32 v94, v94, v102
	v_mul_f32_e32 v95, v95, v103
	v_mov_b32_e32 v127, v96
	v_mov_b32_e32 v143, v97
	v_mov_b32_e32 v177, v98
	v_mov_b32_e32 v193, v99
	v_cvt_pk_bf16_f32 v92, v92, v93
	v_cvt_pk_bf16_f32 v93, v94, v95
	v_cvt_pk_bf16_f32 v96, v96, v97
	v_cvt_pk_bf16_f32 v97, v98, v99
	global_store_dwordx2 v112, v[92:93], s[2:3]
	global_store_dwordx2 v114, v[96:97], s[2:3]
	s_sub_u32 s2, s2, 0x400
	s_subb_u32 s3, s3, 0
	v_lshlrev_b32_e32 v92, 16, v36
	v_and_b32_e32 v93, 0xffff0000, v36
	v_lshlrev_b32_e32 v94, 16, v37
	v_and_b32_e32 v95, 0xffff0000, v37
	v_mul_f32_e32 v92, 0xbfb8aa3b, v92
	v_mul_f32_e32 v93, 0xbfb8aa3b, v93
	v_mul_f32_e32 v94, 0xbfb8aa3b, v94
	v_mul_f32_e32 v95, 0xbfb8aa3b, v95
	v_exp_f32_e32 v92, v92
	v_exp_f32_e32 v93, v93
	v_exp_f32_e32 v94, v94
	v_exp_f32_e32 v95, v95
	v_add_f32_e32 v92, 1.0, v92
	v_add_f32_e32 v93, 1.0, v93
	v_add_f32_e32 v94, 1.0, v94
	v_add_f32_e32 v95, 1.0, v95
	v_rcp_f32_e32 v92, v92
	v_rcp_f32_e32 v93, v93
	v_rcp_f32_e32 v94, v94
	v_rcp_f32_e32 v95, v95
	v_fma_f32 v96, v72, v92, v68
	v_fma_f32 v97, v73, v93, v69
	v_fma_f32 v98, v74, v94, v70
	v_fma_f32 v99, v75, v95, v71
	v_cmp_gt_f32_e64 s[22:23], s30, v96
	v_cmp_gt_f32_e64 s[24:25], s30, v97
	v_cmp_gt_f32_e64 s[26:27], s30, v98
	v_cmp_gt_f32_e64 s[28:29], s30, v99
	v_cndmask_b32_e64 v92, 0, 32, s[22:23]
	v_cndmask_b32_e64 v93, 0, 32, s[24:25]
	v_cndmask_b32_e64 v94, 0, 32, s[26:27]
	v_cndmask_b32_e64 v95, 0, 32, s[28:29]
	v_ldexp_f32 v92, v96, v92
	v_ldexp_f32 v93, v97, v93
	v_ldexp_f32 v94, v98, v94
	v_ldexp_f32 v95, v99, v95
	v_log_f32_e32 v92, v92
	v_log_f32_e32 v93, v93
	v_log_f32_e32 v94, v94
	v_log_f32_e32 v95, v95
	v_mul_f32_e32 v100, 0x3f317217, v92
	v_mul_f32_e32 v101, 0x3f317217, v93
	v_mul_f32_e32 v102, 0x3f317217, v94
	v_mul_f32_e32 v103, 0x3f317217, v95
	v_fma_f32 v100, v92, s31, -v100
	v_fma_f32 v101, v93, s31, -v101
	v_fma_f32 v102, v94, s31, -v102
	v_fma_f32 v103, v95, s31, -v103
	v_fmac_f32_e32 v100, 0x3377d1cf, v92
	v_fmac_f32_e32 v101, 0x3377d1cf, v93
	v_fmac_f32_e32 v102, 0x3377d1cf, v94
	v_fmac_f32_e32 v103, 0x3377d1cf, v95
	v_fmac_f32_e32 v100, 0x3f317217, v92
	v_fmac_f32_e32 v101, 0x3f317217, v93
	v_fmac_f32_e32 v102, 0x3f317217, v94
	v_fmac_f32_e32 v103, 0x3f317217, v95
	v_cmp_lt_f32_e64 vcc, |v92|, s34
	v_cndmask_b32_e32 v92, v92, v100, vcc
	v_cmp_lt_f32_e64 vcc, |v93|, s34
	v_cndmask_b32_e32 v93, v93, v101, vcc
	v_cmp_lt_f32_e64 vcc, |v94|, s34
	v_cndmask_b32_e32 v94, v94, v102, vcc
	v_cmp_lt_f32_e64 vcc, |v95|, s34
	v_cndmask_b32_e32 v95, v95, v103, vcc
	v_cndmask_b32_e64 v100, 0, v213, s[22:23]
	v_cndmask_b32_e64 v101, 0, v213, s[24:25]
	v_cndmask_b32_e64 v102, 0, v213, s[26:27]
	v_cndmask_b32_e64 v103, 0, v213, s[28:29]
	v_sub_f32_e32 v92, v92, v100
	v_sub_f32_e32 v93, v93, v101
	v_sub_f32_e32 v94, v94, v102
	v_sub_f32_e32 v95, v95, v103
	v_add_f32_e32 v64, v64, v92
	v_add_f32_e32 v65, v65, v93
	v_add_f32_e32 v66, v66, v94
	v_add_f32_e32 v67, v67, v95
	v_mul_f32_e32 v92, 0xbfb8aa3b, v64
	v_mul_f32_e32 v93, 0xbfb8aa3b, v65
	v_mul_f32_e32 v94, 0xbfb8aa3b, v66
	v_mul_f32_e32 v95, 0xbfb8aa3b, v67
	v_mul_f32_e32 v100, 0x3fb8aa3b, v64
	v_mul_f32_e32 v101, 0x3fb8aa3b, v65
	v_mul_f32_e32 v102, 0x3fb8aa3b, v66
	v_mul_f32_e32 v103, 0x3fb8aa3b, v67
	v_exp_f32_e32 v92, v92
	v_exp_f32_e32 v93, v93
	v_exp_f32_e32 v94, v94
	v_exp_f32_e32 v95, v95
	v_exp_f32_e32 v100, v100
	v_exp_f32_e32 v101, v101
	v_exp_f32_e32 v102, v102
	v_exp_f32_e32 v103, v103
	v_sub_f32_e32 v96, 1.0, v96
	v_sub_f32_e32 v97, 1.0, v97
	v_sub_f32_e32 v98, 1.0, v98
	v_sub_f32_e32 v99, 1.0, v99
	v_mul_f32_e32 v96, v96, v92
	v_mul_f32_e32 v97, v97, v93
	v_mul_f32_e32 v98, v98, v94
	v_mul_f32_e32 v99, v99, v95
	v_lshlrev_b32_e32 v92, 16, v38
	v_and_b32_e32 v93, 0xffff0000, v38
	v_lshlrev_b32_e32 v94, 16, v39
	v_and_b32_e32 v95, 0xffff0000, v39
	v_mul_f32_e32 v92, v92, v100
	v_mul_f32_e32 v93, v93, v101
	v_mul_f32_e32 v94, v94, v102
	v_mul_f32_e32 v95, v95, v103
	v_cvt_pk_bf16_f32 v127, v96, v127
; DEV u16 f2bf(float f) { return (u16)(pack2(f, f) & 0xffffu); }
; DEV float bf2f(u16 h) { return __uint_as_float(((unsigned)h) << 16); }
; DEV float sigmoid_f(float x) { return __builtin_amdgcn_rcpf(1.f + __expf(-x)); }
; DEV void phase_p15(const Params& p, int g) {
;     ...
;         for (int e = 0; e < 8; ++e) {
;           const int jj = j8 * 8 + e;
;           const int j = dir ? 63 - jj : jj;
;           const size_t tok = (size_t)cidx * 64 + j;
;           const float f = lb[cc] + (1.f - lb[cc]) * sigmoid_f(bf2f(xr[st][cc][e]));
;           G[cc] += __logf(f);
;           const float eg = __expf(G[cc]), ig = __expf(-G[cc]);
;           Qp[tok * 512 + c] = f2bf(bf2f(qr[st][cc][e]) * eg);
;           const u16 kk = f2bf((1.f - f) * ig);
;           Kp[tok * 512 + c] = kk;
;           kb[e] = kk;
;         }
;         const int s0 = dir ? 56 - 8 * j8 : 8 * j8;
;         uint4 w;
;         w.x = dir ? (kb[7] | (kb[6] << 16)) : (kb[0] | (kb[1] << 16));
;         w.y = dir ? (kb[5] | (kb[4] << 16)) : (kb[2] | (kb[3] << 16));
;         w.z = dir ? (kb[3] | (kb[2] << 16)) : (kb[4] | (kb[5] << 16));
;         w.w = dir ? (kb[1] | (kb[0] << 16)) : (kb[6] | (kb[7] << 16));
;         *(uint4*)(KT + (((size_t)cidx * 2 + dir) * 512 + c) * 64 + s0) = w;
	v_cvt_pk_bf16_f32 v143, v97, v143
	v_cvt_pk_bf16_f32 v177, v98, v177
	v_cvt_pk_bf16_f32 v193, v99, v193
	v_cvt_pk_bf16_f32 v92, v92, v93
	v_cvt_pk_bf16_f32 v93, v94, v95
	v_cvt_pk_bf16_f32 v96, v96, v97
	v_cvt_pk_bf16_f32 v97, v98, v99
	global_store_dwordx2 v112, v[92:93], s[2:3]
	global_store_dwordx2 v114, v[96:97], s[2:3]
	s_sub_u32 s2, s2, 0x400
	s_subb_u32 s3, s3, 0
	v_lshlrev_b32_e32 v92, 16, v40
	v_and_b32_e32 v93, 0xffff0000, v40
	v_lshlrev_b32_e32 v94, 16, v41
	v_and_b32_e32 v95, 0xffff0000, v41
	v_mul_f32_e32 v92, 0xbfb8aa3b, v92
	v_mul_f32_e32 v93, 0xbfb8aa3b, v93
	v_mul_f32_e32 v94, 0xbfb8aa3b, v94
	v_mul_f32_e32 v95, 0xbfb8aa3b, v95
	v_exp_f32_e32 v92, v92
	v_exp_f32_e32 v93, v93
	v_exp_f32_e32 v94, v94
	v_exp_f32_e32 v95, v95
	v_add_f32_e32 v92, 1.0, v92
	v_add_f32_e32 v93, 1.0, v93
	v_add_f32_e32 v94, 1.0, v94
	v_add_f32_e32 v95, 1.0, v95
	v_rcp_f32_e32 v92, v92
	v_rcp_f32_e32 v93, v93
	v_rcp_f32_e32 v94, v94
	v_rcp_f32_e32 v95, v95
	v_fma_f32 v96, v72, v92, v68
	v_fma_f32 v97, v73, v93, v69
	v_fma_f32 v98, v74, v94, v70
	v_fma_f32 v99, v75, v95, v71
	v_cmp_gt_f32_e64 s[22:23], s30, v96
	v_cmp_gt_f32_e64 s[24:25], s30, v97
	v_cmp_gt_f32_e64 s[26:27], s30, v98
	v_cmp_gt_f32_e64 s[28:29], s30, v99
	v_cndmask_b32_e64 v92, 0, 32, s[22:23]
	v_cndmask_b32_e64 v93, 0, 32, s[24:25]
	v_cndmask_b32_e64 v94, 0, 32, s[26:27]
	v_cndmask_b32_e64 v95, 0, 32, s[28:29]
	v_ldexp_f32 v92, v96, v92
	v_ldexp_f32 v93, v97, v93
	v_ldexp_f32 v94, v98, v94
	v_ldexp_f32 v95, v99, v95
	v_log_f32_e32 v92, v92
	v_log_f32_e32 v93, v93
	v_log_f32_e32 v94, v94
	v_log_f32_e32 v95, v95
	v_mul_f32_e32 v100, 0x3f317217, v92
	v_mul_f32_e32 v101, 0x3f317217, v93
	v_mul_f32_e32 v102, 0x3f317217, v94
	v_mul_f32_e32 v103, 0x3f317217, v95
	v_fma_f32 v100, v92, s31, -v100
	v_fma_f32 v101, v93, s31, -v101
	v_fma_f32 v102, v94, s31, -v102
	v_fma_f32 v103, v95, s31, -v103
	v_fmac_f32_e32 v100, 0x3377d1cf, v92
	v_fmac_f32_e32 v101, 0x3377d1cf, v93
	v_fmac_f32_e32 v102, 0x3377d1cf, v94
	v_fmac_f32_e32 v103, 0x3377d1cf, v95
	v_fmac_f32_e32 v100, 0x3f317217, v92
	v_fmac_f32_e32 v101, 0x3f317217, v93
	v_fmac_f32_e32 v102, 0x3f317217, v94
	v_fmac_f32_e32 v103, 0x3f317217, v95
	v_cmp_lt_f32_e64 vcc, |v92|, s34
	v_cndmask_b32_e32 v92, v92, v100, vcc
	v_cmp_lt_f32_e64 vcc, |v93|, s34
	v_cndmask_b32_e32 v93, v93, v101, vcc
	v_cmp_lt_f32_e64 vcc, |v94|, s34
	v_cndmask_b32_e32 v94, v94, v102, vcc
	v_cmp_lt_f32_e64 vcc, |v95|, s34
	v_cndmask_b32_e32 v95, v95, v103, vcc
	v_cndmask_b32_e64 v100, 0, v213, s[22:23]
	v_cndmask_b32_e64 v101, 0, v213, s[24:25]
	v_cndmask_b32_e64 v102, 0, v213, s[26:27]
	v_cndmask_b32_e64 v103, 0, v213, s[28:29]
	v_sub_f32_e32 v92, v92, v100
	v_sub_f32_e32 v93, v93, v101
	v_sub_f32_e32 v94, v94, v102
	v_sub_f32_e32 v95, v95, v103
	v_add_f32_e32 v64, v64, v92
	v_add_f32_e32 v65, v65, v93
	v_add_f32_e32 v66, v66, v94
	v_add_f32_e32 v67, v67, v95
	v_mul_f32_e32 v92, 0xbfb8aa3b, v64
	v_mul_f32_e32 v93, 0xbfb8aa3b, v65
	v_mul_f32_e32 v94, 0xbfb8aa3b, v66
	v_mul_f32_e32 v95, 0xbfb8aa3b, v67
	v_mul_f32_e32 v100, 0x3fb8aa3b, v64
	v_mul_f32_e32 v101, 0x3fb8aa3b, v65
	v_mul_f32_e32 v102, 0x3fb8aa3b, v66
	v_mul_f32_e32 v103, 0x3fb8aa3b, v67
	v_exp_f32_e32 v92, v92
	v_exp_f32_e32 v93, v93
	v_exp_f32_e32 v94, v94
	v_exp_f32_e32 v95, v95
	v_exp_f32_e32 v100, v100
	v_exp_f32_e32 v101, v101
	v_exp_f32_e32 v102, v102
	v_exp_f32_e32 v103, v103
	v_sub_f32_e32 v96, 1.0, v96
	v_sub_f32_e32 v97, 1.0, v97
	v_sub_f32_e32 v98, 1.0, v98
	v_sub_f32_e32 v99, 1.0, v99
	v_mul_f32_e32 v96, v96, v92
	v_mul_f32_e32 v97, v97, v93
	v_mul_f32_e32 v98, v98, v94
	v_mul_f32_e32 v99, v99, v95
	v_lshlrev_b32_e32 v92, 16, v42
	v_and_b32_e32 v93, 0xffff0000, v42
	v_lshlrev_b32_e32 v94, 16, v43
	v_and_b32_e32 v95, 0xffff0000, v43
	v_mul_f32_e32 v92, v92, v100
	v_mul_f32_e32 v93, v93, v101
	v_mul_f32_e32 v94, v94, v102
	v_mul_f32_e32 v95, v95, v103
	v_mov_b32_e32 v126, v96
	v_mov_b32_e32 v142, v97
	v_mov_b32_e32 v176, v98
	v_mov_b32_e32 v192, v99
	v_cvt_pk_bf16_f32 v92, v92, v93
	v_cvt_pk_bf16_f32 v93, v94, v95
	v_cvt_pk_bf16_f32 v96, v96, v97
	v_cvt_pk_bf16_f32 v97, v98, v99
	global_store_dwordx2 v112, v[92:93], s[2:3]
	global_store_dwordx2 v114, v[96:97], s[2:3]
	s_sub_u32 s2, s2, 0x400
	s_subb_u32 s3, s3, 0
	v_lshlrev_b32_e32 v92, 16, v44
	v_and_b32_e32 v93, 0xffff0000, v44
	v_lshlrev_b32_e32 v94, 16, v45
	v_and_b32_e32 v95, 0xffff0000, v45
	v_mul_f32_e32 v92, 0xbfb8aa3b, v92
	v_mul_f32_e32 v93, 0xbfb8aa3b, v93
	v_mul_f32_e32 v94, 0xbfb8aa3b, v94
	v_mul_f32_e32 v95, 0xbfb8aa3b, v95
	v_exp_f32_e32 v92, v92
	v_exp_f32_e32 v93, v93
	v_exp_f32_e32 v94, v94
	v_exp_f32_e32 v95, v95
	v_add_f32_e32 v92, 1.0, v92
	v_add_f32_e32 v93, 1.0, v93
	v_add_f32_e32 v94, 1.0, v94
	v_add_f32_e32 v95, 1.0, v95
	v_rcp_f32_e32 v92, v92
	v_rcp_f32_e32 v93, v93
	v_rcp_f32_e32 v94, v94
	v_rcp_f32_e32 v95, v95
	v_fma_f32 v96, v72, v92, v68
	v_fma_f32 v97, v73, v93, v69
	v_fma_f32 v98, v74, v94, v70
	v_fma_f32 v99, v75, v95, v71
	v_cmp_gt_f32_e64 s[22:23], s30, v96
	v_cmp_gt_f32_e64 s[24:25], s30, v97
	v_cmp_gt_f32_e64 s[26:27], s30, v98
	v_cmp_gt_f32_e64 s[28:29], s30, v99
	v_cndmask_b32_e64 v92, 0, 32, s[22:23]
	v_cndmask_b32_e64 v93, 0, 32, s[24:25]
	v_cndmask_b32_e64 v94, 0, 32, s[26:27]
	v_cndmask_b32_e64 v95, 0, 32, s[28:29]
	v_ldexp_f32 v92, v96, v92
	v_ldexp_f32 v93, v97, v93
	v_ldexp_f32 v94, v98, v94
	v_ldexp_f32 v95, v99, v95
	v_log_f32_e32 v92, v92
	v_log_f32_e32 v93, v93
	v_log_f32_e32 v94, v94
	v_log_f32_e32 v95, v95
	v_mul_f32_e32 v100, 0x3f317217, v92
	v_mul_f32_e32 v101, 0x3f317217, v93
	v_mul_f32_e32 v102, 0x3f317217, v94
	v_mul_f32_e32 v103, 0x3f317217, v95
	v_fma_f32 v100, v92, s31, -v100
; DEV u16 f2bf(float f) { return (u16)(pack2(f, f) & 0xffffu); }
; DEV float bf2f(u16 h) { return __uint_as_float(((unsigned)h) << 16); }
; DEV float sigmoid_f(float x) { return __builtin_amdgcn_rcpf(1.f + __expf(-x)); }
; DEV void phase_p15(const Params& p, int g) {
;     ...
;         for (int e = 0; e < 8; ++e) {
;           const int jj = j8 * 8 + e;
;           const int j = dir ? 63 - jj : jj;
;           const size_t tok = (size_t)cidx * 64 + j;
;           const float f = lb[cc] + (1.f - lb[cc]) * sigmoid_f(bf2f(xr[st][cc][e]));
;           G[cc] += __logf(f);
;           const float eg = __expf(G[cc]), ig = __expf(-G[cc]);
;           Qp[tok * 512 + c] = f2bf(bf2f(qr[st][cc][e]) * eg);
;           const u16 kk = f2bf((1.f - f) * ig);
;           Kp[tok * 512 + c] = kk;
;           kb[e] = kk;
;         }
;         const int s0 = dir ? 56 - 8 * j8 : 8 * j8;
;         uint4 w;
;         w.x = dir ? (kb[7] | (kb[6] << 16)) : (kb[0] | (kb[1] << 16));
;         w.y = dir ? (kb[5] | (kb[4] << 16)) : (kb[2] | (kb[3] << 16));
;         w.z = dir ? (kb[3] | (kb[2] << 16)) : (kb[4] | (kb[5] << 16));
;         w.w = dir ? (kb[1] | (kb[0] << 16)) : (kb[6] | (kb[7] << 16));
;         *(uint4*)(KT + (((size_t)cidx * 2 + dir) * 512 + c) * 64 + s0) = w;
	v_fma_f32 v101, v93, s31, -v101
	v_fma_f32 v102, v94, s31, -v102
	v_fma_f32 v103, v95, s31, -v103
	v_fmac_f32_e32 v100, 0x3377d1cf, v92
	v_fmac_f32_e32 v101, 0x3377d1cf, v93
	v_fmac_f32_e32 v102, 0x3377d1cf, v94
	v_fmac_f32_e32 v103, 0x3377d1cf, v95
	v_fmac_f32_e32 v100, 0x3f317217, v92
	v_fmac_f32_e32 v101, 0x3f317217, v93
	v_fmac_f32_e32 v102, 0x3f317217, v94
	v_fmac_f32_e32 v103, 0x3f317217, v95
	v_cmp_lt_f32_e64 vcc, |v92|, s34
	v_cndmask_b32_e32 v92, v92, v100, vcc
	v_cmp_lt_f32_e64 vcc, |v93|, s34
	v_cndmask_b32_e32 v93, v93, v101, vcc
	v_cmp_lt_f32_e64 vcc, |v94|, s34
	v_cndmask_b32_e32 v94, v94, v102, vcc
	v_cmp_lt_f32_e64 vcc, |v95|, s34
	v_cndmask_b32_e32 v95, v95, v103, vcc
	v_cndmask_b32_e64 v100, 0, v213, s[22:23]
	v_cndmask_b32_e64 v101, 0, v213, s[24:25]
	v_cndmask_b32_e64 v102, 0, v213, s[26:27]
	v_cndmask_b32_e64 v103, 0, v213, s[28:29]
	v_sub_f32_e32 v92, v92, v100
	v_sub_f32_e32 v93, v93, v101
	v_sub_f32_e32 v94, v94, v102
	v_sub_f32_e32 v95, v95, v103
	v_add_f32_e32 v64, v64, v92
	v_add_f32_e32 v65, v65, v93
	v_add_f32_e32 v66, v66, v94
	v_add_f32_e32 v67, v67, v95
	v_mul_f32_e32 v92, 0xbfb8aa3b, v64
	v_mul_f32_e32 v93, 0xbfb8aa3b, v65
	v_mul_f32_e32 v94, 0xbfb8aa3b, v66
	v_mul_f32_e32 v95, 0xbfb8aa3b, v67
	v_mul_f32_e32 v100, 0x3fb8aa3b, v64
	v_mul_f32_e32 v101, 0x3fb8aa3b, v65
	v_mul_f32_e32 v102, 0x3fb8aa3b, v66
	v_mul_f32_e32 v103, 0x3fb8aa3b, v67
	v_exp_f32_e32 v92, v92
	v_exp_f32_e32 v93, v93
	v_exp_f32_e32 v94, v94
	v_exp_f32_e32 v95, v95
	v_exp_f32_e32 v100, v100
	v_exp_f32_e32 v101, v101
	v_exp_f32_e32 v102, v102
	v_exp_f32_e32 v103, v103
	v_sub_f32_e32 v96, 1.0, v96
	v_sub_f32_e32 v97, 1.0, v97
	v_sub_f32_e32 v98, 1.0, v98
	v_sub_f32_e32 v99, 1.0, v99
	v_mul_f32_e32 v96, v96, v92
	v_mul_f32_e32 v97, v97, v93
	v_mul_f32_e32 v98, v98, v94
	v_mul_f32_e32 v99, v99, v95
	v_lshlrev_b32_e32 v92, 16, v46
	v_and_b32_e32 v93, 0xffff0000, v46
	v_lshlrev_b32_e32 v94, 16, v47
	v_and_b32_e32 v95, 0xffff0000, v47
	v_mul_f32_e32 v92, v92, v100
	v_mul_f32_e32 v93, v93, v101
	v_mul_f32_e32 v94, v94, v102
	v_mul_f32_e32 v95, v95, v103
	v_cvt_pk_bf16_f32 v126, v96, v126
	v_cvt_pk_bf16_f32 v142, v97, v142
	v_cvt_pk_bf16_f32 v176, v98, v176
	v_cvt_pk_bf16_f32 v192, v99, v192
	v_cvt_pk_bf16_f32 v92, v92, v93
	v_cvt_pk_bf16_f32 v93, v94, v95
	v_cvt_pk_bf16_f32 v96, v96, v97
	v_cvt_pk_bf16_f32 v97, v98, v99
	global_store_dwordx2 v112, v[92:93], s[2:3]
	global_store_dwordx2 v114, v[96:97], s[2:3]
	s_sub_u32 s2, s2, 0x400
	s_subb_u32 s3, s3, 0
	v_lshlrev_b32_e32 v92, 16, v48
	v_and_b32_e32 v93, 0xffff0000, v48
	v_lshlrev_b32_e32 v94, 16, v49
	v_and_b32_e32 v95, 0xffff0000, v49
	v_mul_f32_e32 v92, 0xbfb8aa3b, v92
	v_mul_f32_e32 v93, 0xbfb8aa3b, v93
	v_mul_f32_e32 v94, 0xbfb8aa3b, v94
	v_mul_f32_e32 v95, 0xbfb8aa3b, v95
	v_exp_f32_e32 v92, v92
	v_exp_f32_e32 v93, v93
	v_exp_f32_e32 v94, v94
	v_exp_f32_e32 v95, v95
	v_add_f32_e32 v92, 1.0, v92
	v_add_f32_e32 v93, 1.0, v93
	v_add_f32_e32 v94, 1.0, v94
	v_add_f32_e32 v95, 1.0, v95
	v_rcp_f32_e32 v92, v92
	v_rcp_f32_e32 v93, v93
	v_rcp_f32_e32 v94, v94
	v_rcp_f32_e32 v95, v95
	v_fma_f32 v96, v72, v92, v68
	v_fma_f32 v97, v73, v93, v69
	v_fma_f32 v98, v74, v94, v70
	v_fma_f32 v99, v75, v95, v71
	v_cmp_gt_f32_e64 s[22:23], s30, v96
	v_cmp_gt_f32_e64 s[24:25], s30, v97
	v_cmp_gt_f32_e64 s[26:27], s30, v98
	v_cmp_gt_f32_e64 s[28:29], s30, v99
	v_cndmask_b32_e64 v92, 0, 32, s[22:23]
	v_cndmask_b32_e64 v93, 0, 32, s[24:25]
	v_cndmask_b32_e64 v94, 0, 32, s[26:27]
	v_cndmask_b32_e64 v95, 0, 32, s[28:29]
	v_ldexp_f32 v92, v96, v92
	v_ldexp_f32 v93, v97, v93
	v_ldexp_f32 v94, v98, v94
	v_ldexp_f32 v95, v99, v95
	v_log_f32_e32 v92, v92
	v_log_f32_e32 v93, v93
	v_log_f32_e32 v94, v94
	v_log_f32_e32 v95, v95
	v_mul_f32_e32 v100, 0x3f317217, v92
	v_mul_f32_e32 v101, 0x3f317217, v93
	v_mul_f32_e32 v102, 0x3f317217, v94
	v_mul_f32_e32 v103, 0x3f317217, v95
	v_fma_f32 v100, v92, s31, -v100
	v_fma_f32 v101, v93, s31, -v101
	v_fma_f32 v102, v94, s31, -v102
	v_fma_f32 v103, v95, s31, -v103
	v_fmac_f32_e32 v100, 0x3377d1cf, v92
	v_fmac_f32_e32 v101, 0x3377d1cf, v93
	v_fmac_f32_e32 v102, 0x3377d1cf, v94
	v_fmac_f32_e32 v103, 0x3377d1cf, v95
	v_fmac_f32_e32 v100, 0x3f317217, v92
	v_fmac_f32_e32 v101, 0x3f317217, v93
	v_fmac_f32_e32 v102, 0x3f317217, v94
	v_fmac_f32_e32 v103, 0x3f317217, v95
	v_cmp_lt_f32_e64 vcc, |v92|, s34
	v_cndmask_b32_e32 v92, v92, v100, vcc
	v_cmp_lt_f32_e64 vcc, |v93|, s34
	v_cndmask_b32_e32 v93, v93, v101, vcc
	v_cmp_lt_f32_e64 vcc, |v94|, s34
	v_cndmask_b32_e32 v94, v94, v102, vcc
	v_cmp_lt_f32_e64 vcc, |v95|, s34
	v_cndmask_b32_e32 v95, v95, v103, vcc
	v_cndmask_b32_e64 v100, 0, v213, s[22:23]
	v_cndmask_b32_e64 v101, 0, v213, s[24:25]
	v_cndmask_b32_e64 v102, 0, v213, s[26:27]
	v_cndmask_b32_e64 v103, 0, v213, s[28:29]
	v_sub_f32_e32 v92, v92, v100
	v_sub_f32_e32 v93, v93, v101
	v_sub_f32_e32 v94, v94, v102
	v_sub_f32_e32 v95, v95, v103
	v_add_f32_e32 v64, v64, v92
	v_add_f32_e32 v65, v65, v93
	v_add_f32_e32 v66, v66, v94
	v_add_f32_e32 v67, v67, v95
	v_mul_f32_e32 v92, 0xbfb8aa3b, v64
	v_mul_f32_e32 v93, 0xbfb8aa3b, v65
	v_mul_f32_e32 v94, 0xbfb8aa3b, v66
	v_mul_f32_e32 v95, 0xbfb8aa3b, v67
	v_mul_f32_e32 v100, 0x3fb8aa3b, v64
	v_mul_f32_e32 v101, 0x3fb8aa3b, v65
	v_mul_f32_e32 v102, 0x3fb8aa3b, v66
	v_mul_f32_e32 v103, 0x3fb8aa3b, v67
	v_exp_f32_e32 v92, v92
	v_exp_f32_e32 v93, v93
	v_exp_f32_e32 v94, v94
	v_exp_f32_e32 v95, v95
	v_exp_f32_e32 v100, v100
	v_exp_f32_e32 v101, v101
	v_exp_f32_e32 v102, v102
	v_exp_f32_e32 v103, v103
	v_sub_f32_e32 v96, 1.0, v96
	v_sub_f32_e32 v97, 1.0, v97
	v_sub_f32_e32 v98, 1.0, v98
	v_sub_f32_e32 v99, 1.0, v99
	v_mul_f32_e32 v96, v96, v92
; DEV u16 f2bf(float f) { return (u16)(pack2(f, f) & 0xffffu); }
; DEV float bf2f(u16 h) { return __uint_as_float(((unsigned)h) << 16); }
; DEV float sigmoid_f(float x) { return __builtin_amdgcn_rcpf(1.f + __expf(-x)); }
; DEV void phase_p15(const Params& p, int g) {
;     ...
;         for (int e = 0; e < 8; ++e) {
;           const int jj = j8 * 8 + e;
;           const int j = dir ? 63 - jj : jj;
;           const size_t tok = (size_t)cidx * 64 + j;
;           const float f = lb[cc] + (1.f - lb[cc]) * sigmoid_f(bf2f(xr[st][cc][e]));
;           G[cc] += __logf(f);
;           const float eg = __expf(G[cc]), ig = __expf(-G[cc]);
;           Qp[tok * 512 + c] = f2bf(bf2f(qr[st][cc][e]) * eg);
;           const u16 kk = f2bf((1.f - f) * ig);
;           Kp[tok * 512 + c] = kk;
;           kb[e] = kk;
;         }
;         const int s0 = dir ? 56 - 8 * j8 : 8 * j8;
;         uint4 w;
;         w.x = dir ? (kb[7] | (kb[6] << 16)) : (kb[0] | (kb[1] << 16));
;         w.y = dir ? (kb[5] | (kb[4] << 16)) : (kb[2] | (kb[3] << 16));
;         w.z = dir ? (kb[3] | (kb[2] << 16)) : (kb[4] | (kb[5] << 16));
;         w.w = dir ? (kb[1] | (kb[0] << 16)) : (kb[6] | (kb[7] << 16));
;         *(uint4*)(KT + (((size_t)cidx * 2 + dir) * 512 + c) * 64 + s0) = w;
	v_mul_f32_e32 v97, v97, v93
	v_mul_f32_e32 v98, v98, v94
	v_mul_f32_e32 v99, v99, v95
	v_lshlrev_b32_e32 v92, 16, v50
	v_and_b32_e32 v93, 0xffff0000, v50
	v_lshlrev_b32_e32 v94, 16, v51
	v_and_b32_e32 v95, 0xffff0000, v51
	v_mul_f32_e32 v92, v92, v100
	v_mul_f32_e32 v93, v93, v101
	v_mul_f32_e32 v94, v94, v102
	v_mul_f32_e32 v95, v95, v103
	v_mov_b32_e32 v125, v96
	v_mov_b32_e32 v141, v97
	v_mov_b32_e32 v175, v98
	v_mov_b32_e32 v191, v99
	v_cvt_pk_bf16_f32 v92, v92, v93
	v_cvt_pk_bf16_f32 v93, v94, v95
	v_cvt_pk_bf16_f32 v96, v96, v97
	v_cvt_pk_bf16_f32 v97, v98, v99
	global_store_dwordx2 v112, v[92:93], s[2:3]
	global_store_dwordx2 v114, v[96:97], s[2:3]
	s_sub_u32 s2, s2, 0x400
	s_subb_u32 s3, s3, 0
	v_lshlrev_b32_e32 v92, 16, v52
	v_and_b32_e32 v93, 0xffff0000, v52
	v_lshlrev_b32_e32 v94, 16, v53
	v_and_b32_e32 v95, 0xffff0000, v53
	v_mul_f32_e32 v92, 0xbfb8aa3b, v92
	v_mul_f32_e32 v93, 0xbfb8aa3b, v93
	v_mul_f32_e32 v94, 0xbfb8aa3b, v94
	v_mul_f32_e32 v95, 0xbfb8aa3b, v95
	v_exp_f32_e32 v92, v92
	v_exp_f32_e32 v93, v93
	v_exp_f32_e32 v94, v94
	v_exp_f32_e32 v95, v95
	v_add_f32_e32 v92, 1.0, v92
	v_add_f32_e32 v93, 1.0, v93
	v_add_f32_e32 v94, 1.0, v94
	v_add_f32_e32 v95, 1.0, v95
	v_rcp_f32_e32 v92, v92
	v_rcp_f32_e32 v93, v93
	v_rcp_f32_e32 v94, v94
	v_rcp_f32_e32 v95, v95
	v_fma_f32 v96, v72, v92, v68
	v_fma_f32 v97, v73, v93, v69
	v_fma_f32 v98, v74, v94, v70
	v_fma_f32 v99, v75, v95, v71
	v_cmp_gt_f32_e64 s[22:23], s30, v96
	v_cmp_gt_f32_e64 s[24:25], s30, v97
	v_cmp_gt_f32_e64 s[26:27], s30, v98
	v_cmp_gt_f32_e64 s[28:29], s30, v99
	v_cndmask_b32_e64 v92, 0, 32, s[22:23]
	v_cndmask_b32_e64 v93, 0, 32, s[24:25]
	v_cndmask_b32_e64 v94, 0, 32, s[26:27]
	v_cndmask_b32_e64 v95, 0, 32, s[28:29]
	v_ldexp_f32 v92, v96, v92
	v_ldexp_f32 v93, v97, v93
	v_ldexp_f32 v94, v98, v94
	v_ldexp_f32 v95, v99, v95
	v_log_f32_e32 v92, v92
	v_log_f32_e32 v93, v93
	v_log_f32_e32 v94, v94
	v_log_f32_e32 v95, v95
	v_mul_f32_e32 v100, 0x3f317217, v92
	v_mul_f32_e32 v101, 0x3f317217, v93
	v_mul_f32_e32 v102, 0x3f317217, v94
	v_mul_f32_e32 v103, 0x3f317217, v95
	v_fma_f32 v100, v92, s31, -v100
	v_fma_f32 v101, v93, s31, -v101
	v_fma_f32 v102, v94, s31, -v102
	v_fma_f32 v103, v95, s31, -v103
	v_fmac_f32_e32 v100, 0x3377d1cf, v92
	v_fmac_f32_e32 v101, 0x3377d1cf, v93
	v_fmac_f32_e32 v102, 0x3377d1cf, v94
	v_fmac_f32_e32 v103, 0x3377d1cf, v95
	v_fmac_f32_e32 v100, 0x3f317217, v92
	v_fmac_f32_e32 v101, 0x3f317217, v93
	v_fmac_f32_e32 v102, 0x3f317217, v94
	v_fmac_f32_e32 v103, 0x3f317217, v95
	v_cmp_lt_f32_e64 vcc, |v92|, s34
	v_cndmask_b32_e32 v92, v92, v100, vcc
	v_cmp_lt_f32_e64 vcc, |v93|, s34
	v_cndmask_b32_e32 v93, v93, v101, vcc
	v_cmp_lt_f32_e64 vcc, |v94|, s34
	v_cndmask_b32_e32 v94, v94, v102, vcc
	v_cmp_lt_f32_e64 vcc, |v95|, s34
	v_cndmask_b32_e32 v95, v95, v103, vcc
	v_cndmask_b32_e64 v100, 0, v213, s[22:23]
	v_cndmask_b32_e64 v101, 0, v213, s[24:25]
	v_cndmask_b32_e64 v102, 0, v213, s[26:27]
	v_cndmask_b32_e64 v103, 0, v213, s[28:29]
	v_sub_f32_e32 v92, v92, v100
	v_sub_f32_e32 v93, v93, v101
	v_sub_f32_e32 v94, v94, v102
	v_sub_f32_e32 v95, v95, v103
	v_add_f32_e32 v64, v64, v92
	v_add_f32_e32 v65, v65, v93
	v_add_f32_e32 v66, v66, v94
	v_add_f32_e32 v67, v67, v95
	v_mul_f32_e32 v92, 0xbfb8aa3b, v64
	v_mul_f32_e32 v93, 0xbfb8aa3b, v65
	v_mul_f32_e32 v94, 0xbfb8aa3b, v66
	v_mul_f32_e32 v95, 0xbfb8aa3b, v67
	v_mul_f32_e32 v100, 0x3fb8aa3b, v64
	v_mul_f32_e32 v101, 0x3fb8aa3b, v65
	v_mul_f32_e32 v102, 0x3fb8aa3b, v66
	v_mul_f32_e32 v103, 0x3fb8aa3b, v67
	v_exp_f32_e32 v92, v92
	v_exp_f32_e32 v93, v93
	v_exp_f32_e32 v94, v94
	v_exp_f32_e32 v95, v95
	v_exp_f32_e32 v100, v100
	v_exp_f32_e32 v101, v101
	v_exp_f32_e32 v102, v102
	v_exp_f32_e32 v103, v103
	v_sub_f32_e32 v96, 1.0, v96
	v_sub_f32_e32 v97, 1.0, v97
	v_sub_f32_e32 v98, 1.0, v98
	v_sub_f32_e32 v99, 1.0, v99
	v_mul_f32_e32 v96, v96, v92
	v_mul_f32_e32 v97, v97, v93
	v_mul_f32_e32 v98, v98, v94
	v_mul_f32_e32 v99, v99, v95
	v_lshlrev_b32_e32 v92, 16, v54
	v_and_b32_e32 v93, 0xffff0000, v54
	v_lshlrev_b32_e32 v94, 16, v55
	v_and_b32_e32 v95, 0xffff0000, v55
	v_mul_f32_e32 v92, v92, v100
	v_mul_f32_e32 v93, v93, v101
	v_mul_f32_e32 v94, v94, v102
	v_mul_f32_e32 v95, v95, v103
	v_cvt_pk_bf16_f32 v125, v96, v125
	v_cvt_pk_bf16_f32 v141, v97, v141
	v_cvt_pk_bf16_f32 v175, v98, v175
	v_cvt_pk_bf16_f32 v191, v99, v191
	v_cvt_pk_bf16_f32 v92, v92, v93
	v_cvt_pk_bf16_f32 v93, v94, v95
	v_cvt_pk_bf16_f32 v96, v96, v97
	v_cvt_pk_bf16_f32 v97, v98, v99
	global_store_dwordx2 v112, v[92:93], s[2:3]
	global_store_dwordx2 v114, v[96:97], s[2:3]
	s_sub_u32 s2, s2, 0x400
	s_subb_u32 s3, s3, 0
	v_lshlrev_b32_e32 v92, 16, v56
	v_and_b32_e32 v93, 0xffff0000, v56
	v_lshlrev_b32_e32 v94, 16, v57
	v_and_b32_e32 v95, 0xffff0000, v57
	v_mul_f32_e32 v92, 0xbfb8aa3b, v92
	v_mul_f32_e32 v93, 0xbfb8aa3b, v93
	v_mul_f32_e32 v94, 0xbfb8aa3b, v94
	v_mul_f32_e32 v95, 0xbfb8aa3b, v95
	v_exp_f32_e32 v92, v92
	v_exp_f32_e32 v93, v93
	v_exp_f32_e32 v94, v94
	v_exp_f32_e32 v95, v95
	v_add_f32_e32 v92, 1.0, v92
	v_add_f32_e32 v93, 1.0, v93
	v_add_f32_e32 v94, 1.0, v94
	v_add_f32_e32 v95, 1.0, v95
	v_rcp_f32_e32 v92, v92
	v_rcp_f32_e32 v93, v93
	v_rcp_f32_e32 v94, v94
	v_rcp_f32_e32 v95, v95
	v_fma_f32 v96, v72, v92, v68
	v_fma_f32 v97, v73, v93, v69
	v_fma_f32 v98, v74, v94, v70
	v_fma_f32 v99, v75, v95, v71
	v_cmp_gt_f32_e64 s[22:23], s30, v96
	v_cmp_gt_f32_e64 s[24:25], s30, v97
	v_cmp_gt_f32_e64 s[26:27], s30, v98
	v_cmp_gt_f32_e64 s[28:29], s30, v99
	v_cndmask_b32_e64 v92, 0, 32, s[22:23]
	v_cndmask_b32_e64 v93, 0, 32, s[24:25]
	v_cndmask_b32_e64 v94, 0, 32, s[26:27]
	v_cndmask_b32_e64 v95, 0, 32, s[28:29]
	v_ldexp_f32 v92, v96, v92
; DEV u16 f2bf(float f) { return (u16)(pack2(f, f) & 0xffffu); }
; DEV float bf2f(u16 h) { return __uint_as_float(((unsigned)h) << 16); }
; DEV float sigmoid_f(float x) { return __builtin_amdgcn_rcpf(1.f + __expf(-x)); }
; DEV void phase_p15(const Params& p, int g) {
;     ...
;         for (int e = 0; e < 8; ++e) {
;           const int jj = j8 * 8 + e;
;           const int j = dir ? 63 - jj : jj;
;           const size_t tok = (size_t)cidx * 64 + j;
;           const float f = lb[cc] + (1.f - lb[cc]) * sigmoid_f(bf2f(xr[st][cc][e]));
;           G[cc] += __logf(f);
;           const float eg = __expf(G[cc]), ig = __expf(-G[cc]);
;           Qp[tok * 512 + c] = f2bf(bf2f(qr[st][cc][e]) * eg);
;           const u16 kk = f2bf((1.f - f) * ig);
;           Kp[tok * 512 + c] = kk;
;           kb[e] = kk;
;         }
;         const int s0 = dir ? 56 - 8 * j8 : 8 * j8;
;         uint4 w;
;         w.x = dir ? (kb[7] | (kb[6] << 16)) : (kb[0] | (kb[1] << 16));
;         w.y = dir ? (kb[5] | (kb[4] << 16)) : (kb[2] | (kb[3] << 16));
;         w.z = dir ? (kb[3] | (kb[2] << 16)) : (kb[4] | (kb[5] << 16));
;         w.w = dir ? (kb[1] | (kb[0] << 16)) : (kb[6] | (kb[7] << 16));
;         *(uint4*)(KT + (((size_t)cidx * 2 + dir) * 512 + c) * 64 + s0) = w;
	v_ldexp_f32 v93, v97, v93
	v_ldexp_f32 v94, v98, v94
	v_ldexp_f32 v95, v99, v95
	v_log_f32_e32 v92, v92
	v_log_f32_e32 v93, v93
	v_log_f32_e32 v94, v94
	v_log_f32_e32 v95, v95
	v_mul_f32_e32 v100, 0x3f317217, v92
	v_mul_f32_e32 v101, 0x3f317217, v93
	v_mul_f32_e32 v102, 0x3f317217, v94
	v_mul_f32_e32 v103, 0x3f317217, v95
	v_fma_f32 v100, v92, s31, -v100
	v_fma_f32 v101, v93, s31, -v101
	v_fma_f32 v102, v94, s31, -v102
	v_fma_f32 v103, v95, s31, -v103
	v_fmac_f32_e32 v100, 0x3377d1cf, v92
	v_fmac_f32_e32 v101, 0x3377d1cf, v93
	v_fmac_f32_e32 v102, 0x3377d1cf, v94
	v_fmac_f32_e32 v103, 0x3377d1cf, v95
	v_fmac_f32_e32 v100, 0x3f317217, v92
	v_fmac_f32_e32 v101, 0x3f317217, v93
	v_fmac_f32_e32 v102, 0x3f317217, v94
	v_fmac_f32_e32 v103, 0x3f317217, v95
	v_cmp_lt_f32_e64 vcc, |v92|, s34
	v_cndmask_b32_e32 v92, v92, v100, vcc
	v_cmp_lt_f32_e64 vcc, |v93|, s34
	v_cndmask_b32_e32 v93, v93, v101, vcc
	v_cmp_lt_f32_e64 vcc, |v94|, s34
	v_cndmask_b32_e32 v94, v94, v102, vcc
	v_cmp_lt_f32_e64 vcc, |v95|, s34
	v_cndmask_b32_e32 v95, v95, v103, vcc
	v_cndmask_b32_e64 v100, 0, v213, s[22:23]
	v_cndmask_b32_e64 v101, 0, v213, s[24:25]
	v_cndmask_b32_e64 v102, 0, v213, s[26:27]
	v_cndmask_b32_e64 v103, 0, v213, s[28:29]
	v_sub_f32_e32 v92, v92, v100
	v_sub_f32_e32 v93, v93, v101
	v_sub_f32_e32 v94, v94, v102
	v_sub_f32_e32 v95, v95, v103
	v_add_f32_e32 v64, v64, v92
	v_add_f32_e32 v65, v65, v93
	v_add_f32_e32 v66, v66, v94
	v_add_f32_e32 v67, v67, v95
	v_mul_f32_e32 v92, 0xbfb8aa3b, v64
	v_mul_f32_e32 v93, 0xbfb8aa3b, v65
	v_mul_f32_e32 v94, 0xbfb8aa3b, v66
	v_mul_f32_e32 v95, 0xbfb8aa3b, v67
	v_mul_f32_e32 v100, 0x3fb8aa3b, v64
	v_mul_f32_e32 v101, 0x3fb8aa3b, v65
	v_mul_f32_e32 v102, 0x3fb8aa3b, v66
	v_mul_f32_e32 v103, 0x3fb8aa3b, v67
	v_exp_f32_e32 v92, v92
	v_exp_f32_e32 v93, v93
	v_exp_f32_e32 v94, v94
	v_exp_f32_e32 v95, v95
	v_exp_f32_e32 v100, v100
	v_exp_f32_e32 v101, v101
	v_exp_f32_e32 v102, v102
	v_exp_f32_e32 v103, v103
	v_sub_f32_e32 v96, 1.0, v96
	v_sub_f32_e32 v97, 1.0, v97
	v_sub_f32_e32 v98, 1.0, v98
	v_sub_f32_e32 v99, 1.0, v99
	v_mul_f32_e32 v96, v96, v92
	v_mul_f32_e32 v97, v97, v93
	v_mul_f32_e32 v98, v98, v94
	v_mul_f32_e32 v99, v99, v95
	v_lshlrev_b32_e32 v92, 16, v58
	v_and_b32_e32 v93, 0xffff0000, v58
	v_lshlrev_b32_e32 v94, 16, v59
	v_and_b32_e32 v95, 0xffff0000, v59
	v_mul_f32_e32 v92, v92, v100
	v_mul_f32_e32 v93, v93, v101
	v_mul_f32_e32 v94, v94, v102
	v_mul_f32_e32 v95, v95, v103
	v_mov_b32_e32 v124, v96
	v_mov_b32_e32 v140, v97
	v_mov_b32_e32 v174, v98
	v_mov_b32_e32 v190, v99
	v_cvt_pk_bf16_f32 v92, v92, v93
	v_cvt_pk_bf16_f32 v93, v94, v95
	v_cvt_pk_bf16_f32 v96, v96, v97
	v_cvt_pk_bf16_f32 v97, v98, v99
	global_store_dwordx2 v112, v[92:93], s[2:3]
	global_store_dwordx2 v114, v[96:97], s[2:3]
	s_sub_u32 s2, s2, 0x400
	s_subb_u32 s3, s3, 0
	v_lshlrev_b32_e32 v92, 16, v60
	v_and_b32_e32 v93, 0xffff0000, v60
	v_lshlrev_b32_e32 v94, 16, v61
	v_and_b32_e32 v95, 0xffff0000, v61
	v_mul_f32_e32 v92, 0xbfb8aa3b, v92
	v_mul_f32_e32 v93, 0xbfb8aa3b, v93
	v_mul_f32_e32 v94, 0xbfb8aa3b, v94
	v_mul_f32_e32 v95, 0xbfb8aa3b, v95
	v_exp_f32_e32 v92, v92
	v_exp_f32_e32 v93, v93
	v_exp_f32_e32 v94, v94
	v_exp_f32_e32 v95, v95
	v_add_f32_e32 v92, 1.0, v92
	v_add_f32_e32 v93, 1.0, v93
	v_add_f32_e32 v94, 1.0, v94
	v_add_f32_e32 v95, 1.0, v95
	v_rcp_f32_e32 v92, v92
	v_rcp_f32_e32 v93, v93
	v_rcp_f32_e32 v94, v94
	v_rcp_f32_e32 v95, v95
	v_fma_f32 v96, v72, v92, v68
	v_fma_f32 v97, v73, v93, v69
	v_fma_f32 v98, v74, v94, v70
	v_fma_f32 v99, v75, v95, v71
	v_cmp_gt_f32_e64 s[22:23], s30, v96
	v_cmp_gt_f32_e64 s[24:25], s30, v97
	v_cmp_gt_f32_e64 s[26:27], s30, v98
	v_cmp_gt_f32_e64 s[28:29], s30, v99
	v_cndmask_b32_e64 v92, 0, 32, s[22:23]
	v_cndmask_b32_e64 v93, 0, 32, s[24:25]
	v_cndmask_b32_e64 v94, 0, 32, s[26:27]
	v_cndmask_b32_e64 v95, 0, 32, s[28:29]
	v_ldexp_f32 v92, v96, v92
	v_ldexp_f32 v93, v97, v93
	v_ldexp_f32 v94, v98, v94
	v_ldexp_f32 v95, v99, v95
	v_log_f32_e32 v92, v92
	v_log_f32_e32 v93, v93
	v_log_f32_e32 v94, v94
	v_log_f32_e32 v95, v95
	v_mul_f32_e32 v100, 0x3f317217, v92
	v_mul_f32_e32 v101, 0x3f317217, v93
	v_mul_f32_e32 v102, 0x3f317217, v94
	v_mul_f32_e32 v103, 0x3f317217, v95
	v_fma_f32 v100, v92, s31, -v100
	v_fma_f32 v101, v93, s31, -v101
	v_fma_f32 v102, v94, s31, -v102
	v_fma_f32 v103, v95, s31, -v103
	v_fmac_f32_e32 v100, 0x3377d1cf, v92
	v_fmac_f32_e32 v101, 0x3377d1cf, v93
	v_fmac_f32_e32 v102, 0x3377d1cf, v94
	v_fmac_f32_e32 v103, 0x3377d1cf, v95
	v_fmac_f32_e32 v100, 0x3f317217, v92
	v_fmac_f32_e32 v101, 0x3f317217, v93
	v_fmac_f32_e32 v102, 0x3f317217, v94
	v_fmac_f32_e32 v103, 0x3f317217, v95
	v_cmp_lt_f32_e64 vcc, |v92|, s34
	v_cndmask_b32_e32 v92, v92, v100, vcc
	v_cmp_lt_f32_e64 vcc, |v93|, s34
	v_cndmask_b32_e32 v93, v93, v101, vcc
	v_cmp_lt_f32_e64 vcc, |v94|, s34
	v_cndmask_b32_e32 v94, v94, v102, vcc
	v_cmp_lt_f32_e64 vcc, |v95|, s34
	v_cndmask_b32_e32 v95, v95, v103, vcc
	v_cndmask_b32_e64 v100, 0, v213, s[22:23]
	v_cndmask_b32_e64 v101, 0, v213, s[24:25]
	v_cndmask_b32_e64 v102, 0, v213, s[26:27]
	v_cndmask_b32_e64 v103, 0, v213, s[28:29]
	v_sub_f32_e32 v92, v92, v100
	v_sub_f32_e32 v93, v93, v101
	v_sub_f32_e32 v94, v94, v102
	v_sub_f32_e32 v95, v95, v103
	v_add_f32_e32 v64, v64, v92
	v_add_f32_e32 v65, v65, v93
	v_add_f32_e32 v66, v66, v94
	v_add_f32_e32 v67, v67, v95
	v_mul_f32_e32 v92, 0xbfb8aa3b, v64
	v_mul_f32_e32 v93, 0xbfb8aa3b, v65
	v_mul_f32_e32 v94, 0xbfb8aa3b, v66
	v_mul_f32_e32 v95, 0xbfb8aa3b, v67
	v_mul_f32_e32 v100, 0x3fb8aa3b, v64
	v_mul_f32_e32 v101, 0x3fb8aa3b, v65
	v_mul_f32_e32 v102, 0x3fb8aa3b, v66
	v_mul_f32_e32 v103, 0x3fb8aa3b, v67
	v_exp_f32_e32 v92, v92
; DEV u16 f2bf(float f) { return (u16)(pack2(f, f) & 0xffffu); }
; DEV float bf2f(u16 h) { return __uint_as_float(((unsigned)h) << 16); }
; DEV float sigmoid_f(float x) { return __builtin_amdgcn_rcpf(1.f + __expf(-x)); }
; DEV void phase_p15(const Params& p, int g) {
;     ...
;         for (int e = 0; e < 8; ++e) {
;           const int jj = j8 * 8 + e;
;           const int j = dir ? 63 - jj : jj;
;           const size_t tok = (size_t)cidx * 64 + j;
;           const float f = lb[cc] + (1.f - lb[cc]) * sigmoid_f(bf2f(xr[st][cc][e]));
;           G[cc] += __logf(f);
;           const float eg = __expf(G[cc]), ig = __expf(-G[cc]);
;           Qp[tok * 512 + c] = f2bf(bf2f(qr[st][cc][e]) * eg);
;           const u16 kk = f2bf((1.f - f) * ig);
;           Kp[tok * 512 + c] = kk;
;           kb[e] = kk;
;         }
;         const int s0 = dir ? 56 - 8 * j8 : 8 * j8;
;         uint4 w;
;         w.x = dir ? (kb[7] | (kb[6] << 16)) : (kb[0] | (kb[1] << 16));
;         w.y = dir ? (kb[5] | (kb[4] << 16)) : (kb[2] | (kb[3] << 16));
;         w.z = dir ? (kb[3] | (kb[2] << 16)) : (kb[4] | (kb[5] << 16));
;         w.w = dir ? (kb[1] | (kb[0] << 16)) : (kb[6] | (kb[7] << 16));
;         *(uint4*)(KT + (((size_t)cidx * 2 + dir) * 512 + c) * 64 + s0) = w;
	v_exp_f32_e32 v93, v93
	v_exp_f32_e32 v94, v94
	v_exp_f32_e32 v95, v95
	v_exp_f32_e32 v100, v100
	v_exp_f32_e32 v101, v101
	v_exp_f32_e32 v102, v102
	v_exp_f32_e32 v103, v103
	v_sub_f32_e32 v96, 1.0, v96
	v_sub_f32_e32 v97, 1.0, v97
	v_sub_f32_e32 v98, 1.0, v98
	v_sub_f32_e32 v99, 1.0, v99
	v_mul_f32_e32 v96, v96, v92
	v_mul_f32_e32 v97, v97, v93
	v_mul_f32_e32 v98, v98, v94
	v_mul_f32_e32 v99, v99, v95
	v_lshlrev_b32_e32 v92, 16, v62
	v_and_b32_e32 v93, 0xffff0000, v62
	v_lshlrev_b32_e32 v94, 16, v63
	v_and_b32_e32 v95, 0xffff0000, v63
	v_mul_f32_e32 v92, v92, v100
	v_mul_f32_e32 v93, v93, v101
	v_mul_f32_e32 v94, v94, v102
	v_mul_f32_e32 v95, v95, v103
	v_cvt_pk_bf16_f32 v124, v96, v124
	v_cvt_pk_bf16_f32 v140, v97, v140
	v_cvt_pk_bf16_f32 v174, v98, v174
	v_cvt_pk_bf16_f32 v190, v99, v190
	v_cvt_pk_bf16_f32 v92, v92, v93
	v_cvt_pk_bf16_f32 v93, v94, v95
	v_cvt_pk_bf16_f32 v96, v96, v97
	v_cvt_pk_bf16_f32 v97, v98, v99
	global_store_dwordx2 v112, v[92:93], s[2:3]
	global_store_dwordx2 v114, v[96:97], s[2:3]
	s_sub_u32 s2, s2, 0x400
	s_subb_u32 s3, s3, 0
	global_load_dwordx2 v[32:33], v113, s[0:1]
	global_load_dwordx2 v[34:35], v112, s[0:1]
	s_sub_u32 s0, s0, 0x1400
	s_subb_u32 s1, s1, 0
	global_load_dwordx2 v[36:37], v113, s[0:1]
	global_load_dwordx2 v[38:39], v112, s[0:1]
	s_sub_u32 s0, s0, 0x1400
	s_subb_u32 s1, s1, 0
	global_load_dwordx2 v[40:41], v113, s[0:1]
	global_load_dwordx2 v[42:43], v112, s[0:1]
	s_sub_u32 s0, s0, 0x1400
	s_subb_u32 s1, s1, 0
	global_load_dwordx2 v[44:45], v113, s[0:1]
	global_load_dwordx2 v[46:47], v112, s[0:1]
	s_sub_u32 s0, s0, 0x1400
	s_subb_u32 s1, s1, 0
	global_load_dwordx2 v[48:49], v113, s[0:1]
	global_load_dwordx2 v[50:51], v112, s[0:1]
	s_sub_u32 s0, s0, 0x1400
	s_subb_u32 s1, s1, 0
	global_load_dwordx2 v[52:53], v113, s[0:1]
	global_load_dwordx2 v[54:55], v112, s[0:1]
	s_sub_u32 s0, s0, 0x1400
	s_subb_u32 s1, s1, 0
	global_load_dwordx2 v[56:57], v113, s[0:1]
	global_load_dwordx2 v[58:59], v112, s[0:1]
	s_sub_u32 s0, s0, 0x1400
	s_subb_u32 s1, s1, 0
	global_load_dwordx2 v[60:61], v113, s[0:1]
	global_load_dwordx2 v[62:63], v112, s[0:1]
	s_sub_u32 s0, s0, 0x1400
	s_subb_u32 s1, s1, 0
	s_waitcnt vmcnt(32)
	v_lshlrev_b32_e32 v92, 16, v0
	v_and_b32_e32 v93, 0xffff0000, v0
	v_lshlrev_b32_e32 v94, 16, v1
	v_and_b32_e32 v95, 0xffff0000, v1
	v_mul_f32_e32 v92, 0xbfb8aa3b, v92
	v_mul_f32_e32 v93, 0xbfb8aa3b, v93
	v_mul_f32_e32 v94, 0xbfb8aa3b, v94
	v_mul_f32_e32 v95, 0xbfb8aa3b, v95
	v_exp_f32_e32 v92, v92
	v_exp_f32_e32 v93, v93
	v_exp_f32_e32 v94, v94
	v_exp_f32_e32 v95, v95
	v_add_f32_e32 v92, 1.0, v92
	v_add_f32_e32 v93, 1.0, v93
	v_add_f32_e32 v94, 1.0, v94
	v_add_f32_e32 v95, 1.0, v95
	v_rcp_f32_e32 v92, v92
	v_rcp_f32_e32 v93, v93
	v_rcp_f32_e32 v94, v94
	v_rcp_f32_e32 v95, v95
	v_fma_f32 v96, v72, v92, v68
	v_fma_f32 v97, v73, v93, v69
	v_fma_f32 v98, v74, v94, v70
	v_fma_f32 v99, v75, v95, v71
	v_cmp_gt_f32_e64 s[22:23], s30, v96
	v_cmp_gt_f32_e64 s[24:25], s30, v97
	v_cmp_gt_f32_e64 s[26:27], s30, v98
	v_cmp_gt_f32_e64 s[28:29], s30, v99
	v_cndmask_b32_e64 v92, 0, 32, s[22:23]
	v_cndmask_b32_e64 v93, 0, 32, s[24:25]
	v_cndmask_b32_e64 v94, 0, 32, s[26:27]
	v_cndmask_b32_e64 v95, 0, 32, s[28:29]
	v_ldexp_f32 v92, v96, v92
	v_ldexp_f32 v93, v97, v93
	v_ldexp_f32 v94, v98, v94
	v_ldexp_f32 v95, v99, v95
	v_log_f32_e32 v92, v92
	v_log_f32_e32 v93, v93
	v_log_f32_e32 v94, v94
	v_log_f32_e32 v95, v95
	v_mul_f32_e32 v100, 0x3f317217, v92
	v_mul_f32_e32 v101, 0x3f317217, v93
	v_mul_f32_e32 v102, 0x3f317217, v94
	v_mul_f32_e32 v103, 0x3f317217, v95
	v_fma_f32 v100, v92, s31, -v100
	v_fma_f32 v101, v93, s31, -v101
	v_fma_f32 v102, v94, s31, -v102
	v_fma_f32 v103, v95, s31, -v103
	v_fmac_f32_e32 v100, 0x3377d1cf, v92
	v_fmac_f32_e32 v101, 0x3377d1cf, v93
	v_fmac_f32_e32 v102, 0x3377d1cf, v94
	v_fmac_f32_e32 v103, 0x3377d1cf, v95
	v_fmac_f32_e32 v100, 0x3f317217, v92
	v_fmac_f32_e32 v101, 0x3f317217, v93
	v_fmac_f32_e32 v102, 0x3f317217, v94
	v_fmac_f32_e32 v103, 0x3f317217, v95
	v_cmp_lt_f32_e64 vcc, |v92|, s34
	v_cndmask_b32_e32 v92, v92, v100, vcc
	v_cmp_lt_f32_e64 vcc, |v93|, s34
	v_cndmask_b32_e32 v93, v93, v101, vcc
	v_cmp_lt_f32_e64 vcc, |v94|, s34
	v_cndmask_b32_e32 v94, v94, v102, vcc
	v_cmp_lt_f32_e64 vcc, |v95|, s34
	v_cndmask_b32_e32 v95, v95, v103, vcc
	v_cndmask_b32_e64 v100, 0, v213, s[22:23]
	v_cndmask_b32_e64 v101, 0, v213, s[24:25]
	v_cndmask_b32_e64 v102, 0, v213, s[26:27]
	v_cndmask_b32_e64 v103, 0, v213, s[28:29]
	v_sub_f32_e32 v92, v92, v100
	v_sub_f32_e32 v93, v93, v101
	v_sub_f32_e32 v94, v94, v102
	v_sub_f32_e32 v95, v95, v103
	v_add_f32_e32 v64, v64, v92
	v_add_f32_e32 v65, v65, v93
	v_add_f32_e32 v66, v66, v94
	v_add_f32_e32 v67, v67, v95
	v_mul_f32_e32 v92, 0xbfb8aa3b, v64
	v_mul_f32_e32 v93, 0xbfb8aa3b, v65
	v_mul_f32_e32 v94, 0xbfb8aa3b, v66
	v_mul_f32_e32 v95, 0xbfb8aa3b, v67
	v_mul_f32_e32 v100, 0x3fb8aa3b, v64
	v_mul_f32_e32 v101, 0x3fb8aa3b, v65
	v_mul_f32_e32 v102, 0x3fb8aa3b, v66
	v_mul_f32_e32 v103, 0x3fb8aa3b, v67
	v_exp_f32_e32 v92, v92
	v_exp_f32_e32 v93, v93
	v_exp_f32_e32 v94, v94
	v_exp_f32_e32 v95, v95
	v_exp_f32_e32 v100, v100
	v_exp_f32_e32 v101, v101
	v_exp_f32_e32 v102, v102
	v_exp_f32_e32 v103, v103
	v_sub_f32_e32 v96, 1.0, v96
	v_sub_f32_e32 v97, 1.0, v97
	v_sub_f32_e32 v98, 1.0, v98
	v_sub_f32_e32 v99, 1.0, v99
	v_mul_f32_e32 v96, v96, v92
	v_mul_f32_e32 v97, v97, v93
	v_mul_f32_e32 v98, v98, v94
	v_mul_f32_e32 v99, v99, v95
	v_lshlrev_b32_e32 v92, 16, v2
	v_and_b32_e32 v93, 0xffff0000, v2
	v_lshlrev_b32_e32 v94, 16, v3
	v_and_b32_e32 v95, 0xffff0000, v3
	v_mul_f32_e32 v92, v92, v100
	v_mul_f32_e32 v93, v93, v101
	v_mul_f32_e32 v94, v94, v102
; DEV u16 f2bf(float f) { return (u16)(pack2(f, f) & 0xffffu); }
; DEV float bf2f(u16 h) { return __uint_as_float(((unsigned)h) << 16); }
; DEV float sigmoid_f(float x) { return __builtin_amdgcn_rcpf(1.f + __expf(-x)); }
; DEV void phase_p15(const Params& p, int g) {
;     ...
;         for (int e = 0; e < 8; ++e) {
;           const int jj = j8 * 8 + e;
;           const int j = dir ? 63 - jj : jj;
;           const size_t tok = (size_t)cidx * 64 + j;
;           const float f = lb[cc] + (1.f - lb[cc]) * sigmoid_f(bf2f(xr[st][cc][e]));
;           G[cc] += __logf(f);
;           const float eg = __expf(G[cc]), ig = __expf(-G[cc]);
;           Qp[tok * 512 + c] = f2bf(bf2f(qr[st][cc][e]) * eg);
;           const u16 kk = f2bf((1.f - f) * ig);
;           Kp[tok * 512 + c] = kk;
;           kb[e] = kk;
;         }
;         const int s0 = dir ? 56 - 8 * j8 : 8 * j8;
;         uint4 w;
;         w.x = dir ? (kb[7] | (kb[6] << 16)) : (kb[0] | (kb[1] << 16));
;         w.y = dir ? (kb[5] | (kb[4] << 16)) : (kb[2] | (kb[3] << 16));
;         w.z = dir ? (kb[3] | (kb[2] << 16)) : (kb[4] | (kb[5] << 16));
;         w.w = dir ? (kb[1] | (kb[0] << 16)) : (kb[6] | (kb[7] << 16));
;         *(uint4*)(KT + (((size_t)cidx * 2 + dir) * 512 + c) * 64 + s0) = w;
	v_mul_f32_e32 v95, v95, v103
	v_mov_b32_e32 v123, v96
	v_mov_b32_e32 v139, v97
	v_mov_b32_e32 v173, v98
	v_mov_b32_e32 v189, v99
	v_cvt_pk_bf16_f32 v92, v92, v93
	v_cvt_pk_bf16_f32 v93, v94, v95
	v_cvt_pk_bf16_f32 v96, v96, v97
	v_cvt_pk_bf16_f32 v97, v98, v99
	global_store_dwordx2 v112, v[92:93], s[2:3]
	global_store_dwordx2 v114, v[96:97], s[2:3]
	s_sub_u32 s2, s2, 0x400
	s_subb_u32 s3, s3, 0
	v_lshlrev_b32_e32 v92, 16, v4
	v_and_b32_e32 v93, 0xffff0000, v4
	v_lshlrev_b32_e32 v94, 16, v5
	v_and_b32_e32 v95, 0xffff0000, v5
	v_mul_f32_e32 v92, 0xbfb8aa3b, v92
	v_mul_f32_e32 v93, 0xbfb8aa3b, v93
	v_mul_f32_e32 v94, 0xbfb8aa3b, v94
	v_mul_f32_e32 v95, 0xbfb8aa3b, v95
	v_exp_f32_e32 v92, v92
	v_exp_f32_e32 v93, v93
	v_exp_f32_e32 v94, v94
	v_exp_f32_e32 v95, v95
	v_add_f32_e32 v92, 1.0, v92
	v_add_f32_e32 v93, 1.0, v93
	v_add_f32_e32 v94, 1.0, v94
	v_add_f32_e32 v95, 1.0, v95
	v_rcp_f32_e32 v92, v92
	v_rcp_f32_e32 v93, v93
	v_rcp_f32_e32 v94, v94
	v_rcp_f32_e32 v95, v95
	v_fma_f32 v96, v72, v92, v68
	v_fma_f32 v97, v73, v93, v69
	v_fma_f32 v98, v74, v94, v70
	v_fma_f32 v99, v75, v95, v71
	v_cmp_gt_f32_e64 s[22:23], s30, v96
	v_cmp_gt_f32_e64 s[24:25], s30, v97
	v_cmp_gt_f32_e64 s[26:27], s30, v98
	v_cmp_gt_f32_e64 s[28:29], s30, v99
	v_cndmask_b32_e64 v92, 0, 32, s[22:23]
	v_cndmask_b32_e64 v93, 0, 32, s[24:25]
	v_cndmask_b32_e64 v94, 0, 32, s[26:27]
	v_cndmask_b32_e64 v95, 0, 32, s[28:29]
	v_ldexp_f32 v92, v96, v92
	v_ldexp_f32 v93, v97, v93
	v_ldexp_f32 v94, v98, v94
	v_ldexp_f32 v95, v99, v95
	v_log_f32_e32 v92, v92
	v_log_f32_e32 v93, v93
	v_log_f32_e32 v94, v94
	v_log_f32_e32 v95, v95
	v_mul_f32_e32 v100, 0x3f317217, v92
	v_mul_f32_e32 v101, 0x3f317217, v93
	v_mul_f32_e32 v102, 0x3f317217, v94
	v_mul_f32_e32 v103, 0x3f317217, v95
	v_fma_f32 v100, v92, s31, -v100
	v_fma_f32 v101, v93, s31, -v101
	v_fma_f32 v102, v94, s31, -v102
	v_fma_f32 v103, v95, s31, -v103
	v_fmac_f32_e32 v100, 0x3377d1cf, v92
	v_fmac_f32_e32 v101, 0x3377d1cf, v93
	v_fmac_f32_e32 v102, 0x3377d1cf, v94
	v_fmac_f32_e32 v103, 0x3377d1cf, v95
	v_fmac_f32_e32 v100, 0x3f317217, v92
	v_fmac_f32_e32 v101, 0x3f317217, v93
	v_fmac_f32_e32 v102, 0x3f317217, v94
	v_fmac_f32_e32 v103, 0x3f317217, v95
	v_cmp_lt_f32_e64 vcc, |v92|, s34
	v_cndmask_b32_e32 v92, v92, v100, vcc
	v_cmp_lt_f32_e64 vcc, |v93|, s34
	v_cndmask_b32_e32 v93, v93, v101, vcc
	v_cmp_lt_f32_e64 vcc, |v94|, s34
	v_cndmask_b32_e32 v94, v94, v102, vcc
	v_cmp_lt_f32_e64 vcc, |v95|, s34
	v_cndmask_b32_e32 v95, v95, v103, vcc
	v_cndmask_b32_e64 v100, 0, v213, s[22:23]
	v_cndmask_b32_e64 v101, 0, v213, s[24:25]
	v_cndmask_b32_e64 v102, 0, v213, s[26:27]
	v_cndmask_b32_e64 v103, 0, v213, s[28:29]
	v_sub_f32_e32 v92, v92, v100
	v_sub_f32_e32 v93, v93, v101
	v_sub_f32_e32 v94, v94, v102
	v_sub_f32_e32 v95, v95, v103
	v_add_f32_e32 v64, v64, v92
	v_add_f32_e32 v65, v65, v93
	v_add_f32_e32 v66, v66, v94
	v_add_f32_e32 v67, v67, v95
	v_mul_f32_e32 v92, 0xbfb8aa3b, v64
	v_mul_f32_e32 v93, 0xbfb8aa3b, v65
	v_mul_f32_e32 v94, 0xbfb8aa3b, v66
	v_mul_f32_e32 v95, 0xbfb8aa3b, v67
	v_mul_f32_e32 v100, 0x3fb8aa3b, v64
	v_mul_f32_e32 v101, 0x3fb8aa3b, v65
	v_mul_f32_e32 v102, 0x3fb8aa3b, v66
	v_mul_f32_e32 v103, 0x3fb8aa3b, v67
	v_exp_f32_e32 v92, v92
	v_exp_f32_e32 v93, v93
	v_exp_f32_e32 v94, v94
	v_exp_f32_e32 v95, v95
	v_exp_f32_e32 v100, v100
	v_exp_f32_e32 v101, v101
	v_exp_f32_e32 v102, v102
	v_exp_f32_e32 v103, v103
	v_sub_f32_e32 v96, 1.0, v96
	v_sub_f32_e32 v97, 1.0, v97
	v_sub_f32_e32 v98, 1.0, v98
	v_sub_f32_e32 v99, 1.0, v99
	v_mul_f32_e32 v96, v96, v92
	v_mul_f32_e32 v97, v97, v93
	v_mul_f32_e32 v98, v98, v94
	v_mul_f32_e32 v99, v99, v95
	v_lshlrev_b32_e32 v92, 16, v6
	v_and_b32_e32 v93, 0xffff0000, v6
	v_lshlrev_b32_e32 v94, 16, v7
	v_and_b32_e32 v95, 0xffff0000, v7
	v_mul_f32_e32 v92, v92, v100
	v_mul_f32_e32 v93, v93, v101
	v_mul_f32_e32 v94, v94, v102
	v_mul_f32_e32 v95, v95, v103
	v_cvt_pk_bf16_f32 v123, v96, v123
	v_cvt_pk_bf16_f32 v139, v97, v139
	v_cvt_pk_bf16_f32 v173, v98, v173
	v_cvt_pk_bf16_f32 v189, v99, v189
	v_cvt_pk_bf16_f32 v92, v92, v93
	v_cvt_pk_bf16_f32 v93, v94, v95
	v_cvt_pk_bf16_f32 v96, v96, v97
	v_cvt_pk_bf16_f32 v97, v98, v99
	global_store_dwordx2 v112, v[92:93], s[2:3]
	global_store_dwordx2 v114, v[96:97], s[2:3]
	s_sub_u32 s2, s2, 0x400
	s_subb_u32 s3, s3, 0
	v_lshlrev_b32_e32 v92, 16, v8
	v_and_b32_e32 v93, 0xffff0000, v8
	v_lshlrev_b32_e32 v94, 16, v9
	v_and_b32_e32 v95, 0xffff0000, v9
	v_mul_f32_e32 v92, 0xbfb8aa3b, v92
	v_mul_f32_e32 v93, 0xbfb8aa3b, v93
	v_mul_f32_e32 v94, 0xbfb8aa3b, v94
	v_mul_f32_e32 v95, 0xbfb8aa3b, v95
	v_exp_f32_e32 v92, v92
	v_exp_f32_e32 v93, v93
	v_exp_f32_e32 v94, v94
	v_exp_f32_e32 v95, v95
	v_add_f32_e32 v92, 1.0, v92
	v_add_f32_e32 v93, 1.0, v93
	v_add_f32_e32 v94, 1.0, v94
	v_add_f32_e32 v95, 1.0, v95
	v_rcp_f32_e32 v92, v92
	v_rcp_f32_e32 v93, v93
	v_rcp_f32_e32 v94, v94
	v_rcp_f32_e32 v95, v95
	v_fma_f32 v96, v72, v92, v68
	v_fma_f32 v97, v73, v93, v69
	v_fma_f32 v98, v74, v94, v70
	v_fma_f32 v99, v75, v95, v71
	v_cmp_gt_f32_e64 s[22:23], s30, v96
	v_cmp_gt_f32_e64 s[24:25], s30, v97
	v_cmp_gt_f32_e64 s[26:27], s30, v98
	v_cmp_gt_f32_e64 s[28:29], s30, v99
	v_cndmask_b32_e64 v92, 0, 32, s[22:23]
	v_cndmask_b32_e64 v93, 0, 32, s[24:25]
	v_cndmask_b32_e64 v94, 0, 32, s[26:27]
	v_cndmask_b32_e64 v95, 0, 32, s[28:29]
	v_ldexp_f32 v92, v96, v92
	v_ldexp_f32 v93, v97, v93
	v_ldexp_f32 v94, v98, v94
	v_ldexp_f32 v95, v99, v95
	v_log_f32_e32 v92, v92
	v_log_f32_e32 v93, v93
	v_log_f32_e32 v94, v94
	v_log_f32_e32 v95, v95
	v_mul_f32_e32 v100, 0x3f317217, v92
	v_mul_f32_e32 v101, 0x3f317217, v93
	v_mul_f32_e32 v102, 0x3f317217, v94
	v_mul_f32_e32 v103, 0x3f317217, v95
; DEV u16 f2bf(float f) { return (u16)(pack2(f, f) & 0xffffu); }
; DEV float bf2f(u16 h) { return __uint_as_float(((unsigned)h) << 16); }
; DEV float sigmoid_f(float x) { return __builtin_amdgcn_rcpf(1.f + __expf(-x)); }
; DEV void phase_p15(const Params& p, int g) {
;     ...
;         for (int e = 0; e < 8; ++e) {
;           const int jj = j8 * 8 + e;
;           const int j = dir ? 63 - jj : jj;
;           const size_t tok = (size_t)cidx * 64 + j;
;           const float f = lb[cc] + (1.f - lb[cc]) * sigmoid_f(bf2f(xr[st][cc][e]));
;           G[cc] += __logf(f);
;           const float eg = __expf(G[cc]), ig = __expf(-G[cc]);
;           Qp[tok * 512 + c] = f2bf(bf2f(qr[st][cc][e]) * eg);
;           const u16 kk = f2bf((1.f - f) * ig);
;           Kp[tok * 512 + c] = kk;
;           kb[e] = kk;
;         }
;         const int s0 = dir ? 56 - 8 * j8 : 8 * j8;
;         uint4 w;
;         w.x = dir ? (kb[7] | (kb[6] << 16)) : (kb[0] | (kb[1] << 16));
;         w.y = dir ? (kb[5] | (kb[4] << 16)) : (kb[2] | (kb[3] << 16));
;         w.z = dir ? (kb[3] | (kb[2] << 16)) : (kb[4] | (kb[5] << 16));
;         w.w = dir ? (kb[1] | (kb[0] << 16)) : (kb[6] | (kb[7] << 16));
;         *(uint4*)(KT + (((size_t)cidx * 2 + dir) * 512 + c) * 64 + s0) = w;
	v_fma_f32 v100, v92, s31, -v100
	v_fma_f32 v101, v93, s31, -v101
	v_fma_f32 v102, v94, s31, -v102
	v_fma_f32 v103, v95, s31, -v103
	v_fmac_f32_e32 v100, 0x3377d1cf, v92
	v_fmac_f32_e32 v101, 0x3377d1cf, v93
	v_fmac_f32_e32 v102, 0x3377d1cf, v94
	v_fmac_f32_e32 v103, 0x3377d1cf, v95
	v_fmac_f32_e32 v100, 0x3f317217, v92
	v_fmac_f32_e32 v101, 0x3f317217, v93
	v_fmac_f32_e32 v102, 0x3f317217, v94
	v_fmac_f32_e32 v103, 0x3f317217, v95
	v_cmp_lt_f32_e64 vcc, |v92|, s34
	v_cndmask_b32_e32 v92, v92, v100, vcc
	v_cmp_lt_f32_e64 vcc, |v93|, s34
	v_cndmask_b32_e32 v93, v93, v101, vcc
	v_cmp_lt_f32_e64 vcc, |v94|, s34
	v_cndmask_b32_e32 v94, v94, v102, vcc
	v_cmp_lt_f32_e64 vcc, |v95|, s34
	v_cndmask_b32_e32 v95, v95, v103, vcc
	v_cndmask_b32_e64 v100, 0, v213, s[22:23]
	v_cndmask_b32_e64 v101, 0, v213, s[24:25]
	v_cndmask_b32_e64 v102, 0, v213, s[26:27]
	v_cndmask_b32_e64 v103, 0, v213, s[28:29]
	v_sub_f32_e32 v92, v92, v100
	v_sub_f32_e32 v93, v93, v101
	v_sub_f32_e32 v94, v94, v102
	v_sub_f32_e32 v95, v95, v103
	v_add_f32_e32 v64, v64, v92
	v_add_f32_e32 v65, v65, v93
	v_add_f32_e32 v66, v66, v94
	v_add_f32_e32 v67, v67, v95
	v_mul_f32_e32 v92, 0xbfb8aa3b, v64
	v_mul_f32_e32 v93, 0xbfb8aa3b, v65
	v_mul_f32_e32 v94, 0xbfb8aa3b, v66
	v_mul_f32_e32 v95, 0xbfb8aa3b, v67
	v_mul_f32_e32 v100, 0x3fb8aa3b, v64
	v_mul_f32_e32 v101, 0x3fb8aa3b, v65
	v_mul_f32_e32 v102, 0x3fb8aa3b, v66
	v_mul_f32_e32 v103, 0x3fb8aa3b, v67
	v_exp_f32_e32 v92, v92
	v_exp_f32_e32 v93, v93
	v_exp_f32_e32 v94, v94
	v_exp_f32_e32 v95, v95
	v_exp_f32_e32 v100, v100
	v_exp_f32_e32 v101, v101
	v_exp_f32_e32 v102, v102
	v_exp_f32_e32 v103, v103
	v_sub_f32_e32 v96, 1.0, v96
	v_sub_f32_e32 v97, 1.0, v97
	v_sub_f32_e32 v98, 1.0, v98
	v_sub_f32_e32 v99, 1.0, v99
	v_mul_f32_e32 v96, v96, v92
	v_mul_f32_e32 v97, v97, v93
	v_mul_f32_e32 v98, v98, v94
	v_mul_f32_e32 v99, v99, v95
	v_lshlrev_b32_e32 v92, 16, v10
	v_and_b32_e32 v93, 0xffff0000, v10
	v_lshlrev_b32_e32 v94, 16, v11
	v_and_b32_e32 v95, 0xffff0000, v11
	v_mul_f32_e32 v92, v92, v100
	v_mul_f32_e32 v93, v93, v101
	v_mul_f32_e32 v94, v94, v102
	v_mul_f32_e32 v95, v95, v103
	v_mov_b32_e32 v122, v96
	v_mov_b32_e32 v138, v97
	v_mov_b32_e32 v172, v98
	v_mov_b32_e32 v188, v99
	v_cvt_pk_bf16_f32 v92, v92, v93
	v_cvt_pk_bf16_f32 v93, v94, v95
	v_cvt_pk_bf16_f32 v96, v96, v97
	v_cvt_pk_bf16_f32 v97, v98, v99
	global_store_dwordx2 v112, v[92:93], s[2:3]
	global_store_dwordx2 v114, v[96:97], s[2:3]
	s_sub_u32 s2, s2, 0x400
	s_subb_u32 s3, s3, 0
	v_lshlrev_b32_e32 v92, 16, v12
	v_and_b32_e32 v93, 0xffff0000, v12
	v_lshlrev_b32_e32 v94, 16, v13
	v_and_b32_e32 v95, 0xffff0000, v13
	v_mul_f32_e32 v92, 0xbfb8aa3b, v92
	v_mul_f32_e32 v93, 0xbfb8aa3b, v93
	v_mul_f32_e32 v94, 0xbfb8aa3b, v94
	v_mul_f32_e32 v95, 0xbfb8aa3b, v95
	v_exp_f32_e32 v92, v92
	v_exp_f32_e32 v93, v93
	v_exp_f32_e32 v94, v94
	v_exp_f32_e32 v95, v95
	v_add_f32_e32 v92, 1.0, v92
	v_add_f32_e32 v93, 1.0, v93
	v_add_f32_e32 v94, 1.0, v94
	v_add_f32_e32 v95, 1.0, v95
	v_rcp_f32_e32 v92, v92
	v_rcp_f32_e32 v93, v93
	v_rcp_f32_e32 v94, v94
	v_rcp_f32_e32 v95, v95
	v_fma_f32 v96, v72, v92, v68
	v_fma_f32 v97, v73, v93, v69
	v_fma_f32 v98, v74, v94, v70
	v_fma_f32 v99, v75, v95, v71
	v_cmp_gt_f32_e64 s[22:23], s30, v96
	v_cmp_gt_f32_e64 s[24:25], s30, v97
	v_cmp_gt_f32_e64 s[26:27], s30, v98
	v_cmp_gt_f32_e64 s[28:29], s30, v99
	v_cndmask_b32_e64 v92, 0, 32, s[22:23]
	v_cndmask_b32_e64 v93, 0, 32, s[24:25]
	v_cndmask_b32_e64 v94, 0, 32, s[26:27]
	v_cndmask_b32_e64 v95, 0, 32, s[28:29]
	v_ldexp_f32 v92, v96, v92
	v_ldexp_f32 v93, v97, v93
	v_ldexp_f32 v94, v98, v94
	v_ldexp_f32 v95, v99, v95
	v_log_f32_e32 v92, v92
	v_log_f32_e32 v93, v93
	v_log_f32_e32 v94, v94
	v_log_f32_e32 v95, v95
	v_mul_f32_e32 v100, 0x3f317217, v92
	v_mul_f32_e32 v101, 0x3f317217, v93
	v_mul_f32_e32 v102, 0x3f317217, v94
	v_mul_f32_e32 v103, 0x3f317217, v95
	v_fma_f32 v100, v92, s31, -v100
	v_fma_f32 v101, v93, s31, -v101
	v_fma_f32 v102, v94, s31, -v102
	v_fma_f32 v103, v95, s31, -v103
	v_fmac_f32_e32 v100, 0x3377d1cf, v92
	v_fmac_f32_e32 v101, 0x3377d1cf, v93
	v_fmac_f32_e32 v102, 0x3377d1cf, v94
	v_fmac_f32_e32 v103, 0x3377d1cf, v95
	v_fmac_f32_e32 v100, 0x3f317217, v92
	v_fmac_f32_e32 v101, 0x3f317217, v93
	v_fmac_f32_e32 v102, 0x3f317217, v94
	v_fmac_f32_e32 v103, 0x3f317217, v95
	v_cmp_lt_f32_e64 vcc, |v92|, s34
	v_cndmask_b32_e32 v92, v92, v100, vcc
	v_cmp_lt_f32_e64 vcc, |v93|, s34
	v_cndmask_b32_e32 v93, v93, v101, vcc
	v_cmp_lt_f32_e64 vcc, |v94|, s34
	v_cndmask_b32_e32 v94, v94, v102, vcc
	v_cmp_lt_f32_e64 vcc, |v95|, s34
	v_cndmask_b32_e32 v95, v95, v103, vcc
	v_cndmask_b32_e64 v100, 0, v213, s[22:23]
	v_cndmask_b32_e64 v101, 0, v213, s[24:25]
	v_cndmask_b32_e64 v102, 0, v213, s[26:27]
	v_cndmask_b32_e64 v103, 0, v213, s[28:29]
	v_sub_f32_e32 v92, v92, v100
	v_sub_f32_e32 v93, v93, v101
	v_sub_f32_e32 v94, v94, v102
	v_sub_f32_e32 v95, v95, v103
	v_add_f32_e32 v64, v64, v92
	v_add_f32_e32 v65, v65, v93
	v_add_f32_e32 v66, v66, v94
	v_add_f32_e32 v67, v67, v95
	v_mul_f32_e32 v92, 0xbfb8aa3b, v64
	v_mul_f32_e32 v93, 0xbfb8aa3b, v65
	v_mul_f32_e32 v94, 0xbfb8aa3b, v66
	v_mul_f32_e32 v95, 0xbfb8aa3b, v67
	v_mul_f32_e32 v100, 0x3fb8aa3b, v64
	v_mul_f32_e32 v101, 0x3fb8aa3b, v65
	v_mul_f32_e32 v102, 0x3fb8aa3b, v66
	v_mul_f32_e32 v103, 0x3fb8aa3b, v67
	v_exp_f32_e32 v92, v92
	v_exp_f32_e32 v93, v93
	v_exp_f32_e32 v94, v94
	v_exp_f32_e32 v95, v95
	v_exp_f32_e32 v100, v100
	v_exp_f32_e32 v101, v101
	v_exp_f32_e32 v102, v102
	v_exp_f32_e32 v103, v103
	v_sub_f32_e32 v96, 1.0, v96
	v_sub_f32_e32 v97, 1.0, v97
	v_sub_f32_e32 v98, 1.0, v98
	v_sub_f32_e32 v99, 1.0, v99
	v_mul_f32_e32 v96, v96, v92
; DEV u16 f2bf(float f) { return (u16)(pack2(f, f) & 0xffffu); }
; DEV float bf2f(u16 h) { return __uint_as_float(((unsigned)h) << 16); }
; DEV float sigmoid_f(float x) { return __builtin_amdgcn_rcpf(1.f + __expf(-x)); }
; DEV void phase_p15(const Params& p, int g) {
;     ...
;         for (int e = 0; e < 8; ++e) {
;           const int jj = j8 * 8 + e;
;           const int j = dir ? 63 - jj : jj;
;           const size_t tok = (size_t)cidx * 64 + j;
;           const float f = lb[cc] + (1.f - lb[cc]) * sigmoid_f(bf2f(xr[st][cc][e]));
;           G[cc] += __logf(f);
;           const float eg = __expf(G[cc]), ig = __expf(-G[cc]);
;           Qp[tok * 512 + c] = f2bf(bf2f(qr[st][cc][e]) * eg);
;           const u16 kk = f2bf((1.f - f) * ig);
;           Kp[tok * 512 + c] = kk;
;           kb[e] = kk;
;         }
;         const int s0 = dir ? 56 - 8 * j8 : 8 * j8;
;         uint4 w;
;         w.x = dir ? (kb[7] | (kb[6] << 16)) : (kb[0] | (kb[1] << 16));
;         w.y = dir ? (kb[5] | (kb[4] << 16)) : (kb[2] | (kb[3] << 16));
;         w.z = dir ? (kb[3] | (kb[2] << 16)) : (kb[4] | (kb[5] << 16));
;         w.w = dir ? (kb[1] | (kb[0] << 16)) : (kb[6] | (kb[7] << 16));
;         *(uint4*)(KT + (((size_t)cidx * 2 + dir) * 512 + c) * 64 + s0) = w;
	v_mul_f32_e32 v97, v97, v93
	v_mul_f32_e32 v98, v98, v94
	v_mul_f32_e32 v99, v99, v95
	v_lshlrev_b32_e32 v92, 16, v14
	v_and_b32_e32 v93, 0xffff0000, v14
	v_lshlrev_b32_e32 v94, 16, v15
	v_and_b32_e32 v95, 0xffff0000, v15
	v_mul_f32_e32 v92, v92, v100
	v_mul_f32_e32 v93, v93, v101
	v_mul_f32_e32 v94, v94, v102
	v_mul_f32_e32 v95, v95, v103
	v_cvt_pk_bf16_f32 v122, v96, v122
	v_cvt_pk_bf16_f32 v138, v97, v138
	v_cvt_pk_bf16_f32 v172, v98, v172
	v_cvt_pk_bf16_f32 v188, v99, v188
	v_cvt_pk_bf16_f32 v92, v92, v93
	v_cvt_pk_bf16_f32 v93, v94, v95
	v_cvt_pk_bf16_f32 v96, v96, v97
	v_cvt_pk_bf16_f32 v97, v98, v99
	global_store_dwordx2 v112, v[92:93], s[2:3]
	global_store_dwordx2 v114, v[96:97], s[2:3]
	s_sub_u32 s2, s2, 0x400
	s_subb_u32 s3, s3, 0
	v_lshlrev_b32_e32 v92, 16, v16
	v_and_b32_e32 v93, 0xffff0000, v16
	v_lshlrev_b32_e32 v94, 16, v17
	v_and_b32_e32 v95, 0xffff0000, v17
	v_mul_f32_e32 v92, 0xbfb8aa3b, v92
	v_mul_f32_e32 v93, 0xbfb8aa3b, v93
	v_mul_f32_e32 v94, 0xbfb8aa3b, v94
	v_mul_f32_e32 v95, 0xbfb8aa3b, v95
	v_exp_f32_e32 v92, v92
	v_exp_f32_e32 v93, v93
	v_exp_f32_e32 v94, v94
	v_exp_f32_e32 v95, v95
	v_add_f32_e32 v92, 1.0, v92
	v_add_f32_e32 v93, 1.0, v93
	v_add_f32_e32 v94, 1.0, v94
	v_add_f32_e32 v95, 1.0, v95
	v_rcp_f32_e32 v92, v92
	v_rcp_f32_e32 v93, v93
	v_rcp_f32_e32 v94, v94
	v_rcp_f32_e32 v95, v95
	v_fma_f32 v96, v72, v92, v68
	v_fma_f32 v97, v73, v93, v69
	v_fma_f32 v98, v74, v94, v70
	v_fma_f32 v99, v75, v95, v71
	v_cmp_gt_f32_e64 s[22:23], s30, v96
	v_cmp_gt_f32_e64 s[24:25], s30, v97
	v_cmp_gt_f32_e64 s[26:27], s30, v98
	v_cmp_gt_f32_e64 s[28:29], s30, v99
	v_cndmask_b32_e64 v92, 0, 32, s[22:23]
	v_cndmask_b32_e64 v93, 0, 32, s[24:25]
	v_cndmask_b32_e64 v94, 0, 32, s[26:27]
	v_cndmask_b32_e64 v95, 0, 32, s[28:29]
	v_ldexp_f32 v92, v96, v92
	v_ldexp_f32 v93, v97, v93
	v_ldexp_f32 v94, v98, v94
	v_ldexp_f32 v95, v99, v95
	v_log_f32_e32 v92, v92
	v_log_f32_e32 v93, v93
	v_log_f32_e32 v94, v94
	v_log_f32_e32 v95, v95
	v_mul_f32_e32 v100, 0x3f317217, v92
	v_mul_f32_e32 v101, 0x3f317217, v93
	v_mul_f32_e32 v102, 0x3f317217, v94
	v_mul_f32_e32 v103, 0x3f317217, v95
	v_fma_f32 v100, v92, s31, -v100
	v_fma_f32 v101, v93, s31, -v101
	v_fma_f32 v102, v94, s31, -v102
	v_fma_f32 v103, v95, s31, -v103
	v_fmac_f32_e32 v100, 0x3377d1cf, v92
	v_fmac_f32_e32 v101, 0x3377d1cf, v93
	v_fmac_f32_e32 v102, 0x3377d1cf, v94
	v_fmac_f32_e32 v103, 0x3377d1cf, v95
	v_fmac_f32_e32 v100, 0x3f317217, v92
	v_fmac_f32_e32 v101, 0x3f317217, v93
	v_fmac_f32_e32 v102, 0x3f317217, v94
	v_fmac_f32_e32 v103, 0x3f317217, v95
	v_cmp_lt_f32_e64 vcc, |v92|, s34
	v_cndmask_b32_e32 v92, v92, v100, vcc
	v_cmp_lt_f32_e64 vcc, |v93|, s34
	v_cndmask_b32_e32 v93, v93, v101, vcc
	v_cmp_lt_f32_e64 vcc, |v94|, s34
	v_cndmask_b32_e32 v94, v94, v102, vcc
	v_cmp_lt_f32_e64 vcc, |v95|, s34
	v_cndmask_b32_e32 v95, v95, v103, vcc
	v_cndmask_b32_e64 v100, 0, v213, s[22:23]
	v_cndmask_b32_e64 v101, 0, v213, s[24:25]
	v_cndmask_b32_e64 v102, 0, v213, s[26:27]
	v_cndmask_b32_e64 v103, 0, v213, s[28:29]
	v_sub_f32_e32 v92, v92, v100
	v_sub_f32_e32 v93, v93, v101
	v_sub_f32_e32 v94, v94, v102
	v_sub_f32_e32 v95, v95, v103
	v_add_f32_e32 v64, v64, v92
	v_add_f32_e32 v65, v65, v93
	v_add_f32_e32 v66, v66, v94
	v_add_f32_e32 v67, v67, v95
	v_mul_f32_e32 v92, 0xbfb8aa3b, v64
	v_mul_f32_e32 v93, 0xbfb8aa3b, v65
	v_mul_f32_e32 v94, 0xbfb8aa3b, v66
	v_mul_f32_e32 v95, 0xbfb8aa3b, v67
	v_mul_f32_e32 v100, 0x3fb8aa3b, v64
	v_mul_f32_e32 v101, 0x3fb8aa3b, v65
	v_mul_f32_e32 v102, 0x3fb8aa3b, v66
	v_mul_f32_e32 v103, 0x3fb8aa3b, v67
	v_exp_f32_e32 v92, v92
	v_exp_f32_e32 v93, v93
	v_exp_f32_e32 v94, v94
	v_exp_f32_e32 v95, v95
	v_exp_f32_e32 v100, v100
	v_exp_f32_e32 v101, v101
	v_exp_f32_e32 v102, v102
	v_exp_f32_e32 v103, v103
	v_sub_f32_e32 v96, 1.0, v96
	v_sub_f32_e32 v97, 1.0, v97
	v_sub_f32_e32 v98, 1.0, v98
	v_sub_f32_e32 v99, 1.0, v99
	v_mul_f32_e32 v96, v96, v92
	v_mul_f32_e32 v97, v97, v93
	v_mul_f32_e32 v98, v98, v94
	v_mul_f32_e32 v99, v99, v95
	v_lshlrev_b32_e32 v92, 16, v18
	v_and_b32_e32 v93, 0xffff0000, v18
	v_lshlrev_b32_e32 v94, 16, v19
	v_and_b32_e32 v95, 0xffff0000, v19
	v_mul_f32_e32 v92, v92, v100
	v_mul_f32_e32 v93, v93, v101
	v_mul_f32_e32 v94, v94, v102
	v_mul_f32_e32 v95, v95, v103
	v_mov_b32_e32 v121, v96
	v_mov_b32_e32 v137, v97
	v_mov_b32_e32 v171, v98
	v_mov_b32_e32 v187, v99
	v_cvt_pk_bf16_f32 v92, v92, v93
	v_cvt_pk_bf16_f32 v93, v94, v95
	v_cvt_pk_bf16_f32 v96, v96, v97
	v_cvt_pk_bf16_f32 v97, v98, v99
	global_store_dwordx2 v112, v[92:93], s[2:3]
	global_store_dwordx2 v114, v[96:97], s[2:3]
	s_sub_u32 s2, s2, 0x400
	s_subb_u32 s3, s3, 0
	v_lshlrev_b32_e32 v92, 16, v20
	v_and_b32_e32 v93, 0xffff0000, v20
	v_lshlrev_b32_e32 v94, 16, v21
	v_and_b32_e32 v95, 0xffff0000, v21
	v_mul_f32_e32 v92, 0xbfb8aa3b, v92
	v_mul_f32_e32 v93, 0xbfb8aa3b, v93
	v_mul_f32_e32 v94, 0xbfb8aa3b, v94
	v_mul_f32_e32 v95, 0xbfb8aa3b, v95
	v_exp_f32_e32 v92, v92
	v_exp_f32_e32 v93, v93
	v_exp_f32_e32 v94, v94
	v_exp_f32_e32 v95, v95
	v_add_f32_e32 v92, 1.0, v92
	v_add_f32_e32 v93, 1.0, v93
	v_add_f32_e32 v94, 1.0, v94
	v_add_f32_e32 v95, 1.0, v95
	v_rcp_f32_e32 v92, v92
	v_rcp_f32_e32 v93, v93
	v_rcp_f32_e32 v94, v94
	v_rcp_f32_e32 v95, v95
	v_fma_f32 v96, v72, v92, v68
	v_fma_f32 v97, v73, v93, v69
	v_fma_f32 v98, v74, v94, v70
	v_fma_f32 v99, v75, v95, v71
	v_cmp_gt_f32_e64 s[22:23], s30, v96
	v_cmp_gt_f32_e64 s[24:25], s30, v97
	v_cmp_gt_f32_e64 s[26:27], s30, v98
	v_cmp_gt_f32_e64 s[28:29], s30, v99
	v_cndmask_b32_e64 v92, 0, 32, s[22:23]
	v_cndmask_b32_e64 v93, 0, 32, s[24:25]
	v_cndmask_b32_e64 v94, 0, 32, s[26:27]
	v_cndmask_b32_e64 v95, 0, 32, s[28:29]
	v_ldexp_f32 v92, v96, v92
; DEV u16 f2bf(float f) { return (u16)(pack2(f, f) & 0xffffu); }
; DEV float bf2f(u16 h) { return __uint_as_float(((unsigned)h) << 16); }
; DEV float sigmoid_f(float x) { return __builtin_amdgcn_rcpf(1.f + __expf(-x)); }
; DEV void phase_p15(const Params& p, int g) {
;     ...
;         for (int e = 0; e < 8; ++e) {
;           const int jj = j8 * 8 + e;
;           const int j = dir ? 63 - jj : jj;
;           const size_t tok = (size_t)cidx * 64 + j;
;           const float f = lb[cc] + (1.f - lb[cc]) * sigmoid_f(bf2f(xr[st][cc][e]));
;           G[cc] += __logf(f);
;           const float eg = __expf(G[cc]), ig = __expf(-G[cc]);
;           Qp[tok * 512 + c] = f2bf(bf2f(qr[st][cc][e]) * eg);
;           const u16 kk = f2bf((1.f - f) * ig);
;           Kp[tok * 512 + c] = kk;
;           kb[e] = kk;
;         }
;         const int s0 = dir ? 56 - 8 * j8 : 8 * j8;
;         uint4 w;
;         w.x = dir ? (kb[7] | (kb[6] << 16)) : (kb[0] | (kb[1] << 16));
;         w.y = dir ? (kb[5] | (kb[4] << 16)) : (kb[2] | (kb[3] << 16));
;         w.z = dir ? (kb[3] | (kb[2] << 16)) : (kb[4] | (kb[5] << 16));
;         w.w = dir ? (kb[1] | (kb[0] << 16)) : (kb[6] | (kb[7] << 16));
;         *(uint4*)(KT + (((size_t)cidx * 2 + dir) * 512 + c) * 64 + s0) = w;
	v_ldexp_f32 v93, v97, v93
	v_ldexp_f32 v94, v98, v94
	v_ldexp_f32 v95, v99, v95
	v_log_f32_e32 v92, v92
	v_log_f32_e32 v93, v93
	v_log_f32_e32 v94, v94
	v_log_f32_e32 v95, v95
	v_mul_f32_e32 v100, 0x3f317217, v92
	v_mul_f32_e32 v101, 0x3f317217, v93
	v_mul_f32_e32 v102, 0x3f317217, v94
	v_mul_f32_e32 v103, 0x3f317217, v95
	v_fma_f32 v100, v92, s31, -v100
	v_fma_f32 v101, v93, s31, -v101
	v_fma_f32 v102, v94, s31, -v102
	v_fma_f32 v103, v95, s31, -v103
	v_fmac_f32_e32 v100, 0x3377d1cf, v92
	v_fmac_f32_e32 v101, 0x3377d1cf, v93
	v_fmac_f32_e32 v102, 0x3377d1cf, v94
	v_fmac_f32_e32 v103, 0x3377d1cf, v95
	v_fmac_f32_e32 v100, 0x3f317217, v92
	v_fmac_f32_e32 v101, 0x3f317217, v93
	v_fmac_f32_e32 v102, 0x3f317217, v94
	v_fmac_f32_e32 v103, 0x3f317217, v95
	v_cmp_lt_f32_e64 vcc, |v92|, s34
	v_cndmask_b32_e32 v92, v92, v100, vcc
	v_cmp_lt_f32_e64 vcc, |v93|, s34
	v_cndmask_b32_e32 v93, v93, v101, vcc
	v_cmp_lt_f32_e64 vcc, |v94|, s34
	v_cndmask_b32_e32 v94, v94, v102, vcc
	v_cmp_lt_f32_e64 vcc, |v95|, s34
	v_cndmask_b32_e32 v95, v95, v103, vcc
	v_cndmask_b32_e64 v100, 0, v213, s[22:23]
	v_cndmask_b32_e64 v101, 0, v213, s[24:25]
	v_cndmask_b32_e64 v102, 0, v213, s[26:27]
	v_cndmask_b32_e64 v103, 0, v213, s[28:29]
	v_sub_f32_e32 v92, v92, v100
	v_sub_f32_e32 v93, v93, v101
	v_sub_f32_e32 v94, v94, v102
	v_sub_f32_e32 v95, v95, v103
	v_add_f32_e32 v64, v64, v92
	v_add_f32_e32 v65, v65, v93
	v_add_f32_e32 v66, v66, v94
	v_add_f32_e32 v67, v67, v95
	v_mul_f32_e32 v92, 0xbfb8aa3b, v64
	v_mul_f32_e32 v93, 0xbfb8aa3b, v65
	v_mul_f32_e32 v94, 0xbfb8aa3b, v66
	v_mul_f32_e32 v95, 0xbfb8aa3b, v67
	v_mul_f32_e32 v100, 0x3fb8aa3b, v64
	v_mul_f32_e32 v101, 0x3fb8aa3b, v65
	v_mul_f32_e32 v102, 0x3fb8aa3b, v66
	v_mul_f32_e32 v103, 0x3fb8aa3b, v67
	v_exp_f32_e32 v92, v92
	v_exp_f32_e32 v93, v93
	v_exp_f32_e32 v94, v94
	v_exp_f32_e32 v95, v95
	v_exp_f32_e32 v100, v100
	v_exp_f32_e32 v101, v101
	v_exp_f32_e32 v102, v102
	v_exp_f32_e32 v103, v103
	v_sub_f32_e32 v96, 1.0, v96
	v_sub_f32_e32 v97, 1.0, v97
	v_sub_f32_e32 v98, 1.0, v98
	v_sub_f32_e32 v99, 1.0, v99
	v_mul_f32_e32 v96, v96, v92
	v_mul_f32_e32 v97, v97, v93
	v_mul_f32_e32 v98, v98, v94
	v_mul_f32_e32 v99, v99, v95
	v_lshlrev_b32_e32 v92, 16, v22
	v_and_b32_e32 v93, 0xffff0000, v22
	v_lshlrev_b32_e32 v94, 16, v23
	v_and_b32_e32 v95, 0xffff0000, v23
	v_mul_f32_e32 v92, v92, v100
	v_mul_f32_e32 v93, v93, v101
	v_mul_f32_e32 v94, v94, v102
	v_mul_f32_e32 v95, v95, v103
	v_cvt_pk_bf16_f32 v121, v96, v121
	v_cvt_pk_bf16_f32 v137, v97, v137
	v_cvt_pk_bf16_f32 v171, v98, v171
	v_cvt_pk_bf16_f32 v187, v99, v187
	v_cvt_pk_bf16_f32 v92, v92, v93
	v_cvt_pk_bf16_f32 v93, v94, v95
	v_cvt_pk_bf16_f32 v96, v96, v97
	v_cvt_pk_bf16_f32 v97, v98, v99
	global_store_dwordx2 v112, v[92:93], s[2:3]
	global_store_dwordx2 v114, v[96:97], s[2:3]
	s_sub_u32 s2, s2, 0x400
	s_subb_u32 s3, s3, 0
	v_lshlrev_b32_e32 v92, 16, v24
	v_and_b32_e32 v93, 0xffff0000, v24
	v_lshlrev_b32_e32 v94, 16, v25
	v_and_b32_e32 v95, 0xffff0000, v25
	v_mul_f32_e32 v92, 0xbfb8aa3b, v92
	v_mul_f32_e32 v93, 0xbfb8aa3b, v93
	v_mul_f32_e32 v94, 0xbfb8aa3b, v94
	v_mul_f32_e32 v95, 0xbfb8aa3b, v95
	v_exp_f32_e32 v92, v92
	v_exp_f32_e32 v93, v93
	v_exp_f32_e32 v94, v94
	v_exp_f32_e32 v95, v95
	v_add_f32_e32 v92, 1.0, v92
	v_add_f32_e32 v93, 1.0, v93
	v_add_f32_e32 v94, 1.0, v94
	v_add_f32_e32 v95, 1.0, v95
	v_rcp_f32_e32 v92, v92
	v_rcp_f32_e32 v93, v93
	v_rcp_f32_e32 v94, v94
	v_rcp_f32_e32 v95, v95
	v_fma_f32 v96, v72, v92, v68
	v_fma_f32 v97, v73, v93, v69
	v_fma_f32 v98, v74, v94, v70
	v_fma_f32 v99, v75, v95, v71
	v_cmp_gt_f32_e64 s[22:23], s30, v96
	v_cmp_gt_f32_e64 s[24:25], s30, v97
	v_cmp_gt_f32_e64 s[26:27], s30, v98
	v_cmp_gt_f32_e64 s[28:29], s30, v99
	v_cndmask_b32_e64 v92, 0, 32, s[22:23]
	v_cndmask_b32_e64 v93, 0, 32, s[24:25]
	v_cndmask_b32_e64 v94, 0, 32, s[26:27]
	v_cndmask_b32_e64 v95, 0, 32, s[28:29]
	v_ldexp_f32 v92, v96, v92
	v_ldexp_f32 v93, v97, v93
	v_ldexp_f32 v94, v98, v94
	v_ldexp_f32 v95, v99, v95
	v_log_f32_e32 v92, v92
	v_log_f32_e32 v93, v93
	v_log_f32_e32 v94, v94
	v_log_f32_e32 v95, v95
	v_mul_f32_e32 v100, 0x3f317217, v92
	v_mul_f32_e32 v101, 0x3f317217, v93
	v_mul_f32_e32 v102, 0x3f317217, v94
	v_mul_f32_e32 v103, 0x3f317217, v95
	v_fma_f32 v100, v92, s31, -v100
	v_fma_f32 v101, v93, s31, -v101
	v_fma_f32 v102, v94, s31, -v102
	v_fma_f32 v103, v95, s31, -v103
	v_fmac_f32_e32 v100, 0x3377d1cf, v92
	v_fmac_f32_e32 v101, 0x3377d1cf, v93
	v_fmac_f32_e32 v102, 0x3377d1cf, v94
	v_fmac_f32_e32 v103, 0x3377d1cf, v95
	v_fmac_f32_e32 v100, 0x3f317217, v92
	v_fmac_f32_e32 v101, 0x3f317217, v93
	v_fmac_f32_e32 v102, 0x3f317217, v94
	v_fmac_f32_e32 v103, 0x3f317217, v95
	v_cmp_lt_f32_e64 vcc, |v92|, s34
	v_cndmask_b32_e32 v92, v92, v100, vcc
	v_cmp_lt_f32_e64 vcc, |v93|, s34
	v_cndmask_b32_e32 v93, v93, v101, vcc
	v_cmp_lt_f32_e64 vcc, |v94|, s34
	v_cndmask_b32_e32 v94, v94, v102, vcc
	v_cmp_lt_f32_e64 vcc, |v95|, s34
	v_cndmask_b32_e32 v95, v95, v103, vcc
	v_cndmask_b32_e64 v100, 0, v213, s[22:23]
	v_cndmask_b32_e64 v101, 0, v213, s[24:25]
	v_cndmask_b32_e64 v102, 0, v213, s[26:27]
	v_cndmask_b32_e64 v103, 0, v213, s[28:29]
	v_sub_f32_e32 v92, v92, v100
	v_sub_f32_e32 v93, v93, v101
	v_sub_f32_e32 v94, v94, v102
	v_sub_f32_e32 v95, v95, v103
	v_add_f32_e32 v64, v64, v92
	v_add_f32_e32 v65, v65, v93
	v_add_f32_e32 v66, v66, v94
	v_add_f32_e32 v67, v67, v95
	v_mul_f32_e32 v92, 0xbfb8aa3b, v64
	v_mul_f32_e32 v93, 0xbfb8aa3b, v65
	v_mul_f32_e32 v94, 0xbfb8aa3b, v66
	v_mul_f32_e32 v95, 0xbfb8aa3b, v67
	v_mul_f32_e32 v100, 0x3fb8aa3b, v64
	v_mul_f32_e32 v101, 0x3fb8aa3b, v65
	v_mul_f32_e32 v102, 0x3fb8aa3b, v66
	v_mul_f32_e32 v103, 0x3fb8aa3b, v67
; DEV u16 f2bf(float f) { return (u16)(pack2(f, f) & 0xffffu); }
; DEV float bf2f(u16 h) { return __uint_as_float(((unsigned)h) << 16); }
; DEV float sigmoid_f(float x) { return __builtin_amdgcn_rcpf(1.f + __expf(-x)); }
; DEV void phase_p15(const Params& p, int g) {
;     ...
;         for (int e = 0; e < 8; ++e) {
;           const int jj = j8 * 8 + e;
;           const int j = dir ? 63 - jj : jj;
;           const size_t tok = (size_t)cidx * 64 + j;
;           const float f = lb[cc] + (1.f - lb[cc]) * sigmoid_f(bf2f(xr[st][cc][e]));
;           G[cc] += __logf(f);
;           const float eg = __expf(G[cc]), ig = __expf(-G[cc]);
;           Qp[tok * 512 + c] = f2bf(bf2f(qr[st][cc][e]) * eg);
;           const u16 kk = f2bf((1.f - f) * ig);
;           Kp[tok * 512 + c] = kk;
;           kb[e] = kk;
;         }
;         const int s0 = dir ? 56 - 8 * j8 : 8 * j8;
;         uint4 w;
;         w.x = dir ? (kb[7] | (kb[6] << 16)) : (kb[0] | (kb[1] << 16));
;         w.y = dir ? (kb[5] | (kb[4] << 16)) : (kb[2] | (kb[3] << 16));
;         w.z = dir ? (kb[3] | (kb[2] << 16)) : (kb[4] | (kb[5] << 16));
;         w.w = dir ? (kb[1] | (kb[0] << 16)) : (kb[6] | (kb[7] << 16));
;         *(uint4*)(KT + (((size_t)cidx * 2 + dir) * 512 + c) * 64 + s0) = w;
	v_exp_f32_e32 v92, v92
	v_exp_f32_e32 v93, v93
	v_exp_f32_e32 v94, v94
	v_exp_f32_e32 v95, v95
	v_exp_f32_e32 v100, v100
	v_exp_f32_e32 v101, v101
	v_exp_f32_e32 v102, v102
	v_exp_f32_e32 v103, v103
	v_sub_f32_e32 v96, 1.0, v96
	v_sub_f32_e32 v97, 1.0, v97
	v_sub_f32_e32 v98, 1.0, v98
	v_sub_f32_e32 v99, 1.0, v99
	v_mul_f32_e32 v96, v96, v92
	v_mul_f32_e32 v97, v97, v93
	v_mul_f32_e32 v98, v98, v94
	v_mul_f32_e32 v99, v99, v95
	v_lshlrev_b32_e32 v92, 16, v26
	v_and_b32_e32 v93, 0xffff0000, v26
	v_lshlrev_b32_e32 v94, 16, v27
	v_and_b32_e32 v95, 0xffff0000, v27
	v_mul_f32_e32 v92, v92, v100
	v_mul_f32_e32 v93, v93, v101
	v_mul_f32_e32 v94, v94, v102
	v_mul_f32_e32 v95, v95, v103
	v_mov_b32_e32 v120, v96
	v_mov_b32_e32 v136, v97
	v_mov_b32_e32 v170, v98
	v_mov_b32_e32 v186, v99
	v_cvt_pk_bf16_f32 v92, v92, v93
	v_cvt_pk_bf16_f32 v93, v94, v95
	v_cvt_pk_bf16_f32 v96, v96, v97
	v_cvt_pk_bf16_f32 v97, v98, v99
	global_store_dwordx2 v112, v[92:93], s[2:3]
	global_store_dwordx2 v114, v[96:97], s[2:3]
	s_sub_u32 s2, s2, 0x400
	s_subb_u32 s3, s3, 0
	v_lshlrev_b32_e32 v92, 16, v28
	v_and_b32_e32 v93, 0xffff0000, v28
	v_lshlrev_b32_e32 v94, 16, v29
	v_and_b32_e32 v95, 0xffff0000, v29
	v_mul_f32_e32 v92, 0xbfb8aa3b, v92
	v_mul_f32_e32 v93, 0xbfb8aa3b, v93
	v_mul_f32_e32 v94, 0xbfb8aa3b, v94
	v_mul_f32_e32 v95, 0xbfb8aa3b, v95
	v_exp_f32_e32 v92, v92
	v_exp_f32_e32 v93, v93
	v_exp_f32_e32 v94, v94
	v_exp_f32_e32 v95, v95
	v_add_f32_e32 v92, 1.0, v92
	v_add_f32_e32 v93, 1.0, v93
	v_add_f32_e32 v94, 1.0, v94
	v_add_f32_e32 v95, 1.0, v95
	v_rcp_f32_e32 v92, v92
	v_rcp_f32_e32 v93, v93
	v_rcp_f32_e32 v94, v94
	v_rcp_f32_e32 v95, v95
	v_fma_f32 v96, v72, v92, v68
	v_fma_f32 v97, v73, v93, v69
	v_fma_f32 v98, v74, v94, v70
	v_fma_f32 v99, v75, v95, v71
	v_cmp_gt_f32_e64 s[22:23], s30, v96
	v_cmp_gt_f32_e64 s[24:25], s30, v97
	v_cmp_gt_f32_e64 s[26:27], s30, v98
	v_cmp_gt_f32_e64 s[28:29], s30, v99
	v_cndmask_b32_e64 v92, 0, 32, s[22:23]
	v_cndmask_b32_e64 v93, 0, 32, s[24:25]
	v_cndmask_b32_e64 v94, 0, 32, s[26:27]
	v_cndmask_b32_e64 v95, 0, 32, s[28:29]
	v_ldexp_f32 v92, v96, v92
	v_ldexp_f32 v93, v97, v93
	v_ldexp_f32 v94, v98, v94
	v_ldexp_f32 v95, v99, v95
	v_log_f32_e32 v92, v92
	v_log_f32_e32 v93, v93
	v_log_f32_e32 v94, v94
	v_log_f32_e32 v95, v95
	v_mul_f32_e32 v100, 0x3f317217, v92
	v_mul_f32_e32 v101, 0x3f317217, v93
	v_mul_f32_e32 v102, 0x3f317217, v94
	v_mul_f32_e32 v103, 0x3f317217, v95
	v_fma_f32 v100, v92, s31, -v100
	v_fma_f32 v101, v93, s31, -v101
	v_fma_f32 v102, v94, s31, -v102
	v_fma_f32 v103, v95, s31, -v103
	v_fmac_f32_e32 v100, 0x3377d1cf, v92
	v_fmac_f32_e32 v101, 0x3377d1cf, v93
	v_fmac_f32_e32 v102, 0x3377d1cf, v94
	v_fmac_f32_e32 v103, 0x3377d1cf, v95
	v_fmac_f32_e32 v100, 0x3f317217, v92
	v_fmac_f32_e32 v101, 0x3f317217, v93
	v_fmac_f32_e32 v102, 0x3f317217, v94
	v_fmac_f32_e32 v103, 0x3f317217, v95
	v_cmp_lt_f32_e64 vcc, |v92|, s34
	v_cndmask_b32_e32 v92, v92, v100, vcc
	v_cmp_lt_f32_e64 vcc, |v93|, s34
	v_cndmask_b32_e32 v93, v93, v101, vcc
	v_cmp_lt_f32_e64 vcc, |v94|, s34
	v_cndmask_b32_e32 v94, v94, v102, vcc
	v_cmp_lt_f32_e64 vcc, |v95|, s34
	v_cndmask_b32_e32 v95, v95, v103, vcc
	v_cndmask_b32_e64 v100, 0, v213, s[22:23]
	v_cndmask_b32_e64 v101, 0, v213, s[24:25]
	v_cndmask_b32_e64 v102, 0, v213, s[26:27]
	v_cndmask_b32_e64 v103, 0, v213, s[28:29]
	v_sub_f32_e32 v92, v92, v100
	v_sub_f32_e32 v93, v93, v101
	v_sub_f32_e32 v94, v94, v102
	v_sub_f32_e32 v95, v95, v103
	v_add_f32_e32 v64, v64, v92
	v_add_f32_e32 v65, v65, v93
	v_add_f32_e32 v66, v66, v94
	v_add_f32_e32 v67, v67, v95
	v_mul_f32_e32 v92, 0xbfb8aa3b, v64
	v_mul_f32_e32 v93, 0xbfb8aa3b, v65
	v_mul_f32_e32 v94, 0xbfb8aa3b, v66
	v_mul_f32_e32 v95, 0xbfb8aa3b, v67
	v_mul_f32_e32 v100, 0x3fb8aa3b, v64
	v_mul_f32_e32 v101, 0x3fb8aa3b, v65
	v_mul_f32_e32 v102, 0x3fb8aa3b, v66
	v_mul_f32_e32 v103, 0x3fb8aa3b, v67
	v_exp_f32_e32 v92, v92
	v_exp_f32_e32 v93, v93
	v_exp_f32_e32 v94, v94
	v_exp_f32_e32 v95, v95
	v_exp_f32_e32 v100, v100
	v_exp_f32_e32 v101, v101
	v_exp_f32_e32 v102, v102
	v_exp_f32_e32 v103, v103
	v_sub_f32_e32 v96, 1.0, v96
	v_sub_f32_e32 v97, 1.0, v97
	v_sub_f32_e32 v98, 1.0, v98
	v_sub_f32_e32 v99, 1.0, v99
	v_mul_f32_e32 v96, v96, v92
	v_mul_f32_e32 v97, v97, v93
	v_mul_f32_e32 v98, v98, v94
	v_mul_f32_e32 v99, v99, v95
	v_lshlrev_b32_e32 v92, 16, v30
	v_and_b32_e32 v93, 0xffff0000, v30
	v_lshlrev_b32_e32 v94, 16, v31
	v_and_b32_e32 v95, 0xffff0000, v31
	v_mul_f32_e32 v92, v92, v100
	v_mul_f32_e32 v93, v93, v101
	v_mul_f32_e32 v94, v94, v102
	v_mul_f32_e32 v95, v95, v103
	v_cvt_pk_bf16_f32 v120, v96, v120
	v_cvt_pk_bf16_f32 v136, v97, v136
	v_cvt_pk_bf16_f32 v170, v98, v170
	v_cvt_pk_bf16_f32 v186, v99, v186
	v_cvt_pk_bf16_f32 v92, v92, v93
	v_cvt_pk_bf16_f32 v93, v94, v95
	v_cvt_pk_bf16_f32 v96, v96, v97
	v_cvt_pk_bf16_f32 v97, v98, v99
	global_store_dwordx2 v112, v[92:93], s[2:3]
	global_store_dwordx2 v114, v[96:97], s[2:3]
	s_sub_u32 s2, s2, 0x400
	s_subb_u32 s3, s3, 0
	global_load_dwordx2 v[0:1], v113, s[0:1]
	global_load_dwordx2 v[2:3], v112, s[0:1]
	s_sub_u32 s0, s0, 0x1400
	s_subb_u32 s1, s1, 0
	global_load_dwordx2 v[4:5], v113, s[0:1]
	global_load_dwordx2 v[6:7], v112, s[0:1]
	s_sub_u32 s0, s0, 0x1400
	s_subb_u32 s1, s1, 0
	global_load_dwordx2 v[8:9], v113, s[0:1]
	global_load_dwordx2 v[10:11], v112, s[0:1]
	s_sub_u32 s0, s0, 0x1400
	s_subb_u32 s1, s1, 0
	global_load_dwordx2 v[12:13], v113, s[0:1]
	global_load_dwordx2 v[14:15], v112, s[0:1]
	s_sub_u32 s0, s0, 0x1400
	s_subb_u32 s1, s1, 0
	global_load_dwordx2 v[16:17], v113, s[0:1]
	global_load_dwordx2 v[18:19], v112, s[0:1]
	s_sub_u32 s0, s0, 0x1400
	s_subb_u32 s1, s1, 0
	global_load_dwordx2 v[20:21], v113, s[0:1]
	global_load_dwordx2 v[22:23], v112, s[0:1]
	s_sub_u32 s0, s0, 0x1400
	s_subb_u32 s1, s1, 0
	global_load_dwordx2 v[24:25], v113, s[0:1]
	global_load_dwordx2 v[26:27], v112, s[0:1]
	s_sub_u32 s0, s0, 0x1400
	s_subb_u32 s1, s1, 0
	global_load_dwordx2 v[28:29], v113, s[0:1]
	global_load_dwordx2 v[30:31], v112, s[0:1]
	s_sub_u32 s0, s0, 0x1400
	s_subb_u32 s1, s1, 0
	s_waitcnt vmcnt(32)
; DEV u16 f2bf(float f) { return (u16)(pack2(f, f) & 0xffffu); }
; DEV float bf2f(u16 h) { return __uint_as_float(((unsigned)h) << 16); }
; DEV float sigmoid_f(float x) { return __builtin_amdgcn_rcpf(1.f + __expf(-x)); }
; DEV void phase_p15(const Params& p, int g) {
;     ...
;         for (int e = 0; e < 8; ++e) {
;           const int jj = j8 * 8 + e;
;           const int j = dir ? 63 - jj : jj;
;           const size_t tok = (size_t)cidx * 64 + j;
;           const float f = lb[cc] + (1.f - lb[cc]) * sigmoid_f(bf2f(xr[st][cc][e]));
;           G[cc] += __logf(f);
;           const float eg = __expf(G[cc]), ig = __expf(-G[cc]);
;           Qp[tok * 512 + c] = f2bf(bf2f(qr[st][cc][e]) * eg);
;           const u16 kk = f2bf((1.f - f) * ig);
;           Kp[tok * 512 + c] = kk;
;           kb[e] = kk;
;         }
;         const int s0 = dir ? 56 - 8 * j8 : 8 * j8;
;         uint4 w;
;         w.x = dir ? (kb[7] | (kb[6] << 16)) : (kb[0] | (kb[1] << 16));
;         w.y = dir ? (kb[5] | (kb[4] << 16)) : (kb[2] | (kb[3] << 16));
;         w.z = dir ? (kb[3] | (kb[2] << 16)) : (kb[4] | (kb[5] << 16));
;         w.w = dir ? (kb[1] | (kb[0] << 16)) : (kb[6] | (kb[7] << 16));
;         *(uint4*)(KT + (((size_t)cidx * 2 + dir) * 512 + c) * 64 + s0) = w;
	v_lshlrev_b32_e32 v92, 16, v32
	v_and_b32_e32 v93, 0xffff0000, v32
	v_lshlrev_b32_e32 v94, 16, v33
	v_and_b32_e32 v95, 0xffff0000, v33
	v_mul_f32_e32 v92, 0xbfb8aa3b, v92
	v_mul_f32_e32 v93, 0xbfb8aa3b, v93
	v_mul_f32_e32 v94, 0xbfb8aa3b, v94
	v_mul_f32_e32 v95, 0xbfb8aa3b, v95
	v_exp_f32_e32 v92, v92
	v_exp_f32_e32 v93, v93
	v_exp_f32_e32 v94, v94
	v_exp_f32_e32 v95, v95
	v_add_f32_e32 v92, 1.0, v92
	v_add_f32_e32 v93, 1.0, v93
	v_add_f32_e32 v94, 1.0, v94
	v_add_f32_e32 v95, 1.0, v95
	v_rcp_f32_e32 v92, v92
	v_rcp_f32_e32 v93, v93
	v_rcp_f32_e32 v94, v94
	v_rcp_f32_e32 v95, v95
	v_fma_f32 v96, v72, v92, v68
	v_fma_f32 v97, v73, v93, v69
	v_fma_f32 v98, v74, v94, v70
	v_fma_f32 v99, v75, v95, v71
	v_cmp_gt_f32_e64 s[22:23], s30, v96
	v_cmp_gt_f32_e64 s[24:25], s30, v97
	v_cmp_gt_f32_e64 s[26:27], s30, v98
	v_cmp_gt_f32_e64 s[28:29], s30, v99
	v_cndmask_b32_e64 v92, 0, 32, s[22:23]
	v_cndmask_b32_e64 v93, 0, 32, s[24:25]
	v_cndmask_b32_e64 v94, 0, 32, s[26:27]
	v_cndmask_b32_e64 v95, 0, 32, s[28:29]
	v_ldexp_f32 v92, v96, v92
	v_ldexp_f32 v93, v97, v93
	v_ldexp_f32 v94, v98, v94
	v_ldexp_f32 v95, v99, v95
	v_log_f32_e32 v92, v92
	v_log_f32_e32 v93, v93
	v_log_f32_e32 v94, v94
	v_log_f32_e32 v95, v95
	v_mul_f32_e32 v100, 0x3f317217, v92
	v_mul_f32_e32 v101, 0x3f317217, v93
	v_mul_f32_e32 v102, 0x3f317217, v94
	v_mul_f32_e32 v103, 0x3f317217, v95
	v_fma_f32 v100, v92, s31, -v100
	v_fma_f32 v101, v93, s31, -v101
	v_fma_f32 v102, v94, s31, -v102
	v_fma_f32 v103, v95, s31, -v103
	v_fmac_f32_e32 v100, 0x3377d1cf, v92
	v_fmac_f32_e32 v101, 0x3377d1cf, v93
	v_fmac_f32_e32 v102, 0x3377d1cf, v94
	v_fmac_f32_e32 v103, 0x3377d1cf, v95
	v_fmac_f32_e32 v100, 0x3f317217, v92
	v_fmac_f32_e32 v101, 0x3f317217, v93
	v_fmac_f32_e32 v102, 0x3f317217, v94
	v_fmac_f32_e32 v103, 0x3f317217, v95
	v_cmp_lt_f32_e64 vcc, |v92|, s34
	v_cndmask_b32_e32 v92, v92, v100, vcc
	v_cmp_lt_f32_e64 vcc, |v93|, s34
	v_cndmask_b32_e32 v93, v93, v101, vcc
	v_cmp_lt_f32_e64 vcc, |v94|, s34
	v_cndmask_b32_e32 v94, v94, v102, vcc
	v_cmp_lt_f32_e64 vcc, |v95|, s34
	v_cndmask_b32_e32 v95, v95, v103, vcc
	v_cndmask_b32_e64 v100, 0, v213, s[22:23]
	v_cndmask_b32_e64 v101, 0, v213, s[24:25]
	v_cndmask_b32_e64 v102, 0, v213, s[26:27]
	v_cndmask_b32_e64 v103, 0, v213, s[28:29]
	v_sub_f32_e32 v92, v92, v100
	v_sub_f32_e32 v93, v93, v101
	v_sub_f32_e32 v94, v94, v102
	v_sub_f32_e32 v95, v95, v103
	v_add_f32_e32 v64, v64, v92
	v_add_f32_e32 v65, v65, v93
	v_add_f32_e32 v66, v66, v94
	v_add_f32_e32 v67, v67, v95
	v_mul_f32_e32 v92, 0xbfb8aa3b, v64
	v_mul_f32_e32 v93, 0xbfb8aa3b, v65
	v_mul_f32_e32 v94, 0xbfb8aa3b, v66
	v_mul_f32_e32 v95, 0xbfb8aa3b, v67
	v_mul_f32_e32 v100, 0x3fb8aa3b, v64
	v_mul_f32_e32 v101, 0x3fb8aa3b, v65
	v_mul_f32_e32 v102, 0x3fb8aa3b, v66
	v_mul_f32_e32 v103, 0x3fb8aa3b, v67
	v_exp_f32_e32 v92, v92
	v_exp_f32_e32 v93, v93
	v_exp_f32_e32 v94, v94
	v_exp_f32_e32 v95, v95
	v_exp_f32_e32 v100, v100
	v_exp_f32_e32 v101, v101
	v_exp_f32_e32 v102, v102
	v_exp_f32_e32 v103, v103
	v_sub_f32_e32 v96, 1.0, v96
	v_sub_f32_e32 v97, 1.0, v97
	v_sub_f32_e32 v98, 1.0, v98
	v_sub_f32_e32 v99, 1.0, v99
	v_mul_f32_e32 v96, v96, v92
	v_mul_f32_e32 v97, v97, v93
	v_mul_f32_e32 v98, v98, v94
	v_mul_f32_e32 v99, v99, v95
	v_lshlrev_b32_e32 v92, 16, v34
	v_and_b32_e32 v93, 0xffff0000, v34
	v_lshlrev_b32_e32 v94, 16, v35
	v_and_b32_e32 v95, 0xffff0000, v35
	v_mul_f32_e32 v92, v92, v100
	v_mul_f32_e32 v93, v93, v101
	v_mul_f32_e32 v94, v94, v102
	v_mul_f32_e32 v95, v95, v103
	v_mov_b32_e32 v119, v96
	v_mov_b32_e32 v135, v97
	v_mov_b32_e32 v169, v98
	v_mov_b32_e32 v185, v99
	v_cvt_pk_bf16_f32 v92, v92, v93
	v_cvt_pk_bf16_f32 v93, v94, v95
	v_cvt_pk_bf16_f32 v96, v96, v97
	v_cvt_pk_bf16_f32 v97, v98, v99
	global_store_dwordx2 v112, v[92:93], s[2:3]
	global_store_dwordx2 v114, v[96:97], s[2:3]
	s_sub_u32 s2, s2, 0x400
	s_subb_u32 s3, s3, 0
	v_lshlrev_b32_e32 v92, 16, v36
	v_and_b32_e32 v93, 0xffff0000, v36
	v_lshlrev_b32_e32 v94, 16, v37
	v_and_b32_e32 v95, 0xffff0000, v37
	v_mul_f32_e32 v92, 0xbfb8aa3b, v92
	v_mul_f32_e32 v93, 0xbfb8aa3b, v93
	v_mul_f32_e32 v94, 0xbfb8aa3b, v94
	v_mul_f32_e32 v95, 0xbfb8aa3b, v95
	v_exp_f32_e32 v92, v92
	v_exp_f32_e32 v93, v93
	v_exp_f32_e32 v94, v94
	v_exp_f32_e32 v95, v95
	v_add_f32_e32 v92, 1.0, v92
	v_add_f32_e32 v93, 1.0, v93
	v_add_f32_e32 v94, 1.0, v94
	v_add_f32_e32 v95, 1.0, v95
	v_rcp_f32_e32 v92, v92
	v_rcp_f32_e32 v93, v93
	v_rcp_f32_e32 v94, v94
	v_rcp_f32_e32 v95, v95
	v_fma_f32 v96, v72, v92, v68
	v_fma_f32 v97, v73, v93, v69
	v_fma_f32 v98, v74, v94, v70
	v_fma_f32 v99, v75, v95, v71
	v_cmp_gt_f32_e64 s[22:23], s30, v96
	v_cmp_gt_f32_e64 s[24:25], s30, v97
	v_cmp_gt_f32_e64 s[26:27], s30, v98
	v_cmp_gt_f32_e64 s[28:29], s30, v99
	v_cndmask_b32_e64 v92, 0, 32, s[22:23]
	v_cndmask_b32_e64 v93, 0, 32, s[24:25]
	v_cndmask_b32_e64 v94, 0, 32, s[26:27]
	v_cndmask_b32_e64 v95, 0, 32, s[28:29]
	v_ldexp_f32 v92, v96, v92
	v_ldexp_f32 v93, v97, v93
	v_ldexp_f32 v94, v98, v94
	v_ldexp_f32 v95, v99, v95
	v_log_f32_e32 v92, v92
	v_log_f32_e32 v93, v93
	v_log_f32_e32 v94, v94
	v_log_f32_e32 v95, v95
	v_mul_f32_e32 v100, 0x3f317217, v92
	v_mul_f32_e32 v101, 0x3f317217, v93
	v_mul_f32_e32 v102, 0x3f317217, v94
	v_mul_f32_e32 v103, 0x3f317217, v95
	v_fma_f32 v100, v92, s31, -v100
	v_fma_f32 v101, v93, s31, -v101
	v_fma_f32 v102, v94, s31, -v102
	v_fma_f32 v103, v95, s31, -v103
	v_fmac_f32_e32 v100, 0x3377d1cf, v92
	v_fmac_f32_e32 v101, 0x3377d1cf, v93
	v_fmac_f32_e32 v102, 0x3377d1cf, v94
	v_fmac_f32_e32 v103, 0x3377d1cf, v95
	v_fmac_f32_e32 v100, 0x3f317217, v92
	v_fmac_f32_e32 v101, 0x3f317217, v93
	v_fmac_f32_e32 v102, 0x3f317217, v94
	v_fmac_f32_e32 v103, 0x3f317217, v95
; DEV u16 f2bf(float f) { return (u16)(pack2(f, f) & 0xffffu); }
; DEV float bf2f(u16 h) { return __uint_as_float(((unsigned)h) << 16); }
; DEV float sigmoid_f(float x) { return __builtin_amdgcn_rcpf(1.f + __expf(-x)); }
; DEV void phase_p15(const Params& p, int g) {
;     ...
;         for (int e = 0; e < 8; ++e) {
;           const int jj = j8 * 8 + e;
;           const int j = dir ? 63 - jj : jj;
;           const size_t tok = (size_t)cidx * 64 + j;
;           const float f = lb[cc] + (1.f - lb[cc]) * sigmoid_f(bf2f(xr[st][cc][e]));
;           G[cc] += __logf(f);
;           const float eg = __expf(G[cc]), ig = __expf(-G[cc]);
;           Qp[tok * 512 + c] = f2bf(bf2f(qr[st][cc][e]) * eg);
;           const u16 kk = f2bf((1.f - f) * ig);
;           Kp[tok * 512 + c] = kk;
;           kb[e] = kk;
;         }
;         const int s0 = dir ? 56 - 8 * j8 : 8 * j8;
;         uint4 w;
;         w.x = dir ? (kb[7] | (kb[6] << 16)) : (kb[0] | (kb[1] << 16));
;         w.y = dir ? (kb[5] | (kb[4] << 16)) : (kb[2] | (kb[3] << 16));
;         w.z = dir ? (kb[3] | (kb[2] << 16)) : (kb[4] | (kb[5] << 16));
;         w.w = dir ? (kb[1] | (kb[0] << 16)) : (kb[6] | (kb[7] << 16));
;         *(uint4*)(KT + (((size_t)cidx * 2 + dir) * 512 + c) * 64 + s0) = w;
	v_cmp_lt_f32_e64 vcc, |v92|, s34
	v_cndmask_b32_e32 v92, v92, v100, vcc
	v_cmp_lt_f32_e64 vcc, |v93|, s34
	v_cndmask_b32_e32 v93, v93, v101, vcc
	v_cmp_lt_f32_e64 vcc, |v94|, s34
	v_cndmask_b32_e32 v94, v94, v102, vcc
	v_cmp_lt_f32_e64 vcc, |v95|, s34
	v_cndmask_b32_e32 v95, v95, v103, vcc
	v_cndmask_b32_e64 v100, 0, v213, s[22:23]
	v_cndmask_b32_e64 v101, 0, v213, s[24:25]
	v_cndmask_b32_e64 v102, 0, v213, s[26:27]
	v_cndmask_b32_e64 v103, 0, v213, s[28:29]
	v_sub_f32_e32 v92, v92, v100
	v_sub_f32_e32 v93, v93, v101
	v_sub_f32_e32 v94, v94, v102
	v_sub_f32_e32 v95, v95, v103
	v_add_f32_e32 v64, v64, v92
	v_add_f32_e32 v65, v65, v93
	v_add_f32_e32 v66, v66, v94
	v_add_f32_e32 v67, v67, v95
	v_mul_f32_e32 v92, 0xbfb8aa3b, v64
	v_mul_f32_e32 v93, 0xbfb8aa3b, v65
	v_mul_f32_e32 v94, 0xbfb8aa3b, v66
	v_mul_f32_e32 v95, 0xbfb8aa3b, v67
	v_mul_f32_e32 v100, 0x3fb8aa3b, v64
	v_mul_f32_e32 v101, 0x3fb8aa3b, v65
	v_mul_f32_e32 v102, 0x3fb8aa3b, v66
	v_mul_f32_e32 v103, 0x3fb8aa3b, v67
	v_exp_f32_e32 v92, v92
	v_exp_f32_e32 v93, v93
	v_exp_f32_e32 v94, v94
	v_exp_f32_e32 v95, v95
	v_exp_f32_e32 v100, v100
	v_exp_f32_e32 v101, v101
	v_exp_f32_e32 v102, v102
	v_exp_f32_e32 v103, v103
	v_sub_f32_e32 v96, 1.0, v96
	v_sub_f32_e32 v97, 1.0, v97
	v_sub_f32_e32 v98, 1.0, v98
	v_sub_f32_e32 v99, 1.0, v99
	v_mul_f32_e32 v96, v96, v92
	v_mul_f32_e32 v97, v97, v93
	v_mul_f32_e32 v98, v98, v94
	v_mul_f32_e32 v99, v99, v95
	v_lshlrev_b32_e32 v92, 16, v38
	v_and_b32_e32 v93, 0xffff0000, v38
	v_lshlrev_b32_e32 v94, 16, v39
	v_and_b32_e32 v95, 0xffff0000, v39
	v_mul_f32_e32 v92, v92, v100
	v_mul_f32_e32 v93, v93, v101
	v_mul_f32_e32 v94, v94, v102
	v_mul_f32_e32 v95, v95, v103
	v_cvt_pk_bf16_f32 v119, v96, v119
	v_cvt_pk_bf16_f32 v135, v97, v135
	v_cvt_pk_bf16_f32 v169, v98, v169
	v_cvt_pk_bf16_f32 v185, v99, v185
	v_cvt_pk_bf16_f32 v92, v92, v93
	v_cvt_pk_bf16_f32 v93, v94, v95
	v_cvt_pk_bf16_f32 v96, v96, v97
	v_cvt_pk_bf16_f32 v97, v98, v99
	global_store_dwordx2 v112, v[92:93], s[2:3]
	global_store_dwordx2 v114, v[96:97], s[2:3]
	s_sub_u32 s2, s2, 0x400
	s_subb_u32 s3, s3, 0
	v_lshlrev_b32_e32 v92, 16, v40
	v_and_b32_e32 v93, 0xffff0000, v40
	v_lshlrev_b32_e32 v94, 16, v41
	v_and_b32_e32 v95, 0xffff0000, v41
	v_mul_f32_e32 v92, 0xbfb8aa3b, v92
	v_mul_f32_e32 v93, 0xbfb8aa3b, v93
	v_mul_f32_e32 v94, 0xbfb8aa3b, v94
	v_mul_f32_e32 v95, 0xbfb8aa3b, v95
	v_exp_f32_e32 v92, v92
	v_exp_f32_e32 v93, v93
	v_exp_f32_e32 v94, v94
	v_exp_f32_e32 v95, v95
	v_add_f32_e32 v92, 1.0, v92
	v_add_f32_e32 v93, 1.0, v93
	v_add_f32_e32 v94, 1.0, v94
	v_add_f32_e32 v95, 1.0, v95
	v_rcp_f32_e32 v92, v92
	v_rcp_f32_e32 v93, v93
	v_rcp_f32_e32 v94, v94
	v_rcp_f32_e32 v95, v95
	v_fma_f32 v96, v72, v92, v68
	v_fma_f32 v97, v73, v93, v69
	v_fma_f32 v98, v74, v94, v70
	v_fma_f32 v99, v75, v95, v71
	v_cmp_gt_f32_e64 s[22:23], s30, v96
	v_cmp_gt_f32_e64 s[24:25], s30, v97
	v_cmp_gt_f32_e64 s[26:27], s30, v98
	v_cmp_gt_f32_e64 s[28:29], s30, v99
	v_cndmask_b32_e64 v92, 0, 32, s[22:23]
	v_cndmask_b32_e64 v93, 0, 32, s[24:25]
	v_cndmask_b32_e64 v94, 0, 32, s[26:27]
	v_cndmask_b32_e64 v95, 0, 32, s[28:29]
	v_ldexp_f32 v92, v96, v92
	v_ldexp_f32 v93, v97, v93
	v_ldexp_f32 v94, v98, v94
	v_ldexp_f32 v95, v99, v95
	v_log_f32_e32 v92, v92
	v_log_f32_e32 v93, v93
	v_log_f32_e32 v94, v94
	v_log_f32_e32 v95, v95
	v_mul_f32_e32 v100, 0x3f317217, v92
	v_mul_f32_e32 v101, 0x3f317217, v93
	v_mul_f32_e32 v102, 0x3f317217, v94
	v_mul_f32_e32 v103, 0x3f317217, v95
	v_fma_f32 v100, v92, s31, -v100
	v_fma_f32 v101, v93, s31, -v101
	v_fma_f32 v102, v94, s31, -v102
	v_fma_f32 v103, v95, s31, -v103
	v_fmac_f32_e32 v100, 0x3377d1cf, v92
	v_fmac_f32_e32 v101, 0x3377d1cf, v93
	v_fmac_f32_e32 v102, 0x3377d1cf, v94
	v_fmac_f32_e32 v103, 0x3377d1cf, v95
	v_fmac_f32_e32 v100, 0x3f317217, v92
	v_fmac_f32_e32 v101, 0x3f317217, v93
	v_fmac_f32_e32 v102, 0x3f317217, v94
	v_fmac_f32_e32 v103, 0x3f317217, v95
	v_cmp_lt_f32_e64 vcc, |v92|, s34
	v_cndmask_b32_e32 v92, v92, v100, vcc
	v_cmp_lt_f32_e64 vcc, |v93|, s34
	v_cndmask_b32_e32 v93, v93, v101, vcc
	v_cmp_lt_f32_e64 vcc, |v94|, s34
	v_cndmask_b32_e32 v94, v94, v102, vcc
	v_cmp_lt_f32_e64 vcc, |v95|, s34
	v_cndmask_b32_e32 v95, v95, v103, vcc
	v_cndmask_b32_e64 v100, 0, v213, s[22:23]
	v_cndmask_b32_e64 v101, 0, v213, s[24:25]
	v_cndmask_b32_e64 v102, 0, v213, s[26:27]
	v_cndmask_b32_e64 v103, 0, v213, s[28:29]
	v_sub_f32_e32 v92, v92, v100
	v_sub_f32_e32 v93, v93, v101
	v_sub_f32_e32 v94, v94, v102
	v_sub_f32_e32 v95, v95, v103
	v_add_f32_e32 v64, v64, v92
	v_add_f32_e32 v65, v65, v93
	v_add_f32_e32 v66, v66, v94
	v_add_f32_e32 v67, v67, v95
	v_mul_f32_e32 v92, 0xbfb8aa3b, v64
	v_mul_f32_e32 v93, 0xbfb8aa3b, v65
	v_mul_f32_e32 v94, 0xbfb8aa3b, v66
	v_mul_f32_e32 v95, 0xbfb8aa3b, v67
	v_mul_f32_e32 v100, 0x3fb8aa3b, v64
	v_mul_f32_e32 v101, 0x3fb8aa3b, v65
	v_mul_f32_e32 v102, 0x3fb8aa3b, v66
	v_mul_f32_e32 v103, 0x3fb8aa3b, v67
	v_exp_f32_e32 v92, v92
	v_exp_f32_e32 v93, v93
	v_exp_f32_e32 v94, v94
	v_exp_f32_e32 v95, v95
	v_exp_f32_e32 v100, v100
	v_exp_f32_e32 v101, v101
	v_exp_f32_e32 v102, v102
	v_exp_f32_e32 v103, v103
	v_sub_f32_e32 v96, 1.0, v96
	v_sub_f32_e32 v97, 1.0, v97
	v_sub_f32_e32 v98, 1.0, v98
	v_sub_f32_e32 v99, 1.0, v99
	v_mul_f32_e32 v96, v96, v92
	v_mul_f32_e32 v97, v97, v93
	v_mul_f32_e32 v98, v98, v94
	v_mul_f32_e32 v99, v99, v95
	v_lshlrev_b32_e32 v92, 16, v42
	v_and_b32_e32 v93, 0xffff0000, v42
	v_lshlrev_b32_e32 v94, 16, v43
	v_and_b32_e32 v95, 0xffff0000, v43
	v_mul_f32_e32 v92, v92, v100
	v_mul_f32_e32 v93, v93, v101
	v_mul_f32_e32 v94, v94, v102
	v_mul_f32_e32 v95, v95, v103
	v_mov_b32_e32 v118, v96
	v_mov_b32_e32 v134, v97
	v_mov_b32_e32 v168, v98
; DEV u16 f2bf(float f) { return (u16)(pack2(f, f) & 0xffffu); }
; DEV float bf2f(u16 h) { return __uint_as_float(((unsigned)h) << 16); }
; DEV float sigmoid_f(float x) { return __builtin_amdgcn_rcpf(1.f + __expf(-x)); }
; DEV void phase_p15(const Params& p, int g) {
;     ...
;         for (int e = 0; e < 8; ++e) {
;           const int jj = j8 * 8 + e;
;           const int j = dir ? 63 - jj : jj;
;           const size_t tok = (size_t)cidx * 64 + j;
;           const float f = lb[cc] + (1.f - lb[cc]) * sigmoid_f(bf2f(xr[st][cc][e]));
;           G[cc] += __logf(f);
;           const float eg = __expf(G[cc]), ig = __expf(-G[cc]);
;           Qp[tok * 512 + c] = f2bf(bf2f(qr[st][cc][e]) * eg);
;           const u16 kk = f2bf((1.f - f) * ig);
;           Kp[tok * 512 + c] = kk;
;           kb[e] = kk;
;         }
;         const int s0 = dir ? 56 - 8 * j8 : 8 * j8;
;         uint4 w;
;         w.x = dir ? (kb[7] | (kb[6] << 16)) : (kb[0] | (kb[1] << 16));
;         w.y = dir ? (kb[5] | (kb[4] << 16)) : (kb[2] | (kb[3] << 16));
;         w.z = dir ? (kb[3] | (kb[2] << 16)) : (kb[4] | (kb[5] << 16));
;         w.w = dir ? (kb[1] | (kb[0] << 16)) : (kb[6] | (kb[7] << 16));
;         *(uint4*)(KT + (((size_t)cidx * 2 + dir) * 512 + c) * 64 + s0) = w;
	v_mov_b32_e32 v184, v99
	v_cvt_pk_bf16_f32 v92, v92, v93
	v_cvt_pk_bf16_f32 v93, v94, v95
	v_cvt_pk_bf16_f32 v96, v96, v97
	v_cvt_pk_bf16_f32 v97, v98, v99
	global_store_dwordx2 v112, v[92:93], s[2:3]
	global_store_dwordx2 v114, v[96:97], s[2:3]
	s_sub_u32 s2, s2, 0x400
	s_subb_u32 s3, s3, 0
	v_lshlrev_b32_e32 v92, 16, v44
	v_and_b32_e32 v93, 0xffff0000, v44
	v_lshlrev_b32_e32 v94, 16, v45
	v_and_b32_e32 v95, 0xffff0000, v45
	v_mul_f32_e32 v92, 0xbfb8aa3b, v92
	v_mul_f32_e32 v93, 0xbfb8aa3b, v93
	v_mul_f32_e32 v94, 0xbfb8aa3b, v94
	v_mul_f32_e32 v95, 0xbfb8aa3b, v95
	v_exp_f32_e32 v92, v92
	v_exp_f32_e32 v93, v93
	v_exp_f32_e32 v94, v94
	v_exp_f32_e32 v95, v95
	v_add_f32_e32 v92, 1.0, v92
	v_add_f32_e32 v93, 1.0, v93
	v_add_f32_e32 v94, 1.0, v94
	v_add_f32_e32 v95, 1.0, v95
	v_rcp_f32_e32 v92, v92
	v_rcp_f32_e32 v93, v93
	v_rcp_f32_e32 v94, v94
	v_rcp_f32_e32 v95, v95
	v_fma_f32 v96, v72, v92, v68
	v_fma_f32 v97, v73, v93, v69
	v_fma_f32 v98, v74, v94, v70
	v_fma_f32 v99, v75, v95, v71
	v_cmp_gt_f32_e64 s[22:23], s30, v96
	v_cmp_gt_f32_e64 s[24:25], s30, v97
	v_cmp_gt_f32_e64 s[26:27], s30, v98
	v_cmp_gt_f32_e64 s[28:29], s30, v99
	v_cndmask_b32_e64 v92, 0, 32, s[22:23]
	v_cndmask_b32_e64 v93, 0, 32, s[24:25]
	v_cndmask_b32_e64 v94, 0, 32, s[26:27]
	v_cndmask_b32_e64 v95, 0, 32, s[28:29]
	v_ldexp_f32 v92, v96, v92
	v_ldexp_f32 v93, v97, v93
	v_ldexp_f32 v94, v98, v94
	v_ldexp_f32 v95, v99, v95
	v_log_f32_e32 v92, v92
	v_log_f32_e32 v93, v93
	v_log_f32_e32 v94, v94
	v_log_f32_e32 v95, v95
	v_mul_f32_e32 v100, 0x3f317217, v92
	v_mul_f32_e32 v101, 0x3f317217, v93
	v_mul_f32_e32 v102, 0x3f317217, v94
	v_mul_f32_e32 v103, 0x3f317217, v95
	v_fma_f32 v100, v92, s31, -v100
	v_fma_f32 v101, v93, s31, -v101
	v_fma_f32 v102, v94, s31, -v102
	v_fma_f32 v103, v95, s31, -v103
	v_fmac_f32_e32 v100, 0x3377d1cf, v92
	v_fmac_f32_e32 v101, 0x3377d1cf, v93
	v_fmac_f32_e32 v102, 0x3377d1cf, v94
	v_fmac_f32_e32 v103, 0x3377d1cf, v95
	v_fmac_f32_e32 v100, 0x3f317217, v92
	v_fmac_f32_e32 v101, 0x3f317217, v93
	v_fmac_f32_e32 v102, 0x3f317217, v94
	v_fmac_f32_e32 v103, 0x3f317217, v95
	v_cmp_lt_f32_e64 vcc, |v92|, s34
	v_cndmask_b32_e32 v92, v92, v100, vcc
	v_cmp_lt_f32_e64 vcc, |v93|, s34
	v_cndmask_b32_e32 v93, v93, v101, vcc
	v_cmp_lt_f32_e64 vcc, |v94|, s34
	v_cndmask_b32_e32 v94, v94, v102, vcc
	v_cmp_lt_f32_e64 vcc, |v95|, s34
	v_cndmask_b32_e32 v95, v95, v103, vcc
	v_cndmask_b32_e64 v100, 0, v213, s[22:23]
	v_cndmask_b32_e64 v101, 0, v213, s[24:25]
	v_cndmask_b32_e64 v102, 0, v213, s[26:27]
	v_cndmask_b32_e64 v103, 0, v213, s[28:29]
	v_sub_f32_e32 v92, v92, v100
	v_sub_f32_e32 v93, v93, v101
	v_sub_f32_e32 v94, v94, v102
	v_sub_f32_e32 v95, v95, v103
	v_add_f32_e32 v64, v64, v92
	v_add_f32_e32 v65, v65, v93
	v_add_f32_e32 v66, v66, v94
	v_add_f32_e32 v67, v67, v95
	v_mul_f32_e32 v92, 0xbfb8aa3b, v64
	v_mul_f32_e32 v93, 0xbfb8aa3b, v65
	v_mul_f32_e32 v94, 0xbfb8aa3b, v66
	v_mul_f32_e32 v95, 0xbfb8aa3b, v67
	v_mul_f32_e32 v100, 0x3fb8aa3b, v64
	v_mul_f32_e32 v101, 0x3fb8aa3b, v65
	v_mul_f32_e32 v102, 0x3fb8aa3b, v66
	v_mul_f32_e32 v103, 0x3fb8aa3b, v67
	v_exp_f32_e32 v92, v92
	v_exp_f32_e32 v93, v93
	v_exp_f32_e32 v94, v94
	v_exp_f32_e32 v95, v95
	v_exp_f32_e32 v100, v100
	v_exp_f32_e32 v101, v101
	v_exp_f32_e32 v102, v102
	v_exp_f32_e32 v103, v103
	v_sub_f32_e32 v96, 1.0, v96
	v_sub_f32_e32 v97, 1.0, v97
	v_sub_f32_e32 v98, 1.0, v98
	v_sub_f32_e32 v99, 1.0, v99
	v_mul_f32_e32 v96, v96, v92
	v_mul_f32_e32 v97, v97, v93
	v_mul_f32_e32 v98, v98, v94
	v_mul_f32_e32 v99, v99, v95
	v_lshlrev_b32_e32 v92, 16, v46
	v_and_b32_e32 v93, 0xffff0000, v46
	v_lshlrev_b32_e32 v94, 16, v47
	v_and_b32_e32 v95, 0xffff0000, v47
	v_mul_f32_e32 v92, v92, v100
	v_mul_f32_e32 v93, v93, v101
	v_mul_f32_e32 v94, v94, v102
	v_mul_f32_e32 v95, v95, v103
	v_cvt_pk_bf16_f32 v118, v96, v118
	v_cvt_pk_bf16_f32 v134, v97, v134
	v_cvt_pk_bf16_f32 v168, v98, v168
	v_cvt_pk_bf16_f32 v184, v99, v184
	v_cvt_pk_bf16_f32 v92, v92, v93
	v_cvt_pk_bf16_f32 v93, v94, v95
	v_cvt_pk_bf16_f32 v96, v96, v97
	v_cvt_pk_bf16_f32 v97, v98, v99
	global_store_dwordx2 v112, v[92:93], s[2:3]
	global_store_dwordx2 v114, v[96:97], s[2:3]
	s_sub_u32 s2, s2, 0x400
	s_subb_u32 s3, s3, 0
	v_lshlrev_b32_e32 v92, 16, v48
	v_and_b32_e32 v93, 0xffff0000, v48
	v_lshlrev_b32_e32 v94, 16, v49
	v_and_b32_e32 v95, 0xffff0000, v49
	v_mul_f32_e32 v92, 0xbfb8aa3b, v92
	v_mul_f32_e32 v93, 0xbfb8aa3b, v93
	v_mul_f32_e32 v94, 0xbfb8aa3b, v94
	v_mul_f32_e32 v95, 0xbfb8aa3b, v95
	v_exp_f32_e32 v92, v92
	v_exp_f32_e32 v93, v93
	v_exp_f32_e32 v94, v94
	v_exp_f32_e32 v95, v95
	v_add_f32_e32 v92, 1.0, v92
	v_add_f32_e32 v93, 1.0, v93
	v_add_f32_e32 v94, 1.0, v94
	v_add_f32_e32 v95, 1.0, v95
	v_rcp_f32_e32 v92, v92
	v_rcp_f32_e32 v93, v93
	v_rcp_f32_e32 v94, v94
	v_rcp_f32_e32 v95, v95
	v_fma_f32 v96, v72, v92, v68
	v_fma_f32 v97, v73, v93, v69
	v_fma_f32 v98, v74, v94, v70
	v_fma_f32 v99, v75, v95, v71
	v_cmp_gt_f32_e64 s[22:23], s30, v96
	v_cmp_gt_f32_e64 s[24:25], s30, v97
	v_cmp_gt_f32_e64 s[26:27], s30, v98
	v_cmp_gt_f32_e64 s[28:29], s30, v99
	v_cndmask_b32_e64 v92, 0, 32, s[22:23]
	v_cndmask_b32_e64 v93, 0, 32, s[24:25]
	v_cndmask_b32_e64 v94, 0, 32, s[26:27]
	v_cndmask_b32_e64 v95, 0, 32, s[28:29]
	v_ldexp_f32 v92, v96, v92
	v_ldexp_f32 v93, v97, v93
	v_ldexp_f32 v94, v98, v94
	v_ldexp_f32 v95, v99, v95
	v_log_f32_e32 v92, v92
	v_log_f32_e32 v93, v93
	v_log_f32_e32 v94, v94
	v_log_f32_e32 v95, v95
	v_mul_f32_e32 v100, 0x3f317217, v92
	v_mul_f32_e32 v101, 0x3f317217, v93
	v_mul_f32_e32 v102, 0x3f317217, v94
	v_mul_f32_e32 v103, 0x3f317217, v95
	v_fma_f32 v100, v92, s31, -v100
	v_fma_f32 v101, v93, s31, -v101
	v_fma_f32 v102, v94, s31, -v102
; DEV u16 f2bf(float f) { return (u16)(pack2(f, f) & 0xffffu); }
; DEV float bf2f(u16 h) { return __uint_as_float(((unsigned)h) << 16); }
; DEV float sigmoid_f(float x) { return __builtin_amdgcn_rcpf(1.f + __expf(-x)); }
; DEV void phase_p15(const Params& p, int g) {
;     ...
;         for (int e = 0; e < 8; ++e) {
;           const int jj = j8 * 8 + e;
;           const int j = dir ? 63 - jj : jj;
;           const size_t tok = (size_t)cidx * 64 + j;
;           const float f = lb[cc] + (1.f - lb[cc]) * sigmoid_f(bf2f(xr[st][cc][e]));
;           G[cc] += __logf(f);
;           const float eg = __expf(G[cc]), ig = __expf(-G[cc]);
;           Qp[tok * 512 + c] = f2bf(bf2f(qr[st][cc][e]) * eg);
;           const u16 kk = f2bf((1.f - f) * ig);
;           Kp[tok * 512 + c] = kk;
;           kb[e] = kk;
;         }
;         const int s0 = dir ? 56 - 8 * j8 : 8 * j8;
;         uint4 w;
;         w.x = dir ? (kb[7] | (kb[6] << 16)) : (kb[0] | (kb[1] << 16));
;         w.y = dir ? (kb[5] | (kb[4] << 16)) : (kb[2] | (kb[3] << 16));
;         w.z = dir ? (kb[3] | (kb[2] << 16)) : (kb[4] | (kb[5] << 16));
;         w.w = dir ? (kb[1] | (kb[0] << 16)) : (kb[6] | (kb[7] << 16));
;         *(uint4*)(KT + (((size_t)cidx * 2 + dir) * 512 + c) * 64 + s0) = w;
	v_fma_f32 v103, v95, s31, -v103
	v_fmac_f32_e32 v100, 0x3377d1cf, v92
	v_fmac_f32_e32 v101, 0x3377d1cf, v93
	v_fmac_f32_e32 v102, 0x3377d1cf, v94
	v_fmac_f32_e32 v103, 0x3377d1cf, v95
	v_fmac_f32_e32 v100, 0x3f317217, v92
	v_fmac_f32_e32 v101, 0x3f317217, v93
	v_fmac_f32_e32 v102, 0x3f317217, v94
	v_fmac_f32_e32 v103, 0x3f317217, v95
	v_cmp_lt_f32_e64 vcc, |v92|, s34
	v_cndmask_b32_e32 v92, v92, v100, vcc
	v_cmp_lt_f32_e64 vcc, |v93|, s34
	v_cndmask_b32_e32 v93, v93, v101, vcc
	v_cmp_lt_f32_e64 vcc, |v94|, s34
	v_cndmask_b32_e32 v94, v94, v102, vcc
	v_cmp_lt_f32_e64 vcc, |v95|, s34
	v_cndmask_b32_e32 v95, v95, v103, vcc
	v_cndmask_b32_e64 v100, 0, v213, s[22:23]
	v_cndmask_b32_e64 v101, 0, v213, s[24:25]
	v_cndmask_b32_e64 v102, 0, v213, s[26:27]
	v_cndmask_b32_e64 v103, 0, v213, s[28:29]
	v_sub_f32_e32 v92, v92, v100
	v_sub_f32_e32 v93, v93, v101
	v_sub_f32_e32 v94, v94, v102
	v_sub_f32_e32 v95, v95, v103
	v_add_f32_e32 v64, v64, v92
	v_add_f32_e32 v65, v65, v93
	v_add_f32_e32 v66, v66, v94
	v_add_f32_e32 v67, v67, v95
	v_mul_f32_e32 v92, 0xbfb8aa3b, v64
	v_mul_f32_e32 v93, 0xbfb8aa3b, v65
	v_mul_f32_e32 v94, 0xbfb8aa3b, v66
	v_mul_f32_e32 v95, 0xbfb8aa3b, v67
	v_mul_f32_e32 v100, 0x3fb8aa3b, v64
	v_mul_f32_e32 v101, 0x3fb8aa3b, v65
	v_mul_f32_e32 v102, 0x3fb8aa3b, v66
	v_mul_f32_e32 v103, 0x3fb8aa3b, v67
	v_exp_f32_e32 v92, v92
	v_exp_f32_e32 v93, v93
	v_exp_f32_e32 v94, v94
	v_exp_f32_e32 v95, v95
	v_exp_f32_e32 v100, v100
	v_exp_f32_e32 v101, v101
	v_exp_f32_e32 v102, v102
	v_exp_f32_e32 v103, v103
	v_sub_f32_e32 v96, 1.0, v96
	v_sub_f32_e32 v97, 1.0, v97
	v_sub_f32_e32 v98, 1.0, v98
	v_sub_f32_e32 v99, 1.0, v99
	v_mul_f32_e32 v96, v96, v92
	v_mul_f32_e32 v97, v97, v93
	v_mul_f32_e32 v98, v98, v94
	v_mul_f32_e32 v99, v99, v95
	v_lshlrev_b32_e32 v92, 16, v50
	v_and_b32_e32 v93, 0xffff0000, v50
	v_lshlrev_b32_e32 v94, 16, v51
	v_and_b32_e32 v95, 0xffff0000, v51
	v_mul_f32_e32 v92, v92, v100
	v_mul_f32_e32 v93, v93, v101
	v_mul_f32_e32 v94, v94, v102
	v_mul_f32_e32 v95, v95, v103
	v_mov_b32_e32 v117, v96
	v_mov_b32_e32 v133, v97
	v_mov_b32_e32 v167, v98
	v_mov_b32_e32 v183, v99
	v_cvt_pk_bf16_f32 v92, v92, v93
	v_cvt_pk_bf16_f32 v93, v94, v95
	v_cvt_pk_bf16_f32 v96, v96, v97
	v_cvt_pk_bf16_f32 v97, v98, v99
	global_store_dwordx2 v112, v[92:93], s[2:3]
	global_store_dwordx2 v114, v[96:97], s[2:3]
	s_sub_u32 s2, s2, 0x400
	s_subb_u32 s3, s3, 0
	v_lshlrev_b32_e32 v92, 16, v52
	v_and_b32_e32 v93, 0xffff0000, v52
	v_lshlrev_b32_e32 v94, 16, v53
	v_and_b32_e32 v95, 0xffff0000, v53
	v_mul_f32_e32 v92, 0xbfb8aa3b, v92
	v_mul_f32_e32 v93, 0xbfb8aa3b, v93
	v_mul_f32_e32 v94, 0xbfb8aa3b, v94
	v_mul_f32_e32 v95, 0xbfb8aa3b, v95
	v_exp_f32_e32 v92, v92
	v_exp_f32_e32 v93, v93
	v_exp_f32_e32 v94, v94
	v_exp_f32_e32 v95, v95
	v_add_f32_e32 v92, 1.0, v92
	v_add_f32_e32 v93, 1.0, v93
	v_add_f32_e32 v94, 1.0, v94
	v_add_f32_e32 v95, 1.0, v95
	v_rcp_f32_e32 v92, v92
	v_rcp_f32_e32 v93, v93
	v_rcp_f32_e32 v94, v94
	v_rcp_f32_e32 v95, v95
	v_fma_f32 v96, v72, v92, v68
	v_fma_f32 v97, v73, v93, v69
	v_fma_f32 v98, v74, v94, v70
	v_fma_f32 v99, v75, v95, v71
	v_cmp_gt_f32_e64 s[22:23], s30, v96
	v_cmp_gt_f32_e64 s[24:25], s30, v97
	v_cmp_gt_f32_e64 s[26:27], s30, v98
	v_cmp_gt_f32_e64 s[28:29], s30, v99
	v_cndmask_b32_e64 v92, 0, 32, s[22:23]
	v_cndmask_b32_e64 v93, 0, 32, s[24:25]
	v_cndmask_b32_e64 v94, 0, 32, s[26:27]
	v_cndmask_b32_e64 v95, 0, 32, s[28:29]
	v_ldexp_f32 v92, v96, v92
	v_ldexp_f32 v93, v97, v93
	v_ldexp_f32 v94, v98, v94
	v_ldexp_f32 v95, v99, v95
	v_log_f32_e32 v92, v92
	v_log_f32_e32 v93, v93
	v_log_f32_e32 v94, v94
	v_log_f32_e32 v95, v95
	v_mul_f32_e32 v100, 0x3f317217, v92
	v_mul_f32_e32 v101, 0x3f317217, v93
	v_mul_f32_e32 v102, 0x3f317217, v94
	v_mul_f32_e32 v103, 0x3f317217, v95
	v_fma_f32 v100, v92, s31, -v100
	v_fma_f32 v101, v93, s31, -v101
	v_fma_f32 v102, v94, s31, -v102
	v_fma_f32 v103, v95, s31, -v103
	v_fmac_f32_e32 v100, 0x3377d1cf, v92
	v_fmac_f32_e32 v101, 0x3377d1cf, v93
	v_fmac_f32_e32 v102, 0x3377d1cf, v94
	v_fmac_f32_e32 v103, 0x3377d1cf, v95
	v_fmac_f32_e32 v100, 0x3f317217, v92
	v_fmac_f32_e32 v101, 0x3f317217, v93
	v_fmac_f32_e32 v102, 0x3f317217, v94
	v_fmac_f32_e32 v103, 0x3f317217, v95
	v_cmp_lt_f32_e64 vcc, |v92|, s34
	v_cndmask_b32_e32 v92, v92, v100, vcc
	v_cmp_lt_f32_e64 vcc, |v93|, s34
	v_cndmask_b32_e32 v93, v93, v101, vcc
	v_cmp_lt_f32_e64 vcc, |v94|, s34
	v_cndmask_b32_e32 v94, v94, v102, vcc
	v_cmp_lt_f32_e64 vcc, |v95|, s34
	v_cndmask_b32_e32 v95, v95, v103, vcc
	v_cndmask_b32_e64 v100, 0, v213, s[22:23]
	v_cndmask_b32_e64 v101, 0, v213, s[24:25]
	v_cndmask_b32_e64 v102, 0, v213, s[26:27]
	v_cndmask_b32_e64 v103, 0, v213, s[28:29]
	v_sub_f32_e32 v92, v92, v100
	v_sub_f32_e32 v93, v93, v101
	v_sub_f32_e32 v94, v94, v102
	v_sub_f32_e32 v95, v95, v103
	v_add_f32_e32 v64, v64, v92
	v_add_f32_e32 v65, v65, v93
	v_add_f32_e32 v66, v66, v94
	v_add_f32_e32 v67, v67, v95
	v_mul_f32_e32 v92, 0xbfb8aa3b, v64
	v_mul_f32_e32 v93, 0xbfb8aa3b, v65
	v_mul_f32_e32 v94, 0xbfb8aa3b, v66
	v_mul_f32_e32 v95, 0xbfb8aa3b, v67
	v_mul_f32_e32 v100, 0x3fb8aa3b, v64
	v_mul_f32_e32 v101, 0x3fb8aa3b, v65
	v_mul_f32_e32 v102, 0x3fb8aa3b, v66
	v_mul_f32_e32 v103, 0x3fb8aa3b, v67
	v_exp_f32_e32 v92, v92
	v_exp_f32_e32 v93, v93
	v_exp_f32_e32 v94, v94
	v_exp_f32_e32 v95, v95
	v_exp_f32_e32 v100, v100
	v_exp_f32_e32 v101, v101
	v_exp_f32_e32 v102, v102
	v_exp_f32_e32 v103, v103
	v_sub_f32_e32 v96, 1.0, v96
	v_sub_f32_e32 v97, 1.0, v97
	v_sub_f32_e32 v98, 1.0, v98
	v_sub_f32_e32 v99, 1.0, v99
	v_mul_f32_e32 v96, v96, v92
	v_mul_f32_e32 v97, v97, v93
	v_mul_f32_e32 v98, v98, v94
	v_mul_f32_e32 v99, v99, v95
	v_lshlrev_b32_e32 v92, 16, v54
; DEV u16 f2bf(float f) { return (u16)(pack2(f, f) & 0xffffu); }
; DEV float bf2f(u16 h) { return __uint_as_float(((unsigned)h) << 16); }
; DEV float sigmoid_f(float x) { return __builtin_amdgcn_rcpf(1.f + __expf(-x)); }
; DEV void phase_p15(const Params& p, int g) {
;     ...
;         for (int e = 0; e < 8; ++e) {
;           const int jj = j8 * 8 + e;
;           const int j = dir ? 63 - jj : jj;
;           const size_t tok = (size_t)cidx * 64 + j;
;           const float f = lb[cc] + (1.f - lb[cc]) * sigmoid_f(bf2f(xr[st][cc][e]));
;           G[cc] += __logf(f);
;           const float eg = __expf(G[cc]), ig = __expf(-G[cc]);
;           Qp[tok * 512 + c] = f2bf(bf2f(qr[st][cc][e]) * eg);
;           const u16 kk = f2bf((1.f - f) * ig);
;           Kp[tok * 512 + c] = kk;
;           kb[e] = kk;
;         }
;         const int s0 = dir ? 56 - 8 * j8 : 8 * j8;
;         uint4 w;
;         w.x = dir ? (kb[7] | (kb[6] << 16)) : (kb[0] | (kb[1] << 16));
;         w.y = dir ? (kb[5] | (kb[4] << 16)) : (kb[2] | (kb[3] << 16));
;         w.z = dir ? (kb[3] | (kb[2] << 16)) : (kb[4] | (kb[5] << 16));
;         w.w = dir ? (kb[1] | (kb[0] << 16)) : (kb[6] | (kb[7] << 16));
;         *(uint4*)(KT + (((size_t)cidx * 2 + dir) * 512 + c) * 64 + s0) = w;
	v_and_b32_e32 v93, 0xffff0000, v54
	v_lshlrev_b32_e32 v94, 16, v55
	v_and_b32_e32 v95, 0xffff0000, v55
	v_mul_f32_e32 v92, v92, v100
	v_mul_f32_e32 v93, v93, v101
	v_mul_f32_e32 v94, v94, v102
	v_mul_f32_e32 v95, v95, v103
	v_cvt_pk_bf16_f32 v117, v96, v117
	v_cvt_pk_bf16_f32 v133, v97, v133
	v_cvt_pk_bf16_f32 v167, v98, v167
	v_cvt_pk_bf16_f32 v183, v99, v183
	v_cvt_pk_bf16_f32 v92, v92, v93
	v_cvt_pk_bf16_f32 v93, v94, v95
	v_cvt_pk_bf16_f32 v96, v96, v97
	v_cvt_pk_bf16_f32 v97, v98, v99
	global_store_dwordx2 v112, v[92:93], s[2:3]
	global_store_dwordx2 v114, v[96:97], s[2:3]
	s_sub_u32 s2, s2, 0x400
	s_subb_u32 s3, s3, 0
	v_lshlrev_b32_e32 v92, 16, v56
	v_and_b32_e32 v93, 0xffff0000, v56
	v_lshlrev_b32_e32 v94, 16, v57
	v_and_b32_e32 v95, 0xffff0000, v57
	v_mul_f32_e32 v92, 0xbfb8aa3b, v92
	v_mul_f32_e32 v93, 0xbfb8aa3b, v93
	v_mul_f32_e32 v94, 0xbfb8aa3b, v94
	v_mul_f32_e32 v95, 0xbfb8aa3b, v95
	v_exp_f32_e32 v92, v92
	v_exp_f32_e32 v93, v93
	v_exp_f32_e32 v94, v94
	v_exp_f32_e32 v95, v95
	v_add_f32_e32 v92, 1.0, v92
	v_add_f32_e32 v93, 1.0, v93
	v_add_f32_e32 v94, 1.0, v94
	v_add_f32_e32 v95, 1.0, v95
	v_rcp_f32_e32 v92, v92
	v_rcp_f32_e32 v93, v93
	v_rcp_f32_e32 v94, v94
	v_rcp_f32_e32 v95, v95
	v_fma_f32 v96, v72, v92, v68
	v_fma_f32 v97, v73, v93, v69
	v_fma_f32 v98, v74, v94, v70
	v_fma_f32 v99, v75, v95, v71
	v_cmp_gt_f32_e64 s[22:23], s30, v96
	v_cmp_gt_f32_e64 s[24:25], s30, v97
	v_cmp_gt_f32_e64 s[26:27], s30, v98
	v_cmp_gt_f32_e64 s[28:29], s30, v99
	v_cndmask_b32_e64 v92, 0, 32, s[22:23]
	v_cndmask_b32_e64 v93, 0, 32, s[24:25]
	v_cndmask_b32_e64 v94, 0, 32, s[26:27]
	v_cndmask_b32_e64 v95, 0, 32, s[28:29]
	v_ldexp_f32 v92, v96, v92
	v_ldexp_f32 v93, v97, v93
	v_ldexp_f32 v94, v98, v94
	v_ldexp_f32 v95, v99, v95
	v_log_f32_e32 v92, v92
	v_log_f32_e32 v93, v93
	v_log_f32_e32 v94, v94
	v_log_f32_e32 v95, v95
	v_mul_f32_e32 v100, 0x3f317217, v92
	v_mul_f32_e32 v101, 0x3f317217, v93
	v_mul_f32_e32 v102, 0x3f317217, v94
	v_mul_f32_e32 v103, 0x3f317217, v95
	v_fma_f32 v100, v92, s31, -v100
	v_fma_f32 v101, v93, s31, -v101
	v_fma_f32 v102, v94, s31, -v102
	v_fma_f32 v103, v95, s31, -v103
	v_fmac_f32_e32 v100, 0x3377d1cf, v92
	v_fmac_f32_e32 v101, 0x3377d1cf, v93
	v_fmac_f32_e32 v102, 0x3377d1cf, v94
	v_fmac_f32_e32 v103, 0x3377d1cf, v95
	v_fmac_f32_e32 v100, 0x3f317217, v92
	v_fmac_f32_e32 v101, 0x3f317217, v93
	v_fmac_f32_e32 v102, 0x3f317217, v94
	v_fmac_f32_e32 v103, 0x3f317217, v95
	v_cmp_lt_f32_e64 vcc, |v92|, s34
	v_cndmask_b32_e32 v92, v92, v100, vcc
	v_cmp_lt_f32_e64 vcc, |v93|, s34
	v_cndmask_b32_e32 v93, v93, v101, vcc
	v_cmp_lt_f32_e64 vcc, |v94|, s34
	v_cndmask_b32_e32 v94, v94, v102, vcc
	v_cmp_lt_f32_e64 vcc, |v95|, s34
	v_cndmask_b32_e32 v95, v95, v103, vcc
	v_cndmask_b32_e64 v100, 0, v213, s[22:23]
	v_cndmask_b32_e64 v101, 0, v213, s[24:25]
	v_cndmask_b32_e64 v102, 0, v213, s[26:27]
	v_cndmask_b32_e64 v103, 0, v213, s[28:29]
	v_sub_f32_e32 v92, v92, v100
	v_sub_f32_e32 v93, v93, v101
	v_sub_f32_e32 v94, v94, v102
	v_sub_f32_e32 v95, v95, v103
	v_add_f32_e32 v64, v64, v92
	v_add_f32_e32 v65, v65, v93
	v_add_f32_e32 v66, v66, v94
	v_add_f32_e32 v67, v67, v95
	v_mul_f32_e32 v92, 0xbfb8aa3b, v64
	v_mul_f32_e32 v93, 0xbfb8aa3b, v65
	v_mul_f32_e32 v94, 0xbfb8aa3b, v66
	v_mul_f32_e32 v95, 0xbfb8aa3b, v67
	v_mul_f32_e32 v100, 0x3fb8aa3b, v64
	v_mul_f32_e32 v101, 0x3fb8aa3b, v65
	v_mul_f32_e32 v102, 0x3fb8aa3b, v66
	v_mul_f32_e32 v103, 0x3fb8aa3b, v67
	v_exp_f32_e32 v92, v92
	v_exp_f32_e32 v93, v93
	v_exp_f32_e32 v94, v94
	v_exp_f32_e32 v95, v95
	v_exp_f32_e32 v100, v100
	v_exp_f32_e32 v101, v101
	v_exp_f32_e32 v102, v102
	v_exp_f32_e32 v103, v103
	v_sub_f32_e32 v96, 1.0, v96
	v_sub_f32_e32 v97, 1.0, v97
	v_sub_f32_e32 v98, 1.0, v98
	v_sub_f32_e32 v99, 1.0, v99
	v_mul_f32_e32 v96, v96, v92
	v_mul_f32_e32 v97, v97, v93
	v_mul_f32_e32 v98, v98, v94
	v_mul_f32_e32 v99, v99, v95
	v_lshlrev_b32_e32 v92, 16, v58
	v_and_b32_e32 v93, 0xffff0000, v58
	v_lshlrev_b32_e32 v94, 16, v59
	v_and_b32_e32 v95, 0xffff0000, v59
	v_mul_f32_e32 v92, v92, v100
	v_mul_f32_e32 v93, v93, v101
	v_mul_f32_e32 v94, v94, v102
	v_mul_f32_e32 v95, v95, v103
	v_mov_b32_e32 v116, v96
	v_mov_b32_e32 v132, v97
	v_mov_b32_e32 v166, v98
	v_mov_b32_e32 v182, v99
	v_cvt_pk_bf16_f32 v92, v92, v93
	v_cvt_pk_bf16_f32 v93, v94, v95
	v_cvt_pk_bf16_f32 v96, v96, v97
	v_cvt_pk_bf16_f32 v97, v98, v99
	global_store_dwordx2 v112, v[92:93], s[2:3]
	global_store_dwordx2 v114, v[96:97], s[2:3]
	s_sub_u32 s2, s2, 0x400
	s_subb_u32 s3, s3, 0
	v_lshlrev_b32_e32 v92, 16, v60
	v_and_b32_e32 v93, 0xffff0000, v60
	v_lshlrev_b32_e32 v94, 16, v61
	v_and_b32_e32 v95, 0xffff0000, v61
	v_mul_f32_e32 v92, 0xbfb8aa3b, v92
	v_mul_f32_e32 v93, 0xbfb8aa3b, v93
	v_mul_f32_e32 v94, 0xbfb8aa3b, v94
	v_mul_f32_e32 v95, 0xbfb8aa3b, v95
	v_exp_f32_e32 v92, v92
	v_exp_f32_e32 v93, v93
	v_exp_f32_e32 v94, v94
	v_exp_f32_e32 v95, v95
	v_add_f32_e32 v92, 1.0, v92
	v_add_f32_e32 v93, 1.0, v93
	v_add_f32_e32 v94, 1.0, v94
	v_add_f32_e32 v95, 1.0, v95
	v_rcp_f32_e32 v92, v92
	v_rcp_f32_e32 v93, v93
	v_rcp_f32_e32 v94, v94
	v_rcp_f32_e32 v95, v95
	v_fma_f32 v96, v72, v92, v68
	v_fma_f32 v97, v73, v93, v69
	v_fma_f32 v98, v74, v94, v70
	v_fma_f32 v99, v75, v95, v71
	v_cmp_gt_f32_e64 s[22:23], s30, v96
	v_cmp_gt_f32_e64 s[24:25], s30, v97
	v_cmp_gt_f32_e64 s[26:27], s30, v98
	v_cmp_gt_f32_e64 s[28:29], s30, v99
	v_cndmask_b32_e64 v92, 0, 32, s[22:23]
	v_cndmask_b32_e64 v93, 0, 32, s[24:25]
	v_cndmask_b32_e64 v94, 0, 32, s[26:27]
	v_cndmask_b32_e64 v95, 0, 32, s[28:29]
	v_ldexp_f32 v92, v96, v92
	v_ldexp_f32 v93, v97, v93
	v_ldexp_f32 v94, v98, v94
	v_ldexp_f32 v95, v99, v95
	v_log_f32_e32 v92, v92
; DEV u16 f2bf(float f) { return (u16)(pack2(f, f) & 0xffffu); }
; DEV float bf2f(u16 h) { return __uint_as_float(((unsigned)h) << 16); }
; DEV float sigmoid_f(float x) { return __builtin_amdgcn_rcpf(1.f + __expf(-x)); }
; DEV void phase_p15(const Params& p, int g) {
;     ...
;     P15_LOAD(0, 0);
;     P15_LOAD(1, 1);
; #pragma unroll
;     for (int j8 = 0; j8 < 8; ++j8) {
;       const int st = j8 % 3;
;       if (j8 < 6) { P15_LOAD((j8 + 2) % 3, j8 + 2); }
;     ...
;         for (int e = 0; e < 8; ++e) {
;           const int jj = j8 * 8 + e;
;           const int j = dir ? 63 - jj : jj;
;           const size_t tok = (size_t)cidx * 64 + j;
;           const float f = lb[cc] + (1.f - lb[cc]) * sigmoid_f(bf2f(xr[st][cc][e]));
;           G[cc] += __logf(f);
;           const float eg = __expf(G[cc]), ig = __expf(-G[cc]);
;           Qp[tok * 512 + c] = f2bf(bf2f(qr[st][cc][e]) * eg);
;           const u16 kk = f2bf((1.f - f) * ig);
;           Kp[tok * 512 + c] = kk;
;           kb[e] = kk;
;         }
;         const int s0 = dir ? 56 - 8 * j8 : 8 * j8;
;         uint4 w;
;         w.x = dir ? (kb[7] | (kb[6] << 16)) : (kb[0] | (kb[1] << 16));
;         w.y = dir ? (kb[5] | (kb[4] << 16)) : (kb[2] | (kb[3] << 16));
;         w.z = dir ? (kb[3] | (kb[2] << 16)) : (kb[4] | (kb[5] << 16));
;         w.w = dir ? (kb[1] | (kb[0] << 16)) : (kb[6] | (kb[7] << 16));
;         *(uint4*)(KT + (((size_t)cidx * 2 + dir) * 512 + c) * 64 + s0) = w;
	v_log_f32_e32 v93, v93
	v_log_f32_e32 v94, v94
	v_log_f32_e32 v95, v95
	v_mul_f32_e32 v100, 0x3f317217, v92
	v_mul_f32_e32 v101, 0x3f317217, v93
	v_mul_f32_e32 v102, 0x3f317217, v94
	v_mul_f32_e32 v103, 0x3f317217, v95
	v_fma_f32 v100, v92, s31, -v100
	v_fma_f32 v101, v93, s31, -v101
	v_fma_f32 v102, v94, s31, -v102
	v_fma_f32 v103, v95, s31, -v103
	v_fmac_f32_e32 v100, 0x3377d1cf, v92
	v_fmac_f32_e32 v101, 0x3377d1cf, v93
	v_fmac_f32_e32 v102, 0x3377d1cf, v94
	v_fmac_f32_e32 v103, 0x3377d1cf, v95
	v_fmac_f32_e32 v100, 0x3f317217, v92
	v_fmac_f32_e32 v101, 0x3f317217, v93
	v_fmac_f32_e32 v102, 0x3f317217, v94
	v_fmac_f32_e32 v103, 0x3f317217, v95
	v_cmp_lt_f32_e64 vcc, |v92|, s34
	v_cndmask_b32_e32 v92, v92, v100, vcc
	v_cmp_lt_f32_e64 vcc, |v93|, s34
	v_cndmask_b32_e32 v93, v93, v101, vcc
	v_cmp_lt_f32_e64 vcc, |v94|, s34
	v_cndmask_b32_e32 v94, v94, v102, vcc
	v_cmp_lt_f32_e64 vcc, |v95|, s34
	v_cndmask_b32_e32 v95, v95, v103, vcc
	v_cndmask_b32_e64 v100, 0, v213, s[22:23]
	v_cndmask_b32_e64 v101, 0, v213, s[24:25]
	v_cndmask_b32_e64 v102, 0, v213, s[26:27]
	v_cndmask_b32_e64 v103, 0, v213, s[28:29]
	v_sub_f32_e32 v92, v92, v100
	v_sub_f32_e32 v93, v93, v101
	v_sub_f32_e32 v94, v94, v102
	v_sub_f32_e32 v95, v95, v103
	v_add_f32_e32 v64, v64, v92
	v_add_f32_e32 v65, v65, v93
	v_add_f32_e32 v66, v66, v94
	v_add_f32_e32 v67, v67, v95
	v_mul_f32_e32 v92, 0xbfb8aa3b, v64
	v_mul_f32_e32 v93, 0xbfb8aa3b, v65
	v_mul_f32_e32 v94, 0xbfb8aa3b, v66
	v_mul_f32_e32 v95, 0xbfb8aa3b, v67
	v_mul_f32_e32 v100, 0x3fb8aa3b, v64
	v_mul_f32_e32 v101, 0x3fb8aa3b, v65
	v_mul_f32_e32 v102, 0x3fb8aa3b, v66
	v_mul_f32_e32 v103, 0x3fb8aa3b, v67
	v_exp_f32_e32 v92, v92
	v_exp_f32_e32 v93, v93
	v_exp_f32_e32 v94, v94
	v_exp_f32_e32 v95, v95
	v_exp_f32_e32 v100, v100
	v_exp_f32_e32 v101, v101
	v_exp_f32_e32 v102, v102
	v_exp_f32_e32 v103, v103
	v_sub_f32_e32 v96, 1.0, v96
	v_sub_f32_e32 v97, 1.0, v97
	v_sub_f32_e32 v98, 1.0, v98
	v_sub_f32_e32 v99, 1.0, v99
	v_mul_f32_e32 v96, v96, v92
	v_mul_f32_e32 v97, v97, v93
	v_mul_f32_e32 v98, v98, v94
	v_mul_f32_e32 v99, v99, v95
	v_lshlrev_b32_e32 v92, 16, v62
	v_and_b32_e32 v93, 0xffff0000, v62
	v_lshlrev_b32_e32 v94, 16, v63
	v_and_b32_e32 v95, 0xffff0000, v63
	v_mul_f32_e32 v92, v92, v100
	v_mul_f32_e32 v93, v93, v101
	v_mul_f32_e32 v94, v94, v102
	v_mul_f32_e32 v95, v95, v103
	v_cvt_pk_bf16_f32 v116, v96, v116
	v_cvt_pk_bf16_f32 v132, v97, v132
	v_cvt_pk_bf16_f32 v166, v98, v166
	v_cvt_pk_bf16_f32 v182, v99, v182
	v_cvt_pk_bf16_f32 v92, v92, v93
	v_cvt_pk_bf16_f32 v93, v94, v95
	v_cvt_pk_bf16_f32 v96, v96, v97
	v_cvt_pk_bf16_f32 v97, v98, v99
	global_store_dwordx2 v112, v[92:93], s[2:3]
	global_store_dwordx2 v114, v[96:97], s[2:3]
	s_sub_u32 s2, s2, 0x400
	s_subb_u32 s3, s3, 0
	global_load_dwordx2 v[32:33], v113, s[0:1]
	global_load_dwordx2 v[34:35], v112, s[0:1]
	s_sub_u32 s0, s0, 0x1400
	s_subb_u32 s1, s1, 0
	global_load_dwordx2 v[36:37], v113, s[0:1]
	global_load_dwordx2 v[38:39], v112, s[0:1]
	s_sub_u32 s0, s0, 0x1400
	s_subb_u32 s1, s1, 0
	global_load_dwordx2 v[40:41], v113, s[0:1]
	global_load_dwordx2 v[42:43], v112, s[0:1]
	s_sub_u32 s0, s0, 0x1400
	s_subb_u32 s1, s1, 0
	global_load_dwordx2 v[44:45], v113, s[0:1]
	global_load_dwordx2 v[46:47], v112, s[0:1]
	s_sub_u32 s0, s0, 0x1400
	s_subb_u32 s1, s1, 0
	global_load_dwordx2 v[48:49], v113, s[0:1]
	global_load_dwordx2 v[50:51], v112, s[0:1]
	s_sub_u32 s0, s0, 0x1400
	s_subb_u32 s1, s1, 0
	global_load_dwordx2 v[52:53], v113, s[0:1]
	global_load_dwordx2 v[54:55], v112, s[0:1]
	s_sub_u32 s0, s0, 0x1400
	s_subb_u32 s1, s1, 0
	global_load_dwordx2 v[56:57], v113, s[0:1]
	global_load_dwordx2 v[58:59], v112, s[0:1]
	s_sub_u32 s0, s0, 0x1400
	s_subb_u32 s1, s1, 0
	global_load_dwordx2 v[60:61], v113, s[0:1]
	global_load_dwordx2 v[62:63], v112, s[0:1]
	s_sub_u32 s0, s0, 0x1400
	s_subb_u32 s1, s1, 0
	s_cmp_eq_u32 s35, 0
	s_cbranch_scc0 .Lp15_d1_nopark
	v_mov_b32_e32 v148, v116
	v_mov_b32_e32 v149, v117
	v_mov_b32_e32 v150, v118
	v_mov_b32_e32 v151, v119
	v_mov_b32_e32 v152, v120
	v_mov_b32_e32 v153, v121
	v_mov_b32_e32 v154, v122
	v_mov_b32_e32 v155, v123
	v_mov_b32_e32 v156, v124
	v_mov_b32_e32 v157, v125
	v_mov_b32_e32 v158, v126
	v_mov_b32_e32 v159, v127
	v_mov_b32_e32 v198, v128
	v_mov_b32_e32 v199, v129
	v_mov_b32_e32 v200, v130
	v_mov_b32_e32 v201, v131
	v_mov_b32_e32 v222, v132
	v_mov_b32_e32 v223, v133
	v_mov_b32_e32 v224, v134
	v_mov_b32_e32 v225, v135
	v_mov_b32_e32 v226, v136
	v_mov_b32_e32 v227, v137
	v_mov_b32_e32 v228, v138
	v_mov_b32_e32 v229, v139
	v_mov_b32_e32 v230, v140
	v_mov_b32_e32 v231, v141
	v_mov_b32_e32 v232, v142
	v_mov_b32_e32 v233, v143
	v_mov_b32_e32 v234, v144
	v_mov_b32_e32 v235, v145
	v_mov_b32_e32 v236, v146
	v_mov_b32_e32 v237, v147
	v_mov_b32_e32 v238, v166
	v_mov_b32_e32 v239, v167
	v_mov_b32_e32 v240, v168
	v_mov_b32_e32 v241, v169
	v_mov_b32_e32 v242, v170
	v_mov_b32_e32 v243, v171
	v_mov_b32_e32 v244, v172
	v_mov_b32_e32 v245, v173
	v_mov_b32_e32 v76, v174
	v_mov_b32_e32 v77, v175
	v_mov_b32_e32 v78, v176
	v_mov_b32_e32 v79, v177
	v_mov_b32_e32 v80, v178
	v_mov_b32_e32 v81, v179
	v_mov_b32_e32 v82, v180
	v_mov_b32_e32 v83, v181
	v_mov_b32_e32 v84, v182
	v_mov_b32_e32 v85, v183
	v_mov_b32_e32 v86, v184
	v_mov_b32_e32 v87, v185
	v_mov_b32_e32 v88, v186
	v_mov_b32_e32 v89, v187
	v_mov_b32_e32 v90, v188
	v_mov_b32_e32 v91, v189
	v_mov_b32_e32 v104, v190
	v_mov_b32_e32 v105, v191
	v_mov_b32_e32 v106, v192
	v_mov_b32_e32 v107, v193
	v_mov_b32_e32 v108, v194
	v_mov_b32_e32 v109, v195
	v_mov_b32_e32 v110, v196
	v_mov_b32_e32 v111, v197
; DEV void phase_p15(const Params& p, int g) {
;     ...
;         const int s0 = dir ? 56 - 8 * j8 : 8 * j8;
;         uint4 w;
;         w.x = dir ? (kb[7] | (kb[6] << 16)) : (kb[0] | (kb[1] << 16));
;         w.y = dir ? (kb[5] | (kb[4] << 16)) : (kb[2] | (kb[3] << 16));
;         w.z = dir ? (kb[3] | (kb[2] << 16)) : (kb[4] | (kb[5] << 16));
;         w.w = dir ? (kb[1] | (kb[0] << 16)) : (kb[6] | (kb[7] << 16));
;         *(uint4*)(KT + (((size_t)cidx * 2 + dir) * 512 + c) * 64 + s0) = w;
.Lp15_d1_nopark:
	s_add_u32 s35, s35, 1
	s_cmp_lt_u32 s35, 2
	s_cbranch_scc1 .Lp15_d1_loop
	global_store_dwordx4 v115, v[116:119], s[4:5]
	global_store_dwordx4 v115, v[120:123], s[4:5] offset:16
	global_store_dwordx4 v115, v[124:127], s[4:5] offset:32
	global_store_dwordx4 v115, v[128:131], s[4:5] offset:48
	global_store_dwordx4 v115, v[148:151], s[4:5] offset:64
	global_store_dwordx4 v115, v[152:155], s[4:5] offset:80
	global_store_dwordx4 v115, v[156:159], s[4:5] offset:96
	global_store_dwordx4 v115, v[198:201], s[4:5] offset:112
	global_store_dwordx4 v115, v[132:135], s[4:5] offset:128
	global_store_dwordx4 v115, v[136:139], s[4:5] offset:144
	global_store_dwordx4 v115, v[140:143], s[4:5] offset:160
	global_store_dwordx4 v115, v[144:147], s[4:5] offset:176
	global_store_dwordx4 v115, v[222:225], s[4:5] offset:192
	global_store_dwordx4 v115, v[226:229], s[4:5] offset:208
	global_store_dwordx4 v115, v[230:233], s[4:5] offset:224
	global_store_dwordx4 v115, v[234:237], s[4:5] offset:240
	global_store_dwordx4 v115, v[166:169], s[4:5] offset:256
	global_store_dwordx4 v115, v[170:173], s[4:5] offset:272
	global_store_dwordx4 v115, v[174:177], s[4:5] offset:288
	global_store_dwordx4 v115, v[178:181], s[4:5] offset:304
	global_store_dwordx4 v115, v[238:241], s[4:5] offset:320
	global_store_dwordx4 v115, v[242:245], s[4:5] offset:336
	global_store_dwordx4 v115, v[76:79], s[4:5] offset:352
	global_store_dwordx4 v115, v[80:83], s[4:5] offset:368
	global_store_dwordx4 v115, v[182:185], s[4:5] offset:384
	global_store_dwordx4 v115, v[186:189], s[4:5] offset:400
	global_store_dwordx4 v115, v[190:193], s[4:5] offset:416
	global_store_dwordx4 v115, v[194:197], s[4:5] offset:432
	global_store_dwordx4 v115, v[84:87], s[4:5] offset:448
	global_store_dwordx4 v115, v[88:91], s[4:5] offset:464
	global_store_dwordx4 v115, v[104:107], s[4:5] offset:480
	global_store_dwordx4 v115, v[108:111], s[4:5] offset:496
